# GEMM loops: DMA addresses for the next half are formed during the current MFMAs so the 8 LDS-DMA loads issue right after the barrier
# speedup vs baseline: 1.0994x; 1.0125x over previous
.LBB0_281:
	s_mul_hi_i32 s4, s36, 0x38e38e39
	s_lshr_b32 s8, s4, 31
	s_ashr_i32 s4, s4, 4
	s_add_i32 s4, s4, s8
	s_mul_i32 s8, s4, 0x48
	s_sub_i32 s8, s36, s8
	s_lshl_b32 s8, s8, 7
	v_add_u32_e32 v0, s8, v120
	v_ashrrev_i32_e32 v1, 31, v0
	v_lshlrev_b64 v[32:33], 12, v[0:1]
	v_lshl_add_u64 v[34:35], v[98:99], 0, v[32:33]
	v_add_co_u32_e32 v40, vcc, s87, v34
	s_lshl_b32 s9, s4, 7
	s_nop 0
	v_addc_co_u32_e32 v41, vcc, 0, v35, vcc
	v_add_co_u32_e32 v42, vcc, s66, v34
	v_add_u32_e32 v0, s9, v120
	s_nop 0
	v_addc_co_u32_e32 v43, vcc, 0, v35, vcc
	v_ashrrev_i32_e32 v1, 31, v0
	v_add_co_u32_e32 v44, vcc, s20, v34
	v_lshlrev_b64 v[36:37], 12, v[0:1]
	s_nop 0
	v_addc_co_u32_e32 v45, vcc, 0, v35, vcc
	v_lshl_add_u64 v[38:39], v[100:101], 0, v[36:37]
	v_readfirstlane_b32 s100, v112
	s_nop 3
	s_add_u32 m0, s100, 0x0
	s_nop 0
	global_load_lds_dwordx4 v[34:35], off
	s_add_u32 m0, s100, 0x1000
	s_nop 0
	global_load_lds_dwordx4 v[40:41], off
	s_add_u32 m0, s100, 0x2000
	s_nop 0
	global_load_lds_dwordx4 v[42:43], off
	s_add_u32 m0, s100, 0x3000
	s_nop 0
	global_load_lds_dwordx4 v[44:45], off
	s_add_u32 m0, s100, 0x4000
	s_nop 0
	global_load_lds_dwordx4 v[38:39], off
	v_add_co_u32_e32 v46, vcc, s87, v38
	v_lshl_add_u64 v[104:105], v[102:103], 0, v[36:37]
	s_nop 0
	v_addc_co_u32_e32 v47, vcc, 0, v39, vcc
	v_add_co_u32_e32 v48, vcc, s66, v38
	s_add_u32 m0, s100, 0x5000
	s_nop 0
	global_load_lds_dwordx4 v[46:47], off
	s_nop 0
	v_addc_co_u32_e32 v49, vcc, 0, v39, vcc
	v_add_co_u32_e32 v50, vcc, s20, v38
	s_add_u32 m0, s100, 0x6000
	s_nop 0
	global_load_lds_dwordx4 v[48:49], off
	s_nop 0
	v_addc_co_u32_e32 v51, vcc, 0, v39, vcc
	s_add_u32 m0, s100, 0x7000
	s_nop 0
	global_load_lds_dwordx4 v[50:51], off
	v_lshl_add_u64 v[106:107], v[102:103], 0, v[32:33]
	s_mov_b64 s[34:35], 0
	v_mov_b32_e32 v0, 0
	v_mov_b32_e32 v1, v0
	v_mov_b32_e32 v2, v0
	v_mov_b32_e32 v3, v0
	v_mov_b32_e32 v4, v0
	v_mov_b32_e32 v5, v0
	v_mov_b32_e32 v6, v0
	v_mov_b32_e32 v7, v0
	v_mov_b32_e32 v8, v0
	v_mov_b32_e32 v9, v0
	v_mov_b32_e32 v10, v0
	v_mov_b32_e32 v11, v0
	v_mov_b32_e32 v12, v0
	v_mov_b32_e32 v13, v0
	v_mov_b32_e32 v14, v0
	v_mov_b32_e32 v15, v0
	v_mov_b32_e32 v16, v0
	v_mov_b32_e32 v17, v0
	v_mov_b32_e32 v18, v0
	v_mov_b32_e32 v19, v0
	v_mov_b32_e32 v20, v0
	v_mov_b32_e32 v21, v0
	v_mov_b32_e32 v22, v0
	v_mov_b32_e32 v23, v0
	v_mov_b32_e32 v24, v0
	v_mov_b32_e32 v25, v0
	v_mov_b32_e32 v26, v0
	v_mov_b32_e32 v27, v0
	v_mov_b32_e32 v28, v0
	v_mov_b32_e32 v29, v0
	v_mov_b32_e32 v30, v0
	v_mov_b32_e32 v31, v0
	v_mov_b32_e32 v32, v0
	v_mov_b32_e32 v33, v0
	v_mov_b32_e32 v34, v0
	v_mov_b32_e32 v35, v0
	v_mov_b32_e32 v36, v0
	v_mov_b32_e32 v37, v0
	v_mov_b32_e32 v38, v0
	v_mov_b32_e32 v39, v0
	v_mov_b32_e32 v40, v0
	v_mov_b32_e32 v41, v0
	v_mov_b32_e32 v42, v0
	v_mov_b32_e32 v43, v0
	v_mov_b32_e32 v44, v0
	v_mov_b32_e32 v45, v0
	v_mov_b32_e32 v46, v0
	v_mov_b32_e32 v47, v0
	v_mov_b32_e32 v48, v0
	v_mov_b32_e32 v49, v0
	v_mov_b32_e32 v50, v0
	v_mov_b32_e32 v51, v0
	v_mov_b32_e32 v52, v0
	v_mov_b32_e32 v53, v0
	v_mov_b32_e32 v54, v0
	v_mov_b32_e32 v55, v0
	v_mov_b32_e32 v56, v0
	v_mov_b32_e32 v57, v0
	v_mov_b32_e32 v58, v0
	v_mov_b32_e32 v59, v0
	v_mov_b32_e32 v60, v0
	v_mov_b32_e32 v61, v0
	v_mov_b32_e32 v62, v0
	v_mov_b32_e32 v63, v0
	v_lshl_add_u64 v[144:145], v[106:107], 0, s[34:35]
	v_add_co_u32_e32 v134, vcc, s21, v144
	v_lshl_add_u64 v[146:147], v[104:105], 0, s[34:35]
	s_nop 0
	v_addc_co_u32_e32 v135, vcc, 0, v145, vcc
	v_add_co_u32_e32 v152, vcc, s74, v144
	s_mov_b32 s4, 0x38380000
	s_nop 0
	v_addc_co_u32_e32 v153, vcc, 0, v145, vcc
	v_add_co_u32_e32 v154, vcc, s75, v144
	v_addc_co_u32_e32 v155, vcc, 0, v145, vcc
	v_add_co_u32_e32 v156, vcc, s14, v144
	s_nop 1
	v_addc_co_u32_e32 v157, vcc, 0, v145, vcc
	v_add_co_u32_e32 v178, vcc, s4, v146
	s_mov_b32 s4, 0x383a0000
	s_nop 0
	v_addc_co_u32_e32 v179, vcc, 0, v147, vcc
	v_add_co_u32_e32 v180, vcc, s4, v146
	s_mov_b32 s4, 0x383c0000
	s_nop 0
	v_addc_co_u32_e32 v181, vcc, 0, v147, vcc
	v_add_co_u32_e32 v182, vcc, s4, v146
	s_mov_b32 s4, 0x383e0000
	s_nop 0
	v_addc_co_u32_e32 v183, vcc, 0, v147, vcc
	v_add_co_u32_e32 v184, vcc, s4, v146
	v_addc_co_u32_e32 v185, vcc, 0, v147, vcc
	v_lshl_add_u64 v[134:135], 8, 4, v[134:135]
	v_lshl_add_u64 v[152:153], 8, 4, v[152:153]
	v_lshl_add_u64 v[154:155], 8, 4, v[154:155]
	v_lshl_add_u64 v[156:157], 8, 4, v[156:157]
	v_lshl_add_u64 v[178:179], 8, 4, v[178:179]
	v_lshl_add_u64 v[180:181], 8, 4, v[180:181]
	v_lshl_add_u64 v[182:183], 8, 4, v[182:183]
	v_lshl_add_u64 v[184:185], 8, 4, v[184:185]
	v_and_b32_e32 v130, 15, v143
	v_lshrrev_b32_e32 v131, 1, v130
	v_bfe_u32 v123, v143, 4, 2
	v_xor_b32_e32 v131, v131, v123
	v_lshlrev_b32_e32 v131, 4, v131
	v_lshl_add_u32 v131, v130, 7, v131
	v_lshrrev_b32_e32 v130, 6, v143
	v_lshrrev_b32_e32 v121, 1, v130
	v_and_b32_e32 v130, 1, v130
	v_lshl_add_u32 v121, v121, 13, v131
	v_lshl_add_u32 v122, v130, 13, v131
	v_add_u32_e32 v122, 0x4000, v122
	v_xor_b32_e32 v123, 64, v121
	v_xor_b32_e32 v124, 64, v122
	s_waitcnt vmcnt(0) lgkmcnt(0)
	s_barrier
.LBB0_282:
	s_add_u32 m0, s100, 0x8000
	s_nop 0
	global_load_lds_dwordx4 v[134:135], off
	s_add_u32 m0, s100, 0x9000
	s_nop 0
	global_load_lds_dwordx4 v[152:153], off
	s_add_u32 m0, s100, 0xa000
	s_nop 0
	global_load_lds_dwordx4 v[154:155], off
	s_add_u32 m0, s100, 0xb000
	s_nop 0
	global_load_lds_dwordx4 v[156:157], off
	s_add_u32 m0, s100, 0xc000
	s_nop 0
	global_load_lds_dwordx4 v[178:179], off
	s_add_u32 m0, s100, 0xd000
	s_nop 0
	global_load_lds_dwordx4 v[180:181], off
	s_add_u32 m0, s100, 0xe000
	s_nop 0
	global_load_lds_dwordx4 v[182:183], off
	s_add_u32 m0, s100, 0xf000
	s_nop 0
	global_load_lds_dwordx4 v[184:185], off
	ds_read_b128 a[0:3], v121
	ds_read_b128 v[80:83], v122
	ds_read_b128 a[4:7], v121 offset:2048
	ds_read_b128 a[8:11], v121 offset:4096
	ds_read_b128 a[12:15], v121 offset:6144
	ds_read_b128 v[92:95], v122 offset:2048
	ds_read_b128 v[88:91], v122 offset:4096
	ds_read_b128 v[84:87], v122 offset:6144
	ds_read_b128 a[16:19], v123
	ds_read_b128 a[20:23], v123 offset:2048
	ds_read_b128 a[24:27], v123 offset:4096
	ds_read_b128 a[28:31], v123 offset:6144
	s_setprio 1
	s_waitcnt lgkmcnt(10)
	v_mfma_f32_16x16x32_bf16 v[0:3], a[0:3], v[80:83], v[0:3]
	s_waitcnt lgkmcnt(9)
	v_mfma_f32_16x16x32_bf16 v[16:19], a[4:7], v[80:83], v[16:19]
	s_waitcnt lgkmcnt(8)
	v_mfma_f32_16x16x32_bf16 v[32:35], a[8:11], v[80:83], v[32:35]
	s_waitcnt lgkmcnt(7)
	v_mfma_f32_16x16x32_bf16 v[48:51], a[12:15], v[80:83], v[48:51]
	ds_read_b128 v[80:83], v124
	s_waitcnt lgkmcnt(7)
	v_mfma_f32_16x16x32_bf16 v[4:7], a[0:3], v[92:95], v[4:7]
	v_lshl_add_u64 v[64:65], 8, 4, v[134:135]
	v_lshl_add_u64 v[66:67], 8, 4, v[152:153]
	v_lshl_add_u64 v[68:69], 8, 4, v[154:155]
	v_mfma_f32_16x16x32_bf16 v[20:23], a[4:7], v[92:95], v[20:23]
	v_lshl_add_u64 v[70:71], 8, 4, v[156:157]
	v_lshl_add_u64 v[76:77], 8, 4, v[178:179]
	v_lshl_add_u64 v[78:79], 8, 4, v[180:181]
	v_mfma_f32_16x16x32_bf16 v[36:39], a[8:11], v[92:95], v[36:39]
	v_lshl_add_u64 v[72:73], 8, 4, v[182:183]
	v_lshl_add_u64 v[74:75], 8, 4, v[184:185]
	v_mfma_f32_16x16x32_bf16 v[52:55], a[12:15], v[92:95], v[52:55]
	ds_read_b128 v[92:95], v124 offset:2048
	s_waitcnt lgkmcnt(7)
	v_mfma_f32_16x16x32_bf16 v[8:11], a[0:3], v[88:91], v[8:11]
	v_mfma_f32_16x16x32_bf16 v[24:27], a[4:7], v[88:91], v[24:27]
	v_mfma_f32_16x16x32_bf16 v[40:43], a[8:11], v[88:91], v[40:43]
	v_mfma_f32_16x16x32_bf16 v[56:59], a[12:15], v[88:91], v[56:59]
	ds_read_b128 v[88:91], v124 offset:4096
	s_waitcnt lgkmcnt(7)
	v_mfma_f32_16x16x32_bf16 v[12:15], a[0:3], v[84:87], v[12:15]
	v_mfma_f32_16x16x32_bf16 v[28:31], a[4:7], v[84:87], v[28:31]
	v_mfma_f32_16x16x32_bf16 v[44:47], a[8:11], v[84:87], v[44:47]
	v_mfma_f32_16x16x32_bf16 v[60:63], a[12:15], v[84:87], v[60:63]
	ds_read_b128 v[84:87], v124 offset:6144
	s_waitcnt lgkmcnt(3)
	v_mfma_f32_16x16x32_bf16 v[0:3], a[16:19], v[80:83], v[0:3]
	v_mfma_f32_16x16x32_bf16 v[16:19], a[20:23], v[80:83], v[16:19]
	v_mfma_f32_16x16x32_bf16 v[32:35], a[24:27], v[80:83], v[32:35]
	v_mfma_f32_16x16x32_bf16 v[48:51], a[28:31], v[80:83], v[48:51]
	s_waitcnt lgkmcnt(2)
	v_mfma_f32_16x16x32_bf16 v[4:7], a[16:19], v[92:95], v[4:7]
	v_mfma_f32_16x16x32_bf16 v[20:23], a[20:23], v[92:95], v[20:23]
	v_mfma_f32_16x16x32_bf16 v[36:39], a[24:27], v[92:95], v[36:39]
	v_mfma_f32_16x16x32_bf16 v[52:55], a[28:31], v[92:95], v[52:55]
	s_waitcnt lgkmcnt(1)
	v_mfma_f32_16x16x32_bf16 v[8:11], a[16:19], v[88:91], v[8:11]
	v_mfma_f32_16x16x32_bf16 v[24:27], a[20:23], v[88:91], v[24:27]
	v_mfma_f32_16x16x32_bf16 v[40:43], a[24:27], v[88:91], v[40:43]
	v_mfma_f32_16x16x32_bf16 v[56:59], a[28:31], v[88:91], v[56:59]
	s_waitcnt lgkmcnt(0)
	v_mfma_f32_16x16x32_bf16 v[12:15], a[16:19], v[84:87], v[12:15]
	v_mfma_f32_16x16x32_bf16 v[28:31], a[20:23], v[84:87], v[28:31]
	v_mfma_f32_16x16x32_bf16 v[44:47], a[24:27], v[84:87], v[44:47]
	v_mfma_f32_16x16x32_bf16 v[60:63], a[28:31], v[84:87], v[60:63]
	s_setprio 0
	s_waitcnt vmcnt(0) lgkmcnt(0)
	s_barrier
	s_add_u32 s34, s34, 0x100
	s_addc_u32 s35, s35, 0
	s_add_u32 m0, s100, 0x0
	s_nop 0
	global_load_lds_dwordx4 v[64:65], off
	s_add_u32 m0, s100, 0x1000
	s_nop 0
	global_load_lds_dwordx4 v[66:67], off
	s_add_u32 m0, s100, 0x2000
	s_nop 0
	global_load_lds_dwordx4 v[68:69], off
	s_add_u32 m0, s100, 0x3000
	s_nop 0
	global_load_lds_dwordx4 v[70:71], off
	s_add_u32 m0, s100, 0x4000
	s_nop 0
	global_load_lds_dwordx4 v[76:77], off
	s_add_u32 m0, s100, 0x5000
	s_nop 0
	global_load_lds_dwordx4 v[78:79], off
	s_add_u32 m0, s100, 0x6000
	s_nop 0
	global_load_lds_dwordx4 v[72:73], off
	s_add_u32 m0, s100, 0x7000
	s_nop 0
	global_load_lds_dwordx4 v[74:75], off
	ds_read_b128 a[0:3], v121 offset:32768
	ds_read_b128 v[80:83], v122 offset:32768
	ds_read_b128 a[4:7], v121 offset:34816
	ds_read_b128 a[8:11], v121 offset:36864
	ds_read_b128 a[12:15], v121 offset:38912
	ds_read_b128 v[92:95], v122 offset:34816
	ds_read_b128 v[88:91], v122 offset:36864
	ds_read_b128 v[84:87], v122 offset:38912
	ds_read_b128 a[16:19], v123 offset:32768
	ds_read_b128 a[20:23], v123 offset:34816
	ds_read_b128 a[24:27], v123 offset:36864
	ds_read_b128 a[28:31], v123 offset:38912
	s_setprio 1
	s_waitcnt lgkmcnt(10)
	v_mfma_f32_16x16x32_bf16 v[0:3], a[0:3], v[80:83], v[0:3]
	s_waitcnt lgkmcnt(9)
	v_mfma_f32_16x16x32_bf16 v[16:19], a[4:7], v[80:83], v[16:19]
	s_waitcnt lgkmcnt(8)
	v_mfma_f32_16x16x32_bf16 v[32:35], a[8:11], v[80:83], v[32:35]
	s_waitcnt lgkmcnt(7)
	v_mfma_f32_16x16x32_bf16 v[48:51], a[12:15], v[80:83], v[48:51]
	ds_read_b128 v[80:83], v124 offset:32768
	s_waitcnt lgkmcnt(7)
	v_mfma_f32_16x16x32_bf16 v[4:7], a[0:3], v[92:95], v[4:7]
	v_lshl_add_u64 v[144:145], v[106:107], 0, s[34:35]
	v_add_co_u32_e32 v134, vcc, s21, v144
	v_lshl_add_u64 v[146:147], v[104:105], 0, s[34:35]
	v_mfma_f32_16x16x32_bf16 v[20:23], a[4:7], v[92:95], v[20:23]
	s_nop 0
	v_addc_co_u32_e32 v135, vcc, 0, v145, vcc
	v_add_co_u32_e32 v152, vcc, s74, v144
	v_mfma_f32_16x16x32_bf16 v[36:39], a[8:11], v[92:95], v[36:39]
	s_mov_b32 s4, 0x38380000
	s_nop 0
	v_addc_co_u32_e32 v153, vcc, 0, v145, vcc
	v_mfma_f32_16x16x32_bf16 v[52:55], a[12:15], v[92:95], v[52:55]
	v_add_co_u32_e32 v154, vcc, s75, v144
	v_addc_co_u32_e32 v155, vcc, 0, v145, vcc
	v_add_co_u32_e32 v156, vcc, s14, v144
	ds_read_b128 v[92:95], v124 offset:34816
	s_waitcnt lgkmcnt(7)
	v_mfma_f32_16x16x32_bf16 v[8:11], a[0:3], v[88:91], v[8:11]
	s_nop 1
	v_addc_co_u32_e32 v157, vcc, 0, v145, vcc
	v_add_co_u32_e32 v178, vcc, s4, v146
	v_mfma_f32_16x16x32_bf16 v[24:27], a[4:7], v[88:91], v[24:27]
	s_mov_b32 s4, 0x383a0000
	s_nop 0
	v_addc_co_u32_e32 v179, vcc, 0, v147, vcc
	v_mfma_f32_16x16x32_bf16 v[40:43], a[8:11], v[88:91], v[40:43]
	v_add_co_u32_e32 v180, vcc, s4, v146
	s_mov_b32 s4, 0x383c0000
	s_nop 0
	v_mfma_f32_16x16x32_bf16 v[56:59], a[12:15], v[88:91], v[56:59]
	v_addc_co_u32_e32 v181, vcc, 0, v147, vcc
	v_add_co_u32_e32 v182, vcc, s4, v146
	s_mov_b32 s4, 0x383e0000
	ds_read_b128 v[88:91], v124 offset:36864
	s_waitcnt lgkmcnt(7)
	v_mfma_f32_16x16x32_bf16 v[12:15], a[0:3], v[84:87], v[12:15]
	s_nop 0
	v_addc_co_u32_e32 v183, vcc, 0, v147, vcc
	v_add_co_u32_e32 v184, vcc, s4, v146
	v_mfma_f32_16x16x32_bf16 v[28:31], a[4:7], v[84:87], v[28:31]
	v_addc_co_u32_e32 v185, vcc, 0, v147, vcc
	v_lshl_add_u64 v[134:135], 8, 4, v[134:135]
	v_lshl_add_u64 v[152:153], 8, 4, v[152:153]
	v_mfma_f32_16x16x32_bf16 v[44:47], a[8:11], v[84:87], v[44:47]
	v_lshl_add_u64 v[154:155], 8, 4, v[154:155]
	v_lshl_add_u64 v[156:157], 8, 4, v[156:157]
	v_lshl_add_u64 v[178:179], 8, 4, v[178:179]
	v_mfma_f32_16x16x32_bf16 v[60:63], a[12:15], v[84:87], v[60:63]
	v_lshl_add_u64 v[180:181], 8, 4, v[180:181]
	v_lshl_add_u64 v[182:183], 8, 4, v[182:183]
	v_lshl_add_u64 v[184:185], 8, 4, v[184:185]
	ds_read_b128 v[84:87], v124 offset:38912
	s_waitcnt lgkmcnt(3)
	v_mfma_f32_16x16x32_bf16 v[0:3], a[16:19], v[80:83], v[0:3]
	v_mfma_f32_16x16x32_bf16 v[16:19], a[20:23], v[80:83], v[16:19]
	v_mfma_f32_16x16x32_bf16 v[32:35], a[24:27], v[80:83], v[32:35]
	v_mfma_f32_16x16x32_bf16 v[48:51], a[28:31], v[80:83], v[48:51]
	s_waitcnt lgkmcnt(2)
	v_mfma_f32_16x16x32_bf16 v[4:7], a[16:19], v[92:95], v[4:7]
	v_mfma_f32_16x16x32_bf16 v[20:23], a[20:23], v[92:95], v[20:23]
	v_mfma_f32_16x16x32_bf16 v[36:39], a[24:27], v[92:95], v[36:39]
	v_mfma_f32_16x16x32_bf16 v[52:55], a[28:31], v[92:95], v[52:55]
	s_waitcnt lgkmcnt(1)
	v_mfma_f32_16x16x32_bf16 v[8:11], a[16:19], v[88:91], v[8:11]
	v_mfma_f32_16x16x32_bf16 v[24:27], a[20:23], v[88:91], v[24:27]
	v_mfma_f32_16x16x32_bf16 v[40:43], a[24:27], v[88:91], v[40:43]
	v_mfma_f32_16x16x32_bf16 v[56:59], a[28:31], v[88:91], v[56:59]
	s_waitcnt lgkmcnt(0)
	v_mfma_f32_16x16x32_bf16 v[12:15], a[16:19], v[84:87], v[12:15]
	v_mfma_f32_16x16x32_bf16 v[28:31], a[20:23], v[84:87], v[28:31]
	v_mfma_f32_16x16x32_bf16 v[44:47], a[24:27], v[84:87], v[44:47]
	v_mfma_f32_16x16x32_bf16 v[60:63], a[28:31], v[84:87], v[60:63]
	s_setprio 0
	s_waitcnt vmcnt(0) lgkmcnt(0)
	s_barrier
	s_cmpk_eq_i32 s34, 0xf00
	s_cbranch_scc0 .LBB0_282
	v_lshl_add_u64 v[64:65], 8, 4, v[64:65]
	v_lshl_add_u64 v[66:67], 8, 4, v[66:67]
	v_lshl_add_u64 v[68:69], 8, 4, v[68:69]
	v_lshl_add_u64 v[70:71], 8, 4, v[70:71]
	v_lshl_add_u64 v[76:77], 8, 4, v[76:77]
	v_lshl_add_u64 v[78:79], 8, 4, v[78:79]
	v_lshl_add_u64 v[72:73], 8, 4, v[72:73]
	v_lshl_add_u64 v[74:75], 8, 4, v[74:75]
	s_add_u32 m0, s100, 0x8000
	s_nop 0
	global_load_lds_dwordx4 v[64:65], off
	s_add_u32 m0, s100, 0x9000
	s_nop 0
	global_load_lds_dwordx4 v[66:67], off
	s_add_u32 m0, s100, 0xa000
	s_nop 0
	global_load_lds_dwordx4 v[68:69], off
	s_add_u32 m0, s100, 0xb000
	s_nop 0
	global_load_lds_dwordx4 v[70:71], off
	s_add_u32 m0, s100, 0xc000
	s_nop 0
	global_load_lds_dwordx4 v[76:77], off
	s_add_u32 m0, s100, 0xd000
	s_nop 0
	global_load_lds_dwordx4 v[78:79], off
	s_add_u32 m0, s100, 0xe000
	s_nop 0
	global_load_lds_dwordx4 v[72:73], off
	s_add_u32 m0, s100, 0xf000
	s_nop 0
	global_load_lds_dwordx4 v[74:75], off
	ds_read_b128 a[0:3], v121
	ds_read_b128 v[80:83], v122
	ds_read_b128 a[4:7], v121 offset:2048
	ds_read_b128 a[8:11], v121 offset:4096
	ds_read_b128 a[12:15], v121 offset:6144
	ds_read_b128 v[92:95], v122 offset:2048
	ds_read_b128 v[88:91], v122 offset:4096
	ds_read_b128 v[84:87], v122 offset:6144
	ds_read_b128 a[16:19], v123
	ds_read_b128 a[20:23], v123 offset:2048
	ds_read_b128 a[24:27], v123 offset:4096
	ds_read_b128 a[28:31], v123 offset:6144
	s_setprio 1
	s_waitcnt lgkmcnt(10)
	v_mfma_f32_16x16x32_bf16 v[0:3], a[0:3], v[80:83], v[0:3]
	s_waitcnt lgkmcnt(9)
	v_mfma_f32_16x16x32_bf16 v[16:19], a[4:7], v[80:83], v[16:19]
	s_waitcnt lgkmcnt(8)
	v_mfma_f32_16x16x32_bf16 v[32:35], a[8:11], v[80:83], v[32:35]
	s_waitcnt lgkmcnt(7)
	v_mfma_f32_16x16x32_bf16 v[48:51], a[12:15], v[80:83], v[48:51]
	ds_read_b128 v[80:83], v124
	s_waitcnt lgkmcnt(7)
	v_mfma_f32_16x16x32_bf16 v[4:7], a[0:3], v[92:95], v[4:7]
	v_mfma_f32_16x16x32_bf16 v[20:23], a[4:7], v[92:95], v[20:23]
	v_mfma_f32_16x16x32_bf16 v[36:39], a[8:11], v[92:95], v[36:39]
	v_mfma_f32_16x16x32_bf16 v[52:55], a[12:15], v[92:95], v[52:55]
	ds_read_b128 v[92:95], v124 offset:2048
	s_waitcnt lgkmcnt(7)
	v_mfma_f32_16x16x32_bf16 v[8:11], a[0:3], v[88:91], v[8:11]
	v_mfma_f32_16x16x32_bf16 v[24:27], a[4:7], v[88:91], v[24:27]
	v_mfma_f32_16x16x32_bf16 v[40:43], a[8:11], v[88:91], v[40:43]
	v_mfma_f32_16x16x32_bf16 v[56:59], a[12:15], v[88:91], v[56:59]
	ds_read_b128 v[88:91], v124 offset:4096
	s_waitcnt lgkmcnt(7)
	v_mfma_f32_16x16x32_bf16 v[12:15], a[0:3], v[84:87], v[12:15]
	v_mfma_f32_16x16x32_bf16 v[28:31], a[4:7], v[84:87], v[28:31]
	v_mfma_f32_16x16x32_bf16 v[44:47], a[8:11], v[84:87], v[44:47]
	v_mfma_f32_16x16x32_bf16 v[60:63], a[12:15], v[84:87], v[60:63]
	ds_read_b128 v[84:87], v124 offset:6144
	s_waitcnt lgkmcnt(3)
	v_mfma_f32_16x16x32_bf16 v[0:3], a[16:19], v[80:83], v[0:3]
	v_mfma_f32_16x16x32_bf16 v[16:19], a[20:23], v[80:83], v[16:19]
	v_mfma_f32_16x16x32_bf16 v[32:35], a[24:27], v[80:83], v[32:35]
	v_mfma_f32_16x16x32_bf16 v[48:51], a[28:31], v[80:83], v[48:51]
	s_waitcnt lgkmcnt(2)
	v_mfma_f32_16x16x32_bf16 v[4:7], a[16:19], v[92:95], v[4:7]
	v_mfma_f32_16x16x32_bf16 v[20:23], a[20:23], v[92:95], v[20:23]
	v_mfma_f32_16x16x32_bf16 v[36:39], a[24:27], v[92:95], v[36:39]
	v_mfma_f32_16x16x32_bf16 v[52:55], a[28:31], v[92:95], v[52:55]
	s_waitcnt lgkmcnt(1)
	v_mfma_f32_16x16x32_bf16 v[8:11], a[16:19], v[88:91], v[8:11]
	v_mfma_f32_16x16x32_bf16 v[24:27], a[20:23], v[88:91], v[24:27]
	v_mfma_f32_16x16x32_bf16 v[40:43], a[24:27], v[88:91], v[40:43]
	v_mfma_f32_16x16x32_bf16 v[56:59], a[28:31], v[88:91], v[56:59]
	s_waitcnt lgkmcnt(0)
	v_mfma_f32_16x16x32_bf16 v[12:15], a[16:19], v[84:87], v[12:15]
	v_mfma_f32_16x16x32_bf16 v[28:31], a[20:23], v[84:87], v[28:31]
	v_mfma_f32_16x16x32_bf16 v[44:47], a[24:27], v[84:87], v[44:47]
	v_mfma_f32_16x16x32_bf16 v[60:63], a[28:31], v[84:87], v[60:63]
	s_setprio 0
	s_waitcnt vmcnt(0) lgkmcnt(0)
	s_barrier
	ds_read_b128 a[0:3], v121 offset:32768
	ds_read_b128 v[80:83], v122 offset:32768
	ds_read_b128 a[4:7], v121 offset:34816
	ds_read_b128 a[8:11], v121 offset:36864
	ds_read_b128 a[12:15], v121 offset:38912
	ds_read_b128 v[92:95], v122 offset:34816
	ds_read_b128 v[88:91], v122 offset:36864
	ds_read_b128 v[84:87], v122 offset:38912
	ds_read_b128 a[16:19], v123 offset:32768
	ds_read_b128 a[20:23], v123 offset:34816
	ds_read_b128 a[24:27], v123 offset:36864
	ds_read_b128 a[28:31], v123 offset:38912
	s_setprio 1
	s_waitcnt lgkmcnt(10)
	v_mfma_f32_16x16x32_bf16 v[0:3], a[0:3], v[80:83], v[0:3]
	s_waitcnt lgkmcnt(9)
	v_mfma_f32_16x16x32_bf16 v[16:19], a[4:7], v[80:83], v[16:19]
	s_waitcnt lgkmcnt(8)
	v_mfma_f32_16x16x32_bf16 v[32:35], a[8:11], v[80:83], v[32:35]
	s_waitcnt lgkmcnt(7)
	v_mfma_f32_16x16x32_bf16 v[48:51], a[12:15], v[80:83], v[48:51]
	ds_read_b128 v[80:83], v124 offset:32768
	s_waitcnt lgkmcnt(7)
	v_mfma_f32_16x16x32_bf16 v[4:7], a[0:3], v[92:95], v[4:7]
	v_mfma_f32_16x16x32_bf16 v[20:23], a[4:7], v[92:95], v[20:23]
	v_mfma_f32_16x16x32_bf16 v[36:39], a[8:11], v[92:95], v[36:39]
	v_mfma_f32_16x16x32_bf16 v[52:55], a[12:15], v[92:95], v[52:55]
	ds_read_b128 v[92:95], v124 offset:34816
	s_waitcnt lgkmcnt(7)
	v_mfma_f32_16x16x32_bf16 v[8:11], a[0:3], v[88:91], v[8:11]
	v_mfma_f32_16x16x32_bf16 v[24:27], a[4:7], v[88:91], v[24:27]
	v_mfma_f32_16x16x32_bf16 v[40:43], a[8:11], v[88:91], v[40:43]
	v_mfma_f32_16x16x32_bf16 v[56:59], a[12:15], v[88:91], v[56:59]
	ds_read_b128 v[88:91], v124 offset:36864
	s_waitcnt lgkmcnt(7)
	v_mfma_f32_16x16x32_bf16 v[12:15], a[0:3], v[84:87], v[12:15]
	v_mfma_f32_16x16x32_bf16 v[28:31], a[4:7], v[84:87], v[28:31]
	v_mfma_f32_16x16x32_bf16 v[44:47], a[8:11], v[84:87], v[44:47]
	v_mfma_f32_16x16x32_bf16 v[60:63], a[12:15], v[84:87], v[60:63]
	ds_read_b128 v[84:87], v124 offset:38912
	s_waitcnt lgkmcnt(3)
	v_mfma_f32_16x16x32_bf16 v[0:3], a[16:19], v[80:83], v[0:3]
	v_mfma_f32_16x16x32_bf16 v[16:19], a[20:23], v[80:83], v[16:19]
	v_mfma_f32_16x16x32_bf16 v[32:35], a[24:27], v[80:83], v[32:35]
	v_mfma_f32_16x16x32_bf16 v[48:51], a[28:31], v[80:83], v[48:51]
	s_waitcnt lgkmcnt(2)
	v_mfma_f32_16x16x32_bf16 v[4:7], a[16:19], v[92:95], v[4:7]
	v_mfma_f32_16x16x32_bf16 v[20:23], a[20:23], v[92:95], v[20:23]
	v_mfma_f32_16x16x32_bf16 v[36:39], a[24:27], v[92:95], v[36:39]
	v_mfma_f32_16x16x32_bf16 v[52:55], a[28:31], v[92:95], v[52:55]
	s_waitcnt lgkmcnt(1)
	v_mfma_f32_16x16x32_bf16 v[8:11], a[16:19], v[88:91], v[8:11]
	v_mfma_f32_16x16x32_bf16 v[24:27], a[20:23], v[88:91], v[24:27]
	v_mfma_f32_16x16x32_bf16 v[40:43], a[24:27], v[88:91], v[40:43]
	v_mfma_f32_16x16x32_bf16 v[56:59], a[28:31], v[88:91], v[56:59]
	s_waitcnt lgkmcnt(0)
	v_mfma_f32_16x16x32_bf16 v[12:15], a[16:19], v[84:87], v[12:15]
	v_mfma_f32_16x16x32_bf16 v[28:31], a[20:23], v[84:87], v[28:31]
	v_mfma_f32_16x16x32_bf16 v[44:47], a[24:27], v[84:87], v[44:47]
	v_mfma_f32_16x16x32_bf16 v[60:63], a[28:31], v[84:87], v[60:63]
	s_setprio 0
	v_readfirstlane_b32 s15, v111
	v_readfirstlane_b32 s4, v110
	s_lshl_b32 s15, s15, 6
	s_waitcnt lgkmcnt(0)
	s_barrier
	s_add_i32 s15, s15, s9
	s_lshl_b32 s23, s4, 6
	s_add_i32 s23, s23, s8
	v_or_b32_e32 v67, s15, v109
	s_movk_i32 s4, 0x800
	s_ashr_i32 s22, s23, 11
	v_cmp_gt_i32_e32 vcc, s4, v67
	v_add_u32_e32 v65, 0x1000, v67
	v_add_u32_e32 v64, v67, v97
	v_lshl_or_b32 v66, s23, 11, v97
	s_barrier
	v_and_b32_e32 v130, 15, v143
	v_bfe_u32 v131, v143, 4, 2
	v_xor_b32_e32 v131, v131, v130
	v_lshlrev_b32_e32 v131, 4, v131
	v_lshl_add_u32 v131, v130, 8, v131
	v_lshrrev_b32_e32 v130, 6, v143
	v_lshl_add_u32 v131, v130, 14, v131
	ds_write_b128 v131, v[0:3]
	ds_write_b128 v131, v[4:7] offset:4096
	ds_write_b128 v131, v[8:11] offset:8192
	ds_write_b128 v131, v[12:15] offset:12288
	v_xor_b32_e32 v124, 64, v131
	ds_write_b128 v124, v[16:19]
	ds_write_b128 v124, v[20:23] offset:4096
	ds_write_b128 v124, v[24:27] offset:8192
	ds_write_b128 v124, v[28:31] offset:12288
	v_xor_b32_e32 v124, 128, v131
	ds_write_b128 v124, v[32:35]
	ds_write_b128 v124, v[36:39] offset:4096
	ds_write_b128 v124, v[40:43] offset:8192
	ds_write_b128 v124, v[44:47] offset:12288
	v_xor_b32_e32 v124, 192, v131
	ds_write_b128 v124, v[48:51]
	ds_write_b128 v124, v[52:55] offset:4096
	ds_write_b128 v124, v[56:59] offset:8192
	ds_write_b128 v124, v[60:63] offset:12288
	v_and_b32_e32 v121, 31, v143
	v_bfe_u32 v123, v143, 5, 1
	v_and_b32_e32 v131, 15, v121
	v_xor_b32_e32 v123, v123, v131
	v_lshlrev_b32_e32 v123, 4, v123
	v_lshl_add_u32 v123, v121, 8, v123
	v_lshl_add_u32 v123, v130, 14, v123
	ds_read_b128 v[48:51], v123
	ds_read_b128 v[32:35], v123 offset:8192
	v_xor_b32_e32 v122, 32, v123
	ds_read_b128 v[52:55], v122
	ds_read_b128 v[36:39], v122 offset:8192
	v_xor_b32_e32 v122, 64, v123
	ds_read_b128 v[56:59], v122
	ds_read_b128 v[40:43], v122 offset:8192
	v_xor_b32_e32 v122, 96, v123
	ds_read_b128 v[60:63], v122
	ds_read_b128 v[44:47], v122 offset:8192
	v_xor_b32_e32 v122, 128, v123
	ds_read_b128 v[16:19], v122
	ds_read_b128 v[0:3], v122 offset:8192
	v_xor_b32_e32 v122, 160, v123
	ds_read_b128 v[20:23], v122
	ds_read_b128 v[4:7], v122 offset:8192
	v_xor_b32_e32 v122, 192, v123
	ds_read_b128 v[24:27], v122
	ds_read_b128 v[8:11], v122 offset:8192
	v_xor_b32_e32 v122, 224, v123
	ds_read_b128 v[28:31], v122
	ds_read_b128 v[12:15], v122 offset:8192
	s_waitcnt lgkmcnt(0)
	s_barrier
	s_and_saveexec_b64 s[8:9], vcc
	s_cbranch_execz .LBB0_285
	s_add_i32 s4, s23, 0xffffe000
	s_lshr_b32 s4, s4, 3
	s_or_b32 s4, s4, 4
	s_cmpk_lt_i32 s23, 0x2000
	s_cselect_b32 s4, s22, s4
	s_mulk_i32 s4, 0x3000
	v_add_u32_e32 v68, s4, v65
	v_mov_b32_e32 v69, v140
	v_lshl_add_u64 v[68:69], v[68:69], 2, s[26:27]
	global_load_dword v72, v[68:69], off
	v_add_u32_e32 v68, v66, v67
	v_mov_b32_e32 v69, v140
	v_lshl_add_u64 v[70:71], v[68:69], 2, s[0:1]
	global_load_dword v69, v[70:71], off
	s_waitcnt vmcnt(0)
	v_fmac_f32_e32 v69, v48, v72
	global_store_dword v[70:71], v69, off
	v_add_u32_e32 v70, 0x800, v68
	v_mov_b32_e32 v71, v140
	v_lshl_add_u64 v[70:71], v[70:71], 2, s[0:1]
	global_load_dword v48, v[70:71], off
	s_waitcnt vmcnt(0)
	v_fmac_f32_e32 v48, v49, v72
	global_store_dword v[70:71], v48, off
	v_add_u32_e32 v48, 0x1000, v68
	v_mov_b32_e32 v49, v140
	v_lshl_add_u64 v[48:49], v[48:49], 2, s[0:1]
	global_load_dword v69, v[48:49], off
	s_waitcnt vmcnt(0)
	v_fmac_f32_e32 v69, v50, v72
	global_store_dword v[48:49], v69, off
	v_add_u32_e32 v48, 0x1800, v68
	v_mov_b32_e32 v49, v140
	v_lshl_add_u64 v[48:49], v[48:49], 2, s[0:1]
	global_load_dword v50, v[48:49], off
	s_waitcnt vmcnt(0)
	v_fmac_f32_e32 v50, v51, v72
	global_store_dword v[48:49], v50, off
	s_add_i32 s15, s23, 0xffffe008
	s_lshr_b32 s15, s15, 3
	s_or_b32 s4, s23, 8
	s_or_b32 s15, s15, 4
	s_cmpk_lt_i32 s4, 0x2000
	s_cselect_b32 s15, s22, s15
	s_mulk_i32 s15, 0x3000
	v_add_u32_e32 v48, s15, v65
	v_mov_b32_e32 v49, v140
	v_lshl_add_u64 v[48:49], v[48:49], 2, s[26:27]
	global_load_dword v68, v[48:49], off
	v_lshl_add_u32 v48, s4, 11, v64
	v_mov_b32_e32 v49, v140
	v_lshl_add_u64 v[50:51], v[48:49], 2, s[0:1]
	global_load_dword v49, v[50:51], off
	s_waitcnt vmcnt(0)
	v_fmac_f32_e32 v49, v52, v68
	global_store_dword v[50:51], v49, off
	v_add_u32_e32 v50, 0x800, v48
	v_mov_b32_e32 v51, v140
	v_lshl_add_u64 v[50:51], v[50:51], 2, s[0:1]
	global_load_dword v49, v[50:51], off
	s_waitcnt vmcnt(0)
	v_fmac_f32_e32 v49, v53, v68
	global_store_dword v[50:51], v49, off
	v_add_u32_e32 v50, 0x1000, v48
	v_mov_b32_e32 v51, v140
	v_lshl_add_u64 v[50:51], v[50:51], 2, s[0:1]
	global_load_dword v49, v[50:51], off
	v_add_u32_e32 v48, 0x1800, v48
	s_waitcnt vmcnt(0)
	v_fmac_f32_e32 v49, v54, v68
	global_store_dword v[50:51], v49, off
	v_mov_b32_e32 v49, v140
	v_lshl_add_u64 v[48:49], v[48:49], 2, s[0:1]
	global_load_dword v50, v[48:49], off
	s_waitcnt vmcnt(0)
	v_fmac_f32_e32 v50, v55, v68
	global_store_dword v[48:49], v50, off
	s_add_i32 s15, s23, 0xffffe010
	s_lshr_b32 s15, s15, 3
	s_or_b32 s4, s23, 16
	s_or_b32 s15, s15, 4
	s_cmpk_lt_i32 s4, 0x2000
	s_cselect_b32 s15, s22, s15
	s_mulk_i32 s15, 0x3000
	v_add_u32_e32 v48, s15, v65
	v_mov_b32_e32 v49, v140
	v_lshl_add_u64 v[48:49], v[48:49], 2, s[26:27]
	global_load_dword v52, v[48:49], off
	v_lshl_add_u32 v48, s4, 11, v64
	v_mov_b32_e32 v49, v140
	v_lshl_add_u64 v[50:51], v[48:49], 2, s[0:1]
	global_load_dword v49, v[50:51], off
	s_waitcnt vmcnt(0)
	v_fmac_f32_e32 v49, v56, v52
	global_store_dword v[50:51], v49, off
	v_add_u32_e32 v50, 0x800, v48
	v_mov_b32_e32 v51, v140
	v_lshl_add_u64 v[50:51], v[50:51], 2, s[0:1]
	global_load_dword v49, v[50:51], off
	s_waitcnt vmcnt(0)
	v_fmac_f32_e32 v49, v57, v52
	global_store_dword v[50:51], v49, off
	v_add_u32_e32 v50, 0x1000, v48
	v_mov_b32_e32 v51, v140
	v_lshl_add_u64 v[50:51], v[50:51], 2, s[0:1]
	global_load_dword v49, v[50:51], off
	v_add_u32_e32 v48, 0x1800, v48
	s_waitcnt vmcnt(0)
	v_fmac_f32_e32 v49, v58, v52
	global_store_dword v[50:51], v49, off
	v_mov_b32_e32 v49, v140
	v_lshl_add_u64 v[48:49], v[48:49], 2, s[0:1]
	global_load_dword v50, v[48:49], off
	s_waitcnt vmcnt(0)
	v_fmac_f32_e32 v50, v59, v52
	global_store_dword v[48:49], v50, off
	s_add_i32 s15, s23, 0xffffe018
	s_lshr_b32 s15, s15, 3
	s_or_b32 s4, s23, 24
	s_or_b32 s15, s15, 4
	s_cmpk_lt_i32 s4, 0x2000
	s_cselect_b32 s15, s22, s15
	s_mulk_i32 s15, 0x3000
	v_add_u32_e32 v48, s15, v65
	v_mov_b32_e32 v49, v140
	v_lshl_add_u64 v[48:49], v[48:49], 2, s[26:27]
	global_load_dword v52, v[48:49], off
	v_lshl_add_u32 v48, s4, 11, v64
	v_mov_b32_e32 v49, v140
	v_lshl_add_u64 v[50:51], v[48:49], 2, s[0:1]
	global_load_dword v49, v[50:51], off
	s_waitcnt vmcnt(0)
	v_fmac_f32_e32 v49, v60, v52
	global_store_dword v[50:51], v49, off
	v_add_u32_e32 v50, 0x800, v48
	v_mov_b32_e32 v51, v140
	v_lshl_add_u64 v[50:51], v[50:51], 2, s[0:1]
	global_load_dword v49, v[50:51], off
	s_waitcnt vmcnt(0)
	v_fmac_f32_e32 v49, v61, v52
	global_store_dword v[50:51], v49, off
	v_add_u32_e32 v50, 0x1000, v48
	v_mov_b32_e32 v51, v140
	v_lshl_add_u64 v[50:51], v[50:51], 2, s[0:1]
	global_load_dword v49, v[50:51], off
	v_add_u32_e32 v48, 0x1800, v48
	s_waitcnt vmcnt(0)
	v_fmac_f32_e32 v49, v62, v52
	global_store_dword v[50:51], v49, off
	v_mov_b32_e32 v49, v140
	v_lshl_add_u64 v[48:49], v[48:49], 2, s[0:1]
	global_load_dword v50, v[48:49], off
	s_waitcnt vmcnt(0)
	v_fmac_f32_e32 v50, v63, v52
	global_store_dword v[48:49], v50, off

.LBB0_582:
	s_mul_hi_i32 s4, s22, 0x38e38e39
	s_lshr_b32 s8, s4, 31
	s_ashr_i32 s4, s4, 4
	s_add_i32 s4, s4, s8
	s_mul_i32 s8, s4, 0x48
	s_sub_i32 s8, s22, s8
	v_lshl_add_u32 v0, s8, 7, v109
	v_ashrrev_i32_e32 v1, 31, v0
	v_lshlrev_b64 v[32:33], 12, v[0:1]
	v_lshl_add_u64 v[34:35], v[96:97], 0, v[32:33]
	v_add_co_u32_e32 v40, vcc, s87, v34
	s_lshl_b32 s9, s4, 7
	s_nop 0
	v_addc_co_u32_e32 v41, vcc, 0, v35, vcc
	v_add_co_u32_e32 v42, vcc, s66, v34
	v_add_u32_e32 v0, s9, v109
	s_nop 0
	v_addc_co_u32_e32 v43, vcc, 0, v35, vcc
	v_ashrrev_i32_e32 v1, 31, v0
	v_add_co_u32_e32 v44, vcc, s20, v34
	v_lshlrev_b64 v[36:37], 12, v[0:1]
	s_nop 0
	v_addc_co_u32_e32 v45, vcc, 0, v35, vcc
	v_lshl_add_u64 v[38:39], v[98:99], 0, v[36:37]
	v_readfirstlane_b32 s100, v110
	s_nop 3
	s_add_u32 m0, s100, 0x0
	s_nop 0
	global_load_lds_dwordx4 v[34:35], off
	s_add_u32 m0, s100, 0x1000
	s_nop 0
	global_load_lds_dwordx4 v[40:41], off
	s_add_u32 m0, s100, 0x2000
	s_nop 0
	global_load_lds_dwordx4 v[42:43], off
	s_add_u32 m0, s100, 0x3000
	s_nop 0
	global_load_lds_dwordx4 v[44:45], off
	s_add_u32 m0, s100, 0x4000
	s_nop 0
	global_load_lds_dwordx4 v[38:39], off
	v_add_co_u32_e32 v46, vcc, s87, v38
	v_lshl_add_u64 v[102:103], v[100:101], 0, v[36:37]
	s_nop 0
	v_addc_co_u32_e32 v47, vcc, 0, v39, vcc
	s_waitcnt vmcnt(16)
	v_add_co_u32_e32 v48, vcc, s66, v38
	s_add_u32 m0, s100, 0x5000
	s_nop 0
	global_load_lds_dwordx4 v[46:47], off
	s_nop 0
	v_addc_co_u32_e32 v49, vcc, 0, v39, vcc
	v_add_co_u32_e32 v50, vcc, s20, v38
	s_add_u32 m0, s100, 0x6000
	s_nop 0
	global_load_lds_dwordx4 v[48:49], off
	s_nop 0
	v_addc_co_u32_e32 v51, vcc, 0, v39, vcc
	s_add_u32 m0, s100, 0x7000
	s_nop 0
	global_load_lds_dwordx4 v[50:51], off
	v_lshl_add_u64 v[104:105], v[100:101], 0, v[32:33]
	s_mov_b64 s[28:29], 0
	v_mov_b32_e32 v0, 0
	v_mov_b32_e32 v1, v0
	v_mov_b32_e32 v2, v0
	v_mov_b32_e32 v3, v0
	v_mov_b32_e32 v4, v0
	v_mov_b32_e32 v5, v0
	v_mov_b32_e32 v6, v0
	v_mov_b32_e32 v7, v0
	v_mov_b32_e32 v8, v0
	v_mov_b32_e32 v9, v0
	v_mov_b32_e32 v10, v0
	v_mov_b32_e32 v11, v0
	v_mov_b32_e32 v12, v0
	v_mov_b32_e32 v13, v0
	v_mov_b32_e32 v14, v0
	v_mov_b32_e32 v15, v0
	v_mov_b32_e32 v16, v0
	v_mov_b32_e32 v17, v0
	v_mov_b32_e32 v18, v0
	v_mov_b32_e32 v19, v0
	v_mov_b32_e32 v20, v0
	v_mov_b32_e32 v21, v0
	v_mov_b32_e32 v22, v0
	v_mov_b32_e32 v23, v0
	v_mov_b32_e32 v24, v0
	v_mov_b32_e32 v25, v0
	v_mov_b32_e32 v26, v0
	v_mov_b32_e32 v27, v0
	v_mov_b32_e32 v28, v0
	v_mov_b32_e32 v29, v0
	v_mov_b32_e32 v30, v0
	v_mov_b32_e32 v31, v0
	v_mov_b32_e32 v32, v0
	v_mov_b32_e32 v33, v0
	v_mov_b32_e32 v34, v0
	v_mov_b32_e32 v35, v0
	v_mov_b32_e32 v36, v0
	v_mov_b32_e32 v37, v0
	v_mov_b32_e32 v38, v0
	v_mov_b32_e32 v39, v0
	v_mov_b32_e32 v40, v0
	v_mov_b32_e32 v41, v0
	v_mov_b32_e32 v42, v0
	v_mov_b32_e32 v43, v0
	v_mov_b32_e32 v44, v0
	v_mov_b32_e32 v45, v0
	v_mov_b32_e32 v46, v0
	v_mov_b32_e32 v47, v0
	v_mov_b32_e32 v48, v0
	v_mov_b32_e32 v49, v0
	v_mov_b32_e32 v50, v0
	v_mov_b32_e32 v51, v0
	v_mov_b32_e32 v52, v0
	v_mov_b32_e32 v53, v0
	v_mov_b32_e32 v54, v0
	v_mov_b32_e32 v55, v0
	v_mov_b32_e32 v56, v0
	v_mov_b32_e32 v57, v0
	v_mov_b32_e32 v58, v0
	v_mov_b32_e32 v59, v0
	v_mov_b32_e32 v60, v0
	v_mov_b32_e32 v61, v0
	v_mov_b32_e32 v62, v0
	v_mov_b32_e32 v63, v0
	v_lshl_add_u64 v[128:129], v[104:105], 0, s[28:29]
	s_mov_b32 s4, 0x15ab8000
	v_add_co_u32_e32 v144, vcc, s4, v128
	s_mov_b32 s4, 0x15ad8000
	s_nop 0
	v_addc_co_u32_e32 v145, vcc, 0, v129, vcc
	v_add_co_u32_e32 v146, vcc, s4, v128
	s_mov_b32 s4, 0x15af8000
	s_nop 0
	v_addc_co_u32_e32 v147, vcc, 0, v129, vcc
	v_add_co_u32_e32 v148, vcc, s4, v128
	s_mov_b32 s4, 0x15b18000
	s_nop 0
	v_addc_co_u32_e32 v149, vcc, 0, v129, vcc
	v_add_co_u32_e32 v150, vcc, s4, v128
	v_lshl_add_u64 v[130:131], v[102:103], 0, s[28:29]
	s_nop 0
	v_addc_co_u32_e32 v151, vcc, 0, v129, vcc
	s_mov_b32 s4, 0x36b80000
	v_add_co_u32_e32 v152, vcc, s4, v130
	s_mov_b32 s4, 0x36ba0000
	s_nop 0
	v_addc_co_u32_e32 v153, vcc, 0, v131, vcc
	v_add_co_u32_e32 v154, vcc, s4, v130
	s_mov_b32 s4, 0x36bc0000
	s_nop 0
	v_addc_co_u32_e32 v155, vcc, 0, v131, vcc
	v_add_co_u32_e32 v156, vcc, s4, v130
	s_mov_b32 s4, 0x36be0000
	s_nop 0
	v_addc_co_u32_e32 v157, vcc, 0, v131, vcc
	v_add_co_u32_e32 v178, vcc, s4, v130
	v_addc_co_u32_e32 v179, vcc, 0, v131, vcc
	v_lshl_add_u64 v[144:145], 8, 4, v[144:145]
	v_lshl_add_u64 v[146:147], 8, 4, v[146:147]
	v_lshl_add_u64 v[148:149], 8, 4, v[148:149]
	v_lshl_add_u64 v[150:151], 8, 4, v[150:151]
	v_lshl_add_u64 v[152:153], 8, 4, v[152:153]
	v_lshl_add_u64 v[154:155], 8, 4, v[154:155]
	v_lshl_add_u64 v[156:157], 8, 4, v[156:157]
	v_lshl_add_u64 v[178:179], 8, 4, v[178:179]
	v_and_b32_e32 v124, 15, v143
	v_lshrrev_b32_e32 v125, 1, v124
	v_bfe_u32 v117, v143, 4, 2
	v_xor_b32_e32 v125, v125, v117
	v_lshlrev_b32_e32 v125, 4, v125
	v_lshl_add_u32 v125, v124, 7, v125
	v_lshrrev_b32_e32 v124, 6, v143
	v_lshrrev_b32_e32 v115, 1, v124
	v_and_b32_e32 v124, 1, v124
	v_lshl_add_u32 v115, v115, 13, v125
	v_lshl_add_u32 v116, v124, 13, v125
	v_add_u32_e32 v116, 0x4000, v116
	v_xor_b32_e32 v117, 64, v115
	v_xor_b32_e32 v118, 64, v116
	s_waitcnt vmcnt(0) lgkmcnt(0)
	s_barrier
.LBB0_583:
	s_add_u32 m0, s100, 0x8000
	s_nop 0
	global_load_lds_dwordx4 v[144:145], off
	s_add_u32 m0, s100, 0x9000
	s_nop 0
	global_load_lds_dwordx4 v[146:147], off
	s_add_u32 m0, s100, 0xa000
	s_nop 0
	global_load_lds_dwordx4 v[148:149], off
	s_add_u32 m0, s100, 0xb000
	s_nop 0
	global_load_lds_dwordx4 v[150:151], off
	s_add_u32 m0, s100, 0xc000
	s_nop 0
	global_load_lds_dwordx4 v[152:153], off
	s_add_u32 m0, s100, 0xd000
	s_nop 0
	global_load_lds_dwordx4 v[154:155], off
	s_add_u32 m0, s100, 0xe000
	s_nop 0
	global_load_lds_dwordx4 v[156:157], off
	s_add_u32 m0, s100, 0xf000
	s_nop 0
	global_load_lds_dwordx4 v[178:179], off
	ds_read_b128 a[0:3], v115
	ds_read_b128 v[80:83], v116
	ds_read_b128 a[4:7], v115 offset:2048
	ds_read_b128 a[8:11], v115 offset:4096
	ds_read_b128 a[12:15], v115 offset:6144
	ds_read_b128 v[92:95], v116 offset:2048
	ds_read_b128 v[88:91], v116 offset:4096
	ds_read_b128 v[84:87], v116 offset:6144
	ds_read_b128 a[16:19], v117
	ds_read_b128 a[20:23], v117 offset:2048
	ds_read_b128 a[24:27], v117 offset:4096
	ds_read_b128 a[28:31], v117 offset:6144
	s_setprio 1
	s_waitcnt lgkmcnt(10)
	v_mfma_f32_16x16x32_bf16 v[0:3], a[0:3], v[80:83], v[0:3]
	s_waitcnt lgkmcnt(9)
	v_mfma_f32_16x16x32_bf16 v[16:19], a[4:7], v[80:83], v[16:19]
	s_waitcnt lgkmcnt(8)
	v_mfma_f32_16x16x32_bf16 v[32:35], a[8:11], v[80:83], v[32:35]
	s_waitcnt lgkmcnt(7)
	v_mfma_f32_16x16x32_bf16 v[48:51], a[12:15], v[80:83], v[48:51]
	ds_read_b128 v[80:83], v118
	s_waitcnt lgkmcnt(7)
	v_mfma_f32_16x16x32_bf16 v[4:7], a[0:3], v[92:95], v[4:7]
	v_lshl_add_u64 v[64:65], 8, 4, v[144:145]
	v_lshl_add_u64 v[66:67], 8, 4, v[146:147]
	v_lshl_add_u64 v[68:69], 8, 4, v[148:149]
	v_mfma_f32_16x16x32_bf16 v[20:23], a[4:7], v[92:95], v[20:23]
	v_lshl_add_u64 v[70:71], 8, 4, v[150:151]
	v_lshl_add_u64 v[76:77], 8, 4, v[152:153]
	v_lshl_add_u64 v[78:79], 8, 4, v[154:155]
	v_mfma_f32_16x16x32_bf16 v[36:39], a[8:11], v[92:95], v[36:39]
	v_lshl_add_u64 v[72:73], 8, 4, v[156:157]
	v_lshl_add_u64 v[74:75], 8, 4, v[178:179]
	v_mfma_f32_16x16x32_bf16 v[52:55], a[12:15], v[92:95], v[52:55]
	ds_read_b128 v[92:95], v118 offset:2048
	s_waitcnt lgkmcnt(7)
	v_mfma_f32_16x16x32_bf16 v[8:11], a[0:3], v[88:91], v[8:11]
	v_mfma_f32_16x16x32_bf16 v[24:27], a[4:7], v[88:91], v[24:27]
	v_mfma_f32_16x16x32_bf16 v[40:43], a[8:11], v[88:91], v[40:43]
	v_mfma_f32_16x16x32_bf16 v[56:59], a[12:15], v[88:91], v[56:59]
	ds_read_b128 v[88:91], v118 offset:4096
	s_waitcnt lgkmcnt(7)
	v_mfma_f32_16x16x32_bf16 v[12:15], a[0:3], v[84:87], v[12:15]
	v_mfma_f32_16x16x32_bf16 v[28:31], a[4:7], v[84:87], v[28:31]
	v_mfma_f32_16x16x32_bf16 v[44:47], a[8:11], v[84:87], v[44:47]
	v_mfma_f32_16x16x32_bf16 v[60:63], a[12:15], v[84:87], v[60:63]
	ds_read_b128 v[84:87], v118 offset:6144
	s_waitcnt lgkmcnt(3)
	v_mfma_f32_16x16x32_bf16 v[0:3], a[16:19], v[80:83], v[0:3]
	v_mfma_f32_16x16x32_bf16 v[16:19], a[20:23], v[80:83], v[16:19]
	v_mfma_f32_16x16x32_bf16 v[32:35], a[24:27], v[80:83], v[32:35]
	v_mfma_f32_16x16x32_bf16 v[48:51], a[28:31], v[80:83], v[48:51]
	s_waitcnt lgkmcnt(2)
	v_mfma_f32_16x16x32_bf16 v[4:7], a[16:19], v[92:95], v[4:7]
	v_mfma_f32_16x16x32_bf16 v[20:23], a[20:23], v[92:95], v[20:23]
	v_mfma_f32_16x16x32_bf16 v[36:39], a[24:27], v[92:95], v[36:39]
	v_mfma_f32_16x16x32_bf16 v[52:55], a[28:31], v[92:95], v[52:55]
	s_waitcnt lgkmcnt(1)
	v_mfma_f32_16x16x32_bf16 v[8:11], a[16:19], v[88:91], v[8:11]
	v_mfma_f32_16x16x32_bf16 v[24:27], a[20:23], v[88:91], v[24:27]
	v_mfma_f32_16x16x32_bf16 v[40:43], a[24:27], v[88:91], v[40:43]
	v_mfma_f32_16x16x32_bf16 v[56:59], a[28:31], v[88:91], v[56:59]
	s_waitcnt lgkmcnt(0)
	v_mfma_f32_16x16x32_bf16 v[12:15], a[16:19], v[84:87], v[12:15]
	v_mfma_f32_16x16x32_bf16 v[28:31], a[20:23], v[84:87], v[28:31]
	v_mfma_f32_16x16x32_bf16 v[44:47], a[24:27], v[84:87], v[44:47]
	v_mfma_f32_16x16x32_bf16 v[60:63], a[28:31], v[84:87], v[60:63]
	s_setprio 0
	s_waitcnt vmcnt(0) lgkmcnt(0)
	s_barrier
	s_add_u32 s28, s28, 0x100
	s_addc_u32 s29, s29, 0
	s_add_u32 m0, s100, 0x0
	s_nop 0
	global_load_lds_dwordx4 v[64:65], off
	s_add_u32 m0, s100, 0x1000
	s_nop 0
	global_load_lds_dwordx4 v[66:67], off
	s_add_u32 m0, s100, 0x2000
	s_nop 0
	global_load_lds_dwordx4 v[68:69], off
	s_add_u32 m0, s100, 0x3000
	s_nop 0
	global_load_lds_dwordx4 v[70:71], off
	s_add_u32 m0, s100, 0x4000
	s_nop 0
	global_load_lds_dwordx4 v[76:77], off
	s_add_u32 m0, s100, 0x5000
	s_nop 0
	global_load_lds_dwordx4 v[78:79], off
	s_add_u32 m0, s100, 0x6000
	s_nop 0
	global_load_lds_dwordx4 v[72:73], off
	s_add_u32 m0, s100, 0x7000
	s_nop 0
	global_load_lds_dwordx4 v[74:75], off
	ds_read_b128 a[0:3], v115 offset:32768
	ds_read_b128 v[80:83], v116 offset:32768
	ds_read_b128 a[4:7], v115 offset:34816
	ds_read_b128 a[8:11], v115 offset:36864
	ds_read_b128 a[12:15], v115 offset:38912
	ds_read_b128 v[92:95], v116 offset:34816
	ds_read_b128 v[88:91], v116 offset:36864
	ds_read_b128 v[84:87], v116 offset:38912
	ds_read_b128 a[16:19], v117 offset:32768
	ds_read_b128 a[20:23], v117 offset:34816
	ds_read_b128 a[24:27], v117 offset:36864
	ds_read_b128 a[28:31], v117 offset:38912
	s_setprio 1
	s_waitcnt lgkmcnt(10)
	v_mfma_f32_16x16x32_bf16 v[0:3], a[0:3], v[80:83], v[0:3]
	s_waitcnt lgkmcnt(9)
	v_mfma_f32_16x16x32_bf16 v[16:19], a[4:7], v[80:83], v[16:19]
	s_waitcnt lgkmcnt(8)
	v_mfma_f32_16x16x32_bf16 v[32:35], a[8:11], v[80:83], v[32:35]
	s_waitcnt lgkmcnt(7)
	v_mfma_f32_16x16x32_bf16 v[48:51], a[12:15], v[80:83], v[48:51]
	ds_read_b128 v[80:83], v118 offset:32768
	s_waitcnt lgkmcnt(7)
	v_mfma_f32_16x16x32_bf16 v[4:7], a[0:3], v[92:95], v[4:7]
	v_lshl_add_u64 v[128:129], v[104:105], 0, s[28:29]
	s_mov_b32 s4, 0x15ab8000
	v_add_co_u32_e32 v144, vcc, s4, v128
	v_mfma_f32_16x16x32_bf16 v[20:23], a[4:7], v[92:95], v[20:23]
	s_mov_b32 s4, 0x15ad8000
	s_nop 0
	v_addc_co_u32_e32 v145, vcc, 0, v129, vcc
	v_mfma_f32_16x16x32_bf16 v[36:39], a[8:11], v[92:95], v[36:39]
	v_add_co_u32_e32 v146, vcc, s4, v128
	s_mov_b32 s4, 0x15af8000
	s_nop 0
	v_mfma_f32_16x16x32_bf16 v[52:55], a[12:15], v[92:95], v[52:55]
	v_addc_co_u32_e32 v147, vcc, 0, v129, vcc
	v_add_co_u32_e32 v148, vcc, s4, v128
	s_mov_b32 s4, 0x15b18000
	ds_read_b128 v[92:95], v118 offset:34816
	s_waitcnt lgkmcnt(7)
	v_mfma_f32_16x16x32_bf16 v[8:11], a[0:3], v[88:91], v[8:11]
	s_nop 0
	v_addc_co_u32_e32 v149, vcc, 0, v129, vcc
	v_add_co_u32_e32 v150, vcc, s4, v128
	v_mfma_f32_16x16x32_bf16 v[24:27], a[4:7], v[88:91], v[24:27]
	v_lshl_add_u64 v[130:131], v[102:103], 0, s[28:29]
	s_nop 0
	v_addc_co_u32_e32 v151, vcc, 0, v129, vcc
	v_mfma_f32_16x16x32_bf16 v[40:43], a[8:11], v[88:91], v[40:43]
	s_mov_b32 s4, 0x36b80000
	v_add_co_u32_e32 v152, vcc, s4, v130
	s_mov_b32 s4, 0x36ba0000
	v_mfma_f32_16x16x32_bf16 v[56:59], a[12:15], v[88:91], v[56:59]
	s_nop 0
	v_addc_co_u32_e32 v153, vcc, 0, v131, vcc
	v_add_co_u32_e32 v154, vcc, s4, v130
	ds_read_b128 v[88:91], v118 offset:36864
	s_waitcnt lgkmcnt(7)
	v_mfma_f32_16x16x32_bf16 v[12:15], a[0:3], v[84:87], v[12:15]
	s_mov_b32 s4, 0x36bc0000
	s_nop 0
	v_addc_co_u32_e32 v155, vcc, 0, v131, vcc
	v_mfma_f32_16x16x32_bf16 v[28:31], a[4:7], v[84:87], v[28:31]
	v_add_co_u32_e32 v156, vcc, s4, v130
	s_mov_b32 s4, 0x36be0000
	s_nop 0
	v_mfma_f32_16x16x32_bf16 v[44:47], a[8:11], v[84:87], v[44:47]
	v_addc_co_u32_e32 v157, vcc, 0, v131, vcc
	v_add_co_u32_e32 v178, vcc, s4, v130
	v_addc_co_u32_e32 v179, vcc, 0, v131, vcc
	v_mfma_f32_16x16x32_bf16 v[60:63], a[12:15], v[84:87], v[60:63]
	v_lshl_add_u64 v[144:145], 8, 4, v[144:145]
	v_lshl_add_u64 v[146:147], 8, 4, v[146:147]
	v_lshl_add_u64 v[148:149], 8, 4, v[148:149]
	ds_read_b128 v[84:87], v118 offset:38912
	s_waitcnt lgkmcnt(3)
	v_mfma_f32_16x16x32_bf16 v[0:3], a[16:19], v[80:83], v[0:3]
	v_lshl_add_u64 v[150:151], 8, 4, v[150:151]
	v_lshl_add_u64 v[152:153], 8, 4, v[152:153]
	v_lshl_add_u64 v[154:155], 8, 4, v[154:155]
	v_mfma_f32_16x16x32_bf16 v[16:19], a[20:23], v[80:83], v[16:19]
	v_lshl_add_u64 v[156:157], 8, 4, v[156:157]
	v_lshl_add_u64 v[178:179], 8, 4, v[178:179]
	v_mfma_f32_16x16x32_bf16 v[32:35], a[24:27], v[80:83], v[32:35]
	v_mfma_f32_16x16x32_bf16 v[48:51], a[28:31], v[80:83], v[48:51]
	s_waitcnt lgkmcnt(2)
	v_mfma_f32_16x16x32_bf16 v[4:7], a[16:19], v[92:95], v[4:7]
	v_mfma_f32_16x16x32_bf16 v[20:23], a[20:23], v[92:95], v[20:23]
	v_mfma_f32_16x16x32_bf16 v[36:39], a[24:27], v[92:95], v[36:39]
	v_mfma_f32_16x16x32_bf16 v[52:55], a[28:31], v[92:95], v[52:55]
	s_waitcnt lgkmcnt(1)
	v_mfma_f32_16x16x32_bf16 v[8:11], a[16:19], v[88:91], v[8:11]
	v_mfma_f32_16x16x32_bf16 v[24:27], a[20:23], v[88:91], v[24:27]
	v_mfma_f32_16x16x32_bf16 v[40:43], a[24:27], v[88:91], v[40:43]
	v_mfma_f32_16x16x32_bf16 v[56:59], a[28:31], v[88:91], v[56:59]
	s_waitcnt lgkmcnt(0)
	v_mfma_f32_16x16x32_bf16 v[12:15], a[16:19], v[84:87], v[12:15]
	v_mfma_f32_16x16x32_bf16 v[28:31], a[20:23], v[84:87], v[28:31]
	v_mfma_f32_16x16x32_bf16 v[44:47], a[24:27], v[84:87], v[44:47]
	v_mfma_f32_16x16x32_bf16 v[60:63], a[28:31], v[84:87], v[60:63]
	s_setprio 0
	s_waitcnt vmcnt(0) lgkmcnt(0)
	s_barrier
	s_cmpk_eq_i32 s28, 0xf00
	s_cbranch_scc0 .LBB0_583
	v_lshl_add_u64 v[64:65], 8, 4, v[64:65]
	v_lshl_add_u64 v[66:67], 8, 4, v[66:67]
	v_lshl_add_u64 v[68:69], 8, 4, v[68:69]
	v_lshl_add_u64 v[70:71], 8, 4, v[70:71]
	v_lshl_add_u64 v[76:77], 8, 4, v[76:77]
	v_lshl_add_u64 v[78:79], 8, 4, v[78:79]
	v_lshl_add_u64 v[72:73], 8, 4, v[72:73]
	v_lshl_add_u64 v[74:75], 8, 4, v[74:75]
	s_add_u32 m0, s100, 0x8000
	s_nop 0
	global_load_lds_dwordx4 v[64:65], off
	s_add_u32 m0, s100, 0x9000
	s_nop 0
	global_load_lds_dwordx4 v[66:67], off
	s_add_u32 m0, s100, 0xa000
	s_nop 0
	global_load_lds_dwordx4 v[68:69], off
	s_add_u32 m0, s100, 0xb000
	s_nop 0
	global_load_lds_dwordx4 v[70:71], off
	s_add_u32 m0, s100, 0xc000
	s_nop 0
	global_load_lds_dwordx4 v[76:77], off
	s_add_u32 m0, s100, 0xd000
	s_nop 0
	global_load_lds_dwordx4 v[78:79], off
	s_add_u32 m0, s100, 0xe000
	s_nop 0
	global_load_lds_dwordx4 v[72:73], off
	s_add_u32 m0, s100, 0xf000
	s_nop 0
	global_load_lds_dwordx4 v[74:75], off
	ds_read_b128 a[0:3], v115
	ds_read_b128 v[80:83], v116
	ds_read_b128 a[4:7], v115 offset:2048
	ds_read_b128 a[8:11], v115 offset:4096
	ds_read_b128 a[12:15], v115 offset:6144
	ds_read_b128 v[92:95], v116 offset:2048
	ds_read_b128 v[88:91], v116 offset:4096
	ds_read_b128 v[84:87], v116 offset:6144
	ds_read_b128 a[16:19], v117
	ds_read_b128 a[20:23], v117 offset:2048
	ds_read_b128 a[24:27], v117 offset:4096
	ds_read_b128 a[28:31], v117 offset:6144
	s_setprio 1
	s_waitcnt lgkmcnt(10)
	v_mfma_f32_16x16x32_bf16 v[0:3], a[0:3], v[80:83], v[0:3]
	s_waitcnt lgkmcnt(9)
	v_mfma_f32_16x16x32_bf16 v[16:19], a[4:7], v[80:83], v[16:19]
	s_waitcnt lgkmcnt(8)
	v_mfma_f32_16x16x32_bf16 v[32:35], a[8:11], v[80:83], v[32:35]
	s_waitcnt lgkmcnt(7)
	v_mfma_f32_16x16x32_bf16 v[48:51], a[12:15], v[80:83], v[48:51]
	ds_read_b128 v[80:83], v118
	s_waitcnt lgkmcnt(7)
	v_mfma_f32_16x16x32_bf16 v[4:7], a[0:3], v[92:95], v[4:7]
	v_mfma_f32_16x16x32_bf16 v[20:23], a[4:7], v[92:95], v[20:23]
	v_mfma_f32_16x16x32_bf16 v[36:39], a[8:11], v[92:95], v[36:39]
	v_mfma_f32_16x16x32_bf16 v[52:55], a[12:15], v[92:95], v[52:55]
	ds_read_b128 v[92:95], v118 offset:2048
	s_waitcnt lgkmcnt(7)
	v_mfma_f32_16x16x32_bf16 v[8:11], a[0:3], v[88:91], v[8:11]
	v_mfma_f32_16x16x32_bf16 v[24:27], a[4:7], v[88:91], v[24:27]
	v_mfma_f32_16x16x32_bf16 v[40:43], a[8:11], v[88:91], v[40:43]
	v_mfma_f32_16x16x32_bf16 v[56:59], a[12:15], v[88:91], v[56:59]
	ds_read_b128 v[88:91], v118 offset:4096
	s_waitcnt lgkmcnt(7)
	v_mfma_f32_16x16x32_bf16 v[12:15], a[0:3], v[84:87], v[12:15]
	v_mfma_f32_16x16x32_bf16 v[28:31], a[4:7], v[84:87], v[28:31]
	v_mfma_f32_16x16x32_bf16 v[44:47], a[8:11], v[84:87], v[44:47]
	v_mfma_f32_16x16x32_bf16 v[60:63], a[12:15], v[84:87], v[60:63]
	ds_read_b128 v[84:87], v118 offset:6144
	s_waitcnt lgkmcnt(3)
	v_mfma_f32_16x16x32_bf16 v[0:3], a[16:19], v[80:83], v[0:3]
	v_mfma_f32_16x16x32_bf16 v[16:19], a[20:23], v[80:83], v[16:19]
	v_mfma_f32_16x16x32_bf16 v[32:35], a[24:27], v[80:83], v[32:35]
	v_mfma_f32_16x16x32_bf16 v[48:51], a[28:31], v[80:83], v[48:51]
	s_waitcnt lgkmcnt(2)
	v_mfma_f32_16x16x32_bf16 v[4:7], a[16:19], v[92:95], v[4:7]
	v_mfma_f32_16x16x32_bf16 v[20:23], a[20:23], v[92:95], v[20:23]
	v_mfma_f32_16x16x32_bf16 v[36:39], a[24:27], v[92:95], v[36:39]
	v_mfma_f32_16x16x32_bf16 v[52:55], a[28:31], v[92:95], v[52:55]
	s_waitcnt lgkmcnt(1)
	v_mfma_f32_16x16x32_bf16 v[8:11], a[16:19], v[88:91], v[8:11]
	v_mfma_f32_16x16x32_bf16 v[24:27], a[20:23], v[88:91], v[24:27]
	v_mfma_f32_16x16x32_bf16 v[40:43], a[24:27], v[88:91], v[40:43]
	v_mfma_f32_16x16x32_bf16 v[56:59], a[28:31], v[88:91], v[56:59]
	s_waitcnt lgkmcnt(0)
	v_mfma_f32_16x16x32_bf16 v[12:15], a[16:19], v[84:87], v[12:15]
	v_mfma_f32_16x16x32_bf16 v[28:31], a[20:23], v[84:87], v[28:31]
	v_mfma_f32_16x16x32_bf16 v[44:47], a[24:27], v[84:87], v[44:47]
	v_mfma_f32_16x16x32_bf16 v[60:63], a[28:31], v[84:87], v[60:63]
	s_setprio 0
	s_waitcnt vmcnt(0) lgkmcnt(0)
	s_barrier
	ds_read_b128 a[0:3], v115 offset:32768
	ds_read_b128 v[80:83], v116 offset:32768
	ds_read_b128 a[4:7], v115 offset:34816
	ds_read_b128 a[8:11], v115 offset:36864
	ds_read_b128 a[12:15], v115 offset:38912
	ds_read_b128 v[92:95], v116 offset:34816
	ds_read_b128 v[88:91], v116 offset:36864
	ds_read_b128 v[84:87], v116 offset:38912
	ds_read_b128 a[16:19], v117 offset:32768
	ds_read_b128 a[20:23], v117 offset:34816
	ds_read_b128 a[24:27], v117 offset:36864
	ds_read_b128 a[28:31], v117 offset:38912
	s_setprio 1
	s_waitcnt lgkmcnt(10)
	v_mfma_f32_16x16x32_bf16 v[0:3], a[0:3], v[80:83], v[0:3]
	s_waitcnt lgkmcnt(9)
	v_mfma_f32_16x16x32_bf16 v[16:19], a[4:7], v[80:83], v[16:19]
	s_waitcnt lgkmcnt(8)
	v_mfma_f32_16x16x32_bf16 v[32:35], a[8:11], v[80:83], v[32:35]
	s_waitcnt lgkmcnt(7)
	v_mfma_f32_16x16x32_bf16 v[48:51], a[12:15], v[80:83], v[48:51]
	ds_read_b128 v[80:83], v118 offset:32768
	s_waitcnt lgkmcnt(7)
	v_mfma_f32_16x16x32_bf16 v[4:7], a[0:3], v[92:95], v[4:7]
	v_mfma_f32_16x16x32_bf16 v[20:23], a[4:7], v[92:95], v[20:23]
	v_mfma_f32_16x16x32_bf16 v[36:39], a[8:11], v[92:95], v[36:39]
	v_mfma_f32_16x16x32_bf16 v[52:55], a[12:15], v[92:95], v[52:55]
	ds_read_b128 v[92:95], v118 offset:34816
	s_waitcnt lgkmcnt(7)
	v_mfma_f32_16x16x32_bf16 v[8:11], a[0:3], v[88:91], v[8:11]
	v_mfma_f32_16x16x32_bf16 v[24:27], a[4:7], v[88:91], v[24:27]
	v_mfma_f32_16x16x32_bf16 v[40:43], a[8:11], v[88:91], v[40:43]
	v_mfma_f32_16x16x32_bf16 v[56:59], a[12:15], v[88:91], v[56:59]
	ds_read_b128 v[88:91], v118 offset:36864
	s_waitcnt lgkmcnt(7)
	v_mfma_f32_16x16x32_bf16 v[12:15], a[0:3], v[84:87], v[12:15]
	v_mfma_f32_16x16x32_bf16 v[28:31], a[4:7], v[84:87], v[28:31]
	v_mfma_f32_16x16x32_bf16 v[44:47], a[8:11], v[84:87], v[44:47]
	v_mfma_f32_16x16x32_bf16 v[60:63], a[12:15], v[84:87], v[60:63]
	ds_read_b128 v[84:87], v118 offset:38912
	s_waitcnt lgkmcnt(3)
	v_mfma_f32_16x16x32_bf16 v[0:3], a[16:19], v[80:83], v[0:3]
	v_mfma_f32_16x16x32_bf16 v[16:19], a[20:23], v[80:83], v[16:19]
	v_mfma_f32_16x16x32_bf16 v[32:35], a[24:27], v[80:83], v[32:35]
	v_mfma_f32_16x16x32_bf16 v[48:51], a[28:31], v[80:83], v[48:51]
	s_waitcnt lgkmcnt(2)
	v_mfma_f32_16x16x32_bf16 v[4:7], a[16:19], v[92:95], v[4:7]
	v_mfma_f32_16x16x32_bf16 v[20:23], a[20:23], v[92:95], v[20:23]
	v_mfma_f32_16x16x32_bf16 v[36:39], a[24:27], v[92:95], v[36:39]
	v_mfma_f32_16x16x32_bf16 v[52:55], a[28:31], v[92:95], v[52:55]
	s_waitcnt lgkmcnt(1)
	v_mfma_f32_16x16x32_bf16 v[8:11], a[16:19], v[88:91], v[8:11]
	v_mfma_f32_16x16x32_bf16 v[24:27], a[20:23], v[88:91], v[24:27]
	v_mfma_f32_16x16x32_bf16 v[40:43], a[24:27], v[88:91], v[40:43]
	v_mfma_f32_16x16x32_bf16 v[56:59], a[28:31], v[88:91], v[56:59]
	s_waitcnt lgkmcnt(0)
	v_mfma_f32_16x16x32_bf16 v[12:15], a[16:19], v[84:87], v[12:15]
	v_mfma_f32_16x16x32_bf16 v[28:31], a[20:23], v[84:87], v[28:31]
	v_mfma_f32_16x16x32_bf16 v[44:47], a[24:27], v[84:87], v[44:47]
	v_mfma_f32_16x16x32_bf16 v[60:63], a[28:31], v[84:87], v[60:63]
	s_setprio 0
	v_readfirstlane_b32 s15, v107
	v_readfirstlane_b32 s4, v106
	s_lshl_b32 s15, s15, 6
	s_waitcnt lgkmcnt(0)
	s_barrier
	s_add_i32 s9, s15, s9
	s_lshl_b32 s15, s4, 17
	s_lshl_b32 s4, s8, 18
	s_add_i32 s15, s15, s4
	v_or_b32_e32 v64, s9, v108
	s_movk_i32 s4, 0x800
	v_cmp_gt_i32_e32 vcc, s4, v64
	s_barrier
	v_and_b32_e32 v124, 15, v143
	v_bfe_u32 v125, v143, 4, 2
	v_xor_b32_e32 v125, v125, v124
	v_lshlrev_b32_e32 v125, 4, v125
	v_lshl_add_u32 v125, v124, 8, v125
	v_lshrrev_b32_e32 v124, 6, v143
	v_lshl_add_u32 v125, v124, 14, v125
	ds_write_b128 v125, v[0:3]
	ds_write_b128 v125, v[4:7] offset:4096
	ds_write_b128 v125, v[8:11] offset:8192
	ds_write_b128 v125, v[12:15] offset:12288
	v_xor_b32_e32 v118, 64, v125
	ds_write_b128 v118, v[16:19]
	ds_write_b128 v118, v[20:23] offset:4096
	ds_write_b128 v118, v[24:27] offset:8192
	ds_write_b128 v118, v[28:31] offset:12288
	v_xor_b32_e32 v118, 128, v125
	ds_write_b128 v118, v[32:35]
	ds_write_b128 v118, v[36:39] offset:4096
	ds_write_b128 v118, v[40:43] offset:8192
	ds_write_b128 v118, v[44:47] offset:12288
	v_xor_b32_e32 v118, 192, v125
	ds_write_b128 v118, v[48:51]
	ds_write_b128 v118, v[52:55] offset:4096
	ds_write_b128 v118, v[56:59] offset:8192
	ds_write_b128 v118, v[60:63] offset:12288
	v_and_b32_e32 v115, 31, v143
	v_bfe_u32 v117, v143, 5, 1
	v_and_b32_e32 v125, 15, v115
	v_xor_b32_e32 v117, v117, v125
	v_lshlrev_b32_e32 v117, 4, v117
	v_lshl_add_u32 v117, v115, 8, v117
	v_lshl_add_u32 v117, v124, 14, v117
	ds_read_b128 v[48:51], v117
	ds_read_b128 v[32:35], v117 offset:8192
	v_xor_b32_e32 v116, 32, v117
	ds_read_b128 v[52:55], v116
	ds_read_b128 v[36:39], v116 offset:8192
	v_xor_b32_e32 v116, 64, v117
	ds_read_b128 v[56:59], v116
	ds_read_b128 v[40:43], v116 offset:8192
	v_xor_b32_e32 v116, 96, v117
	ds_read_b128 v[60:63], v116
	ds_read_b128 v[44:47], v116 offset:8192
	v_xor_b32_e32 v116, 128, v117
	ds_read_b128 v[16:19], v116
	ds_read_b128 v[0:3], v116 offset:8192
	v_xor_b32_e32 v116, 160, v117
	ds_read_b128 v[20:23], v116
	ds_read_b128 v[4:7], v116 offset:8192
	v_xor_b32_e32 v116, 192, v117
	ds_read_b128 v[24:27], v116
	ds_read_b128 v[8:11], v116 offset:8192
	v_xor_b32_e32 v116, 224, v117
	ds_read_b128 v[28:31], v116
	ds_read_b128 v[12:15], v116 offset:8192
	s_waitcnt lgkmcnt(0)
	s_barrier
	s_and_saveexec_b64 s[8:9], vcc
	s_cbranch_execz .LBB0_586
	v_add_u32_e32 v65, s15, v64
	v_add_u32_e32 v66, v65, v111
	v_mov_b32_e32 v67, v140
	v_lshl_add_u64 v[68:69], v[66:67], 2, s[26:27]
	global_store_dword v[68:69], v48, off
	v_add_u32_e32 v68, 0x800, v66
	v_mov_b32_e32 v69, v140
	v_lshl_add_u64 v[68:69], v[68:69], 2, s[26:27]
	global_store_dword v[68:69], v49, off
	v_add_u32_e32 v48, 0x1000, v66
	v_mov_b32_e32 v49, v140
	v_lshl_add_u64 v[48:49], v[48:49], 2, s[26:27]
	global_store_dword v[48:49], v50, off
	v_add_u32_e32 v48, 0x1800, v66
	v_mov_b32_e32 v49, v140
	v_lshl_add_u64 v[48:49], v[48:49], 2, s[26:27]
	global_store_dword v[48:49], v51, off
	v_add_u32_e32 v48, v65, v112
	v_mov_b32_e32 v49, v140
	v_lshl_add_u64 v[50:51], v[48:49], 2, s[26:27]
	global_store_dword v[50:51], v52, off
	v_add_u32_e32 v50, 0x800, v48
	v_mov_b32_e32 v51, v140
	v_lshl_add_u64 v[50:51], v[50:51], 2, s[26:27]
	global_store_dword v[50:51], v53, off
	v_add_u32_e32 v50, 0x1000, v48
	v_mov_b32_e32 v51, v140
	v_add_u32_e32 v48, 0x1800, v48
	v_lshl_add_u64 v[50:51], v[50:51], 2, s[26:27]
	v_lshl_add_u64 v[48:49], v[48:49], 2, s[26:27]
	global_store_dword v[50:51], v54, off
	global_store_dword v[48:49], v55, off
	v_add_u32_e32 v48, v65, v113
	v_mov_b32_e32 v49, v140
	v_lshl_add_u64 v[50:51], v[48:49], 2, s[26:27]
	global_store_dword v[50:51], v56, off
	v_add_u32_e32 v50, 0x800, v48
	v_mov_b32_e32 v51, v140
	v_lshl_add_u64 v[50:51], v[50:51], 2, s[26:27]
	global_store_dword v[50:51], v57, off
	v_add_u32_e32 v50, 0x1000, v48
	v_mov_b32_e32 v51, v140
	v_add_u32_e32 v48, 0x1800, v48
	v_lshl_add_u64 v[50:51], v[50:51], 2, s[26:27]
	v_lshl_add_u64 v[48:49], v[48:49], 2, s[26:27]
	global_store_dword v[50:51], v58, off
	global_store_dword v[48:49], v59, off
	v_add_u32_e32 v48, v65, v114
	v_mov_b32_e32 v49, v140
	v_lshl_add_u64 v[50:51], v[48:49], 2, s[26:27]
	global_store_dword v[50:51], v60, off
	v_add_u32_e32 v50, 0x800, v48
	v_mov_b32_e32 v51, v140
	v_lshl_add_u64 v[50:51], v[50:51], 2, s[26:27]
	global_store_dword v[50:51], v61, off
	v_add_u32_e32 v50, 0x1000, v48
	v_mov_b32_e32 v51, v140
	v_add_u32_e32 v48, 0x1800, v48
	v_lshl_add_u64 v[50:51], v[50:51], 2, s[26:27]
	v_lshl_add_u64 v[48:49], v[48:49], 2, s[26:27]
	global_store_dword v[50:51], v62, off
	global_store_dword v[48:49], v63, off

.LBB0_595:
	s_mul_hi_i32 s4, s22, 0x38e38e39
	s_lshr_b32 s8, s4, 31
	s_ashr_i32 s4, s4, 4
	s_add_i32 s4, s4, s8
	s_mul_i32 s8, s4, 0x48
	s_sub_i32 s8, s22, s8
	v_lshl_add_u32 v0, s8, 7, v109
	v_ashrrev_i32_e32 v1, 31, v0
	v_lshlrev_b64 v[32:33], 12, v[0:1]
	v_lshl_add_u64 v[34:35], v[96:97], 0, v[32:33]
	v_add_co_u32_e32 v40, vcc, s87, v34
	s_lshl_b32 s9, s4, 7
	s_nop 0
	v_addc_co_u32_e32 v41, vcc, 0, v35, vcc
	v_add_co_u32_e32 v42, vcc, s66, v34
	v_add_u32_e32 v0, s9, v109
	s_nop 0
	v_addc_co_u32_e32 v43, vcc, 0, v35, vcc
	v_ashrrev_i32_e32 v1, 31, v0
	v_add_co_u32_e32 v44, vcc, s20, v34
	v_lshlrev_b64 v[36:37], 12, v[0:1]
	s_nop 0
	v_addc_co_u32_e32 v45, vcc, 0, v35, vcc
	v_lshl_add_u64 v[38:39], v[98:99], 0, v[36:37]
	v_readfirstlane_b32 s100, v110
	s_nop 3
	s_add_u32 m0, s100, 0x0
	s_nop 0
	global_load_lds_dwordx4 v[34:35], off
	s_add_u32 m0, s100, 0x1000
	s_nop 0
	global_load_lds_dwordx4 v[40:41], off
	s_add_u32 m0, s100, 0x2000
	s_nop 0
	global_load_lds_dwordx4 v[42:43], off
	s_add_u32 m0, s100, 0x3000
	s_nop 0
	global_load_lds_dwordx4 v[44:45], off
	s_add_u32 m0, s100, 0x4000
	s_nop 0
	global_load_lds_dwordx4 v[38:39], off
	v_add_co_u32_e32 v46, vcc, s87, v38
	v_lshl_add_u64 v[102:103], v[100:101], 0, v[36:37]
	s_nop 0
	v_addc_co_u32_e32 v47, vcc, 0, v39, vcc
	s_waitcnt vmcnt(16)
	v_add_co_u32_e32 v48, vcc, s66, v38
	s_add_u32 m0, s100, 0x5000
	s_nop 0
	global_load_lds_dwordx4 v[46:47], off
	s_nop 0
	v_addc_co_u32_e32 v49, vcc, 0, v39, vcc
	v_add_co_u32_e32 v50, vcc, s20, v38
	s_add_u32 m0, s100, 0x6000
	s_nop 0
	global_load_lds_dwordx4 v[48:49], off
	s_nop 0
	v_addc_co_u32_e32 v51, vcc, 0, v39, vcc
	s_add_u32 m0, s100, 0x7000
	s_nop 0
	global_load_lds_dwordx4 v[50:51], off
	v_lshl_add_u64 v[104:105], v[100:101], 0, v[32:33]
	s_mov_b64 s[28:29], 0
	v_mov_b32_e32 v0, 0
	v_mov_b32_e32 v1, v0
	v_mov_b32_e32 v2, v0
	v_mov_b32_e32 v3, v0
	v_mov_b32_e32 v4, v0
	v_mov_b32_e32 v5, v0
	v_mov_b32_e32 v6, v0
	v_mov_b32_e32 v7, v0
	v_mov_b32_e32 v8, v0
	v_mov_b32_e32 v9, v0
	v_mov_b32_e32 v10, v0
	v_mov_b32_e32 v11, v0
	v_mov_b32_e32 v12, v0
	v_mov_b32_e32 v13, v0
	v_mov_b32_e32 v14, v0
	v_mov_b32_e32 v15, v0
	v_mov_b32_e32 v16, v0
	v_mov_b32_e32 v17, v0
	v_mov_b32_e32 v18, v0
	v_mov_b32_e32 v19, v0
	v_mov_b32_e32 v20, v0
	v_mov_b32_e32 v21, v0
	v_mov_b32_e32 v22, v0
	v_mov_b32_e32 v23, v0
	v_mov_b32_e32 v24, v0
	v_mov_b32_e32 v25, v0
	v_mov_b32_e32 v26, v0
	v_mov_b32_e32 v27, v0
	v_mov_b32_e32 v28, v0
	v_mov_b32_e32 v29, v0
	v_mov_b32_e32 v30, v0
	v_mov_b32_e32 v31, v0
	v_mov_b32_e32 v32, v0
	v_mov_b32_e32 v33, v0
	v_mov_b32_e32 v34, v0
	v_mov_b32_e32 v35, v0
	v_mov_b32_e32 v36, v0
	v_mov_b32_e32 v37, v0
	v_mov_b32_e32 v38, v0
	v_mov_b32_e32 v39, v0
	v_mov_b32_e32 v40, v0
	v_mov_b32_e32 v41, v0
	v_mov_b32_e32 v42, v0
	v_mov_b32_e32 v43, v0
	v_mov_b32_e32 v44, v0
	v_mov_b32_e32 v45, v0
	v_mov_b32_e32 v46, v0
	v_mov_b32_e32 v47, v0
	v_mov_b32_e32 v48, v0
	v_mov_b32_e32 v49, v0
	v_mov_b32_e32 v50, v0
	v_mov_b32_e32 v51, v0
	v_mov_b32_e32 v52, v0
	v_mov_b32_e32 v53, v0
	v_mov_b32_e32 v54, v0
	v_mov_b32_e32 v55, v0
	v_mov_b32_e32 v56, v0
	v_mov_b32_e32 v57, v0
	v_mov_b32_e32 v58, v0
	v_mov_b32_e32 v59, v0
	v_mov_b32_e32 v60, v0
	v_mov_b32_e32 v61, v0
	v_mov_b32_e32 v62, v0
	v_mov_b32_e32 v63, v0
	v_lshl_add_u64 v[128:129], v[104:105], 0, s[28:29]
	s_mov_b32 s4, 0x1a2b8000
	v_add_co_u32_e32 v144, vcc, s4, v128
	s_mov_b32 s4, 0x1a2d8000
	s_nop 0
	v_addc_co_u32_e32 v145, vcc, 0, v129, vcc
	v_add_co_u32_e32 v146, vcc, s4, v128
	s_mov_b32 s4, 0x1a2f8000
	s_nop 0
	v_addc_co_u32_e32 v147, vcc, 0, v129, vcc
	v_add_co_u32_e32 v148, vcc, s4, v128
	s_mov_b32 s4, 0x1a318000
	s_nop 0
	v_addc_co_u32_e32 v149, vcc, 0, v129, vcc
	v_add_co_u32_e32 v150, vcc, s4, v128
	v_lshl_add_u64 v[130:131], v[102:103], 0, s[28:29]
	s_nop 0
	v_addc_co_u32_e32 v151, vcc, 0, v129, vcc
	s_mov_b32 s4, 0x37380000
	v_add_co_u32_e32 v152, vcc, s4, v130
	s_mov_b32 s4, 0x373a0000
	s_nop 0
	v_addc_co_u32_e32 v153, vcc, 0, v131, vcc
	v_add_co_u32_e32 v154, vcc, s4, v130
	s_mov_b32 s4, 0x373c0000
	s_nop 0
	v_addc_co_u32_e32 v155, vcc, 0, v131, vcc
	v_add_co_u32_e32 v156, vcc, s4, v130
	s_mov_b32 s4, 0x373e0000
	s_nop 0
	v_addc_co_u32_e32 v157, vcc, 0, v131, vcc
	v_add_co_u32_e32 v178, vcc, s4, v130
	v_addc_co_u32_e32 v179, vcc, 0, v131, vcc
	v_lshl_add_u64 v[144:145], 8, 4, v[144:145]
	v_lshl_add_u64 v[146:147], 8, 4, v[146:147]
	v_lshl_add_u64 v[148:149], 8, 4, v[148:149]
	v_lshl_add_u64 v[150:151], 8, 4, v[150:151]
	v_lshl_add_u64 v[152:153], 8, 4, v[152:153]
	v_lshl_add_u64 v[154:155], 8, 4, v[154:155]
	v_lshl_add_u64 v[156:157], 8, 4, v[156:157]
	v_lshl_add_u64 v[178:179], 8, 4, v[178:179]
	v_and_b32_e32 v124, 15, v143
	v_lshrrev_b32_e32 v125, 1, v124
	v_bfe_u32 v117, v143, 4, 2
	v_xor_b32_e32 v125, v125, v117
	v_lshlrev_b32_e32 v125, 4, v125
	v_lshl_add_u32 v125, v124, 7, v125
	v_lshrrev_b32_e32 v124, 6, v143
	v_lshrrev_b32_e32 v115, 1, v124
	v_and_b32_e32 v124, 1, v124
	v_lshl_add_u32 v115, v115, 13, v125
	v_lshl_add_u32 v116, v124, 13, v125
	v_add_u32_e32 v116, 0x4000, v116
	v_xor_b32_e32 v117, 64, v115
	v_xor_b32_e32 v118, 64, v116
	s_waitcnt vmcnt(0) lgkmcnt(0)
	s_barrier
.LBB0_596:
	s_add_u32 m0, s100, 0x8000
	s_nop 0
	global_load_lds_dwordx4 v[144:145], off
	s_add_u32 m0, s100, 0x9000
	s_nop 0
	global_load_lds_dwordx4 v[146:147], off
	s_add_u32 m0, s100, 0xa000
	s_nop 0
	global_load_lds_dwordx4 v[148:149], off
	s_add_u32 m0, s100, 0xb000
	s_nop 0
	global_load_lds_dwordx4 v[150:151], off
	s_add_u32 m0, s100, 0xc000
	s_nop 0
	global_load_lds_dwordx4 v[152:153], off
	s_add_u32 m0, s100, 0xd000
	s_nop 0
	global_load_lds_dwordx4 v[154:155], off
	s_add_u32 m0, s100, 0xe000
	s_nop 0
	global_load_lds_dwordx4 v[156:157], off
	s_add_u32 m0, s100, 0xf000
	s_nop 0
	global_load_lds_dwordx4 v[178:179], off
	ds_read_b128 a[0:3], v115
	ds_read_b128 v[80:83], v116
	ds_read_b128 a[4:7], v115 offset:2048
	ds_read_b128 a[8:11], v115 offset:4096
	ds_read_b128 a[12:15], v115 offset:6144
	ds_read_b128 v[92:95], v116 offset:2048
	ds_read_b128 v[88:91], v116 offset:4096
	ds_read_b128 v[84:87], v116 offset:6144
	ds_read_b128 a[16:19], v117
	ds_read_b128 a[20:23], v117 offset:2048
	ds_read_b128 a[24:27], v117 offset:4096
	ds_read_b128 a[28:31], v117 offset:6144
	s_setprio 1
	s_waitcnt lgkmcnt(10)
	v_mfma_f32_16x16x32_bf16 v[0:3], a[0:3], v[80:83], v[0:3]
	s_waitcnt lgkmcnt(9)
	v_mfma_f32_16x16x32_bf16 v[16:19], a[4:7], v[80:83], v[16:19]
	s_waitcnt lgkmcnt(8)
	v_mfma_f32_16x16x32_bf16 v[32:35], a[8:11], v[80:83], v[32:35]
	s_waitcnt lgkmcnt(7)
	v_mfma_f32_16x16x32_bf16 v[48:51], a[12:15], v[80:83], v[48:51]
	ds_read_b128 v[80:83], v118
	s_waitcnt lgkmcnt(7)
	v_mfma_f32_16x16x32_bf16 v[4:7], a[0:3], v[92:95], v[4:7]
	v_lshl_add_u64 v[64:65], 8, 4, v[144:145]
	v_lshl_add_u64 v[66:67], 8, 4, v[146:147]
	v_lshl_add_u64 v[68:69], 8, 4, v[148:149]
	v_mfma_f32_16x16x32_bf16 v[20:23], a[4:7], v[92:95], v[20:23]
	v_lshl_add_u64 v[70:71], 8, 4, v[150:151]
	v_lshl_add_u64 v[76:77], 8, 4, v[152:153]
	v_lshl_add_u64 v[78:79], 8, 4, v[154:155]
	v_mfma_f32_16x16x32_bf16 v[36:39], a[8:11], v[92:95], v[36:39]
	v_lshl_add_u64 v[72:73], 8, 4, v[156:157]
	v_lshl_add_u64 v[74:75], 8, 4, v[178:179]
	v_mfma_f32_16x16x32_bf16 v[52:55], a[12:15], v[92:95], v[52:55]
	ds_read_b128 v[92:95], v118 offset:2048
	s_waitcnt lgkmcnt(7)
	v_mfma_f32_16x16x32_bf16 v[8:11], a[0:3], v[88:91], v[8:11]
	v_mfma_f32_16x16x32_bf16 v[24:27], a[4:7], v[88:91], v[24:27]
	v_mfma_f32_16x16x32_bf16 v[40:43], a[8:11], v[88:91], v[40:43]
	v_mfma_f32_16x16x32_bf16 v[56:59], a[12:15], v[88:91], v[56:59]
	ds_read_b128 v[88:91], v118 offset:4096
	s_waitcnt lgkmcnt(7)
	v_mfma_f32_16x16x32_bf16 v[12:15], a[0:3], v[84:87], v[12:15]
	v_mfma_f32_16x16x32_bf16 v[28:31], a[4:7], v[84:87], v[28:31]
	v_mfma_f32_16x16x32_bf16 v[44:47], a[8:11], v[84:87], v[44:47]
	v_mfma_f32_16x16x32_bf16 v[60:63], a[12:15], v[84:87], v[60:63]
	ds_read_b128 v[84:87], v118 offset:6144
	s_waitcnt lgkmcnt(3)
	v_mfma_f32_16x16x32_bf16 v[0:3], a[16:19], v[80:83], v[0:3]
	v_mfma_f32_16x16x32_bf16 v[16:19], a[20:23], v[80:83], v[16:19]
	v_mfma_f32_16x16x32_bf16 v[32:35], a[24:27], v[80:83], v[32:35]
	v_mfma_f32_16x16x32_bf16 v[48:51], a[28:31], v[80:83], v[48:51]
	s_waitcnt lgkmcnt(2)
	v_mfma_f32_16x16x32_bf16 v[4:7], a[16:19], v[92:95], v[4:7]
	v_mfma_f32_16x16x32_bf16 v[20:23], a[20:23], v[92:95], v[20:23]
	v_mfma_f32_16x16x32_bf16 v[36:39], a[24:27], v[92:95], v[36:39]
	v_mfma_f32_16x16x32_bf16 v[52:55], a[28:31], v[92:95], v[52:55]
	s_waitcnt lgkmcnt(1)
	v_mfma_f32_16x16x32_bf16 v[8:11], a[16:19], v[88:91], v[8:11]
	v_mfma_f32_16x16x32_bf16 v[24:27], a[20:23], v[88:91], v[24:27]
	v_mfma_f32_16x16x32_bf16 v[40:43], a[24:27], v[88:91], v[40:43]
	v_mfma_f32_16x16x32_bf16 v[56:59], a[28:31], v[88:91], v[56:59]
	s_waitcnt lgkmcnt(0)
	v_mfma_f32_16x16x32_bf16 v[12:15], a[16:19], v[84:87], v[12:15]
	v_mfma_f32_16x16x32_bf16 v[28:31], a[20:23], v[84:87], v[28:31]
	v_mfma_f32_16x16x32_bf16 v[44:47], a[24:27], v[84:87], v[44:47]
	v_mfma_f32_16x16x32_bf16 v[60:63], a[28:31], v[84:87], v[60:63]
	s_setprio 0
	s_waitcnt vmcnt(0) lgkmcnt(0)
	s_barrier
	s_add_u32 s28, s28, 0x100
	s_addc_u32 s29, s29, 0
	s_add_u32 m0, s100, 0x0
	s_nop 0
	global_load_lds_dwordx4 v[64:65], off
	s_add_u32 m0, s100, 0x1000
	s_nop 0
	global_load_lds_dwordx4 v[66:67], off
	s_add_u32 m0, s100, 0x2000
	s_nop 0
	global_load_lds_dwordx4 v[68:69], off
	s_add_u32 m0, s100, 0x3000
	s_nop 0
	global_load_lds_dwordx4 v[70:71], off
	s_add_u32 m0, s100, 0x4000
	s_nop 0
	global_load_lds_dwordx4 v[76:77], off
	s_add_u32 m0, s100, 0x5000
	s_nop 0
	global_load_lds_dwordx4 v[78:79], off
	s_add_u32 m0, s100, 0x6000
	s_nop 0
	global_load_lds_dwordx4 v[72:73], off
	s_add_u32 m0, s100, 0x7000
	s_nop 0
	global_load_lds_dwordx4 v[74:75], off
	ds_read_b128 a[0:3], v115 offset:32768
	ds_read_b128 v[80:83], v116 offset:32768
	ds_read_b128 a[4:7], v115 offset:34816
	ds_read_b128 a[8:11], v115 offset:36864
	ds_read_b128 a[12:15], v115 offset:38912
	ds_read_b128 v[92:95], v116 offset:34816
	ds_read_b128 v[88:91], v116 offset:36864
	ds_read_b128 v[84:87], v116 offset:38912
	ds_read_b128 a[16:19], v117 offset:32768
	ds_read_b128 a[20:23], v117 offset:34816
	ds_read_b128 a[24:27], v117 offset:36864
	ds_read_b128 a[28:31], v117 offset:38912
	s_setprio 1
	s_waitcnt lgkmcnt(10)
	v_mfma_f32_16x16x32_bf16 v[0:3], a[0:3], v[80:83], v[0:3]
	s_waitcnt lgkmcnt(9)
	v_mfma_f32_16x16x32_bf16 v[16:19], a[4:7], v[80:83], v[16:19]
	s_waitcnt lgkmcnt(8)
	v_mfma_f32_16x16x32_bf16 v[32:35], a[8:11], v[80:83], v[32:35]
	s_waitcnt lgkmcnt(7)
	v_mfma_f32_16x16x32_bf16 v[48:51], a[12:15], v[80:83], v[48:51]
	ds_read_b128 v[80:83], v118 offset:32768
	s_waitcnt lgkmcnt(7)
	v_mfma_f32_16x16x32_bf16 v[4:7], a[0:3], v[92:95], v[4:7]
	v_lshl_add_u64 v[128:129], v[104:105], 0, s[28:29]
	s_mov_b32 s4, 0x1a2b8000
	v_add_co_u32_e32 v144, vcc, s4, v128
	v_mfma_f32_16x16x32_bf16 v[20:23], a[4:7], v[92:95], v[20:23]
	s_mov_b32 s4, 0x1a2d8000
	s_nop 0
	v_addc_co_u32_e32 v145, vcc, 0, v129, vcc
	v_mfma_f32_16x16x32_bf16 v[36:39], a[8:11], v[92:95], v[36:39]
	v_add_co_u32_e32 v146, vcc, s4, v128
	s_mov_b32 s4, 0x1a2f8000
	s_nop 0
	v_mfma_f32_16x16x32_bf16 v[52:55], a[12:15], v[92:95], v[52:55]
	v_addc_co_u32_e32 v147, vcc, 0, v129, vcc
	v_add_co_u32_e32 v148, vcc, s4, v128
	s_mov_b32 s4, 0x1a318000
	ds_read_b128 v[92:95], v118 offset:34816
	s_waitcnt lgkmcnt(7)
	v_mfma_f32_16x16x32_bf16 v[8:11], a[0:3], v[88:91], v[8:11]
	s_nop 0
	v_addc_co_u32_e32 v149, vcc, 0, v129, vcc
	v_add_co_u32_e32 v150, vcc, s4, v128
	v_mfma_f32_16x16x32_bf16 v[24:27], a[4:7], v[88:91], v[24:27]
	v_lshl_add_u64 v[130:131], v[102:103], 0, s[28:29]
	s_nop 0
	v_addc_co_u32_e32 v151, vcc, 0, v129, vcc
	v_mfma_f32_16x16x32_bf16 v[40:43], a[8:11], v[88:91], v[40:43]
	s_mov_b32 s4, 0x37380000
	v_add_co_u32_e32 v152, vcc, s4, v130
	s_mov_b32 s4, 0x373a0000
	v_mfma_f32_16x16x32_bf16 v[56:59], a[12:15], v[88:91], v[56:59]
	s_nop 0
	v_addc_co_u32_e32 v153, vcc, 0, v131, vcc
	v_add_co_u32_e32 v154, vcc, s4, v130
	ds_read_b128 v[88:91], v118 offset:36864
	s_waitcnt lgkmcnt(7)
	v_mfma_f32_16x16x32_bf16 v[12:15], a[0:3], v[84:87], v[12:15]
	s_mov_b32 s4, 0x373c0000
	s_nop 0
	v_addc_co_u32_e32 v155, vcc, 0, v131, vcc
	v_mfma_f32_16x16x32_bf16 v[28:31], a[4:7], v[84:87], v[28:31]
	v_add_co_u32_e32 v156, vcc, s4, v130
	s_mov_b32 s4, 0x373e0000
	s_nop 0
	v_mfma_f32_16x16x32_bf16 v[44:47], a[8:11], v[84:87], v[44:47]
	v_addc_co_u32_e32 v157, vcc, 0, v131, vcc
	v_add_co_u32_e32 v178, vcc, s4, v130
	v_addc_co_u32_e32 v179, vcc, 0, v131, vcc
	v_mfma_f32_16x16x32_bf16 v[60:63], a[12:15], v[84:87], v[60:63]
	v_lshl_add_u64 v[144:145], 8, 4, v[144:145]
	v_lshl_add_u64 v[146:147], 8, 4, v[146:147]
	v_lshl_add_u64 v[148:149], 8, 4, v[148:149]
	ds_read_b128 v[84:87], v118 offset:38912
	s_waitcnt lgkmcnt(3)
	v_mfma_f32_16x16x32_bf16 v[0:3], a[16:19], v[80:83], v[0:3]
	v_lshl_add_u64 v[150:151], 8, 4, v[150:151]
	v_lshl_add_u64 v[152:153], 8, 4, v[152:153]
	v_lshl_add_u64 v[154:155], 8, 4, v[154:155]
	v_mfma_f32_16x16x32_bf16 v[16:19], a[20:23], v[80:83], v[16:19]
	v_lshl_add_u64 v[156:157], 8, 4, v[156:157]
	v_lshl_add_u64 v[178:179], 8, 4, v[178:179]
	v_mfma_f32_16x16x32_bf16 v[32:35], a[24:27], v[80:83], v[32:35]
	v_mfma_f32_16x16x32_bf16 v[48:51], a[28:31], v[80:83], v[48:51]
	s_waitcnt lgkmcnt(2)
	v_mfma_f32_16x16x32_bf16 v[4:7], a[16:19], v[92:95], v[4:7]
	v_mfma_f32_16x16x32_bf16 v[20:23], a[20:23], v[92:95], v[20:23]
	v_mfma_f32_16x16x32_bf16 v[36:39], a[24:27], v[92:95], v[36:39]
	v_mfma_f32_16x16x32_bf16 v[52:55], a[28:31], v[92:95], v[52:55]
	s_waitcnt lgkmcnt(1)
	v_mfma_f32_16x16x32_bf16 v[8:11], a[16:19], v[88:91], v[8:11]
	v_mfma_f32_16x16x32_bf16 v[24:27], a[20:23], v[88:91], v[24:27]
	v_mfma_f32_16x16x32_bf16 v[40:43], a[24:27], v[88:91], v[40:43]
	v_mfma_f32_16x16x32_bf16 v[56:59], a[28:31], v[88:91], v[56:59]
	s_waitcnt lgkmcnt(0)
	v_mfma_f32_16x16x32_bf16 v[12:15], a[16:19], v[84:87], v[12:15]
	v_mfma_f32_16x16x32_bf16 v[28:31], a[20:23], v[84:87], v[28:31]
	v_mfma_f32_16x16x32_bf16 v[44:47], a[24:27], v[84:87], v[44:47]
	v_mfma_f32_16x16x32_bf16 v[60:63], a[28:31], v[84:87], v[60:63]
	s_setprio 0
	s_waitcnt vmcnt(0) lgkmcnt(0)
	s_barrier
	s_cmpk_eq_i32 s28, 0xf00
	s_cbranch_scc0 .LBB0_596
	v_lshl_add_u64 v[64:65], 8, 4, v[64:65]
	v_lshl_add_u64 v[66:67], 8, 4, v[66:67]
	v_lshl_add_u64 v[68:69], 8, 4, v[68:69]
	v_lshl_add_u64 v[70:71], 8, 4, v[70:71]
	v_lshl_add_u64 v[76:77], 8, 4, v[76:77]
	v_lshl_add_u64 v[78:79], 8, 4, v[78:79]
	v_lshl_add_u64 v[72:73], 8, 4, v[72:73]
	v_lshl_add_u64 v[74:75], 8, 4, v[74:75]
	s_add_u32 m0, s100, 0x8000
	s_nop 0
	global_load_lds_dwordx4 v[64:65], off
	s_add_u32 m0, s100, 0x9000
	s_nop 0
	global_load_lds_dwordx4 v[66:67], off
	s_add_u32 m0, s100, 0xa000
	s_nop 0
	global_load_lds_dwordx4 v[68:69], off
	s_add_u32 m0, s100, 0xb000
	s_nop 0
	global_load_lds_dwordx4 v[70:71], off
	s_add_u32 m0, s100, 0xc000
	s_nop 0
	global_load_lds_dwordx4 v[76:77], off
	s_add_u32 m0, s100, 0xd000
	s_nop 0
	global_load_lds_dwordx4 v[78:79], off
	s_add_u32 m0, s100, 0xe000
	s_nop 0
	global_load_lds_dwordx4 v[72:73], off
	s_add_u32 m0, s100, 0xf000
	s_nop 0
	global_load_lds_dwordx4 v[74:75], off
	ds_read_b128 a[0:3], v115
	ds_read_b128 v[80:83], v116
	ds_read_b128 a[4:7], v115 offset:2048
	ds_read_b128 a[8:11], v115 offset:4096
	ds_read_b128 a[12:15], v115 offset:6144
	ds_read_b128 v[92:95], v116 offset:2048
	ds_read_b128 v[88:91], v116 offset:4096
	ds_read_b128 v[84:87], v116 offset:6144
	ds_read_b128 a[16:19], v117
	ds_read_b128 a[20:23], v117 offset:2048
	ds_read_b128 a[24:27], v117 offset:4096
	ds_read_b128 a[28:31], v117 offset:6144
	s_setprio 1
	s_waitcnt lgkmcnt(10)
	v_mfma_f32_16x16x32_bf16 v[0:3], a[0:3], v[80:83], v[0:3]
	s_waitcnt lgkmcnt(9)
	v_mfma_f32_16x16x32_bf16 v[16:19], a[4:7], v[80:83], v[16:19]
	s_waitcnt lgkmcnt(8)
	v_mfma_f32_16x16x32_bf16 v[32:35], a[8:11], v[80:83], v[32:35]
	s_waitcnt lgkmcnt(7)
	v_mfma_f32_16x16x32_bf16 v[48:51], a[12:15], v[80:83], v[48:51]
	ds_read_b128 v[80:83], v118
	s_waitcnt lgkmcnt(7)
	v_mfma_f32_16x16x32_bf16 v[4:7], a[0:3], v[92:95], v[4:7]
	v_mfma_f32_16x16x32_bf16 v[20:23], a[4:7], v[92:95], v[20:23]
	v_mfma_f32_16x16x32_bf16 v[36:39], a[8:11], v[92:95], v[36:39]
	v_mfma_f32_16x16x32_bf16 v[52:55], a[12:15], v[92:95], v[52:55]
	ds_read_b128 v[92:95], v118 offset:2048
	s_waitcnt lgkmcnt(7)
	v_mfma_f32_16x16x32_bf16 v[8:11], a[0:3], v[88:91], v[8:11]
	v_mfma_f32_16x16x32_bf16 v[24:27], a[4:7], v[88:91], v[24:27]
	v_mfma_f32_16x16x32_bf16 v[40:43], a[8:11], v[88:91], v[40:43]
	v_mfma_f32_16x16x32_bf16 v[56:59], a[12:15], v[88:91], v[56:59]
	ds_read_b128 v[88:91], v118 offset:4096
	s_waitcnt lgkmcnt(7)
	v_mfma_f32_16x16x32_bf16 v[12:15], a[0:3], v[84:87], v[12:15]
	v_mfma_f32_16x16x32_bf16 v[28:31], a[4:7], v[84:87], v[28:31]
	v_mfma_f32_16x16x32_bf16 v[44:47], a[8:11], v[84:87], v[44:47]
	v_mfma_f32_16x16x32_bf16 v[60:63], a[12:15], v[84:87], v[60:63]
	ds_read_b128 v[84:87], v118 offset:6144
	s_waitcnt lgkmcnt(3)
	v_mfma_f32_16x16x32_bf16 v[0:3], a[16:19], v[80:83], v[0:3]
	v_mfma_f32_16x16x32_bf16 v[16:19], a[20:23], v[80:83], v[16:19]
	v_mfma_f32_16x16x32_bf16 v[32:35], a[24:27], v[80:83], v[32:35]
	v_mfma_f32_16x16x32_bf16 v[48:51], a[28:31], v[80:83], v[48:51]
	s_waitcnt lgkmcnt(2)
	v_mfma_f32_16x16x32_bf16 v[4:7], a[16:19], v[92:95], v[4:7]
	v_mfma_f32_16x16x32_bf16 v[20:23], a[20:23], v[92:95], v[20:23]
	v_mfma_f32_16x16x32_bf16 v[36:39], a[24:27], v[92:95], v[36:39]
	v_mfma_f32_16x16x32_bf16 v[52:55], a[28:31], v[92:95], v[52:55]
	s_waitcnt lgkmcnt(1)
	v_mfma_f32_16x16x32_bf16 v[8:11], a[16:19], v[88:91], v[8:11]
	v_mfma_f32_16x16x32_bf16 v[24:27], a[20:23], v[88:91], v[24:27]
	v_mfma_f32_16x16x32_bf16 v[40:43], a[24:27], v[88:91], v[40:43]
	v_mfma_f32_16x16x32_bf16 v[56:59], a[28:31], v[88:91], v[56:59]
	s_waitcnt lgkmcnt(0)
	v_mfma_f32_16x16x32_bf16 v[12:15], a[16:19], v[84:87], v[12:15]
	v_mfma_f32_16x16x32_bf16 v[28:31], a[20:23], v[84:87], v[28:31]
	v_mfma_f32_16x16x32_bf16 v[44:47], a[24:27], v[84:87], v[44:47]
	v_mfma_f32_16x16x32_bf16 v[60:63], a[28:31], v[84:87], v[60:63]
	s_setprio 0
	s_waitcnt vmcnt(0) lgkmcnt(0)
	s_barrier
	ds_read_b128 a[0:3], v115 offset:32768
	ds_read_b128 v[80:83], v116 offset:32768
	ds_read_b128 a[4:7], v115 offset:34816
	ds_read_b128 a[8:11], v115 offset:36864
	ds_read_b128 a[12:15], v115 offset:38912
	ds_read_b128 v[92:95], v116 offset:34816
	ds_read_b128 v[88:91], v116 offset:36864
	ds_read_b128 v[84:87], v116 offset:38912
	ds_read_b128 a[16:19], v117 offset:32768
	ds_read_b128 a[20:23], v117 offset:34816
	ds_read_b128 a[24:27], v117 offset:36864
	ds_read_b128 a[28:31], v117 offset:38912
	s_setprio 1
	s_waitcnt lgkmcnt(10)
	v_mfma_f32_16x16x32_bf16 v[0:3], a[0:3], v[80:83], v[0:3]
	s_waitcnt lgkmcnt(9)
	v_mfma_f32_16x16x32_bf16 v[16:19], a[4:7], v[80:83], v[16:19]
	s_waitcnt lgkmcnt(8)
	v_mfma_f32_16x16x32_bf16 v[32:35], a[8:11], v[80:83], v[32:35]
	s_waitcnt lgkmcnt(7)
	v_mfma_f32_16x16x32_bf16 v[48:51], a[12:15], v[80:83], v[48:51]
	ds_read_b128 v[80:83], v118 offset:32768
	s_waitcnt lgkmcnt(7)
	v_mfma_f32_16x16x32_bf16 v[4:7], a[0:3], v[92:95], v[4:7]
	v_mfma_f32_16x16x32_bf16 v[20:23], a[4:7], v[92:95], v[20:23]
	v_mfma_f32_16x16x32_bf16 v[36:39], a[8:11], v[92:95], v[36:39]
	v_mfma_f32_16x16x32_bf16 v[52:55], a[12:15], v[92:95], v[52:55]
	ds_read_b128 v[92:95], v118 offset:34816
	s_waitcnt lgkmcnt(7)
	v_mfma_f32_16x16x32_bf16 v[8:11], a[0:3], v[88:91], v[8:11]
	v_mfma_f32_16x16x32_bf16 v[24:27], a[4:7], v[88:91], v[24:27]
	v_mfma_f32_16x16x32_bf16 v[40:43], a[8:11], v[88:91], v[40:43]
	v_mfma_f32_16x16x32_bf16 v[56:59], a[12:15], v[88:91], v[56:59]
	ds_read_b128 v[88:91], v118 offset:36864
	s_waitcnt lgkmcnt(7)
	v_mfma_f32_16x16x32_bf16 v[12:15], a[0:3], v[84:87], v[12:15]
	v_mfma_f32_16x16x32_bf16 v[28:31], a[4:7], v[84:87], v[28:31]
	v_mfma_f32_16x16x32_bf16 v[44:47], a[8:11], v[84:87], v[44:47]
	v_mfma_f32_16x16x32_bf16 v[60:63], a[12:15], v[84:87], v[60:63]
	ds_read_b128 v[84:87], v118 offset:38912
	s_waitcnt lgkmcnt(3)
	v_mfma_f32_16x16x32_bf16 v[0:3], a[16:19], v[80:83], v[0:3]
	v_mfma_f32_16x16x32_bf16 v[16:19], a[20:23], v[80:83], v[16:19]
	v_mfma_f32_16x16x32_bf16 v[32:35], a[24:27], v[80:83], v[32:35]
	v_mfma_f32_16x16x32_bf16 v[48:51], a[28:31], v[80:83], v[48:51]
	s_waitcnt lgkmcnt(2)
	v_mfma_f32_16x16x32_bf16 v[4:7], a[16:19], v[92:95], v[4:7]
	v_mfma_f32_16x16x32_bf16 v[20:23], a[20:23], v[92:95], v[20:23]
	v_mfma_f32_16x16x32_bf16 v[36:39], a[24:27], v[92:95], v[36:39]
	v_mfma_f32_16x16x32_bf16 v[52:55], a[28:31], v[92:95], v[52:55]
	s_waitcnt lgkmcnt(1)
	v_mfma_f32_16x16x32_bf16 v[8:11], a[16:19], v[88:91], v[8:11]
	v_mfma_f32_16x16x32_bf16 v[24:27], a[20:23], v[88:91], v[24:27]
	v_mfma_f32_16x16x32_bf16 v[40:43], a[24:27], v[88:91], v[40:43]
	v_mfma_f32_16x16x32_bf16 v[56:59], a[28:31], v[88:91], v[56:59]
	s_waitcnt lgkmcnt(0)
	v_mfma_f32_16x16x32_bf16 v[12:15], a[16:19], v[84:87], v[12:15]
	v_mfma_f32_16x16x32_bf16 v[28:31], a[20:23], v[84:87], v[28:31]
	v_mfma_f32_16x16x32_bf16 v[44:47], a[24:27], v[84:87], v[44:47]
	v_mfma_f32_16x16x32_bf16 v[60:63], a[28:31], v[84:87], v[60:63]
	s_setprio 0
	v_readfirstlane_b32 s15, v107
	v_readfirstlane_b32 s4, v106
	s_lshl_b32 s15, s15, 6
	s_waitcnt lgkmcnt(0)
	s_barrier
	s_add_i32 s9, s15, s9
	s_lshl_b32 s15, s4, 17
	s_lshl_b32 s4, s8, 18
	s_add_i32 s15, s15, s4
	v_or_b32_e32 v64, s9, v108
	s_movk_i32 s4, 0x800
	v_cmp_gt_i32_e32 vcc, s4, v64
	s_barrier
	v_and_b32_e32 v124, 15, v143
	v_bfe_u32 v125, v143, 4, 2
	v_xor_b32_e32 v125, v125, v124
	v_lshlrev_b32_e32 v125, 4, v125
	v_lshl_add_u32 v125, v124, 8, v125
	v_lshrrev_b32_e32 v124, 6, v143
	v_lshl_add_u32 v125, v124, 14, v125
	ds_write_b128 v125, v[0:3]
	ds_write_b128 v125, v[4:7] offset:4096
	ds_write_b128 v125, v[8:11] offset:8192
	ds_write_b128 v125, v[12:15] offset:12288
	v_xor_b32_e32 v118, 64, v125
	ds_write_b128 v118, v[16:19]
	ds_write_b128 v118, v[20:23] offset:4096
	ds_write_b128 v118, v[24:27] offset:8192
	ds_write_b128 v118, v[28:31] offset:12288
	v_xor_b32_e32 v118, 128, v125
	ds_write_b128 v118, v[32:35]
	ds_write_b128 v118, v[36:39] offset:4096
	ds_write_b128 v118, v[40:43] offset:8192
	ds_write_b128 v118, v[44:47] offset:12288
	v_xor_b32_e32 v118, 192, v125
	ds_write_b128 v118, v[48:51]
	ds_write_b128 v118, v[52:55] offset:4096
	ds_write_b128 v118, v[56:59] offset:8192
	ds_write_b128 v118, v[60:63] offset:12288
	v_and_b32_e32 v115, 31, v143
	v_bfe_u32 v117, v143, 5, 1
	v_and_b32_e32 v125, 15, v115
	v_xor_b32_e32 v117, v117, v125
	v_lshlrev_b32_e32 v117, 4, v117
	v_lshl_add_u32 v117, v115, 8, v117
	v_lshl_add_u32 v117, v124, 14, v117
	ds_read_b128 v[48:51], v117
	ds_read_b128 v[32:35], v117 offset:8192
	v_xor_b32_e32 v116, 32, v117
	ds_read_b128 v[52:55], v116
	ds_read_b128 v[36:39], v116 offset:8192
	v_xor_b32_e32 v116, 64, v117
	ds_read_b128 v[56:59], v116
	ds_read_b128 v[40:43], v116 offset:8192
	v_xor_b32_e32 v116, 96, v117
	ds_read_b128 v[60:63], v116
	ds_read_b128 v[44:47], v116 offset:8192
	v_xor_b32_e32 v116, 128, v117
	ds_read_b128 v[16:19], v116
	ds_read_b128 v[0:3], v116 offset:8192
	v_xor_b32_e32 v116, 160, v117
	ds_read_b128 v[20:23], v116
	ds_read_b128 v[4:7], v116 offset:8192
	v_xor_b32_e32 v116, 192, v117
	ds_read_b128 v[24:27], v116
	ds_read_b128 v[8:11], v116 offset:8192
	v_xor_b32_e32 v116, 224, v117
	ds_read_b128 v[28:31], v116
	ds_read_b128 v[12:15], v116 offset:8192
	s_waitcnt lgkmcnt(0)
	s_barrier
	s_and_saveexec_b64 s[8:9], vcc
	s_cbranch_execz .LBB0_599
	v_add_u32_e32 v65, s15, v64
	v_add_u32_e32 v66, v65, v111
	v_mov_b32_e32 v67, v140
	v_lshl_add_u64 v[68:69], v[66:67], 2, s[26:27]
	global_store_dword v[68:69], v48, off
	v_add_u32_e32 v68, 0x800, v66
	v_mov_b32_e32 v69, v140
	v_lshl_add_u64 v[68:69], v[68:69], 2, s[26:27]
	global_store_dword v[68:69], v49, off
	v_add_u32_e32 v48, 0x1000, v66
	v_mov_b32_e32 v49, v140
	v_lshl_add_u64 v[48:49], v[48:49], 2, s[26:27]
	global_store_dword v[48:49], v50, off
	v_add_u32_e32 v48, 0x1800, v66
	v_mov_b32_e32 v49, v140
	v_lshl_add_u64 v[48:49], v[48:49], 2, s[26:27]
	global_store_dword v[48:49], v51, off
	v_add_u32_e32 v48, v65, v112
	v_mov_b32_e32 v49, v140
	v_lshl_add_u64 v[50:51], v[48:49], 2, s[26:27]
	global_store_dword v[50:51], v52, off
	v_add_u32_e32 v50, 0x800, v48
	v_mov_b32_e32 v51, v140
	v_lshl_add_u64 v[50:51], v[50:51], 2, s[26:27]
	global_store_dword v[50:51], v53, off
	v_add_u32_e32 v50, 0x1000, v48
	v_mov_b32_e32 v51, v140
	v_add_u32_e32 v48, 0x1800, v48
	v_lshl_add_u64 v[50:51], v[50:51], 2, s[26:27]
	v_lshl_add_u64 v[48:49], v[48:49], 2, s[26:27]
	global_store_dword v[50:51], v54, off
	global_store_dword v[48:49], v55, off
	v_add_u32_e32 v48, v65, v113
	v_mov_b32_e32 v49, v140
	v_lshl_add_u64 v[50:51], v[48:49], 2, s[26:27]
	global_store_dword v[50:51], v56, off
	v_add_u32_e32 v50, 0x800, v48
	v_mov_b32_e32 v51, v140
	v_lshl_add_u64 v[50:51], v[50:51], 2, s[26:27]
	global_store_dword v[50:51], v57, off
	v_add_u32_e32 v50, 0x1000, v48
	v_mov_b32_e32 v51, v140
	v_add_u32_e32 v48, 0x1800, v48
	v_lshl_add_u64 v[50:51], v[50:51], 2, s[26:27]
	v_lshl_add_u64 v[48:49], v[48:49], 2, s[26:27]
	global_store_dword v[50:51], v58, off
	global_store_dword v[48:49], v59, off
	v_add_u32_e32 v48, v65, v114
	v_mov_b32_e32 v49, v140
	v_lshl_add_u64 v[50:51], v[48:49], 2, s[26:27]
	global_store_dword v[50:51], v60, off
	v_add_u32_e32 v50, 0x800, v48
	v_mov_b32_e32 v51, v140
	v_lshl_add_u64 v[50:51], v[50:51], 2, s[26:27]
	global_store_dword v[50:51], v61, off
	v_add_u32_e32 v50, 0x1000, v48
	v_mov_b32_e32 v51, v140
	v_add_u32_e32 v48, 0x1800, v48
	v_lshl_add_u64 v[50:51], v[50:51], 2, s[26:27]
	v_lshl_add_u64 v[48:49], v[48:49], 2, s[26:27]
	global_store_dword v[50:51], v62, off
	global_store_dword v[48:49], v63, off

.LBB0_608:
	s_mul_hi_i32 s4, s22, 0x38e38e39
	s_lshr_b32 s8, s4, 31
	s_ashr_i32 s4, s4, 4
	s_add_i32 s4, s4, s8
	s_mul_i32 s8, s4, 0x48
	s_sub_i32 s8, s22, s8
	v_lshl_add_u32 v0, s8, 7, v109
	v_ashrrev_i32_e32 v1, 31, v0
	v_lshlrev_b64 v[32:33], 12, v[0:1]
	v_lshl_add_u64 v[34:35], v[96:97], 0, v[32:33]
	v_add_co_u32_e32 v40, vcc, s87, v34
	s_lshl_b32 s9, s4, 7
	s_nop 0
	v_addc_co_u32_e32 v41, vcc, 0, v35, vcc
	v_add_co_u32_e32 v42, vcc, s66, v34
	v_add_u32_e32 v0, s9, v109
	s_nop 0
	v_addc_co_u32_e32 v43, vcc, 0, v35, vcc
	v_ashrrev_i32_e32 v1, 31, v0
	v_add_co_u32_e32 v44, vcc, s20, v34
	v_lshlrev_b64 v[36:37], 12, v[0:1]
	s_nop 0
	v_addc_co_u32_e32 v45, vcc, 0, v35, vcc
	v_lshl_add_u64 v[38:39], v[98:99], 0, v[36:37]
	v_readfirstlane_b32 s100, v110
	s_nop 3
	s_add_u32 m0, s100, 0x0
	s_nop 0
	global_load_lds_dwordx4 v[34:35], off
	s_add_u32 m0, s100, 0x1000
	s_nop 0
	global_load_lds_dwordx4 v[40:41], off
	s_add_u32 m0, s100, 0x2000
	s_nop 0
	global_load_lds_dwordx4 v[42:43], off
	s_add_u32 m0, s100, 0x3000
	s_nop 0
	global_load_lds_dwordx4 v[44:45], off
	s_add_u32 m0, s100, 0x4000
	s_nop 0
	global_load_lds_dwordx4 v[38:39], off
	v_add_co_u32_e32 v46, vcc, s87, v38
	v_lshl_add_u64 v[102:103], v[100:101], 0, v[36:37]
	s_nop 0
	v_addc_co_u32_e32 v47, vcc, 0, v39, vcc
	s_waitcnt vmcnt(16)
	v_add_co_u32_e32 v48, vcc, s66, v38
	s_add_u32 m0, s100, 0x5000
	s_nop 0
	global_load_lds_dwordx4 v[46:47], off
	s_nop 0
	v_addc_co_u32_e32 v49, vcc, 0, v39, vcc
	v_add_co_u32_e32 v50, vcc, s20, v38
	s_add_u32 m0, s100, 0x6000
	s_nop 0
	global_load_lds_dwordx4 v[48:49], off
	s_nop 0
	v_addc_co_u32_e32 v51, vcc, 0, v39, vcc
	s_add_u32 m0, s100, 0x7000
	s_nop 0
	global_load_lds_dwordx4 v[50:51], off
	v_lshl_add_u64 v[104:105], v[100:101], 0, v[32:33]
	s_mov_b64 s[28:29], 0
	v_mov_b32_e32 v0, 0
	v_mov_b32_e32 v1, v0
	v_mov_b32_e32 v2, v0
	v_mov_b32_e32 v3, v0
	v_mov_b32_e32 v4, v0
	v_mov_b32_e32 v5, v0
	v_mov_b32_e32 v6, v0
	v_mov_b32_e32 v7, v0
	v_mov_b32_e32 v8, v0
	v_mov_b32_e32 v9, v0
	v_mov_b32_e32 v10, v0
	v_mov_b32_e32 v11, v0
	v_mov_b32_e32 v12, v0
	v_mov_b32_e32 v13, v0
	v_mov_b32_e32 v14, v0
	v_mov_b32_e32 v15, v0
	v_mov_b32_e32 v16, v0
	v_mov_b32_e32 v17, v0
	v_mov_b32_e32 v18, v0
	v_mov_b32_e32 v19, v0
	v_mov_b32_e32 v20, v0
	v_mov_b32_e32 v21, v0
	v_mov_b32_e32 v22, v0
	v_mov_b32_e32 v23, v0
	v_mov_b32_e32 v24, v0
	v_mov_b32_e32 v25, v0
	v_mov_b32_e32 v26, v0
	v_mov_b32_e32 v27, v0
	v_mov_b32_e32 v28, v0
	v_mov_b32_e32 v29, v0
	v_mov_b32_e32 v30, v0
	v_mov_b32_e32 v31, v0
	v_mov_b32_e32 v32, v0
	v_mov_b32_e32 v33, v0
	v_mov_b32_e32 v34, v0
	v_mov_b32_e32 v35, v0
	v_mov_b32_e32 v36, v0
	v_mov_b32_e32 v37, v0
	v_mov_b32_e32 v38, v0
	v_mov_b32_e32 v39, v0
	v_mov_b32_e32 v40, v0
	v_mov_b32_e32 v41, v0
	v_mov_b32_e32 v42, v0
	v_mov_b32_e32 v43, v0
	v_mov_b32_e32 v44, v0
	v_mov_b32_e32 v45, v0
	v_mov_b32_e32 v46, v0
	v_mov_b32_e32 v47, v0
	v_mov_b32_e32 v48, v0
	v_mov_b32_e32 v49, v0
	v_mov_b32_e32 v50, v0
	v_mov_b32_e32 v51, v0
	v_mov_b32_e32 v52, v0
	v_mov_b32_e32 v53, v0
	v_mov_b32_e32 v54, v0
	v_mov_b32_e32 v55, v0
	v_mov_b32_e32 v56, v0
	v_mov_b32_e32 v57, v0
	v_mov_b32_e32 v58, v0
	v_mov_b32_e32 v59, v0
	v_mov_b32_e32 v60, v0
	v_mov_b32_e32 v61, v0
	v_mov_b32_e32 v62, v0
	v_mov_b32_e32 v63, v0
	v_lshl_add_u64 v[128:129], v[104:105], 0, s[28:29]
	s_mov_b32 s4, 0x1c6b8000
	v_add_co_u32_e32 v144, vcc, s4, v128
	s_mov_b32 s4, 0x1c6d8000
	s_nop 0
	v_addc_co_u32_e32 v145, vcc, 0, v129, vcc
	v_add_co_u32_e32 v146, vcc, s4, v128
	s_mov_b32 s4, 0x1c6f8000
	s_nop 0
	v_addc_co_u32_e32 v147, vcc, 0, v129, vcc
	v_add_co_u32_e32 v148, vcc, s4, v128
	s_mov_b32 s4, 0x1c718000
	s_nop 0
	v_addc_co_u32_e32 v149, vcc, 0, v129, vcc
	v_add_co_u32_e32 v150, vcc, s4, v128
	v_lshl_add_u64 v[130:131], v[102:103], 0, s[28:29]
	s_nop 0
	v_addc_co_u32_e32 v151, vcc, 0, v129, vcc
	s_mov_b32 s4, 0x37b80000
	v_add_co_u32_e32 v152, vcc, s4, v130
	s_mov_b32 s4, 0x37ba0000
	s_nop 0
	v_addc_co_u32_e32 v153, vcc, 0, v131, vcc
	v_add_co_u32_e32 v154, vcc, s4, v130
	s_mov_b32 s4, 0x37bc0000
	s_nop 0
	v_addc_co_u32_e32 v155, vcc, 0, v131, vcc
	v_add_co_u32_e32 v156, vcc, s4, v130
	s_mov_b32 s4, 0x37be0000
	s_nop 0
	v_addc_co_u32_e32 v157, vcc, 0, v131, vcc
	v_add_co_u32_e32 v178, vcc, s4, v130
	v_addc_co_u32_e32 v179, vcc, 0, v131, vcc
	v_lshl_add_u64 v[144:145], 8, 4, v[144:145]
	v_lshl_add_u64 v[146:147], 8, 4, v[146:147]
	v_lshl_add_u64 v[148:149], 8, 4, v[148:149]
	v_lshl_add_u64 v[150:151], 8, 4, v[150:151]
	v_lshl_add_u64 v[152:153], 8, 4, v[152:153]
	v_lshl_add_u64 v[154:155], 8, 4, v[154:155]
	v_lshl_add_u64 v[156:157], 8, 4, v[156:157]
	v_lshl_add_u64 v[178:179], 8, 4, v[178:179]
	v_and_b32_e32 v124, 15, v143
	v_lshrrev_b32_e32 v125, 1, v124
	v_bfe_u32 v117, v143, 4, 2
	v_xor_b32_e32 v125, v125, v117
	v_lshlrev_b32_e32 v125, 4, v125
	v_lshl_add_u32 v125, v124, 7, v125
	v_lshrrev_b32_e32 v124, 6, v143
	v_lshrrev_b32_e32 v115, 1, v124
	v_and_b32_e32 v124, 1, v124
	v_lshl_add_u32 v115, v115, 13, v125
	v_lshl_add_u32 v116, v124, 13, v125
	v_add_u32_e32 v116, 0x4000, v116
	v_xor_b32_e32 v117, 64, v115
	v_xor_b32_e32 v118, 64, v116
	s_waitcnt vmcnt(0) lgkmcnt(0)
	s_barrier
.LBB0_609:
	s_add_u32 m0, s100, 0x8000
	s_nop 0
	global_load_lds_dwordx4 v[144:145], off
	s_add_u32 m0, s100, 0x9000
	s_nop 0
	global_load_lds_dwordx4 v[146:147], off
	s_add_u32 m0, s100, 0xa000
	s_nop 0
	global_load_lds_dwordx4 v[148:149], off
	s_add_u32 m0, s100, 0xb000
	s_nop 0
	global_load_lds_dwordx4 v[150:151], off
	s_add_u32 m0, s100, 0xc000
	s_nop 0
	global_load_lds_dwordx4 v[152:153], off
	s_add_u32 m0, s100, 0xd000
	s_nop 0
	global_load_lds_dwordx4 v[154:155], off
	s_add_u32 m0, s100, 0xe000
	s_nop 0
	global_load_lds_dwordx4 v[156:157], off
	s_add_u32 m0, s100, 0xf000
	s_nop 0
	global_load_lds_dwordx4 v[178:179], off
	ds_read_b128 a[0:3], v115
	ds_read_b128 v[80:83], v116
	ds_read_b128 a[4:7], v115 offset:2048
	ds_read_b128 a[8:11], v115 offset:4096
	ds_read_b128 a[12:15], v115 offset:6144
	ds_read_b128 v[92:95], v116 offset:2048
	ds_read_b128 v[88:91], v116 offset:4096
	ds_read_b128 v[84:87], v116 offset:6144
	ds_read_b128 a[16:19], v117
	ds_read_b128 a[20:23], v117 offset:2048
	ds_read_b128 a[24:27], v117 offset:4096
	ds_read_b128 a[28:31], v117 offset:6144
	s_setprio 1
	s_waitcnt lgkmcnt(10)
	v_mfma_f32_16x16x32_bf16 v[0:3], a[0:3], v[80:83], v[0:3]
	s_waitcnt lgkmcnt(9)
	v_mfma_f32_16x16x32_bf16 v[16:19], a[4:7], v[80:83], v[16:19]
	s_waitcnt lgkmcnt(8)
	v_mfma_f32_16x16x32_bf16 v[32:35], a[8:11], v[80:83], v[32:35]
	s_waitcnt lgkmcnt(7)
	v_mfma_f32_16x16x32_bf16 v[48:51], a[12:15], v[80:83], v[48:51]
	ds_read_b128 v[80:83], v118
	s_waitcnt lgkmcnt(7)
	v_mfma_f32_16x16x32_bf16 v[4:7], a[0:3], v[92:95], v[4:7]
	v_lshl_add_u64 v[64:65], 8, 4, v[144:145]
	v_lshl_add_u64 v[66:67], 8, 4, v[146:147]
	v_lshl_add_u64 v[68:69], 8, 4, v[148:149]
	v_mfma_f32_16x16x32_bf16 v[20:23], a[4:7], v[92:95], v[20:23]
	v_lshl_add_u64 v[70:71], 8, 4, v[150:151]
	v_lshl_add_u64 v[76:77], 8, 4, v[152:153]
	v_lshl_add_u64 v[78:79], 8, 4, v[154:155]
	v_mfma_f32_16x16x32_bf16 v[36:39], a[8:11], v[92:95], v[36:39]
	v_lshl_add_u64 v[72:73], 8, 4, v[156:157]
	v_lshl_add_u64 v[74:75], 8, 4, v[178:179]
	v_mfma_f32_16x16x32_bf16 v[52:55], a[12:15], v[92:95], v[52:55]
	ds_read_b128 v[92:95], v118 offset:2048
	s_waitcnt lgkmcnt(7)
	v_mfma_f32_16x16x32_bf16 v[8:11], a[0:3], v[88:91], v[8:11]
	v_mfma_f32_16x16x32_bf16 v[24:27], a[4:7], v[88:91], v[24:27]
	v_mfma_f32_16x16x32_bf16 v[40:43], a[8:11], v[88:91], v[40:43]
	v_mfma_f32_16x16x32_bf16 v[56:59], a[12:15], v[88:91], v[56:59]
	ds_read_b128 v[88:91], v118 offset:4096
	s_waitcnt lgkmcnt(7)
	v_mfma_f32_16x16x32_bf16 v[12:15], a[0:3], v[84:87], v[12:15]
	v_mfma_f32_16x16x32_bf16 v[28:31], a[4:7], v[84:87], v[28:31]
	v_mfma_f32_16x16x32_bf16 v[44:47], a[8:11], v[84:87], v[44:47]
	v_mfma_f32_16x16x32_bf16 v[60:63], a[12:15], v[84:87], v[60:63]
	ds_read_b128 v[84:87], v118 offset:6144
	s_waitcnt lgkmcnt(3)
	v_mfma_f32_16x16x32_bf16 v[0:3], a[16:19], v[80:83], v[0:3]
	v_mfma_f32_16x16x32_bf16 v[16:19], a[20:23], v[80:83], v[16:19]
	v_mfma_f32_16x16x32_bf16 v[32:35], a[24:27], v[80:83], v[32:35]
	v_mfma_f32_16x16x32_bf16 v[48:51], a[28:31], v[80:83], v[48:51]
	s_waitcnt lgkmcnt(2)
	v_mfma_f32_16x16x32_bf16 v[4:7], a[16:19], v[92:95], v[4:7]
	v_mfma_f32_16x16x32_bf16 v[20:23], a[20:23], v[92:95], v[20:23]
	v_mfma_f32_16x16x32_bf16 v[36:39], a[24:27], v[92:95], v[36:39]
	v_mfma_f32_16x16x32_bf16 v[52:55], a[28:31], v[92:95], v[52:55]
	s_waitcnt lgkmcnt(1)
	v_mfma_f32_16x16x32_bf16 v[8:11], a[16:19], v[88:91], v[8:11]
	v_mfma_f32_16x16x32_bf16 v[24:27], a[20:23], v[88:91], v[24:27]
	v_mfma_f32_16x16x32_bf16 v[40:43], a[24:27], v[88:91], v[40:43]
	v_mfma_f32_16x16x32_bf16 v[56:59], a[28:31], v[88:91], v[56:59]
	s_waitcnt lgkmcnt(0)
	v_mfma_f32_16x16x32_bf16 v[12:15], a[16:19], v[84:87], v[12:15]
	v_mfma_f32_16x16x32_bf16 v[28:31], a[20:23], v[84:87], v[28:31]
	v_mfma_f32_16x16x32_bf16 v[44:47], a[24:27], v[84:87], v[44:47]
	v_mfma_f32_16x16x32_bf16 v[60:63], a[28:31], v[84:87], v[60:63]
	s_setprio 0
	s_waitcnt vmcnt(0) lgkmcnt(0)
	s_barrier
	s_add_u32 s28, s28, 0x100
	s_addc_u32 s29, s29, 0
	s_add_u32 m0, s100, 0x0
	s_nop 0
	global_load_lds_dwordx4 v[64:65], off
	s_add_u32 m0, s100, 0x1000
	s_nop 0
	global_load_lds_dwordx4 v[66:67], off
	s_add_u32 m0, s100, 0x2000
	s_nop 0
	global_load_lds_dwordx4 v[68:69], off
	s_add_u32 m0, s100, 0x3000
	s_nop 0
	global_load_lds_dwordx4 v[70:71], off
	s_add_u32 m0, s100, 0x4000
	s_nop 0
	global_load_lds_dwordx4 v[76:77], off
	s_add_u32 m0, s100, 0x5000
	s_nop 0
	global_load_lds_dwordx4 v[78:79], off
	s_add_u32 m0, s100, 0x6000
	s_nop 0
	global_load_lds_dwordx4 v[72:73], off
	s_add_u32 m0, s100, 0x7000
	s_nop 0
	global_load_lds_dwordx4 v[74:75], off
	ds_read_b128 a[0:3], v115 offset:32768
	ds_read_b128 v[80:83], v116 offset:32768
	ds_read_b128 a[4:7], v115 offset:34816
	ds_read_b128 a[8:11], v115 offset:36864
	ds_read_b128 a[12:15], v115 offset:38912
	ds_read_b128 v[92:95], v116 offset:34816
	ds_read_b128 v[88:91], v116 offset:36864
	ds_read_b128 v[84:87], v116 offset:38912
	ds_read_b128 a[16:19], v117 offset:32768
	ds_read_b128 a[20:23], v117 offset:34816
	ds_read_b128 a[24:27], v117 offset:36864
	ds_read_b128 a[28:31], v117 offset:38912
	s_setprio 1
	s_waitcnt lgkmcnt(10)
	v_mfma_f32_16x16x32_bf16 v[0:3], a[0:3], v[80:83], v[0:3]
	s_waitcnt lgkmcnt(9)
	v_mfma_f32_16x16x32_bf16 v[16:19], a[4:7], v[80:83], v[16:19]
	s_waitcnt lgkmcnt(8)
	v_mfma_f32_16x16x32_bf16 v[32:35], a[8:11], v[80:83], v[32:35]
	s_waitcnt lgkmcnt(7)
	v_mfma_f32_16x16x32_bf16 v[48:51], a[12:15], v[80:83], v[48:51]
	ds_read_b128 v[80:83], v118 offset:32768
	s_waitcnt lgkmcnt(7)
	v_mfma_f32_16x16x32_bf16 v[4:7], a[0:3], v[92:95], v[4:7]
	v_lshl_add_u64 v[128:129], v[104:105], 0, s[28:29]
	s_mov_b32 s4, 0x1c6b8000
	v_add_co_u32_e32 v144, vcc, s4, v128
	v_mfma_f32_16x16x32_bf16 v[20:23], a[4:7], v[92:95], v[20:23]
	s_mov_b32 s4, 0x1c6d8000
	s_nop 0
	v_addc_co_u32_e32 v145, vcc, 0, v129, vcc
	v_mfma_f32_16x16x32_bf16 v[36:39], a[8:11], v[92:95], v[36:39]
	v_add_co_u32_e32 v146, vcc, s4, v128
	s_mov_b32 s4, 0x1c6f8000
	s_nop 0
	v_mfma_f32_16x16x32_bf16 v[52:55], a[12:15], v[92:95], v[52:55]
	v_addc_co_u32_e32 v147, vcc, 0, v129, vcc
	v_add_co_u32_e32 v148, vcc, s4, v128
	s_mov_b32 s4, 0x1c718000
	ds_read_b128 v[92:95], v118 offset:34816
	s_waitcnt lgkmcnt(7)
	v_mfma_f32_16x16x32_bf16 v[8:11], a[0:3], v[88:91], v[8:11]
	s_nop 0
	v_addc_co_u32_e32 v149, vcc, 0, v129, vcc
	v_add_co_u32_e32 v150, vcc, s4, v128
	v_mfma_f32_16x16x32_bf16 v[24:27], a[4:7], v[88:91], v[24:27]
	v_lshl_add_u64 v[130:131], v[102:103], 0, s[28:29]
	s_nop 0
	v_addc_co_u32_e32 v151, vcc, 0, v129, vcc
	v_mfma_f32_16x16x32_bf16 v[40:43], a[8:11], v[88:91], v[40:43]
	s_mov_b32 s4, 0x37b80000
	v_add_co_u32_e32 v152, vcc, s4, v130
	s_mov_b32 s4, 0x37ba0000
	v_mfma_f32_16x16x32_bf16 v[56:59], a[12:15], v[88:91], v[56:59]
	s_nop 0
	v_addc_co_u32_e32 v153, vcc, 0, v131, vcc
	v_add_co_u32_e32 v154, vcc, s4, v130
	ds_read_b128 v[88:91], v118 offset:36864
	s_waitcnt lgkmcnt(7)
	v_mfma_f32_16x16x32_bf16 v[12:15], a[0:3], v[84:87], v[12:15]
	s_mov_b32 s4, 0x37bc0000
	s_nop 0
	v_addc_co_u32_e32 v155, vcc, 0, v131, vcc
	v_mfma_f32_16x16x32_bf16 v[28:31], a[4:7], v[84:87], v[28:31]
	v_add_co_u32_e32 v156, vcc, s4, v130
	s_mov_b32 s4, 0x37be0000
	s_nop 0
	v_mfma_f32_16x16x32_bf16 v[44:47], a[8:11], v[84:87], v[44:47]
	v_addc_co_u32_e32 v157, vcc, 0, v131, vcc
	v_add_co_u32_e32 v178, vcc, s4, v130
	v_addc_co_u32_e32 v179, vcc, 0, v131, vcc
	v_mfma_f32_16x16x32_bf16 v[60:63], a[12:15], v[84:87], v[60:63]
	v_lshl_add_u64 v[144:145], 8, 4, v[144:145]
	v_lshl_add_u64 v[146:147], 8, 4, v[146:147]
	v_lshl_add_u64 v[148:149], 8, 4, v[148:149]
	ds_read_b128 v[84:87], v118 offset:38912
	s_waitcnt lgkmcnt(3)
	v_mfma_f32_16x16x32_bf16 v[0:3], a[16:19], v[80:83], v[0:3]
	v_lshl_add_u64 v[150:151], 8, 4, v[150:151]
	v_lshl_add_u64 v[152:153], 8, 4, v[152:153]
	v_lshl_add_u64 v[154:155], 8, 4, v[154:155]
	v_mfma_f32_16x16x32_bf16 v[16:19], a[20:23], v[80:83], v[16:19]
	v_lshl_add_u64 v[156:157], 8, 4, v[156:157]
	v_lshl_add_u64 v[178:179], 8, 4, v[178:179]
	v_mfma_f32_16x16x32_bf16 v[32:35], a[24:27], v[80:83], v[32:35]
	v_mfma_f32_16x16x32_bf16 v[48:51], a[28:31], v[80:83], v[48:51]
	s_waitcnt lgkmcnt(2)
	v_mfma_f32_16x16x32_bf16 v[4:7], a[16:19], v[92:95], v[4:7]
	v_mfma_f32_16x16x32_bf16 v[20:23], a[20:23], v[92:95], v[20:23]
	v_mfma_f32_16x16x32_bf16 v[36:39], a[24:27], v[92:95], v[36:39]
	v_mfma_f32_16x16x32_bf16 v[52:55], a[28:31], v[92:95], v[52:55]
	s_waitcnt lgkmcnt(1)
	v_mfma_f32_16x16x32_bf16 v[8:11], a[16:19], v[88:91], v[8:11]
	v_mfma_f32_16x16x32_bf16 v[24:27], a[20:23], v[88:91], v[24:27]
	v_mfma_f32_16x16x32_bf16 v[40:43], a[24:27], v[88:91], v[40:43]
	v_mfma_f32_16x16x32_bf16 v[56:59], a[28:31], v[88:91], v[56:59]
	s_waitcnt lgkmcnt(0)
	v_mfma_f32_16x16x32_bf16 v[12:15], a[16:19], v[84:87], v[12:15]
	v_mfma_f32_16x16x32_bf16 v[28:31], a[20:23], v[84:87], v[28:31]
	v_mfma_f32_16x16x32_bf16 v[44:47], a[24:27], v[84:87], v[44:47]
	v_mfma_f32_16x16x32_bf16 v[60:63], a[28:31], v[84:87], v[60:63]
	s_setprio 0
	s_waitcnt vmcnt(0) lgkmcnt(0)
	s_barrier
	s_cmpk_eq_i32 s28, 0xf00
	s_cbranch_scc0 .LBB0_609
	v_lshl_add_u64 v[64:65], 8, 4, v[64:65]
	v_lshl_add_u64 v[66:67], 8, 4, v[66:67]
	v_lshl_add_u64 v[68:69], 8, 4, v[68:69]
	v_lshl_add_u64 v[70:71], 8, 4, v[70:71]
	v_lshl_add_u64 v[76:77], 8, 4, v[76:77]
	v_lshl_add_u64 v[78:79], 8, 4, v[78:79]
	v_lshl_add_u64 v[72:73], 8, 4, v[72:73]
	v_lshl_add_u64 v[74:75], 8, 4, v[74:75]
	s_add_u32 m0, s100, 0x8000
	s_nop 0
	global_load_lds_dwordx4 v[64:65], off
	s_add_u32 m0, s100, 0x9000
	s_nop 0
	global_load_lds_dwordx4 v[66:67], off
	s_add_u32 m0, s100, 0xa000
	s_nop 0
	global_load_lds_dwordx4 v[68:69], off
	s_add_u32 m0, s100, 0xb000
	s_nop 0
	global_load_lds_dwordx4 v[70:71], off
	s_add_u32 m0, s100, 0xc000
	s_nop 0
	global_load_lds_dwordx4 v[76:77], off
	s_add_u32 m0, s100, 0xd000
	s_nop 0
	global_load_lds_dwordx4 v[78:79], off
	s_add_u32 m0, s100, 0xe000
	s_nop 0
	global_load_lds_dwordx4 v[72:73], off
	s_add_u32 m0, s100, 0xf000
	s_nop 0
	global_load_lds_dwordx4 v[74:75], off
	ds_read_b128 a[0:3], v115
	ds_read_b128 v[80:83], v116
	ds_read_b128 a[4:7], v115 offset:2048
	ds_read_b128 a[8:11], v115 offset:4096
	ds_read_b128 a[12:15], v115 offset:6144
	ds_read_b128 v[92:95], v116 offset:2048
	ds_read_b128 v[88:91], v116 offset:4096
	ds_read_b128 v[84:87], v116 offset:6144
	ds_read_b128 a[16:19], v117
	ds_read_b128 a[20:23], v117 offset:2048
	ds_read_b128 a[24:27], v117 offset:4096
	ds_read_b128 a[28:31], v117 offset:6144
	s_setprio 1
	s_waitcnt lgkmcnt(10)
	v_mfma_f32_16x16x32_bf16 v[0:3], a[0:3], v[80:83], v[0:3]
	s_waitcnt lgkmcnt(9)
	v_mfma_f32_16x16x32_bf16 v[16:19], a[4:7], v[80:83], v[16:19]
	s_waitcnt lgkmcnt(8)
	v_mfma_f32_16x16x32_bf16 v[32:35], a[8:11], v[80:83], v[32:35]
	s_waitcnt lgkmcnt(7)
	v_mfma_f32_16x16x32_bf16 v[48:51], a[12:15], v[80:83], v[48:51]
	ds_read_b128 v[80:83], v118
	s_waitcnt lgkmcnt(7)
	v_mfma_f32_16x16x32_bf16 v[4:7], a[0:3], v[92:95], v[4:7]
	v_mfma_f32_16x16x32_bf16 v[20:23], a[4:7], v[92:95], v[20:23]
	v_mfma_f32_16x16x32_bf16 v[36:39], a[8:11], v[92:95], v[36:39]
	v_mfma_f32_16x16x32_bf16 v[52:55], a[12:15], v[92:95], v[52:55]
	ds_read_b128 v[92:95], v118 offset:2048
	s_waitcnt lgkmcnt(7)
	v_mfma_f32_16x16x32_bf16 v[8:11], a[0:3], v[88:91], v[8:11]
	v_mfma_f32_16x16x32_bf16 v[24:27], a[4:7], v[88:91], v[24:27]
	v_mfma_f32_16x16x32_bf16 v[40:43], a[8:11], v[88:91], v[40:43]
	v_mfma_f32_16x16x32_bf16 v[56:59], a[12:15], v[88:91], v[56:59]
	ds_read_b128 v[88:91], v118 offset:4096
	s_waitcnt lgkmcnt(7)
	v_mfma_f32_16x16x32_bf16 v[12:15], a[0:3], v[84:87], v[12:15]
	v_mfma_f32_16x16x32_bf16 v[28:31], a[4:7], v[84:87], v[28:31]
	v_mfma_f32_16x16x32_bf16 v[44:47], a[8:11], v[84:87], v[44:47]
	v_mfma_f32_16x16x32_bf16 v[60:63], a[12:15], v[84:87], v[60:63]
	ds_read_b128 v[84:87], v118 offset:6144
	s_waitcnt lgkmcnt(3)
	v_mfma_f32_16x16x32_bf16 v[0:3], a[16:19], v[80:83], v[0:3]
	v_mfma_f32_16x16x32_bf16 v[16:19], a[20:23], v[80:83], v[16:19]
	v_mfma_f32_16x16x32_bf16 v[32:35], a[24:27], v[80:83], v[32:35]
	v_mfma_f32_16x16x32_bf16 v[48:51], a[28:31], v[80:83], v[48:51]
	s_waitcnt lgkmcnt(2)
	v_mfma_f32_16x16x32_bf16 v[4:7], a[16:19], v[92:95], v[4:7]
	v_mfma_f32_16x16x32_bf16 v[20:23], a[20:23], v[92:95], v[20:23]
	v_mfma_f32_16x16x32_bf16 v[36:39], a[24:27], v[92:95], v[36:39]
	v_mfma_f32_16x16x32_bf16 v[52:55], a[28:31], v[92:95], v[52:55]
	s_waitcnt lgkmcnt(1)
	v_mfma_f32_16x16x32_bf16 v[8:11], a[16:19], v[88:91], v[8:11]
	v_mfma_f32_16x16x32_bf16 v[24:27], a[20:23], v[88:91], v[24:27]
	v_mfma_f32_16x16x32_bf16 v[40:43], a[24:27], v[88:91], v[40:43]
	v_mfma_f32_16x16x32_bf16 v[56:59], a[28:31], v[88:91], v[56:59]
	s_waitcnt lgkmcnt(0)
	v_mfma_f32_16x16x32_bf16 v[12:15], a[16:19], v[84:87], v[12:15]
	v_mfma_f32_16x16x32_bf16 v[28:31], a[20:23], v[84:87], v[28:31]
	v_mfma_f32_16x16x32_bf16 v[44:47], a[24:27], v[84:87], v[44:47]
	v_mfma_f32_16x16x32_bf16 v[60:63], a[28:31], v[84:87], v[60:63]
	s_setprio 0
	s_waitcnt vmcnt(0) lgkmcnt(0)
	s_barrier
	ds_read_b128 a[0:3], v115 offset:32768
	ds_read_b128 v[80:83], v116 offset:32768
	ds_read_b128 a[4:7], v115 offset:34816
	ds_read_b128 a[8:11], v115 offset:36864
	ds_read_b128 a[12:15], v115 offset:38912
	ds_read_b128 v[92:95], v116 offset:34816
	ds_read_b128 v[88:91], v116 offset:36864
	ds_read_b128 v[84:87], v116 offset:38912
	ds_read_b128 a[16:19], v117 offset:32768
	ds_read_b128 a[20:23], v117 offset:34816
	ds_read_b128 a[24:27], v117 offset:36864
	ds_read_b128 a[28:31], v117 offset:38912
	s_setprio 1
	s_waitcnt lgkmcnt(10)
	v_mfma_f32_16x16x32_bf16 v[0:3], a[0:3], v[80:83], v[0:3]
	s_waitcnt lgkmcnt(9)
	v_mfma_f32_16x16x32_bf16 v[16:19], a[4:7], v[80:83], v[16:19]
	s_waitcnt lgkmcnt(8)
	v_mfma_f32_16x16x32_bf16 v[32:35], a[8:11], v[80:83], v[32:35]
	s_waitcnt lgkmcnt(7)
	v_mfma_f32_16x16x32_bf16 v[48:51], a[12:15], v[80:83], v[48:51]
	ds_read_b128 v[80:83], v118 offset:32768
	s_waitcnt lgkmcnt(7)
	v_mfma_f32_16x16x32_bf16 v[4:7], a[0:3], v[92:95], v[4:7]
	v_mfma_f32_16x16x32_bf16 v[20:23], a[4:7], v[92:95], v[20:23]
	v_mfma_f32_16x16x32_bf16 v[36:39], a[8:11], v[92:95], v[36:39]
	v_mfma_f32_16x16x32_bf16 v[52:55], a[12:15], v[92:95], v[52:55]
	ds_read_b128 v[92:95], v118 offset:34816
	s_waitcnt lgkmcnt(7)
	v_mfma_f32_16x16x32_bf16 v[8:11], a[0:3], v[88:91], v[8:11]
	v_mfma_f32_16x16x32_bf16 v[24:27], a[4:7], v[88:91], v[24:27]
	v_mfma_f32_16x16x32_bf16 v[40:43], a[8:11], v[88:91], v[40:43]
	v_mfma_f32_16x16x32_bf16 v[56:59], a[12:15], v[88:91], v[56:59]
	ds_read_b128 v[88:91], v118 offset:36864
	s_waitcnt lgkmcnt(7)
	v_mfma_f32_16x16x32_bf16 v[12:15], a[0:3], v[84:87], v[12:15]
	v_mfma_f32_16x16x32_bf16 v[28:31], a[4:7], v[84:87], v[28:31]
	v_mfma_f32_16x16x32_bf16 v[44:47], a[8:11], v[84:87], v[44:47]
	v_mfma_f32_16x16x32_bf16 v[60:63], a[12:15], v[84:87], v[60:63]
	ds_read_b128 v[84:87], v118 offset:38912
	s_waitcnt lgkmcnt(3)
	v_mfma_f32_16x16x32_bf16 v[0:3], a[16:19], v[80:83], v[0:3]
	v_mfma_f32_16x16x32_bf16 v[16:19], a[20:23], v[80:83], v[16:19]
	v_mfma_f32_16x16x32_bf16 v[32:35], a[24:27], v[80:83], v[32:35]
	v_mfma_f32_16x16x32_bf16 v[48:51], a[28:31], v[80:83], v[48:51]
	s_waitcnt lgkmcnt(2)
	v_mfma_f32_16x16x32_bf16 v[4:7], a[16:19], v[92:95], v[4:7]
	v_mfma_f32_16x16x32_bf16 v[20:23], a[20:23], v[92:95], v[20:23]
	v_mfma_f32_16x16x32_bf16 v[36:39], a[24:27], v[92:95], v[36:39]
	v_mfma_f32_16x16x32_bf16 v[52:55], a[28:31], v[92:95], v[52:55]
	s_waitcnt lgkmcnt(1)
	v_mfma_f32_16x16x32_bf16 v[8:11], a[16:19], v[88:91], v[8:11]
	v_mfma_f32_16x16x32_bf16 v[24:27], a[20:23], v[88:91], v[24:27]
	v_mfma_f32_16x16x32_bf16 v[40:43], a[24:27], v[88:91], v[40:43]
	v_mfma_f32_16x16x32_bf16 v[56:59], a[28:31], v[88:91], v[56:59]
	s_waitcnt lgkmcnt(0)
	v_mfma_f32_16x16x32_bf16 v[12:15], a[16:19], v[84:87], v[12:15]
	v_mfma_f32_16x16x32_bf16 v[28:31], a[20:23], v[84:87], v[28:31]
	v_mfma_f32_16x16x32_bf16 v[44:47], a[24:27], v[84:87], v[44:47]
	v_mfma_f32_16x16x32_bf16 v[60:63], a[28:31], v[84:87], v[60:63]
	s_setprio 0
	v_readfirstlane_b32 s15, v107
	v_readfirstlane_b32 s4, v106
	s_lshl_b32 s15, s15, 6
	s_waitcnt lgkmcnt(0)
	s_barrier
	s_add_i32 s9, s15, s9
	s_lshl_b32 s15, s4, 17
	s_lshl_b32 s4, s8, 18
	s_add_i32 s15, s15, s4
	v_or_b32_e32 v64, s9, v108
	s_movk_i32 s4, 0x800
	v_cmp_gt_i32_e32 vcc, s4, v64
	s_barrier
	v_and_b32_e32 v124, 15, v143
	v_bfe_u32 v125, v143, 4, 2
	v_xor_b32_e32 v125, v125, v124
	v_lshlrev_b32_e32 v125, 4, v125
	v_lshl_add_u32 v125, v124, 8, v125
	v_lshrrev_b32_e32 v124, 6, v143
	v_lshl_add_u32 v125, v124, 14, v125
	ds_write_b128 v125, v[0:3]
	ds_write_b128 v125, v[4:7] offset:4096
	ds_write_b128 v125, v[8:11] offset:8192
	ds_write_b128 v125, v[12:15] offset:12288
	v_xor_b32_e32 v118, 64, v125
	ds_write_b128 v118, v[16:19]
	ds_write_b128 v118, v[20:23] offset:4096
	ds_write_b128 v118, v[24:27] offset:8192
	ds_write_b128 v118, v[28:31] offset:12288
	v_xor_b32_e32 v118, 128, v125
	ds_write_b128 v118, v[32:35]
	ds_write_b128 v118, v[36:39] offset:4096
	ds_write_b128 v118, v[40:43] offset:8192
	ds_write_b128 v118, v[44:47] offset:12288
	v_xor_b32_e32 v118, 192, v125
	ds_write_b128 v118, v[48:51]
	ds_write_b128 v118, v[52:55] offset:4096
	ds_write_b128 v118, v[56:59] offset:8192
	ds_write_b128 v118, v[60:63] offset:12288
	v_and_b32_e32 v115, 31, v143
	v_bfe_u32 v117, v143, 5, 1
	v_and_b32_e32 v125, 15, v115
	v_xor_b32_e32 v117, v117, v125
	v_lshlrev_b32_e32 v117, 4, v117
	v_lshl_add_u32 v117, v115, 8, v117
	v_lshl_add_u32 v117, v124, 14, v117
	ds_read_b128 v[48:51], v117
	ds_read_b128 v[32:35], v117 offset:8192
	v_xor_b32_e32 v116, 32, v117
	ds_read_b128 v[52:55], v116
	ds_read_b128 v[36:39], v116 offset:8192
	v_xor_b32_e32 v116, 64, v117
	ds_read_b128 v[56:59], v116
	ds_read_b128 v[40:43], v116 offset:8192
	v_xor_b32_e32 v116, 96, v117
	ds_read_b128 v[60:63], v116
	ds_read_b128 v[44:47], v116 offset:8192
	v_xor_b32_e32 v116, 128, v117
	ds_read_b128 v[16:19], v116
	ds_read_b128 v[0:3], v116 offset:8192
	v_xor_b32_e32 v116, 160, v117
	ds_read_b128 v[20:23], v116
	ds_read_b128 v[4:7], v116 offset:8192
	v_xor_b32_e32 v116, 192, v117
	ds_read_b128 v[24:27], v116
	ds_read_b128 v[8:11], v116 offset:8192
	v_xor_b32_e32 v116, 224, v117
	ds_read_b128 v[28:31], v116
	ds_read_b128 v[12:15], v116 offset:8192
	s_waitcnt lgkmcnt(0)
	s_barrier
	s_and_saveexec_b64 s[8:9], vcc
	s_cbranch_execz .LBB0_612
	v_add_u32_e32 v65, s15, v64
	v_add_u32_e32 v66, v65, v111
	v_mov_b32_e32 v67, v140
	v_lshl_add_u64 v[68:69], v[66:67], 2, s[26:27]
	global_store_dword v[68:69], v48, off
	v_add_u32_e32 v68, 0x800, v66
	v_mov_b32_e32 v69, v140
	v_lshl_add_u64 v[68:69], v[68:69], 2, s[26:27]
	global_store_dword v[68:69], v49, off
	v_add_u32_e32 v48, 0x1000, v66
	v_mov_b32_e32 v49, v140
	v_lshl_add_u64 v[48:49], v[48:49], 2, s[26:27]
	global_store_dword v[48:49], v50, off
	v_add_u32_e32 v48, 0x1800, v66
	v_mov_b32_e32 v49, v140
	v_lshl_add_u64 v[48:49], v[48:49], 2, s[26:27]
	global_store_dword v[48:49], v51, off
	v_add_u32_e32 v48, v65, v112
	v_mov_b32_e32 v49, v140
	v_lshl_add_u64 v[50:51], v[48:49], 2, s[26:27]
	global_store_dword v[50:51], v52, off
	v_add_u32_e32 v50, 0x800, v48
	v_mov_b32_e32 v51, v140
	v_lshl_add_u64 v[50:51], v[50:51], 2, s[26:27]
	global_store_dword v[50:51], v53, off
	v_add_u32_e32 v50, 0x1000, v48
	v_mov_b32_e32 v51, v140
	v_add_u32_e32 v48, 0x1800, v48
	v_lshl_add_u64 v[50:51], v[50:51], 2, s[26:27]
	v_lshl_add_u64 v[48:49], v[48:49], 2, s[26:27]
	global_store_dword v[50:51], v54, off
	global_store_dword v[48:49], v55, off
	v_add_u32_e32 v48, v65, v113
	v_mov_b32_e32 v49, v140
	v_lshl_add_u64 v[50:51], v[48:49], 2, s[26:27]
	global_store_dword v[50:51], v56, off
	v_add_u32_e32 v50, 0x800, v48
	v_mov_b32_e32 v51, v140
	v_lshl_add_u64 v[50:51], v[50:51], 2, s[26:27]
	global_store_dword v[50:51], v57, off
	v_add_u32_e32 v50, 0x1000, v48
	v_mov_b32_e32 v51, v140
	v_add_u32_e32 v48, 0x1800, v48
	v_lshl_add_u64 v[50:51], v[50:51], 2, s[26:27]
	v_lshl_add_u64 v[48:49], v[48:49], 2, s[26:27]
	global_store_dword v[50:51], v58, off
	global_store_dword v[48:49], v59, off
	v_add_u32_e32 v48, v65, v114
	v_mov_b32_e32 v49, v140
	v_lshl_add_u64 v[50:51], v[48:49], 2, s[26:27]
	global_store_dword v[50:51], v60, off
	v_add_u32_e32 v50, 0x800, v48
	v_mov_b32_e32 v51, v140
	v_lshl_add_u64 v[50:51], v[50:51], 2, s[26:27]
	global_store_dword v[50:51], v61, off
	v_add_u32_e32 v50, 0x1000, v48
	v_mov_b32_e32 v51, v140
	v_add_u32_e32 v48, 0x1800, v48
	v_lshl_add_u64 v[50:51], v[50:51], 2, s[26:27]
	v_lshl_add_u64 v[48:49], v[48:49], 2, s[26:27]
	global_store_dword v[50:51], v62, off
	global_store_dword v[48:49], v63, off

.LBB0_622:
	s_mul_hi_i32 s4, s30, 0x38e38e39
	s_lshr_b32 s8, s4, 31
	s_ashr_i32 s4, s4, 4
	s_add_i32 s4, s4, s8
	s_mul_i32 s8, s4, 0x48
	s_sub_i32 s8, s30, s8
	v_lshl_add_u32 v0, s8, 7, v109
	v_ashrrev_i32_e32 v1, 31, v0
	v_lshlrev_b64 v[32:33], 12, v[0:1]
	v_lshl_add_u64 v[34:35], v[96:97], 0, v[32:33]
	v_add_co_u32_e32 v40, vcc, s87, v34
	s_lshl_b32 s9, s4, 7
	s_nop 0
	v_addc_co_u32_e32 v41, vcc, 0, v35, vcc
	v_add_co_u32_e32 v42, vcc, s66, v34
	v_add_u32_e32 v0, s9, v109
	s_nop 0
	v_addc_co_u32_e32 v43, vcc, 0, v35, vcc
	v_ashrrev_i32_e32 v1, 31, v0
	v_add_co_u32_e32 v44, vcc, s20, v34
	v_lshlrev_b64 v[36:37], 12, v[0:1]
	s_nop 0
	v_addc_co_u32_e32 v45, vcc, 0, v35, vcc
	v_lshl_add_u64 v[38:39], v[98:99], 0, v[36:37]
	v_readfirstlane_b32 s100, v110
	s_nop 3
	s_add_u32 m0, s100, 0x0
	s_nop 0
	global_load_lds_dwordx4 v[34:35], off
	s_add_u32 m0, s100, 0x1000
	s_nop 0
	global_load_lds_dwordx4 v[40:41], off
	s_add_u32 m0, s100, 0x2000
	s_nop 0
	global_load_lds_dwordx4 v[42:43], off
	s_add_u32 m0, s100, 0x3000
	s_nop 0
	global_load_lds_dwordx4 v[44:45], off
	s_add_u32 m0, s100, 0x4000
	s_nop 0
	global_load_lds_dwordx4 v[38:39], off
	v_add_co_u32_e32 v46, vcc, s87, v38
	v_lshl_add_u64 v[102:103], v[100:101], 0, v[36:37]
	s_nop 0
	v_addc_co_u32_e32 v47, vcc, 0, v39, vcc
	s_waitcnt vmcnt(16)
	v_add_co_u32_e32 v48, vcc, s66, v38
	s_add_u32 m0, s100, 0x5000
	s_nop 0
	global_load_lds_dwordx4 v[46:47], off
	s_nop 0
	v_addc_co_u32_e32 v49, vcc, 0, v39, vcc
	v_add_co_u32_e32 v50, vcc, s20, v38
	s_add_u32 m0, s100, 0x6000
	s_nop 0
	global_load_lds_dwordx4 v[48:49], off
	s_nop 0
	v_addc_co_u32_e32 v51, vcc, 0, v39, vcc
	s_add_u32 m0, s100, 0x7000
	s_nop 0
	global_load_lds_dwordx4 v[50:51], off
	v_lshl_add_u64 v[104:105], v[100:101], 0, v[32:33]
	s_mov_b64 s[28:29], 0
	v_mov_b32_e32 v0, 0
	v_mov_b32_e32 v1, v0
	v_mov_b32_e32 v2, v0
	v_mov_b32_e32 v3, v0
	v_mov_b32_e32 v4, v0
	v_mov_b32_e32 v5, v0
	v_mov_b32_e32 v6, v0
	v_mov_b32_e32 v7, v0
	v_mov_b32_e32 v8, v0
	v_mov_b32_e32 v9, v0
	v_mov_b32_e32 v10, v0
	v_mov_b32_e32 v11, v0
	v_mov_b32_e32 v12, v0
	v_mov_b32_e32 v13, v0
	v_mov_b32_e32 v14, v0
	v_mov_b32_e32 v15, v0
	v_mov_b32_e32 v16, v0
	v_mov_b32_e32 v17, v0
	v_mov_b32_e32 v18, v0
	v_mov_b32_e32 v19, v0
	v_mov_b32_e32 v20, v0
	v_mov_b32_e32 v21, v0
	v_mov_b32_e32 v22, v0
	v_mov_b32_e32 v23, v0
	v_mov_b32_e32 v24, v0
	v_mov_b32_e32 v25, v0
	v_mov_b32_e32 v26, v0
	v_mov_b32_e32 v27, v0
	v_mov_b32_e32 v28, v0
	v_mov_b32_e32 v29, v0
	v_mov_b32_e32 v30, v0
	v_mov_b32_e32 v31, v0
	v_mov_b32_e32 v32, v0
	v_mov_b32_e32 v33, v0
	v_mov_b32_e32 v34, v0
	v_mov_b32_e32 v35, v0
	v_mov_b32_e32 v36, v0
	v_mov_b32_e32 v37, v0
	v_mov_b32_e32 v38, v0
	v_mov_b32_e32 v39, v0
	v_mov_b32_e32 v40, v0
	v_mov_b32_e32 v41, v0
	v_mov_b32_e32 v42, v0
	v_mov_b32_e32 v43, v0
	v_mov_b32_e32 v44, v0
	v_mov_b32_e32 v45, v0
	v_mov_b32_e32 v46, v0
	v_mov_b32_e32 v47, v0
	v_mov_b32_e32 v48, v0
	v_mov_b32_e32 v49, v0
	v_mov_b32_e32 v50, v0
	v_mov_b32_e32 v51, v0
	v_mov_b32_e32 v52, v0
	v_mov_b32_e32 v53, v0
	v_mov_b32_e32 v54, v0
	v_mov_b32_e32 v55, v0
	v_mov_b32_e32 v56, v0
	v_mov_b32_e32 v57, v0
	v_mov_b32_e32 v58, v0
	v_mov_b32_e32 v59, v0
	v_mov_b32_e32 v60, v0
	v_mov_b32_e32 v61, v0
	v_mov_b32_e32 v62, v0
	v_mov_b32_e32 v63, v0
	v_lshl_add_u64 v[124:125], v[104:105], 0, s[28:29]
	s_mov_b32 s4, 0x17eb8000
	v_add_co_u32_e32 v132, vcc, s4, v124
	s_mov_b32 s4, 0x17ed8000
	s_nop 0
	v_addc_co_u32_e32 v133, vcc, 0, v125, vcc
	v_add_co_u32_e32 v134, vcc, s4, v124
	s_mov_b32 s4, 0x17ef8000
	s_nop 0
	v_addc_co_u32_e32 v135, vcc, 0, v125, vcc
	v_add_co_u32_e32 v144, vcc, s4, v124
	s_mov_b32 s4, 0x17f18000
	s_nop 0
	v_addc_co_u32_e32 v145, vcc, 0, v125, vcc
	v_add_co_u32_e32 v146, vcc, s4, v124
	v_lshl_add_u64 v[126:127], v[102:103], 0, s[28:29]
	s_nop 0
	v_addc_co_u32_e32 v147, vcc, 0, v125, vcc
	s_mov_b32 s4, 0x38b80000
	v_add_co_u32_e32 v148, vcc, s4, v126
	s_mov_b32 s4, 0x38ba0000
	s_nop 0
	v_addc_co_u32_e32 v149, vcc, 0, v127, vcc
	v_add_co_u32_e32 v150, vcc, s4, v126
	s_mov_b32 s4, 0x38bc0000
	s_nop 0
	v_addc_co_u32_e32 v151, vcc, 0, v127, vcc
	v_add_co_u32_e32 v152, vcc, s4, v126
	s_mov_b32 s4, 0x38be0000
	s_nop 0
	v_addc_co_u32_e32 v153, vcc, 0, v127, vcc
	v_add_co_u32_e32 v154, vcc, s4, v126
	v_addc_co_u32_e32 v155, vcc, 0, v127, vcc
	v_lshl_add_u64 v[132:133], 8, 4, v[132:133]
	v_lshl_add_u64 v[134:135], 8, 4, v[134:135]
	v_lshl_add_u64 v[144:145], 8, 4, v[144:145]
	v_lshl_add_u64 v[146:147], 8, 4, v[146:147]
	v_lshl_add_u64 v[148:149], 8, 4, v[148:149]
	v_lshl_add_u64 v[150:151], 8, 4, v[150:151]
	v_lshl_add_u64 v[152:153], 8, 4, v[152:153]
	v_lshl_add_u64 v[154:155], 8, 4, v[154:155]
	v_and_b32_e32 v120, 15, v143
	v_lshrrev_b32_e32 v121, 1, v120
	v_bfe_u32 v114, v143, 4, 2
	v_xor_b32_e32 v121, v121, v114
	v_lshlrev_b32_e32 v121, 4, v121
	v_lshl_add_u32 v121, v120, 7, v121
	v_lshrrev_b32_e32 v120, 6, v143
	v_lshrrev_b32_e32 v112, 1, v120
	v_and_b32_e32 v120, 1, v120
	v_lshl_add_u32 v112, v112, 13, v121
	v_lshl_add_u32 v113, v120, 13, v121
	v_add_u32_e32 v113, 0x4000, v113
	v_xor_b32_e32 v114, 64, v112
	v_xor_b32_e32 v115, 64, v113
	s_waitcnt vmcnt(0) lgkmcnt(0)
	s_barrier
.LBB0_623:
	s_add_u32 m0, s100, 0x8000
	s_nop 0
	global_load_lds_dwordx4 v[132:133], off
	s_add_u32 m0, s100, 0x9000
	s_nop 0
	global_load_lds_dwordx4 v[134:135], off
	s_add_u32 m0, s100, 0xa000
	s_nop 0
	global_load_lds_dwordx4 v[144:145], off
	s_add_u32 m0, s100, 0xb000
	s_nop 0
	global_load_lds_dwordx4 v[146:147], off
	s_add_u32 m0, s100, 0xc000
	s_nop 0
	global_load_lds_dwordx4 v[148:149], off
	s_add_u32 m0, s100, 0xd000
	s_nop 0
	global_load_lds_dwordx4 v[150:151], off
	s_add_u32 m0, s100, 0xe000
	s_nop 0
	global_load_lds_dwordx4 v[152:153], off
	s_add_u32 m0, s100, 0xf000
	s_nop 0
	global_load_lds_dwordx4 v[154:155], off
	ds_read_b128 a[0:3], v112
	ds_read_b128 v[80:83], v113
	ds_read_b128 a[4:7], v112 offset:2048
	ds_read_b128 a[8:11], v112 offset:4096
	ds_read_b128 a[12:15], v112 offset:6144
	ds_read_b128 v[92:95], v113 offset:2048
	ds_read_b128 v[88:91], v113 offset:4096
	ds_read_b128 v[84:87], v113 offset:6144
	ds_read_b128 a[16:19], v114
	ds_read_b128 a[20:23], v114 offset:2048
	ds_read_b128 a[24:27], v114 offset:4096
	ds_read_b128 a[28:31], v114 offset:6144
	s_setprio 1
	s_waitcnt lgkmcnt(10)
	v_mfma_f32_16x16x32_bf16 v[0:3], a[0:3], v[80:83], v[0:3]
	s_waitcnt lgkmcnt(9)
	v_mfma_f32_16x16x32_bf16 v[16:19], a[4:7], v[80:83], v[16:19]
	s_waitcnt lgkmcnt(8)
	v_mfma_f32_16x16x32_bf16 v[32:35], a[8:11], v[80:83], v[32:35]
	s_waitcnt lgkmcnt(7)
	v_mfma_f32_16x16x32_bf16 v[48:51], a[12:15], v[80:83], v[48:51]
	ds_read_b128 v[80:83], v115
	s_waitcnt lgkmcnt(7)
	v_mfma_f32_16x16x32_bf16 v[4:7], a[0:3], v[92:95], v[4:7]
	v_lshl_add_u64 v[64:65], 8, 4, v[132:133]
	v_lshl_add_u64 v[66:67], 8, 4, v[134:135]
	v_lshl_add_u64 v[68:69], 8, 4, v[144:145]
	v_mfma_f32_16x16x32_bf16 v[20:23], a[4:7], v[92:95], v[20:23]
	v_lshl_add_u64 v[70:71], 8, 4, v[146:147]
	v_lshl_add_u64 v[76:77], 8, 4, v[148:149]
	v_lshl_add_u64 v[78:79], 8, 4, v[150:151]
	v_mfma_f32_16x16x32_bf16 v[36:39], a[8:11], v[92:95], v[36:39]
	v_lshl_add_u64 v[72:73], 8, 4, v[152:153]
	v_lshl_add_u64 v[74:75], 8, 4, v[154:155]
	v_mfma_f32_16x16x32_bf16 v[52:55], a[12:15], v[92:95], v[52:55]
	ds_read_b128 v[92:95], v115 offset:2048
	s_waitcnt lgkmcnt(7)
	v_mfma_f32_16x16x32_bf16 v[8:11], a[0:3], v[88:91], v[8:11]
	v_mfma_f32_16x16x32_bf16 v[24:27], a[4:7], v[88:91], v[24:27]
	v_mfma_f32_16x16x32_bf16 v[40:43], a[8:11], v[88:91], v[40:43]
	v_mfma_f32_16x16x32_bf16 v[56:59], a[12:15], v[88:91], v[56:59]
	ds_read_b128 v[88:91], v115 offset:4096
	s_waitcnt lgkmcnt(7)
	v_mfma_f32_16x16x32_bf16 v[12:15], a[0:3], v[84:87], v[12:15]
	v_mfma_f32_16x16x32_bf16 v[28:31], a[4:7], v[84:87], v[28:31]
	v_mfma_f32_16x16x32_bf16 v[44:47], a[8:11], v[84:87], v[44:47]
	v_mfma_f32_16x16x32_bf16 v[60:63], a[12:15], v[84:87], v[60:63]
	ds_read_b128 v[84:87], v115 offset:6144
	s_waitcnt lgkmcnt(3)
	v_mfma_f32_16x16x32_bf16 v[0:3], a[16:19], v[80:83], v[0:3]
	v_mfma_f32_16x16x32_bf16 v[16:19], a[20:23], v[80:83], v[16:19]
	v_mfma_f32_16x16x32_bf16 v[32:35], a[24:27], v[80:83], v[32:35]
	v_mfma_f32_16x16x32_bf16 v[48:51], a[28:31], v[80:83], v[48:51]
	s_waitcnt lgkmcnt(2)
	v_mfma_f32_16x16x32_bf16 v[4:7], a[16:19], v[92:95], v[4:7]
	v_mfma_f32_16x16x32_bf16 v[20:23], a[20:23], v[92:95], v[20:23]
	v_mfma_f32_16x16x32_bf16 v[36:39], a[24:27], v[92:95], v[36:39]
	v_mfma_f32_16x16x32_bf16 v[52:55], a[28:31], v[92:95], v[52:55]
	s_waitcnt lgkmcnt(1)
	v_mfma_f32_16x16x32_bf16 v[8:11], a[16:19], v[88:91], v[8:11]
	v_mfma_f32_16x16x32_bf16 v[24:27], a[20:23], v[88:91], v[24:27]
	v_mfma_f32_16x16x32_bf16 v[40:43], a[24:27], v[88:91], v[40:43]
	v_mfma_f32_16x16x32_bf16 v[56:59], a[28:31], v[88:91], v[56:59]
	s_waitcnt lgkmcnt(0)
	v_mfma_f32_16x16x32_bf16 v[12:15], a[16:19], v[84:87], v[12:15]
	v_mfma_f32_16x16x32_bf16 v[28:31], a[20:23], v[84:87], v[28:31]
	v_mfma_f32_16x16x32_bf16 v[44:47], a[24:27], v[84:87], v[44:47]
	v_mfma_f32_16x16x32_bf16 v[60:63], a[28:31], v[84:87], v[60:63]
	s_setprio 0
	s_waitcnt vmcnt(0) lgkmcnt(0)
	s_barrier
	s_add_u32 s28, s28, 0x100
	s_addc_u32 s29, s29, 0
	s_add_u32 m0, s100, 0x0
	s_nop 0
	global_load_lds_dwordx4 v[64:65], off
	s_add_u32 m0, s100, 0x1000
	s_nop 0
	global_load_lds_dwordx4 v[66:67], off
	s_add_u32 m0, s100, 0x2000
	s_nop 0
	global_load_lds_dwordx4 v[68:69], off
	s_add_u32 m0, s100, 0x3000
	s_nop 0
	global_load_lds_dwordx4 v[70:71], off
	s_add_u32 m0, s100, 0x4000
	s_nop 0
	global_load_lds_dwordx4 v[76:77], off
	s_add_u32 m0, s100, 0x5000
	s_nop 0
	global_load_lds_dwordx4 v[78:79], off
	s_add_u32 m0, s100, 0x6000
	s_nop 0
	global_load_lds_dwordx4 v[72:73], off
	s_add_u32 m0, s100, 0x7000
	s_nop 0
	global_load_lds_dwordx4 v[74:75], off
	ds_read_b128 a[0:3], v112 offset:32768
	ds_read_b128 v[80:83], v113 offset:32768
	ds_read_b128 a[4:7], v112 offset:34816
	ds_read_b128 a[8:11], v112 offset:36864
	ds_read_b128 a[12:15], v112 offset:38912
	ds_read_b128 v[92:95], v113 offset:34816
	ds_read_b128 v[88:91], v113 offset:36864
	ds_read_b128 v[84:87], v113 offset:38912
	ds_read_b128 a[16:19], v114 offset:32768
	ds_read_b128 a[20:23], v114 offset:34816
	ds_read_b128 a[24:27], v114 offset:36864
	ds_read_b128 a[28:31], v114 offset:38912
	s_setprio 1
	s_waitcnt lgkmcnt(10)
	v_mfma_f32_16x16x32_bf16 v[0:3], a[0:3], v[80:83], v[0:3]
	s_waitcnt lgkmcnt(9)
	v_mfma_f32_16x16x32_bf16 v[16:19], a[4:7], v[80:83], v[16:19]
	s_waitcnt lgkmcnt(8)
	v_mfma_f32_16x16x32_bf16 v[32:35], a[8:11], v[80:83], v[32:35]
	s_waitcnt lgkmcnt(7)
	v_mfma_f32_16x16x32_bf16 v[48:51], a[12:15], v[80:83], v[48:51]
	ds_read_b128 v[80:83], v115 offset:32768
	s_waitcnt lgkmcnt(7)
	v_mfma_f32_16x16x32_bf16 v[4:7], a[0:3], v[92:95], v[4:7]
	v_lshl_add_u64 v[124:125], v[104:105], 0, s[28:29]
	s_mov_b32 s4, 0x17eb8000
	v_add_co_u32_e32 v132, vcc, s4, v124
	v_mfma_f32_16x16x32_bf16 v[20:23], a[4:7], v[92:95], v[20:23]
	s_mov_b32 s4, 0x17ed8000
	s_nop 0
	v_addc_co_u32_e32 v133, vcc, 0, v125, vcc
	v_mfma_f32_16x16x32_bf16 v[36:39], a[8:11], v[92:95], v[36:39]
	v_add_co_u32_e32 v134, vcc, s4, v124
	s_mov_b32 s4, 0x17ef8000
	s_nop 0
	v_mfma_f32_16x16x32_bf16 v[52:55], a[12:15], v[92:95], v[52:55]
	v_addc_co_u32_e32 v135, vcc, 0, v125, vcc
	v_add_co_u32_e32 v144, vcc, s4, v124
	s_mov_b32 s4, 0x17f18000
	ds_read_b128 v[92:95], v115 offset:34816
	s_waitcnt lgkmcnt(7)
	v_mfma_f32_16x16x32_bf16 v[8:11], a[0:3], v[88:91], v[8:11]
	s_nop 0
	v_addc_co_u32_e32 v145, vcc, 0, v125, vcc
	v_add_co_u32_e32 v146, vcc, s4, v124
	v_mfma_f32_16x16x32_bf16 v[24:27], a[4:7], v[88:91], v[24:27]
	v_lshl_add_u64 v[126:127], v[102:103], 0, s[28:29]
	s_nop 0
	v_addc_co_u32_e32 v147, vcc, 0, v125, vcc
	v_mfma_f32_16x16x32_bf16 v[40:43], a[8:11], v[88:91], v[40:43]
	s_mov_b32 s4, 0x38b80000
	v_add_co_u32_e32 v148, vcc, s4, v126
	s_mov_b32 s4, 0x38ba0000
	v_mfma_f32_16x16x32_bf16 v[56:59], a[12:15], v[88:91], v[56:59]
	s_nop 0
	v_addc_co_u32_e32 v149, vcc, 0, v127, vcc
	v_add_co_u32_e32 v150, vcc, s4, v126
	ds_read_b128 v[88:91], v115 offset:36864
	s_waitcnt lgkmcnt(7)
	v_mfma_f32_16x16x32_bf16 v[12:15], a[0:3], v[84:87], v[12:15]
	s_mov_b32 s4, 0x38bc0000
	s_nop 0
	v_addc_co_u32_e32 v151, vcc, 0, v127, vcc
	v_mfma_f32_16x16x32_bf16 v[28:31], a[4:7], v[84:87], v[28:31]
	v_add_co_u32_e32 v152, vcc, s4, v126
	s_mov_b32 s4, 0x38be0000
	s_nop 0
	v_mfma_f32_16x16x32_bf16 v[44:47], a[8:11], v[84:87], v[44:47]
	v_addc_co_u32_e32 v153, vcc, 0, v127, vcc
	v_add_co_u32_e32 v154, vcc, s4, v126
	v_addc_co_u32_e32 v155, vcc, 0, v127, vcc
	v_mfma_f32_16x16x32_bf16 v[60:63], a[12:15], v[84:87], v[60:63]
	v_lshl_add_u64 v[132:133], 8, 4, v[132:133]
	v_lshl_add_u64 v[134:135], 8, 4, v[134:135]
	v_lshl_add_u64 v[144:145], 8, 4, v[144:145]
	ds_read_b128 v[84:87], v115 offset:38912
	s_waitcnt lgkmcnt(3)
	v_mfma_f32_16x16x32_bf16 v[0:3], a[16:19], v[80:83], v[0:3]
	v_lshl_add_u64 v[146:147], 8, 4, v[146:147]
	v_lshl_add_u64 v[148:149], 8, 4, v[148:149]
	v_lshl_add_u64 v[150:151], 8, 4, v[150:151]
	v_mfma_f32_16x16x32_bf16 v[16:19], a[20:23], v[80:83], v[16:19]
	v_lshl_add_u64 v[152:153], 8, 4, v[152:153]
	v_lshl_add_u64 v[154:155], 8, 4, v[154:155]
	v_mfma_f32_16x16x32_bf16 v[32:35], a[24:27], v[80:83], v[32:35]
	v_mfma_f32_16x16x32_bf16 v[48:51], a[28:31], v[80:83], v[48:51]
	s_waitcnt lgkmcnt(2)
	v_mfma_f32_16x16x32_bf16 v[4:7], a[16:19], v[92:95], v[4:7]
	v_mfma_f32_16x16x32_bf16 v[20:23], a[20:23], v[92:95], v[20:23]
	v_mfma_f32_16x16x32_bf16 v[36:39], a[24:27], v[92:95], v[36:39]
	v_mfma_f32_16x16x32_bf16 v[52:55], a[28:31], v[92:95], v[52:55]
	s_waitcnt lgkmcnt(1)
	v_mfma_f32_16x16x32_bf16 v[8:11], a[16:19], v[88:91], v[8:11]
	v_mfma_f32_16x16x32_bf16 v[24:27], a[20:23], v[88:91], v[24:27]
	v_mfma_f32_16x16x32_bf16 v[40:43], a[24:27], v[88:91], v[40:43]
	v_mfma_f32_16x16x32_bf16 v[56:59], a[28:31], v[88:91], v[56:59]
	s_waitcnt lgkmcnt(0)
	v_mfma_f32_16x16x32_bf16 v[12:15], a[16:19], v[84:87], v[12:15]
	v_mfma_f32_16x16x32_bf16 v[28:31], a[20:23], v[84:87], v[28:31]
	v_mfma_f32_16x16x32_bf16 v[44:47], a[24:27], v[84:87], v[44:47]
	v_mfma_f32_16x16x32_bf16 v[60:63], a[28:31], v[84:87], v[60:63]
	s_setprio 0
	s_waitcnt vmcnt(0) lgkmcnt(0)
	s_barrier
	s_cmpk_eq_i32 s28, 0xf00
	s_cbranch_scc0 .LBB0_623
	v_lshl_add_u64 v[64:65], 8, 4, v[64:65]
	v_lshl_add_u64 v[66:67], 8, 4, v[66:67]
	v_lshl_add_u64 v[68:69], 8, 4, v[68:69]
	v_lshl_add_u64 v[70:71], 8, 4, v[70:71]
	v_lshl_add_u64 v[76:77], 8, 4, v[76:77]
	v_lshl_add_u64 v[78:79], 8, 4, v[78:79]
	v_lshl_add_u64 v[72:73], 8, 4, v[72:73]
	v_lshl_add_u64 v[74:75], 8, 4, v[74:75]
	s_add_u32 m0, s100, 0x8000
	s_nop 0
	global_load_lds_dwordx4 v[64:65], off
	s_add_u32 m0, s100, 0x9000
	s_nop 0
	global_load_lds_dwordx4 v[66:67], off
	s_add_u32 m0, s100, 0xa000
	s_nop 0
	global_load_lds_dwordx4 v[68:69], off
	s_add_u32 m0, s100, 0xb000
	s_nop 0
	global_load_lds_dwordx4 v[70:71], off
	s_add_u32 m0, s100, 0xc000
	s_nop 0
	global_load_lds_dwordx4 v[76:77], off
	s_add_u32 m0, s100, 0xd000
	s_nop 0
	global_load_lds_dwordx4 v[78:79], off
	s_add_u32 m0, s100, 0xe000
	s_nop 0
	global_load_lds_dwordx4 v[72:73], off
	s_add_u32 m0, s100, 0xf000
	s_nop 0
	global_load_lds_dwordx4 v[74:75], off
	ds_read_b128 a[0:3], v112
	ds_read_b128 v[80:83], v113
	ds_read_b128 a[4:7], v112 offset:2048
	ds_read_b128 a[8:11], v112 offset:4096
	ds_read_b128 a[12:15], v112 offset:6144
	ds_read_b128 v[92:95], v113 offset:2048
	ds_read_b128 v[88:91], v113 offset:4096
	ds_read_b128 v[84:87], v113 offset:6144
	ds_read_b128 a[16:19], v114
	ds_read_b128 a[20:23], v114 offset:2048
	ds_read_b128 a[24:27], v114 offset:4096
	ds_read_b128 a[28:31], v114 offset:6144
	s_setprio 1
	s_waitcnt lgkmcnt(10)
	v_mfma_f32_16x16x32_bf16 v[0:3], a[0:3], v[80:83], v[0:3]
	s_waitcnt lgkmcnt(9)
	v_mfma_f32_16x16x32_bf16 v[16:19], a[4:7], v[80:83], v[16:19]
	s_waitcnt lgkmcnt(8)
	v_mfma_f32_16x16x32_bf16 v[32:35], a[8:11], v[80:83], v[32:35]
	s_waitcnt lgkmcnt(7)
	v_mfma_f32_16x16x32_bf16 v[48:51], a[12:15], v[80:83], v[48:51]
	ds_read_b128 v[80:83], v115
	s_waitcnt lgkmcnt(7)
	v_mfma_f32_16x16x32_bf16 v[4:7], a[0:3], v[92:95], v[4:7]
	v_mfma_f32_16x16x32_bf16 v[20:23], a[4:7], v[92:95], v[20:23]
	v_mfma_f32_16x16x32_bf16 v[36:39], a[8:11], v[92:95], v[36:39]
	v_mfma_f32_16x16x32_bf16 v[52:55], a[12:15], v[92:95], v[52:55]
	ds_read_b128 v[92:95], v115 offset:2048
	s_waitcnt lgkmcnt(7)
	v_mfma_f32_16x16x32_bf16 v[8:11], a[0:3], v[88:91], v[8:11]
	v_mfma_f32_16x16x32_bf16 v[24:27], a[4:7], v[88:91], v[24:27]
	v_mfma_f32_16x16x32_bf16 v[40:43], a[8:11], v[88:91], v[40:43]
	v_mfma_f32_16x16x32_bf16 v[56:59], a[12:15], v[88:91], v[56:59]
	ds_read_b128 v[88:91], v115 offset:4096
	s_waitcnt lgkmcnt(7)
	v_mfma_f32_16x16x32_bf16 v[12:15], a[0:3], v[84:87], v[12:15]
	v_mfma_f32_16x16x32_bf16 v[28:31], a[4:7], v[84:87], v[28:31]
	v_mfma_f32_16x16x32_bf16 v[44:47], a[8:11], v[84:87], v[44:47]
	v_mfma_f32_16x16x32_bf16 v[60:63], a[12:15], v[84:87], v[60:63]
	ds_read_b128 v[84:87], v115 offset:6144
	s_waitcnt lgkmcnt(3)
	v_mfma_f32_16x16x32_bf16 v[0:3], a[16:19], v[80:83], v[0:3]
	v_mfma_f32_16x16x32_bf16 v[16:19], a[20:23], v[80:83], v[16:19]
	v_mfma_f32_16x16x32_bf16 v[32:35], a[24:27], v[80:83], v[32:35]
	v_mfma_f32_16x16x32_bf16 v[48:51], a[28:31], v[80:83], v[48:51]
	s_waitcnt lgkmcnt(2)
	v_mfma_f32_16x16x32_bf16 v[4:7], a[16:19], v[92:95], v[4:7]
	v_mfma_f32_16x16x32_bf16 v[20:23], a[20:23], v[92:95], v[20:23]
	v_mfma_f32_16x16x32_bf16 v[36:39], a[24:27], v[92:95], v[36:39]
	v_mfma_f32_16x16x32_bf16 v[52:55], a[28:31], v[92:95], v[52:55]
	s_waitcnt lgkmcnt(1)
	v_mfma_f32_16x16x32_bf16 v[8:11], a[16:19], v[88:91], v[8:11]
	v_mfma_f32_16x16x32_bf16 v[24:27], a[20:23], v[88:91], v[24:27]
	v_mfma_f32_16x16x32_bf16 v[40:43], a[24:27], v[88:91], v[40:43]
	v_mfma_f32_16x16x32_bf16 v[56:59], a[28:31], v[88:91], v[56:59]
	s_waitcnt lgkmcnt(0)
	v_mfma_f32_16x16x32_bf16 v[12:15], a[16:19], v[84:87], v[12:15]
	v_mfma_f32_16x16x32_bf16 v[28:31], a[20:23], v[84:87], v[28:31]
	v_mfma_f32_16x16x32_bf16 v[44:47], a[24:27], v[84:87], v[44:47]
	v_mfma_f32_16x16x32_bf16 v[60:63], a[28:31], v[84:87], v[60:63]
	s_setprio 0
	s_waitcnt vmcnt(0) lgkmcnt(0)
	s_barrier
	ds_read_b128 a[0:3], v112 offset:32768
	ds_read_b128 v[80:83], v113 offset:32768
	ds_read_b128 a[4:7], v112 offset:34816
	ds_read_b128 a[8:11], v112 offset:36864
	ds_read_b128 a[12:15], v112 offset:38912
	ds_read_b128 v[92:95], v113 offset:34816
	ds_read_b128 v[88:91], v113 offset:36864
	ds_read_b128 v[84:87], v113 offset:38912
	ds_read_b128 a[16:19], v114 offset:32768
	ds_read_b128 a[20:23], v114 offset:34816
	ds_read_b128 a[24:27], v114 offset:36864
	ds_read_b128 a[28:31], v114 offset:38912
	s_setprio 1
	s_waitcnt lgkmcnt(10)
	v_mfma_f32_16x16x32_bf16 v[0:3], a[0:3], v[80:83], v[0:3]
	s_waitcnt lgkmcnt(9)
	v_mfma_f32_16x16x32_bf16 v[16:19], a[4:7], v[80:83], v[16:19]
	s_waitcnt lgkmcnt(8)
	v_mfma_f32_16x16x32_bf16 v[32:35], a[8:11], v[80:83], v[32:35]
	s_waitcnt lgkmcnt(7)
	v_mfma_f32_16x16x32_bf16 v[48:51], a[12:15], v[80:83], v[48:51]
	ds_read_b128 v[80:83], v115 offset:32768
	s_waitcnt lgkmcnt(7)
	v_mfma_f32_16x16x32_bf16 v[4:7], a[0:3], v[92:95], v[4:7]
	v_mfma_f32_16x16x32_bf16 v[20:23], a[4:7], v[92:95], v[20:23]
	v_mfma_f32_16x16x32_bf16 v[36:39], a[8:11], v[92:95], v[36:39]
	v_mfma_f32_16x16x32_bf16 v[52:55], a[12:15], v[92:95], v[52:55]
	ds_read_b128 v[92:95], v115 offset:34816
	s_waitcnt lgkmcnt(7)
	v_mfma_f32_16x16x32_bf16 v[8:11], a[0:3], v[88:91], v[8:11]
	v_mfma_f32_16x16x32_bf16 v[24:27], a[4:7], v[88:91], v[24:27]
	v_mfma_f32_16x16x32_bf16 v[40:43], a[8:11], v[88:91], v[40:43]
	v_mfma_f32_16x16x32_bf16 v[56:59], a[12:15], v[88:91], v[56:59]
	ds_read_b128 v[88:91], v115 offset:36864
	s_waitcnt lgkmcnt(7)
	v_mfma_f32_16x16x32_bf16 v[12:15], a[0:3], v[84:87], v[12:15]
	v_mfma_f32_16x16x32_bf16 v[28:31], a[4:7], v[84:87], v[28:31]
	v_mfma_f32_16x16x32_bf16 v[44:47], a[8:11], v[84:87], v[44:47]
	v_mfma_f32_16x16x32_bf16 v[60:63], a[12:15], v[84:87], v[60:63]
	ds_read_b128 v[84:87], v115 offset:38912
	s_waitcnt lgkmcnt(3)
	v_mfma_f32_16x16x32_bf16 v[0:3], a[16:19], v[80:83], v[0:3]
	v_mfma_f32_16x16x32_bf16 v[16:19], a[20:23], v[80:83], v[16:19]
	v_mfma_f32_16x16x32_bf16 v[32:35], a[24:27], v[80:83], v[32:35]
	v_mfma_f32_16x16x32_bf16 v[48:51], a[28:31], v[80:83], v[48:51]
	s_waitcnt lgkmcnt(2)
	v_mfma_f32_16x16x32_bf16 v[4:7], a[16:19], v[92:95], v[4:7]
	v_mfma_f32_16x16x32_bf16 v[20:23], a[20:23], v[92:95], v[20:23]
	v_mfma_f32_16x16x32_bf16 v[36:39], a[24:27], v[92:95], v[36:39]
	v_mfma_f32_16x16x32_bf16 v[52:55], a[28:31], v[92:95], v[52:55]
	s_waitcnt lgkmcnt(1)
	v_mfma_f32_16x16x32_bf16 v[8:11], a[16:19], v[88:91], v[8:11]
	v_mfma_f32_16x16x32_bf16 v[24:27], a[20:23], v[88:91], v[24:27]
	v_mfma_f32_16x16x32_bf16 v[40:43], a[24:27], v[88:91], v[40:43]
	v_mfma_f32_16x16x32_bf16 v[56:59], a[28:31], v[88:91], v[56:59]
	s_waitcnt lgkmcnt(0)
	v_mfma_f32_16x16x32_bf16 v[12:15], a[16:19], v[84:87], v[12:15]
	v_mfma_f32_16x16x32_bf16 v[28:31], a[20:23], v[84:87], v[28:31]
	v_mfma_f32_16x16x32_bf16 v[44:47], a[24:27], v[84:87], v[44:47]
	v_mfma_f32_16x16x32_bf16 v[60:63], a[28:31], v[84:87], v[60:63]
	s_setprio 0
	v_readfirstlane_b32 s15, v107
	v_readfirstlane_b32 s4, v106
	s_lshl_b32 s15, s15, 6
	s_waitcnt lgkmcnt(0)
	s_barrier
	s_add_i32 s15, s15, s9
	s_lshl_b32 s31, s4, 13
	s_lshl_b32 s4, s8, 14
	s_add_i32 s31, s31, s4
	v_or_b32_e32 v64, s15, v108
	s_movk_i32 s4, 0x80
	v_cmp_gt_i32_e32 vcc, s4, v64
	s_barrier
	v_and_b32_e32 v120, 15, v143
	v_bfe_u32 v121, v143, 4, 2
	v_xor_b32_e32 v121, v121, v120
	v_lshlrev_b32_e32 v121, 4, v121
	v_lshl_add_u32 v121, v120, 8, v121
	v_lshrrev_b32_e32 v120, 6, v143
	v_lshl_add_u32 v121, v120, 14, v121
	ds_write_b128 v121, v[0:3]
	ds_write_b128 v121, v[4:7] offset:4096
	ds_write_b128 v121, v[8:11] offset:8192
	ds_write_b128 v121, v[12:15] offset:12288
	v_xor_b32_e32 v115, 64, v121
	ds_write_b128 v115, v[16:19]
	ds_write_b128 v115, v[20:23] offset:4096
	ds_write_b128 v115, v[24:27] offset:8192
	ds_write_b128 v115, v[28:31] offset:12288
	v_xor_b32_e32 v115, 128, v121
	ds_write_b128 v115, v[32:35]
	ds_write_b128 v115, v[36:39] offset:4096
	ds_write_b128 v115, v[40:43] offset:8192
	ds_write_b128 v115, v[44:47] offset:12288
	v_xor_b32_e32 v115, 192, v121
	ds_write_b128 v115, v[48:51]
	ds_write_b128 v115, v[52:55] offset:4096
	ds_write_b128 v115, v[56:59] offset:8192
	ds_write_b128 v115, v[60:63] offset:12288
	v_and_b32_e32 v112, 31, v143
	v_bfe_u32 v114, v143, 5, 1
	v_and_b32_e32 v121, 15, v112
	v_xor_b32_e32 v114, v114, v121
	v_lshlrev_b32_e32 v114, 4, v114
	v_lshl_add_u32 v114, v112, 8, v114
	v_lshl_add_u32 v114, v120, 14, v114
	ds_read_b128 v[48:51], v114
	ds_read_b128 v[32:35], v114 offset:8192
	v_xor_b32_e32 v113, 32, v114
	ds_read_b128 v[52:55], v113
	ds_read_b128 v[36:39], v113 offset:8192
	v_xor_b32_e32 v113, 64, v114
	ds_read_b128 v[56:59], v113
	ds_read_b128 v[40:43], v113 offset:8192
	v_xor_b32_e32 v113, 96, v114
	ds_read_b128 v[60:63], v113
	ds_read_b128 v[44:47], v113 offset:8192
	v_xor_b32_e32 v113, 128, v114
	ds_read_b128 v[16:19], v113
	ds_read_b128 v[0:3], v113 offset:8192
	v_xor_b32_e32 v113, 160, v114
	ds_read_b128 v[20:23], v113
	ds_read_b128 v[4:7], v113 offset:8192
	v_xor_b32_e32 v113, 192, v114
	ds_read_b128 v[24:27], v113
	ds_read_b128 v[8:11], v113 offset:8192
	v_xor_b32_e32 v113, 224, v114
	ds_read_b128 v[28:31], v113
	ds_read_b128 v[12:15], v113 offset:8192
	s_waitcnt lgkmcnt(0)
	s_barrier
	s_and_saveexec_b64 s[28:29], vcc
	s_cbranch_execz .LBB0_690
	v_cmp_nlt_f32_e64 s[8:9], |v48|, s56
	s_and_saveexec_b64 s[22:23], s[8:9]
	s_xor_b64 s[8:9], exec, s[22:23]
	s_cbranch_execz .LBB0_627
	v_add_f32_e64 v65, |v48|, |v48|
	v_mul_f32_e32 v66, 0x3fb8aa3b, v65
	v_rndne_f32_e32 v67, v66
	v_sub_f32_e32 v68, v66, v67
	v_fma_f32 v66, v65, s67, -v66
	v_fmac_f32_e32 v66, 0x32a5705f, v65
	v_add_f32_e32 v66, v68, v66
	v_cvt_i32_f32_e32 v67, v67
	v_exp_f32_e32 v66, v66
	v_cmp_ngt_f32_e64 s[38:39], s57, v65
	v_ldexp_f32 v66, v66, v67
	s_nop 0
	v_cndmask_b32_e64 v66, 0, v66, s[38:39]
	v_cmp_nlt_f32_e64 s[38:39], s58, v65
	s_nop 1
	v_cndmask_b32_e64 v65, v172, v66, s[38:39]
	v_add_f32_e32 v65, 1.0, v65
	v_rcp_f32_e32 v65, v65
	s_nop 0
	v_fma_f32 v65, v65, -2.0, 1.0

.LBB0_890:
	s_mul_hi_i32 s4, s22, 0x38e38e39
	s_lshr_b32 s8, s4, 31
	s_ashr_i32 s4, s4, 4
	s_add_i32 s4, s4, s8
	s_mul_i32 s8, s4, 0x48
	s_sub_i32 s8, s22, s8
	v_lshl_add_u32 v0, s8, 7, v109
	v_ashrrev_i32_e32 v1, 31, v0
	v_lshlrev_b64 v[32:33], 12, v[0:1]
	v_lshl_add_u64 v[34:35], v[96:97], 0, v[32:33]
	v_add_co_u32_e32 v40, vcc, s87, v34
	s_lshl_b32 s9, s4, 7
	s_nop 0
	v_addc_co_u32_e32 v41, vcc, 0, v35, vcc
	v_add_co_u32_e32 v42, vcc, s66, v34
	v_add_u32_e32 v0, s9, v109
	s_nop 0
	v_addc_co_u32_e32 v43, vcc, 0, v35, vcc
	v_ashrrev_i32_e32 v1, 31, v0
	v_add_co_u32_e32 v44, vcc, s20, v34
	v_lshlrev_b64 v[36:37], 12, v[0:1]
	s_nop 0
	v_addc_co_u32_e32 v45, vcc, 0, v35, vcc
	v_lshl_add_u64 v[38:39], v[98:99], 0, v[36:37]
	v_readfirstlane_b32 s100, v110
	s_nop 3
	s_add_u32 m0, s100, 0x0
	s_nop 0
	global_load_lds_dwordx4 v[34:35], off
	s_add_u32 m0, s100, 0x1000
	s_nop 0
	global_load_lds_dwordx4 v[40:41], off
	s_add_u32 m0, s100, 0x2000
	s_nop 0
	global_load_lds_dwordx4 v[42:43], off
	s_add_u32 m0, s100, 0x3000
	s_nop 0
	global_load_lds_dwordx4 v[44:45], off
	s_add_u32 m0, s100, 0x4000
	s_nop 0
	global_load_lds_dwordx4 v[38:39], off
	v_add_co_u32_e32 v46, vcc, s87, v38
	v_lshl_add_u64 v[102:103], v[100:101], 0, v[36:37]
	s_nop 0
	v_addc_co_u32_e32 v47, vcc, 0, v39, vcc
	s_waitcnt vmcnt(16)
	v_add_co_u32_e32 v48, vcc, s66, v38
	s_add_u32 m0, s100, 0x5000
	s_nop 0
	global_load_lds_dwordx4 v[46:47], off
	s_nop 0
	v_addc_co_u32_e32 v49, vcc, 0, v39, vcc
	v_add_co_u32_e32 v50, vcc, s20, v38
	s_add_u32 m0, s100, 0x6000
	s_nop 0
	global_load_lds_dwordx4 v[48:49], off
	s_nop 0
	v_addc_co_u32_e32 v51, vcc, 0, v39, vcc
	s_add_u32 m0, s100, 0x7000
	s_nop 0
	global_load_lds_dwordx4 v[50:51], off
	v_lshl_add_u64 v[104:105], v[100:101], 0, v[32:33]
	s_mov_b64 s[28:29], 0
	v_mov_b32_e32 v0, 0
	v_mov_b32_e32 v1, v0
	v_mov_b32_e32 v2, v0
	v_mov_b32_e32 v3, v0
	v_mov_b32_e32 v4, v0
	v_mov_b32_e32 v5, v0
	v_mov_b32_e32 v6, v0
	v_mov_b32_e32 v7, v0
	v_mov_b32_e32 v8, v0
	v_mov_b32_e32 v9, v0
	v_mov_b32_e32 v10, v0
	v_mov_b32_e32 v11, v0
	v_mov_b32_e32 v12, v0
	v_mov_b32_e32 v13, v0
	v_mov_b32_e32 v14, v0
	v_mov_b32_e32 v15, v0
	v_mov_b32_e32 v16, v0
	v_mov_b32_e32 v17, v0
	v_mov_b32_e32 v18, v0
	v_mov_b32_e32 v19, v0
	v_mov_b32_e32 v20, v0
	v_mov_b32_e32 v21, v0
	v_mov_b32_e32 v22, v0
	v_mov_b32_e32 v23, v0
	v_mov_b32_e32 v24, v0
	v_mov_b32_e32 v25, v0
	v_mov_b32_e32 v26, v0
	v_mov_b32_e32 v27, v0
	v_mov_b32_e32 v28, v0
	v_mov_b32_e32 v29, v0
	v_mov_b32_e32 v30, v0
	v_mov_b32_e32 v31, v0
	v_mov_b32_e32 v32, v0
	v_mov_b32_e32 v33, v0
	v_mov_b32_e32 v34, v0
	v_mov_b32_e32 v35, v0
	v_mov_b32_e32 v36, v0
	v_mov_b32_e32 v37, v0
	v_mov_b32_e32 v38, v0
	v_mov_b32_e32 v39, v0
	v_mov_b32_e32 v40, v0
	v_mov_b32_e32 v41, v0
	v_mov_b32_e32 v42, v0
	v_mov_b32_e32 v43, v0
	v_mov_b32_e32 v44, v0
	v_mov_b32_e32 v45, v0
	v_mov_b32_e32 v46, v0
	v_mov_b32_e32 v47, v0
	v_mov_b32_e32 v48, v0
	v_mov_b32_e32 v49, v0
	v_mov_b32_e32 v50, v0
	v_mov_b32_e32 v51, v0
	v_mov_b32_e32 v52, v0
	v_mov_b32_e32 v53, v0
	v_mov_b32_e32 v54, v0
	v_mov_b32_e32 v55, v0
	v_mov_b32_e32 v56, v0
	v_mov_b32_e32 v57, v0
	v_mov_b32_e32 v58, v0
	v_mov_b32_e32 v59, v0
	v_mov_b32_e32 v60, v0
	v_mov_b32_e32 v61, v0
	v_mov_b32_e32 v62, v0
	v_mov_b32_e32 v63, v0
	v_lshl_add_u64 v[128:129], v[104:105], 0, s[28:29]
	s_mov_b32 s4, 0x1eab8000
	v_add_co_u32_e32 v144, vcc, s4, v128
	s_mov_b32 s4, 0x1ead8000
	s_nop 0
	v_addc_co_u32_e32 v145, vcc, 0, v129, vcc
	v_add_co_u32_e32 v146, vcc, s4, v128
	s_mov_b32 s4, 0x1eaf8000
	s_nop 0
	v_addc_co_u32_e32 v147, vcc, 0, v129, vcc
	v_add_co_u32_e32 v148, vcc, s4, v128
	s_mov_b32 s4, 0x1eb18000
	s_nop 0
	v_addc_co_u32_e32 v149, vcc, 0, v129, vcc
	v_add_co_u32_e32 v150, vcc, s4, v128
	v_lshl_add_u64 v[130:131], v[102:103], 0, s[28:29]
	s_nop 0
	v_addc_co_u32_e32 v151, vcc, 0, v129, vcc
	s_mov_b32 s4, 0x38c00000
	v_add_co_u32_e32 v152, vcc, s4, v130
	s_mov_b32 s4, 0x38c20000
	s_nop 0
	v_addc_co_u32_e32 v153, vcc, 0, v131, vcc
	v_add_co_u32_e32 v154, vcc, s4, v130
	s_mov_b32 s4, 0x38c40000
	s_nop 0
	v_addc_co_u32_e32 v155, vcc, 0, v131, vcc
	v_add_co_u32_e32 v156, vcc, s4, v130
	s_mov_b32 s4, 0x38c60000
	s_nop 0
	v_addc_co_u32_e32 v157, vcc, 0, v131, vcc
	v_add_co_u32_e32 v178, vcc, s4, v130
	v_addc_co_u32_e32 v179, vcc, 0, v131, vcc
	v_lshl_add_u64 v[144:145], 8, 4, v[144:145]
	v_lshl_add_u64 v[146:147], 8, 4, v[146:147]
	v_lshl_add_u64 v[148:149], 8, 4, v[148:149]
	v_lshl_add_u64 v[150:151], 8, 4, v[150:151]
	v_lshl_add_u64 v[152:153], 8, 4, v[152:153]
	v_lshl_add_u64 v[154:155], 8, 4, v[154:155]
	v_lshl_add_u64 v[156:157], 8, 4, v[156:157]
	v_lshl_add_u64 v[178:179], 8, 4, v[178:179]
	v_and_b32_e32 v124, 15, v143
	v_lshrrev_b32_e32 v125, 1, v124
	v_bfe_u32 v117, v143, 4, 2
	v_xor_b32_e32 v125, v125, v117
	v_lshlrev_b32_e32 v125, 4, v125
	v_lshl_add_u32 v125, v124, 7, v125
	v_lshrrev_b32_e32 v124, 6, v143
	v_lshrrev_b32_e32 v115, 1, v124
	v_and_b32_e32 v124, 1, v124
	v_lshl_add_u32 v115, v115, 13, v125
	v_lshl_add_u32 v116, v124, 13, v125
	v_add_u32_e32 v116, 0x4000, v116
	v_xor_b32_e32 v117, 64, v115
	v_xor_b32_e32 v118, 64, v116
	s_waitcnt vmcnt(0) lgkmcnt(0)
	s_barrier
.LBB0_891:
	s_add_u32 m0, s100, 0x8000
	s_nop 0
	global_load_lds_dwordx4 v[144:145], off
	s_add_u32 m0, s100, 0x9000
	s_nop 0
	global_load_lds_dwordx4 v[146:147], off
	s_add_u32 m0, s100, 0xa000
	s_nop 0
	global_load_lds_dwordx4 v[148:149], off
	s_add_u32 m0, s100, 0xb000
	s_nop 0
	global_load_lds_dwordx4 v[150:151], off
	s_add_u32 m0, s100, 0xc000
	s_nop 0
	global_load_lds_dwordx4 v[152:153], off
	s_add_u32 m0, s100, 0xd000
	s_nop 0
	global_load_lds_dwordx4 v[154:155], off
	s_add_u32 m0, s100, 0xe000
	s_nop 0
	global_load_lds_dwordx4 v[156:157], off
	s_add_u32 m0, s100, 0xf000
	s_nop 0
	global_load_lds_dwordx4 v[178:179], off
	ds_read_b128 a[0:3], v115
	ds_read_b128 v[80:83], v116
	ds_read_b128 a[4:7], v115 offset:2048
	ds_read_b128 a[8:11], v115 offset:4096
	ds_read_b128 a[12:15], v115 offset:6144
	ds_read_b128 v[92:95], v116 offset:2048
	ds_read_b128 v[88:91], v116 offset:4096
	ds_read_b128 v[84:87], v116 offset:6144
	ds_read_b128 a[16:19], v117
	ds_read_b128 a[20:23], v117 offset:2048
	ds_read_b128 a[24:27], v117 offset:4096
	ds_read_b128 a[28:31], v117 offset:6144
	s_setprio 1
	s_waitcnt lgkmcnt(10)
	v_mfma_f32_16x16x32_bf16 v[0:3], a[0:3], v[80:83], v[0:3]
	s_waitcnt lgkmcnt(9)
	v_mfma_f32_16x16x32_bf16 v[16:19], a[4:7], v[80:83], v[16:19]
	s_waitcnt lgkmcnt(8)
	v_mfma_f32_16x16x32_bf16 v[32:35], a[8:11], v[80:83], v[32:35]
	s_waitcnt lgkmcnt(7)
	v_mfma_f32_16x16x32_bf16 v[48:51], a[12:15], v[80:83], v[48:51]
	ds_read_b128 v[80:83], v118
	s_waitcnt lgkmcnt(7)
	v_mfma_f32_16x16x32_bf16 v[4:7], a[0:3], v[92:95], v[4:7]
	v_lshl_add_u64 v[64:65], 8, 4, v[144:145]
	v_lshl_add_u64 v[66:67], 8, 4, v[146:147]
	v_lshl_add_u64 v[68:69], 8, 4, v[148:149]
	v_mfma_f32_16x16x32_bf16 v[20:23], a[4:7], v[92:95], v[20:23]
	v_lshl_add_u64 v[70:71], 8, 4, v[150:151]
	v_lshl_add_u64 v[76:77], 8, 4, v[152:153]
	v_lshl_add_u64 v[78:79], 8, 4, v[154:155]
	v_mfma_f32_16x16x32_bf16 v[36:39], a[8:11], v[92:95], v[36:39]
	v_lshl_add_u64 v[72:73], 8, 4, v[156:157]
	v_lshl_add_u64 v[74:75], 8, 4, v[178:179]
	v_mfma_f32_16x16x32_bf16 v[52:55], a[12:15], v[92:95], v[52:55]
	ds_read_b128 v[92:95], v118 offset:2048
	s_waitcnt lgkmcnt(7)
	v_mfma_f32_16x16x32_bf16 v[8:11], a[0:3], v[88:91], v[8:11]
	v_mfma_f32_16x16x32_bf16 v[24:27], a[4:7], v[88:91], v[24:27]
	v_mfma_f32_16x16x32_bf16 v[40:43], a[8:11], v[88:91], v[40:43]
	v_mfma_f32_16x16x32_bf16 v[56:59], a[12:15], v[88:91], v[56:59]
	ds_read_b128 v[88:91], v118 offset:4096
	s_waitcnt lgkmcnt(7)
	v_mfma_f32_16x16x32_bf16 v[12:15], a[0:3], v[84:87], v[12:15]
	v_mfma_f32_16x16x32_bf16 v[28:31], a[4:7], v[84:87], v[28:31]
	v_mfma_f32_16x16x32_bf16 v[44:47], a[8:11], v[84:87], v[44:47]
	v_mfma_f32_16x16x32_bf16 v[60:63], a[12:15], v[84:87], v[60:63]
	ds_read_b128 v[84:87], v118 offset:6144
	s_waitcnt lgkmcnt(3)
	v_mfma_f32_16x16x32_bf16 v[0:3], a[16:19], v[80:83], v[0:3]
	v_mfma_f32_16x16x32_bf16 v[16:19], a[20:23], v[80:83], v[16:19]
	v_mfma_f32_16x16x32_bf16 v[32:35], a[24:27], v[80:83], v[32:35]
	v_mfma_f32_16x16x32_bf16 v[48:51], a[28:31], v[80:83], v[48:51]
	s_waitcnt lgkmcnt(2)
	v_mfma_f32_16x16x32_bf16 v[4:7], a[16:19], v[92:95], v[4:7]
	v_mfma_f32_16x16x32_bf16 v[20:23], a[20:23], v[92:95], v[20:23]
	v_mfma_f32_16x16x32_bf16 v[36:39], a[24:27], v[92:95], v[36:39]
	v_mfma_f32_16x16x32_bf16 v[52:55], a[28:31], v[92:95], v[52:55]
	s_waitcnt lgkmcnt(1)
	v_mfma_f32_16x16x32_bf16 v[8:11], a[16:19], v[88:91], v[8:11]
	v_mfma_f32_16x16x32_bf16 v[24:27], a[20:23], v[88:91], v[24:27]
	v_mfma_f32_16x16x32_bf16 v[40:43], a[24:27], v[88:91], v[40:43]
	v_mfma_f32_16x16x32_bf16 v[56:59], a[28:31], v[88:91], v[56:59]
	s_waitcnt lgkmcnt(0)
	v_mfma_f32_16x16x32_bf16 v[12:15], a[16:19], v[84:87], v[12:15]
	v_mfma_f32_16x16x32_bf16 v[28:31], a[20:23], v[84:87], v[28:31]
	v_mfma_f32_16x16x32_bf16 v[44:47], a[24:27], v[84:87], v[44:47]
	v_mfma_f32_16x16x32_bf16 v[60:63], a[28:31], v[84:87], v[60:63]
	s_setprio 0
	s_waitcnt vmcnt(0) lgkmcnt(0)
	s_barrier
	s_add_u32 s28, s28, 0x100
	s_addc_u32 s29, s29, 0
	s_add_u32 m0, s100, 0x0
	s_nop 0
	global_load_lds_dwordx4 v[64:65], off
	s_add_u32 m0, s100, 0x1000
	s_nop 0
	global_load_lds_dwordx4 v[66:67], off
	s_add_u32 m0, s100, 0x2000
	s_nop 0
	global_load_lds_dwordx4 v[68:69], off
	s_add_u32 m0, s100, 0x3000
	s_nop 0
	global_load_lds_dwordx4 v[70:71], off
	s_add_u32 m0, s100, 0x4000
	s_nop 0
	global_load_lds_dwordx4 v[76:77], off
	s_add_u32 m0, s100, 0x5000
	s_nop 0
	global_load_lds_dwordx4 v[78:79], off
	s_add_u32 m0, s100, 0x6000
	s_nop 0
	global_load_lds_dwordx4 v[72:73], off
	s_add_u32 m0, s100, 0x7000
	s_nop 0
	global_load_lds_dwordx4 v[74:75], off
	ds_read_b128 a[0:3], v115 offset:32768
	ds_read_b128 v[80:83], v116 offset:32768
	ds_read_b128 a[4:7], v115 offset:34816
	ds_read_b128 a[8:11], v115 offset:36864
	ds_read_b128 a[12:15], v115 offset:38912
	ds_read_b128 v[92:95], v116 offset:34816
	ds_read_b128 v[88:91], v116 offset:36864
	ds_read_b128 v[84:87], v116 offset:38912
	ds_read_b128 a[16:19], v117 offset:32768
	ds_read_b128 a[20:23], v117 offset:34816
	ds_read_b128 a[24:27], v117 offset:36864
	ds_read_b128 a[28:31], v117 offset:38912
	s_setprio 1
	s_waitcnt lgkmcnt(10)
	v_mfma_f32_16x16x32_bf16 v[0:3], a[0:3], v[80:83], v[0:3]
	s_waitcnt lgkmcnt(9)
	v_mfma_f32_16x16x32_bf16 v[16:19], a[4:7], v[80:83], v[16:19]
	s_waitcnt lgkmcnt(8)
	v_mfma_f32_16x16x32_bf16 v[32:35], a[8:11], v[80:83], v[32:35]
	s_waitcnt lgkmcnt(7)
	v_mfma_f32_16x16x32_bf16 v[48:51], a[12:15], v[80:83], v[48:51]
	ds_read_b128 v[80:83], v118 offset:32768
	s_waitcnt lgkmcnt(7)
	v_mfma_f32_16x16x32_bf16 v[4:7], a[0:3], v[92:95], v[4:7]
	v_lshl_add_u64 v[128:129], v[104:105], 0, s[28:29]
	s_mov_b32 s4, 0x1eab8000
	v_add_co_u32_e32 v144, vcc, s4, v128
	v_mfma_f32_16x16x32_bf16 v[20:23], a[4:7], v[92:95], v[20:23]
	s_mov_b32 s4, 0x1ead8000
	s_nop 0
	v_addc_co_u32_e32 v145, vcc, 0, v129, vcc
	v_mfma_f32_16x16x32_bf16 v[36:39], a[8:11], v[92:95], v[36:39]
	v_add_co_u32_e32 v146, vcc, s4, v128
	s_mov_b32 s4, 0x1eaf8000
	s_nop 0
	v_mfma_f32_16x16x32_bf16 v[52:55], a[12:15], v[92:95], v[52:55]
	v_addc_co_u32_e32 v147, vcc, 0, v129, vcc
	v_add_co_u32_e32 v148, vcc, s4, v128
	s_mov_b32 s4, 0x1eb18000
	ds_read_b128 v[92:95], v118 offset:34816
	s_waitcnt lgkmcnt(7)
	v_mfma_f32_16x16x32_bf16 v[8:11], a[0:3], v[88:91], v[8:11]
	s_nop 0
	v_addc_co_u32_e32 v149, vcc, 0, v129, vcc
	v_add_co_u32_e32 v150, vcc, s4, v128
	v_mfma_f32_16x16x32_bf16 v[24:27], a[4:7], v[88:91], v[24:27]
	v_lshl_add_u64 v[130:131], v[102:103], 0, s[28:29]
	s_nop 0
	v_addc_co_u32_e32 v151, vcc, 0, v129, vcc
	v_mfma_f32_16x16x32_bf16 v[40:43], a[8:11], v[88:91], v[40:43]
	s_mov_b32 s4, 0x38c00000
	v_add_co_u32_e32 v152, vcc, s4, v130
	s_mov_b32 s4, 0x38c20000
	v_mfma_f32_16x16x32_bf16 v[56:59], a[12:15], v[88:91], v[56:59]
	s_nop 0
	v_addc_co_u32_e32 v153, vcc, 0, v131, vcc
	v_add_co_u32_e32 v154, vcc, s4, v130
	ds_read_b128 v[88:91], v118 offset:36864
	s_waitcnt lgkmcnt(7)
	v_mfma_f32_16x16x32_bf16 v[12:15], a[0:3], v[84:87], v[12:15]
	s_mov_b32 s4, 0x38c40000
	s_nop 0
	v_addc_co_u32_e32 v155, vcc, 0, v131, vcc
	v_mfma_f32_16x16x32_bf16 v[28:31], a[4:7], v[84:87], v[28:31]
	v_add_co_u32_e32 v156, vcc, s4, v130
	s_mov_b32 s4, 0x38c60000
	s_nop 0
	v_mfma_f32_16x16x32_bf16 v[44:47], a[8:11], v[84:87], v[44:47]
	v_addc_co_u32_e32 v157, vcc, 0, v131, vcc
	v_add_co_u32_e32 v178, vcc, s4, v130
	v_addc_co_u32_e32 v179, vcc, 0, v131, vcc
	v_mfma_f32_16x16x32_bf16 v[60:63], a[12:15], v[84:87], v[60:63]
	v_lshl_add_u64 v[144:145], 8, 4, v[144:145]
	v_lshl_add_u64 v[146:147], 8, 4, v[146:147]
	v_lshl_add_u64 v[148:149], 8, 4, v[148:149]
	ds_read_b128 v[84:87], v118 offset:38912
	s_waitcnt lgkmcnt(3)
	v_mfma_f32_16x16x32_bf16 v[0:3], a[16:19], v[80:83], v[0:3]
	v_lshl_add_u64 v[150:151], 8, 4, v[150:151]
	v_lshl_add_u64 v[152:153], 8, 4, v[152:153]
	v_lshl_add_u64 v[154:155], 8, 4, v[154:155]
	v_mfma_f32_16x16x32_bf16 v[16:19], a[20:23], v[80:83], v[16:19]
	v_lshl_add_u64 v[156:157], 8, 4, v[156:157]
	v_lshl_add_u64 v[178:179], 8, 4, v[178:179]
	v_mfma_f32_16x16x32_bf16 v[32:35], a[24:27], v[80:83], v[32:35]
	v_mfma_f32_16x16x32_bf16 v[48:51], a[28:31], v[80:83], v[48:51]
	s_waitcnt lgkmcnt(2)
	v_mfma_f32_16x16x32_bf16 v[4:7], a[16:19], v[92:95], v[4:7]
	v_mfma_f32_16x16x32_bf16 v[20:23], a[20:23], v[92:95], v[20:23]
	v_mfma_f32_16x16x32_bf16 v[36:39], a[24:27], v[92:95], v[36:39]
	v_mfma_f32_16x16x32_bf16 v[52:55], a[28:31], v[92:95], v[52:55]
	s_waitcnt lgkmcnt(1)
	v_mfma_f32_16x16x32_bf16 v[8:11], a[16:19], v[88:91], v[8:11]
	v_mfma_f32_16x16x32_bf16 v[24:27], a[20:23], v[88:91], v[24:27]
	v_mfma_f32_16x16x32_bf16 v[40:43], a[24:27], v[88:91], v[40:43]
	v_mfma_f32_16x16x32_bf16 v[56:59], a[28:31], v[88:91], v[56:59]
	s_waitcnt lgkmcnt(0)
	v_mfma_f32_16x16x32_bf16 v[12:15], a[16:19], v[84:87], v[12:15]
	v_mfma_f32_16x16x32_bf16 v[28:31], a[20:23], v[84:87], v[28:31]
	v_mfma_f32_16x16x32_bf16 v[44:47], a[24:27], v[84:87], v[44:47]
	v_mfma_f32_16x16x32_bf16 v[60:63], a[28:31], v[84:87], v[60:63]
	s_setprio 0
	s_waitcnt vmcnt(0) lgkmcnt(0)
	s_barrier
	s_cmpk_eq_i32 s28, 0xf00
	s_cbranch_scc0 .LBB0_891
	v_lshl_add_u64 v[64:65], 8, 4, v[64:65]
	v_lshl_add_u64 v[66:67], 8, 4, v[66:67]
	v_lshl_add_u64 v[68:69], 8, 4, v[68:69]
	v_lshl_add_u64 v[70:71], 8, 4, v[70:71]
	v_lshl_add_u64 v[76:77], 8, 4, v[76:77]
	v_lshl_add_u64 v[78:79], 8, 4, v[78:79]
	v_lshl_add_u64 v[72:73], 8, 4, v[72:73]
	v_lshl_add_u64 v[74:75], 8, 4, v[74:75]
	s_add_u32 m0, s100, 0x8000
	s_nop 0
	global_load_lds_dwordx4 v[64:65], off
	s_add_u32 m0, s100, 0x9000
	s_nop 0
	global_load_lds_dwordx4 v[66:67], off
	s_add_u32 m0, s100, 0xa000
	s_nop 0
	global_load_lds_dwordx4 v[68:69], off
	s_add_u32 m0, s100, 0xb000
	s_nop 0
	global_load_lds_dwordx4 v[70:71], off
	s_add_u32 m0, s100, 0xc000
	s_nop 0
	global_load_lds_dwordx4 v[76:77], off
	s_add_u32 m0, s100, 0xd000
	s_nop 0
	global_load_lds_dwordx4 v[78:79], off
	s_add_u32 m0, s100, 0xe000
	s_nop 0
	global_load_lds_dwordx4 v[72:73], off
	s_add_u32 m0, s100, 0xf000
	s_nop 0
	global_load_lds_dwordx4 v[74:75], off
	ds_read_b128 a[0:3], v115
	ds_read_b128 v[80:83], v116
	ds_read_b128 a[4:7], v115 offset:2048
	ds_read_b128 a[8:11], v115 offset:4096
	ds_read_b128 a[12:15], v115 offset:6144
	ds_read_b128 v[92:95], v116 offset:2048
	ds_read_b128 v[88:91], v116 offset:4096
	ds_read_b128 v[84:87], v116 offset:6144
	ds_read_b128 a[16:19], v117
	ds_read_b128 a[20:23], v117 offset:2048
	ds_read_b128 a[24:27], v117 offset:4096
	ds_read_b128 a[28:31], v117 offset:6144
	s_setprio 1
	s_waitcnt lgkmcnt(10)
	v_mfma_f32_16x16x32_bf16 v[0:3], a[0:3], v[80:83], v[0:3]
	s_waitcnt lgkmcnt(9)
	v_mfma_f32_16x16x32_bf16 v[16:19], a[4:7], v[80:83], v[16:19]
	s_waitcnt lgkmcnt(8)
	v_mfma_f32_16x16x32_bf16 v[32:35], a[8:11], v[80:83], v[32:35]
	s_waitcnt lgkmcnt(7)
	v_mfma_f32_16x16x32_bf16 v[48:51], a[12:15], v[80:83], v[48:51]
	ds_read_b128 v[80:83], v118
	s_waitcnt lgkmcnt(7)
	v_mfma_f32_16x16x32_bf16 v[4:7], a[0:3], v[92:95], v[4:7]
	v_mfma_f32_16x16x32_bf16 v[20:23], a[4:7], v[92:95], v[20:23]
	v_mfma_f32_16x16x32_bf16 v[36:39], a[8:11], v[92:95], v[36:39]
	v_mfma_f32_16x16x32_bf16 v[52:55], a[12:15], v[92:95], v[52:55]
	ds_read_b128 v[92:95], v118 offset:2048
	s_waitcnt lgkmcnt(7)
	v_mfma_f32_16x16x32_bf16 v[8:11], a[0:3], v[88:91], v[8:11]
	v_mfma_f32_16x16x32_bf16 v[24:27], a[4:7], v[88:91], v[24:27]
	v_mfma_f32_16x16x32_bf16 v[40:43], a[8:11], v[88:91], v[40:43]
	v_mfma_f32_16x16x32_bf16 v[56:59], a[12:15], v[88:91], v[56:59]
	ds_read_b128 v[88:91], v118 offset:4096
	s_waitcnt lgkmcnt(7)
	v_mfma_f32_16x16x32_bf16 v[12:15], a[0:3], v[84:87], v[12:15]
	v_mfma_f32_16x16x32_bf16 v[28:31], a[4:7], v[84:87], v[28:31]
	v_mfma_f32_16x16x32_bf16 v[44:47], a[8:11], v[84:87], v[44:47]
	v_mfma_f32_16x16x32_bf16 v[60:63], a[12:15], v[84:87], v[60:63]
	ds_read_b128 v[84:87], v118 offset:6144
	s_waitcnt lgkmcnt(3)
	v_mfma_f32_16x16x32_bf16 v[0:3], a[16:19], v[80:83], v[0:3]
	v_mfma_f32_16x16x32_bf16 v[16:19], a[20:23], v[80:83], v[16:19]
	v_mfma_f32_16x16x32_bf16 v[32:35], a[24:27], v[80:83], v[32:35]
	v_mfma_f32_16x16x32_bf16 v[48:51], a[28:31], v[80:83], v[48:51]
	s_waitcnt lgkmcnt(2)
	v_mfma_f32_16x16x32_bf16 v[4:7], a[16:19], v[92:95], v[4:7]
	v_mfma_f32_16x16x32_bf16 v[20:23], a[20:23], v[92:95], v[20:23]
	v_mfma_f32_16x16x32_bf16 v[36:39], a[24:27], v[92:95], v[36:39]
	v_mfma_f32_16x16x32_bf16 v[52:55], a[28:31], v[92:95], v[52:55]
	s_waitcnt lgkmcnt(1)
	v_mfma_f32_16x16x32_bf16 v[8:11], a[16:19], v[88:91], v[8:11]
	v_mfma_f32_16x16x32_bf16 v[24:27], a[20:23], v[88:91], v[24:27]
	v_mfma_f32_16x16x32_bf16 v[40:43], a[24:27], v[88:91], v[40:43]
	v_mfma_f32_16x16x32_bf16 v[56:59], a[28:31], v[88:91], v[56:59]
	s_waitcnt lgkmcnt(0)
	v_mfma_f32_16x16x32_bf16 v[12:15], a[16:19], v[84:87], v[12:15]
	v_mfma_f32_16x16x32_bf16 v[28:31], a[20:23], v[84:87], v[28:31]
	v_mfma_f32_16x16x32_bf16 v[44:47], a[24:27], v[84:87], v[44:47]
	v_mfma_f32_16x16x32_bf16 v[60:63], a[28:31], v[84:87], v[60:63]
	s_setprio 0
	s_waitcnt vmcnt(0) lgkmcnt(0)
	s_barrier
	ds_read_b128 a[0:3], v115 offset:32768
	ds_read_b128 v[80:83], v116 offset:32768
	ds_read_b128 a[4:7], v115 offset:34816
	ds_read_b128 a[8:11], v115 offset:36864
	ds_read_b128 a[12:15], v115 offset:38912
	ds_read_b128 v[92:95], v116 offset:34816
	ds_read_b128 v[88:91], v116 offset:36864
	ds_read_b128 v[84:87], v116 offset:38912
	ds_read_b128 a[16:19], v117 offset:32768
	ds_read_b128 a[20:23], v117 offset:34816
	ds_read_b128 a[24:27], v117 offset:36864
	ds_read_b128 a[28:31], v117 offset:38912
	s_setprio 1
	s_waitcnt lgkmcnt(10)
	v_mfma_f32_16x16x32_bf16 v[0:3], a[0:3], v[80:83], v[0:3]
	s_waitcnt lgkmcnt(9)
	v_mfma_f32_16x16x32_bf16 v[16:19], a[4:7], v[80:83], v[16:19]
	s_waitcnt lgkmcnt(8)
	v_mfma_f32_16x16x32_bf16 v[32:35], a[8:11], v[80:83], v[32:35]
	s_waitcnt lgkmcnt(7)
	v_mfma_f32_16x16x32_bf16 v[48:51], a[12:15], v[80:83], v[48:51]
	ds_read_b128 v[80:83], v118 offset:32768
	s_waitcnt lgkmcnt(7)
	v_mfma_f32_16x16x32_bf16 v[4:7], a[0:3], v[92:95], v[4:7]
	v_mfma_f32_16x16x32_bf16 v[20:23], a[4:7], v[92:95], v[20:23]
	v_mfma_f32_16x16x32_bf16 v[36:39], a[8:11], v[92:95], v[36:39]
	v_mfma_f32_16x16x32_bf16 v[52:55], a[12:15], v[92:95], v[52:55]
	ds_read_b128 v[92:95], v118 offset:34816
	s_waitcnt lgkmcnt(7)
	v_mfma_f32_16x16x32_bf16 v[8:11], a[0:3], v[88:91], v[8:11]
	v_mfma_f32_16x16x32_bf16 v[24:27], a[4:7], v[88:91], v[24:27]
	v_mfma_f32_16x16x32_bf16 v[40:43], a[8:11], v[88:91], v[40:43]
	v_mfma_f32_16x16x32_bf16 v[56:59], a[12:15], v[88:91], v[56:59]
	ds_read_b128 v[88:91], v118 offset:36864
	s_waitcnt lgkmcnt(7)
	v_mfma_f32_16x16x32_bf16 v[12:15], a[0:3], v[84:87], v[12:15]
	v_mfma_f32_16x16x32_bf16 v[28:31], a[4:7], v[84:87], v[28:31]
	v_mfma_f32_16x16x32_bf16 v[44:47], a[8:11], v[84:87], v[44:47]
	v_mfma_f32_16x16x32_bf16 v[60:63], a[12:15], v[84:87], v[60:63]
	ds_read_b128 v[84:87], v118 offset:38912
	s_waitcnt lgkmcnt(3)
	v_mfma_f32_16x16x32_bf16 v[0:3], a[16:19], v[80:83], v[0:3]
	v_mfma_f32_16x16x32_bf16 v[16:19], a[20:23], v[80:83], v[16:19]
	v_mfma_f32_16x16x32_bf16 v[32:35], a[24:27], v[80:83], v[32:35]
	v_mfma_f32_16x16x32_bf16 v[48:51], a[28:31], v[80:83], v[48:51]
	s_waitcnt lgkmcnt(2)
	v_mfma_f32_16x16x32_bf16 v[4:7], a[16:19], v[92:95], v[4:7]
	v_mfma_f32_16x16x32_bf16 v[20:23], a[20:23], v[92:95], v[20:23]
	v_mfma_f32_16x16x32_bf16 v[36:39], a[24:27], v[92:95], v[36:39]
	v_mfma_f32_16x16x32_bf16 v[52:55], a[28:31], v[92:95], v[52:55]
	s_waitcnt lgkmcnt(1)
	v_mfma_f32_16x16x32_bf16 v[8:11], a[16:19], v[88:91], v[8:11]
	v_mfma_f32_16x16x32_bf16 v[24:27], a[20:23], v[88:91], v[24:27]
	v_mfma_f32_16x16x32_bf16 v[40:43], a[24:27], v[88:91], v[40:43]
	v_mfma_f32_16x16x32_bf16 v[56:59], a[28:31], v[88:91], v[56:59]
	s_waitcnt lgkmcnt(0)
	v_mfma_f32_16x16x32_bf16 v[12:15], a[16:19], v[84:87], v[12:15]
	v_mfma_f32_16x16x32_bf16 v[28:31], a[20:23], v[84:87], v[28:31]
	v_mfma_f32_16x16x32_bf16 v[44:47], a[24:27], v[84:87], v[44:47]
	v_mfma_f32_16x16x32_bf16 v[60:63], a[28:31], v[84:87], v[60:63]
	s_setprio 0
	v_readfirstlane_b32 s15, v107
	v_readfirstlane_b32 s4, v106
	s_lshl_b32 s15, s15, 6
	s_waitcnt lgkmcnt(0)
	s_barrier
	s_add_i32 s9, s15, s9
	s_lshl_b32 s15, s4, 13
	s_lshl_b32 s4, s8, 14
	s_add_i32 s15, s15, s4
	v_or_b32_e32 v64, s9, v108
	s_movk_i32 s4, 0x80
	v_cmp_gt_i32_e32 vcc, s4, v64
	s_barrier
	v_and_b32_e32 v124, 15, v143
	v_bfe_u32 v125, v143, 4, 2
	v_xor_b32_e32 v125, v125, v124
	v_lshlrev_b32_e32 v125, 4, v125
	v_lshl_add_u32 v125, v124, 8, v125
	v_lshrrev_b32_e32 v124, 6, v143
	v_lshl_add_u32 v125, v124, 14, v125
	ds_write_b128 v125, v[0:3]
	ds_write_b128 v125, v[4:7] offset:4096
	ds_write_b128 v125, v[8:11] offset:8192
	ds_write_b128 v125, v[12:15] offset:12288
	v_xor_b32_e32 v118, 64, v125
	ds_write_b128 v118, v[16:19]
	ds_write_b128 v118, v[20:23] offset:4096
	ds_write_b128 v118, v[24:27] offset:8192
	ds_write_b128 v118, v[28:31] offset:12288
	v_xor_b32_e32 v118, 128, v125
	ds_write_b128 v118, v[32:35]
	ds_write_b128 v118, v[36:39] offset:4096
	ds_write_b128 v118, v[40:43] offset:8192
	ds_write_b128 v118, v[44:47] offset:12288
	v_xor_b32_e32 v118, 192, v125
	ds_write_b128 v118, v[48:51]
	ds_write_b128 v118, v[52:55] offset:4096
	ds_write_b128 v118, v[56:59] offset:8192
	ds_write_b128 v118, v[60:63] offset:12288
	v_and_b32_e32 v115, 31, v143
	v_bfe_u32 v117, v143, 5, 1
	v_and_b32_e32 v125, 15, v115
	v_xor_b32_e32 v117, v117, v125
	v_lshlrev_b32_e32 v117, 4, v117
	v_lshl_add_u32 v117, v115, 8, v117
	v_lshl_add_u32 v117, v124, 14, v117
	ds_read_b128 v[48:51], v117
	ds_read_b128 v[32:35], v117 offset:8192
	v_xor_b32_e32 v116, 32, v117
	ds_read_b128 v[52:55], v116
	ds_read_b128 v[36:39], v116 offset:8192
	v_xor_b32_e32 v116, 64, v117
	ds_read_b128 v[56:59], v116
	ds_read_b128 v[40:43], v116 offset:8192
	v_xor_b32_e32 v116, 96, v117
	ds_read_b128 v[60:63], v116
	ds_read_b128 v[44:47], v116 offset:8192
	v_xor_b32_e32 v116, 128, v117
	ds_read_b128 v[16:19], v116
	ds_read_b128 v[0:3], v116 offset:8192
	v_xor_b32_e32 v116, 160, v117
	ds_read_b128 v[20:23], v116
	ds_read_b128 v[4:7], v116 offset:8192
	v_xor_b32_e32 v116, 192, v117
	ds_read_b128 v[24:27], v116
	ds_read_b128 v[8:11], v116 offset:8192
	v_xor_b32_e32 v116, 224, v117
	ds_read_b128 v[28:31], v116
	ds_read_b128 v[12:15], v116 offset:8192
	s_waitcnt lgkmcnt(0)
	s_barrier
	s_and_saveexec_b64 s[8:9], vcc
	s_cbranch_execz .LBB0_894
	v_add_u32_e32 v65, s15, v64
	v_add_u32_e32 v66, v65, v111
	v_mov_b32_e32 v67, v140
	v_cvt_pk_bf16_f32 v48, v48, s0
	v_lshl_add_u64 v[68:69], v[66:67], 1, s[26:27]
	global_store_short v[68:69], v48, off
	v_cvt_pk_bf16_f32 v67, v49, s0
	v_add_u32_e32 v48, 0x80, v66
	v_mov_b32_e32 v49, v140
	v_lshl_add_u64 v[48:49], v[48:49], 1, s[26:27]
	global_store_short v[48:49], v67, off
	v_add_u32_e32 v48, 0x100, v66
	v_mov_b32_e32 v49, v140
	v_cvt_pk_bf16_f32 v50, v50, s0
	v_lshl_add_u64 v[48:49], v[48:49], 1, s[26:27]
	global_store_short v[48:49], v50, off
	v_add_u32_e32 v48, 0x180, v66
	v_mov_b32_e32 v49, v140
	v_cvt_pk_bf16_f32 v50, v51, s0
	v_lshl_add_u64 v[48:49], v[48:49], 1, s[26:27]
	global_store_short v[48:49], v50, off
	v_add_u32_e32 v48, v65, v112
	v_mov_b32_e32 v49, v140
	v_cvt_pk_bf16_f32 v52, v52, s0
	v_lshl_add_u64 v[50:51], v[48:49], 1, s[26:27]
	global_store_short v[50:51], v52, off
	v_add_u32_e32 v50, 0x80, v48
	v_mov_b32_e32 v51, v140
	v_cvt_pk_bf16_f32 v49, v53, s0
	v_lshl_add_u64 v[50:51], v[50:51], 1, s[26:27]
	global_store_short v[50:51], v49, off
	v_add_u32_e32 v50, 0x100, v48
	v_mov_b32_e32 v51, v140
	v_cvt_pk_bf16_f32 v49, v54, s0
	v_lshl_add_u64 v[50:51], v[50:51], 1, s[26:27]
	global_store_short v[50:51], v49, off
	v_add_u32_e32 v48, 0x180, v48
	v_mov_b32_e32 v49, v140
	v_cvt_pk_bf16_f32 v50, v55, s0
	v_lshl_add_u64 v[48:49], v[48:49], 1, s[26:27]
	global_store_short v[48:49], v50, off
	v_add_u32_e32 v48, v65, v113
	v_mov_b32_e32 v49, v140
	v_cvt_pk_bf16_f32 v52, v56, s0
	v_lshl_add_u64 v[50:51], v[48:49], 1, s[26:27]
	global_store_short v[50:51], v52, off
	v_add_u32_e32 v50, 0x80, v48
	v_mov_b32_e32 v51, v140
	v_cvt_pk_bf16_f32 v49, v57, s0
	v_lshl_add_u64 v[50:51], v[50:51], 1, s[26:27]
	global_store_short v[50:51], v49, off
	v_add_u32_e32 v50, 0x100, v48
	v_mov_b32_e32 v51, v140
	v_cvt_pk_bf16_f32 v49, v58, s0
	v_lshl_add_u64 v[50:51], v[50:51], 1, s[26:27]
	global_store_short v[50:51], v49, off
	v_add_u32_e32 v48, 0x180, v48
	v_mov_b32_e32 v49, v140
	v_cvt_pk_bf16_f32 v50, v59, s0
	v_lshl_add_u64 v[48:49], v[48:49], 1, s[26:27]
	global_store_short v[48:49], v50, off
	v_add_u32_e32 v48, v65, v114
	v_mov_b32_e32 v49, v140
	v_cvt_pk_bf16_f32 v52, v60, s0
	v_lshl_add_u64 v[50:51], v[48:49], 1, s[26:27]
	global_store_short v[50:51], v52, off
	v_add_u32_e32 v50, 0x80, v48
	v_mov_b32_e32 v51, v140
	v_cvt_pk_bf16_f32 v49, v61, s0
	v_lshl_add_u64 v[50:51], v[50:51], 1, s[26:27]
	global_store_short v[50:51], v49, off
	v_add_u32_e32 v50, 0x100, v48
	v_mov_b32_e32 v51, v140
	v_cvt_pk_bf16_f32 v49, v62, s0
	v_lshl_add_u64 v[50:51], v[50:51], 1, s[26:27]
	global_store_short v[50:51], v49, off
	v_add_u32_e32 v48, 0x180, v48
	v_mov_b32_e32 v49, v140
	v_cvt_pk_bf16_f32 v50, v63, s0
	v_lshl_add_u64 v[48:49], v[48:49], 1, s[26:27]
	global_store_short v[48:49], v50, off

.LBB0_903:
	s_mul_hi_i32 s0, s8, 0x38e38e39
	s_lshr_b32 s1, s0, 31
	s_ashr_i32 s0, s0, 4
	s_add_i32 s0, s0, s1
	s_mul_i32 s1, s0, 0x48
	s_sub_i32 s9, s8, s1
	v_lshl_add_u32 v0, s9, 7, v109
	v_ashrrev_i32_e32 v1, 31, v0
	v_lshlrev_b64 v[32:33], 12, v[0:1]
	v_lshl_add_u64 v[34:35], v[96:97], 0, v[32:33]
	v_add_co_u32_e32 v40, vcc, s87, v34
	s_lshl_b32 s15, s0, 7
	s_nop 0
	v_addc_co_u32_e32 v41, vcc, 0, v35, vcc
	v_add_co_u32_e32 v42, vcc, s66, v34
	v_add_u32_e32 v0, s15, v109
	s_nop 0
	v_addc_co_u32_e32 v43, vcc, 0, v35, vcc
	v_ashrrev_i32_e32 v1, 31, v0
	v_add_co_u32_e32 v44, vcc, s20, v34
	v_lshlrev_b64 v[36:37], 12, v[0:1]
	s_nop 0
	v_addc_co_u32_e32 v45, vcc, 0, v35, vcc
	v_lshl_add_u64 v[38:39], v[98:99], 0, v[36:37]
	v_readfirstlane_b32 s100, v110
	s_nop 3
	s_add_u32 m0, s100, 0x0
	s_nop 0
	global_load_lds_dwordx4 v[34:35], off
	s_add_u32 m0, s100, 0x1000
	s_nop 0
	global_load_lds_dwordx4 v[40:41], off
	s_add_u32 m0, s100, 0x2000
	s_nop 0
	global_load_lds_dwordx4 v[42:43], off
	s_add_u32 m0, s100, 0x3000
	s_nop 0
	global_load_lds_dwordx4 v[44:45], off
	s_add_u32 m0, s100, 0x4000
	s_nop 0
	global_load_lds_dwordx4 v[38:39], off
	v_add_co_u32_e32 v46, vcc, s87, v38
	v_lshl_add_u64 v[102:103], v[100:101], 0, v[36:37]
	s_nop 0
	v_addc_co_u32_e32 v47, vcc, 0, v39, vcc
	s_waitcnt vmcnt(16)
	v_add_co_u32_e32 v48, vcc, s66, v38
	s_add_u32 m0, s100, 0x5000
	s_nop 0
	global_load_lds_dwordx4 v[46:47], off
	s_nop 0
	v_addc_co_u32_e32 v49, vcc, 0, v39, vcc
	v_add_co_u32_e32 v50, vcc, s20, v38
	s_add_u32 m0, s100, 0x6000
	s_nop 0
	global_load_lds_dwordx4 v[48:49], off
	s_nop 0
	v_addc_co_u32_e32 v51, vcc, 0, v39, vcc
	s_add_u32 m0, s100, 0x7000
	s_nop 0
	global_load_lds_dwordx4 v[50:51], off
	v_lshl_add_u64 v[104:105], v[100:101], 0, v[32:33]
	s_mov_b64 s[0:1], 0
	v_mov_b32_e32 v0, 0
	v_mov_b32_e32 v1, v0
	v_mov_b32_e32 v2, v0
	v_mov_b32_e32 v3, v0
	v_mov_b32_e32 v4, v0
	v_mov_b32_e32 v5, v0
	v_mov_b32_e32 v6, v0
	v_mov_b32_e32 v7, v0
	v_mov_b32_e32 v8, v0
	v_mov_b32_e32 v9, v0
	v_mov_b32_e32 v10, v0
	v_mov_b32_e32 v11, v0
	v_mov_b32_e32 v12, v0
	v_mov_b32_e32 v13, v0
	v_mov_b32_e32 v14, v0
	v_mov_b32_e32 v15, v0
	v_mov_b32_e32 v16, v0
	v_mov_b32_e32 v17, v0
	v_mov_b32_e32 v18, v0
	v_mov_b32_e32 v19, v0
	v_mov_b32_e32 v20, v0
	v_mov_b32_e32 v21, v0
	v_mov_b32_e32 v22, v0
	v_mov_b32_e32 v23, v0
	v_mov_b32_e32 v24, v0
	v_mov_b32_e32 v25, v0
	v_mov_b32_e32 v26, v0
	v_mov_b32_e32 v27, v0
	v_mov_b32_e32 v28, v0
	v_mov_b32_e32 v29, v0
	v_mov_b32_e32 v30, v0
	v_mov_b32_e32 v31, v0
	v_mov_b32_e32 v32, v0
	v_mov_b32_e32 v33, v0
	v_mov_b32_e32 v34, v0
	v_mov_b32_e32 v35, v0
	v_mov_b32_e32 v36, v0
	v_mov_b32_e32 v37, v0
	v_mov_b32_e32 v38, v0
	v_mov_b32_e32 v39, v0
	v_mov_b32_e32 v40, v0
	v_mov_b32_e32 v41, v0
	v_mov_b32_e32 v42, v0
	v_mov_b32_e32 v43, v0
	v_mov_b32_e32 v44, v0
	v_mov_b32_e32 v45, v0
	v_mov_b32_e32 v46, v0
	v_mov_b32_e32 v47, v0
	v_mov_b32_e32 v48, v0
	v_mov_b32_e32 v49, v0
	v_mov_b32_e32 v50, v0
	v_mov_b32_e32 v51, v0
	v_mov_b32_e32 v52, v0
	v_mov_b32_e32 v53, v0
	v_mov_b32_e32 v54, v0
	v_mov_b32_e32 v55, v0
	v_mov_b32_e32 v56, v0
	v_mov_b32_e32 v57, v0
	v_mov_b32_e32 v58, v0
	v_mov_b32_e32 v59, v0
	v_mov_b32_e32 v60, v0
	v_mov_b32_e32 v61, v0
	v_mov_b32_e32 v62, v0
	v_mov_b32_e32 v63, v0
	v_lshl_add_u64 v[128:129], v[104:105], 0, s[0:1]
	s_mov_b32 s4, 0x20eb8000
	v_add_co_u32_e32 v144, vcc, s4, v128
	s_mov_b32 s4, 0x20ed8000
	s_nop 0
	v_addc_co_u32_e32 v145, vcc, 0, v129, vcc
	v_add_co_u32_e32 v146, vcc, s4, v128
	s_mov_b32 s4, 0x20ef8000
	s_nop 0
	v_addc_co_u32_e32 v147, vcc, 0, v129, vcc
	v_add_co_u32_e32 v148, vcc, s4, v128
	s_mov_b32 s4, 0x20f18000
	s_nop 0
	v_addc_co_u32_e32 v149, vcc, 0, v129, vcc
	v_add_co_u32_e32 v150, vcc, s4, v128
	v_lshl_add_u64 v[130:131], v[102:103], 0, s[0:1]
	s_nop 0
	v_addc_co_u32_e32 v151, vcc, 0, v129, vcc
	s_mov_b32 s4, 0x38c80000
	v_add_co_u32_e32 v152, vcc, s4, v130
	s_mov_b32 s4, 0x38ca0000
	s_nop 0
	v_addc_co_u32_e32 v153, vcc, 0, v131, vcc
	v_add_co_u32_e32 v154, vcc, s4, v130
	s_mov_b32 s4, 0x38cc0000
	s_nop 0
	v_addc_co_u32_e32 v155, vcc, 0, v131, vcc
	v_add_co_u32_e32 v156, vcc, s4, v130
	s_mov_b32 s4, 0x38ce0000
	s_nop 0
	v_addc_co_u32_e32 v157, vcc, 0, v131, vcc
	v_add_co_u32_e32 v178, vcc, s4, v130
	v_addc_co_u32_e32 v179, vcc, 0, v131, vcc
	v_lshl_add_u64 v[144:145], 8, 4, v[144:145]
	v_lshl_add_u64 v[146:147], 8, 4, v[146:147]
	v_lshl_add_u64 v[148:149], 8, 4, v[148:149]
	v_lshl_add_u64 v[150:151], 8, 4, v[150:151]
	v_lshl_add_u64 v[152:153], 8, 4, v[152:153]
	v_lshl_add_u64 v[154:155], 8, 4, v[154:155]
	v_lshl_add_u64 v[156:157], 8, 4, v[156:157]
	v_lshl_add_u64 v[178:179], 8, 4, v[178:179]
	v_and_b32_e32 v124, 15, v143
	v_lshrrev_b32_e32 v125, 1, v124
	v_bfe_u32 v117, v143, 4, 2
	v_xor_b32_e32 v125, v125, v117
	v_lshlrev_b32_e32 v125, 4, v125
	v_lshl_add_u32 v125, v124, 7, v125
	v_lshrrev_b32_e32 v124, 6, v143
	v_lshrrev_b32_e32 v115, 1, v124
	v_and_b32_e32 v124, 1, v124
	v_lshl_add_u32 v115, v115, 13, v125
	v_lshl_add_u32 v116, v124, 13, v125
	v_add_u32_e32 v116, 0x4000, v116
	v_xor_b32_e32 v117, 64, v115
	v_xor_b32_e32 v118, 64, v116
	s_waitcnt vmcnt(0) lgkmcnt(0)
	s_barrier
.LBB0_904:
	s_add_u32 m0, s100, 0x8000
	s_nop 0
	global_load_lds_dwordx4 v[144:145], off
	s_add_u32 m0, s100, 0x9000
	s_nop 0
	global_load_lds_dwordx4 v[146:147], off
	s_add_u32 m0, s100, 0xa000
	s_nop 0
	global_load_lds_dwordx4 v[148:149], off
	s_add_u32 m0, s100, 0xb000
	s_nop 0
	global_load_lds_dwordx4 v[150:151], off
	s_add_u32 m0, s100, 0xc000
	s_nop 0
	global_load_lds_dwordx4 v[152:153], off
	s_add_u32 m0, s100, 0xd000
	s_nop 0
	global_load_lds_dwordx4 v[154:155], off
	s_add_u32 m0, s100, 0xe000
	s_nop 0
	global_load_lds_dwordx4 v[156:157], off
	s_add_u32 m0, s100, 0xf000
	s_nop 0
	global_load_lds_dwordx4 v[178:179], off
	ds_read_b128 a[0:3], v115
	ds_read_b128 v[80:83], v116
	ds_read_b128 a[4:7], v115 offset:2048
	ds_read_b128 a[8:11], v115 offset:4096
	ds_read_b128 a[12:15], v115 offset:6144
	ds_read_b128 v[92:95], v116 offset:2048
	ds_read_b128 v[88:91], v116 offset:4096
	ds_read_b128 v[84:87], v116 offset:6144
	ds_read_b128 a[16:19], v117
	ds_read_b128 a[20:23], v117 offset:2048
	ds_read_b128 a[24:27], v117 offset:4096
	ds_read_b128 a[28:31], v117 offset:6144
	s_setprio 1
	s_waitcnt lgkmcnt(10)
	v_mfma_f32_16x16x32_bf16 v[0:3], a[0:3], v[80:83], v[0:3]
	s_waitcnt lgkmcnt(9)
	v_mfma_f32_16x16x32_bf16 v[16:19], a[4:7], v[80:83], v[16:19]
	s_waitcnt lgkmcnt(8)
	v_mfma_f32_16x16x32_bf16 v[32:35], a[8:11], v[80:83], v[32:35]
	s_waitcnt lgkmcnt(7)
	v_mfma_f32_16x16x32_bf16 v[48:51], a[12:15], v[80:83], v[48:51]
	ds_read_b128 v[80:83], v118
	s_waitcnt lgkmcnt(7)
	v_mfma_f32_16x16x32_bf16 v[4:7], a[0:3], v[92:95], v[4:7]
	v_lshl_add_u64 v[64:65], 8, 4, v[144:145]
	v_lshl_add_u64 v[66:67], 8, 4, v[146:147]
	v_lshl_add_u64 v[68:69], 8, 4, v[148:149]
	v_mfma_f32_16x16x32_bf16 v[20:23], a[4:7], v[92:95], v[20:23]
	v_lshl_add_u64 v[70:71], 8, 4, v[150:151]
	v_lshl_add_u64 v[76:77], 8, 4, v[152:153]
	v_lshl_add_u64 v[78:79], 8, 4, v[154:155]
	v_mfma_f32_16x16x32_bf16 v[36:39], a[8:11], v[92:95], v[36:39]
	v_lshl_add_u64 v[72:73], 8, 4, v[156:157]
	v_lshl_add_u64 v[74:75], 8, 4, v[178:179]
	v_mfma_f32_16x16x32_bf16 v[52:55], a[12:15], v[92:95], v[52:55]
	ds_read_b128 v[92:95], v118 offset:2048
	s_waitcnt lgkmcnt(7)
	v_mfma_f32_16x16x32_bf16 v[8:11], a[0:3], v[88:91], v[8:11]
	v_mfma_f32_16x16x32_bf16 v[24:27], a[4:7], v[88:91], v[24:27]
	v_mfma_f32_16x16x32_bf16 v[40:43], a[8:11], v[88:91], v[40:43]
	v_mfma_f32_16x16x32_bf16 v[56:59], a[12:15], v[88:91], v[56:59]
	ds_read_b128 v[88:91], v118 offset:4096
	s_waitcnt lgkmcnt(7)
	v_mfma_f32_16x16x32_bf16 v[12:15], a[0:3], v[84:87], v[12:15]
	v_mfma_f32_16x16x32_bf16 v[28:31], a[4:7], v[84:87], v[28:31]
	v_mfma_f32_16x16x32_bf16 v[44:47], a[8:11], v[84:87], v[44:47]
	v_mfma_f32_16x16x32_bf16 v[60:63], a[12:15], v[84:87], v[60:63]
	ds_read_b128 v[84:87], v118 offset:6144
	s_waitcnt lgkmcnt(3)
	v_mfma_f32_16x16x32_bf16 v[0:3], a[16:19], v[80:83], v[0:3]
	v_mfma_f32_16x16x32_bf16 v[16:19], a[20:23], v[80:83], v[16:19]
	v_mfma_f32_16x16x32_bf16 v[32:35], a[24:27], v[80:83], v[32:35]
	v_mfma_f32_16x16x32_bf16 v[48:51], a[28:31], v[80:83], v[48:51]
	s_waitcnt lgkmcnt(2)
	v_mfma_f32_16x16x32_bf16 v[4:7], a[16:19], v[92:95], v[4:7]
	v_mfma_f32_16x16x32_bf16 v[20:23], a[20:23], v[92:95], v[20:23]
	v_mfma_f32_16x16x32_bf16 v[36:39], a[24:27], v[92:95], v[36:39]
	v_mfma_f32_16x16x32_bf16 v[52:55], a[28:31], v[92:95], v[52:55]
	s_waitcnt lgkmcnt(1)
	v_mfma_f32_16x16x32_bf16 v[8:11], a[16:19], v[88:91], v[8:11]
	v_mfma_f32_16x16x32_bf16 v[24:27], a[20:23], v[88:91], v[24:27]
	v_mfma_f32_16x16x32_bf16 v[40:43], a[24:27], v[88:91], v[40:43]
	v_mfma_f32_16x16x32_bf16 v[56:59], a[28:31], v[88:91], v[56:59]
	s_waitcnt lgkmcnt(0)
	v_mfma_f32_16x16x32_bf16 v[12:15], a[16:19], v[84:87], v[12:15]
	v_mfma_f32_16x16x32_bf16 v[28:31], a[20:23], v[84:87], v[28:31]
	v_mfma_f32_16x16x32_bf16 v[44:47], a[24:27], v[84:87], v[44:47]
	v_mfma_f32_16x16x32_bf16 v[60:63], a[28:31], v[84:87], v[60:63]
	s_setprio 0
	s_waitcnt vmcnt(0) lgkmcnt(0)
	s_barrier
	s_add_u32 s0, s0, 0x100
	s_addc_u32 s1, s1, 0
	s_add_u32 m0, s100, 0x0
	s_nop 0
	global_load_lds_dwordx4 v[64:65], off
	s_add_u32 m0, s100, 0x1000
	s_nop 0
	global_load_lds_dwordx4 v[66:67], off
	s_add_u32 m0, s100, 0x2000
	s_nop 0
	global_load_lds_dwordx4 v[68:69], off
	s_add_u32 m0, s100, 0x3000
	s_nop 0
	global_load_lds_dwordx4 v[70:71], off
	s_add_u32 m0, s100, 0x4000
	s_nop 0
	global_load_lds_dwordx4 v[76:77], off
	s_add_u32 m0, s100, 0x5000
	s_nop 0
	global_load_lds_dwordx4 v[78:79], off
	s_add_u32 m0, s100, 0x6000
	s_nop 0
	global_load_lds_dwordx4 v[72:73], off
	s_add_u32 m0, s100, 0x7000
	s_nop 0
	global_load_lds_dwordx4 v[74:75], off
	ds_read_b128 a[0:3], v115 offset:32768
	ds_read_b128 v[80:83], v116 offset:32768
	ds_read_b128 a[4:7], v115 offset:34816
	ds_read_b128 a[8:11], v115 offset:36864
	ds_read_b128 a[12:15], v115 offset:38912
	ds_read_b128 v[92:95], v116 offset:34816
	ds_read_b128 v[88:91], v116 offset:36864
	ds_read_b128 v[84:87], v116 offset:38912
	ds_read_b128 a[16:19], v117 offset:32768
	ds_read_b128 a[20:23], v117 offset:34816
	ds_read_b128 a[24:27], v117 offset:36864
	ds_read_b128 a[28:31], v117 offset:38912
	s_setprio 1
	s_waitcnt lgkmcnt(10)
	v_mfma_f32_16x16x32_bf16 v[0:3], a[0:3], v[80:83], v[0:3]
	s_waitcnt lgkmcnt(9)
	v_mfma_f32_16x16x32_bf16 v[16:19], a[4:7], v[80:83], v[16:19]
	s_waitcnt lgkmcnt(8)
	v_mfma_f32_16x16x32_bf16 v[32:35], a[8:11], v[80:83], v[32:35]
	s_waitcnt lgkmcnt(7)
	v_mfma_f32_16x16x32_bf16 v[48:51], a[12:15], v[80:83], v[48:51]
	ds_read_b128 v[80:83], v118 offset:32768
	s_waitcnt lgkmcnt(7)
	v_mfma_f32_16x16x32_bf16 v[4:7], a[0:3], v[92:95], v[4:7]
	v_lshl_add_u64 v[128:129], v[104:105], 0, s[0:1]
	s_mov_b32 s4, 0x20eb8000
	v_add_co_u32_e32 v144, vcc, s4, v128
	v_mfma_f32_16x16x32_bf16 v[20:23], a[4:7], v[92:95], v[20:23]
	s_mov_b32 s4, 0x20ed8000
	s_nop 0
	v_addc_co_u32_e32 v145, vcc, 0, v129, vcc
	v_mfma_f32_16x16x32_bf16 v[36:39], a[8:11], v[92:95], v[36:39]
	v_add_co_u32_e32 v146, vcc, s4, v128
	s_mov_b32 s4, 0x20ef8000
	s_nop 0
	v_mfma_f32_16x16x32_bf16 v[52:55], a[12:15], v[92:95], v[52:55]
	v_addc_co_u32_e32 v147, vcc, 0, v129, vcc
	v_add_co_u32_e32 v148, vcc, s4, v128
	s_mov_b32 s4, 0x20f18000
	ds_read_b128 v[92:95], v118 offset:34816
	s_waitcnt lgkmcnt(7)
	v_mfma_f32_16x16x32_bf16 v[8:11], a[0:3], v[88:91], v[8:11]
	s_nop 0
	v_addc_co_u32_e32 v149, vcc, 0, v129, vcc
	v_add_co_u32_e32 v150, vcc, s4, v128
	v_mfma_f32_16x16x32_bf16 v[24:27], a[4:7], v[88:91], v[24:27]
	v_lshl_add_u64 v[130:131], v[102:103], 0, s[0:1]
	s_nop 0
	v_addc_co_u32_e32 v151, vcc, 0, v129, vcc
	v_mfma_f32_16x16x32_bf16 v[40:43], a[8:11], v[88:91], v[40:43]
	s_mov_b32 s4, 0x38c80000
	v_add_co_u32_e32 v152, vcc, s4, v130
	s_mov_b32 s4, 0x38ca0000
	v_mfma_f32_16x16x32_bf16 v[56:59], a[12:15], v[88:91], v[56:59]
	s_nop 0
	v_addc_co_u32_e32 v153, vcc, 0, v131, vcc
	v_add_co_u32_e32 v154, vcc, s4, v130
	ds_read_b128 v[88:91], v118 offset:36864
	s_waitcnt lgkmcnt(7)
	v_mfma_f32_16x16x32_bf16 v[12:15], a[0:3], v[84:87], v[12:15]
	s_mov_b32 s4, 0x38cc0000
	s_nop 0
	v_addc_co_u32_e32 v155, vcc, 0, v131, vcc
	v_mfma_f32_16x16x32_bf16 v[28:31], a[4:7], v[84:87], v[28:31]
	v_add_co_u32_e32 v156, vcc, s4, v130
	s_mov_b32 s4, 0x38ce0000
	s_nop 0
	v_mfma_f32_16x16x32_bf16 v[44:47], a[8:11], v[84:87], v[44:47]
	v_addc_co_u32_e32 v157, vcc, 0, v131, vcc
	v_add_co_u32_e32 v178, vcc, s4, v130
	v_addc_co_u32_e32 v179, vcc, 0, v131, vcc
	v_mfma_f32_16x16x32_bf16 v[60:63], a[12:15], v[84:87], v[60:63]
	v_lshl_add_u64 v[144:145], 8, 4, v[144:145]
	v_lshl_add_u64 v[146:147], 8, 4, v[146:147]
	v_lshl_add_u64 v[148:149], 8, 4, v[148:149]
	ds_read_b128 v[84:87], v118 offset:38912
	s_waitcnt lgkmcnt(3)
	v_mfma_f32_16x16x32_bf16 v[0:3], a[16:19], v[80:83], v[0:3]
	v_lshl_add_u64 v[150:151], 8, 4, v[150:151]
	v_lshl_add_u64 v[152:153], 8, 4, v[152:153]
	v_lshl_add_u64 v[154:155], 8, 4, v[154:155]
	v_mfma_f32_16x16x32_bf16 v[16:19], a[20:23], v[80:83], v[16:19]
	v_lshl_add_u64 v[156:157], 8, 4, v[156:157]
	v_lshl_add_u64 v[178:179], 8, 4, v[178:179]
	v_mfma_f32_16x16x32_bf16 v[32:35], a[24:27], v[80:83], v[32:35]
	v_mfma_f32_16x16x32_bf16 v[48:51], a[28:31], v[80:83], v[48:51]
	s_waitcnt lgkmcnt(2)
	v_mfma_f32_16x16x32_bf16 v[4:7], a[16:19], v[92:95], v[4:7]
	v_mfma_f32_16x16x32_bf16 v[20:23], a[20:23], v[92:95], v[20:23]
	v_mfma_f32_16x16x32_bf16 v[36:39], a[24:27], v[92:95], v[36:39]
	v_mfma_f32_16x16x32_bf16 v[52:55], a[28:31], v[92:95], v[52:55]
	s_waitcnt lgkmcnt(1)
	v_mfma_f32_16x16x32_bf16 v[8:11], a[16:19], v[88:91], v[8:11]
	v_mfma_f32_16x16x32_bf16 v[24:27], a[20:23], v[88:91], v[24:27]
	v_mfma_f32_16x16x32_bf16 v[40:43], a[24:27], v[88:91], v[40:43]
	v_mfma_f32_16x16x32_bf16 v[56:59], a[28:31], v[88:91], v[56:59]
	s_waitcnt lgkmcnt(0)
	v_mfma_f32_16x16x32_bf16 v[12:15], a[16:19], v[84:87], v[12:15]
	v_mfma_f32_16x16x32_bf16 v[28:31], a[20:23], v[84:87], v[28:31]
	v_mfma_f32_16x16x32_bf16 v[44:47], a[24:27], v[84:87], v[44:47]
	v_mfma_f32_16x16x32_bf16 v[60:63], a[28:31], v[84:87], v[60:63]
	s_setprio 0
	s_waitcnt vmcnt(0) lgkmcnt(0)
	s_barrier
	s_cmpk_eq_i32 s0, 0xf00
	s_cbranch_scc0 .LBB0_904
	v_lshl_add_u64 v[64:65], 8, 4, v[64:65]
	v_lshl_add_u64 v[66:67], 8, 4, v[66:67]
	v_lshl_add_u64 v[68:69], 8, 4, v[68:69]
	v_lshl_add_u64 v[70:71], 8, 4, v[70:71]
	v_lshl_add_u64 v[76:77], 8, 4, v[76:77]
	v_lshl_add_u64 v[78:79], 8, 4, v[78:79]
	v_lshl_add_u64 v[72:73], 8, 4, v[72:73]
	v_lshl_add_u64 v[74:75], 8, 4, v[74:75]
	s_add_u32 m0, s100, 0x8000
	s_nop 0
	global_load_lds_dwordx4 v[64:65], off
	s_add_u32 m0, s100, 0x9000
	s_nop 0
	global_load_lds_dwordx4 v[66:67], off
	s_add_u32 m0, s100, 0xa000
	s_nop 0
	global_load_lds_dwordx4 v[68:69], off
	s_add_u32 m0, s100, 0xb000
	s_nop 0
	global_load_lds_dwordx4 v[70:71], off
	s_add_u32 m0, s100, 0xc000
	s_nop 0
	global_load_lds_dwordx4 v[76:77], off
	s_add_u32 m0, s100, 0xd000
	s_nop 0
	global_load_lds_dwordx4 v[78:79], off
	s_add_u32 m0, s100, 0xe000
	s_nop 0
	global_load_lds_dwordx4 v[72:73], off
	s_add_u32 m0, s100, 0xf000
	s_nop 0
	global_load_lds_dwordx4 v[74:75], off
	ds_read_b128 a[0:3], v115
	ds_read_b128 v[80:83], v116
	ds_read_b128 a[4:7], v115 offset:2048
	ds_read_b128 a[8:11], v115 offset:4096
	ds_read_b128 a[12:15], v115 offset:6144
	ds_read_b128 v[92:95], v116 offset:2048
	ds_read_b128 v[88:91], v116 offset:4096
	ds_read_b128 v[84:87], v116 offset:6144
	ds_read_b128 a[16:19], v117
	ds_read_b128 a[20:23], v117 offset:2048
	ds_read_b128 a[24:27], v117 offset:4096
	ds_read_b128 a[28:31], v117 offset:6144
	s_setprio 1
	s_waitcnt lgkmcnt(10)
	v_mfma_f32_16x16x32_bf16 v[0:3], a[0:3], v[80:83], v[0:3]
	s_waitcnt lgkmcnt(9)
	v_mfma_f32_16x16x32_bf16 v[16:19], a[4:7], v[80:83], v[16:19]
	s_waitcnt lgkmcnt(8)
	v_mfma_f32_16x16x32_bf16 v[32:35], a[8:11], v[80:83], v[32:35]
	s_waitcnt lgkmcnt(7)
	v_mfma_f32_16x16x32_bf16 v[48:51], a[12:15], v[80:83], v[48:51]
	ds_read_b128 v[80:83], v118
	s_waitcnt lgkmcnt(7)
	v_mfma_f32_16x16x32_bf16 v[4:7], a[0:3], v[92:95], v[4:7]
	v_mfma_f32_16x16x32_bf16 v[20:23], a[4:7], v[92:95], v[20:23]
	v_mfma_f32_16x16x32_bf16 v[36:39], a[8:11], v[92:95], v[36:39]
	v_mfma_f32_16x16x32_bf16 v[52:55], a[12:15], v[92:95], v[52:55]
	ds_read_b128 v[92:95], v118 offset:2048
	s_waitcnt lgkmcnt(7)
	v_mfma_f32_16x16x32_bf16 v[8:11], a[0:3], v[88:91], v[8:11]
	v_mfma_f32_16x16x32_bf16 v[24:27], a[4:7], v[88:91], v[24:27]
	v_mfma_f32_16x16x32_bf16 v[40:43], a[8:11], v[88:91], v[40:43]
	v_mfma_f32_16x16x32_bf16 v[56:59], a[12:15], v[88:91], v[56:59]
	ds_read_b128 v[88:91], v118 offset:4096
	s_waitcnt lgkmcnt(7)
	v_mfma_f32_16x16x32_bf16 v[12:15], a[0:3], v[84:87], v[12:15]
	v_mfma_f32_16x16x32_bf16 v[28:31], a[4:7], v[84:87], v[28:31]
	v_mfma_f32_16x16x32_bf16 v[44:47], a[8:11], v[84:87], v[44:47]
	v_mfma_f32_16x16x32_bf16 v[60:63], a[12:15], v[84:87], v[60:63]
	ds_read_b128 v[84:87], v118 offset:6144
	s_waitcnt lgkmcnt(3)
	v_mfma_f32_16x16x32_bf16 v[0:3], a[16:19], v[80:83], v[0:3]
	v_mfma_f32_16x16x32_bf16 v[16:19], a[20:23], v[80:83], v[16:19]
	v_mfma_f32_16x16x32_bf16 v[32:35], a[24:27], v[80:83], v[32:35]
	v_mfma_f32_16x16x32_bf16 v[48:51], a[28:31], v[80:83], v[48:51]
	s_waitcnt lgkmcnt(2)
	v_mfma_f32_16x16x32_bf16 v[4:7], a[16:19], v[92:95], v[4:7]
	v_mfma_f32_16x16x32_bf16 v[20:23], a[20:23], v[92:95], v[20:23]
	v_mfma_f32_16x16x32_bf16 v[36:39], a[24:27], v[92:95], v[36:39]
	v_mfma_f32_16x16x32_bf16 v[52:55], a[28:31], v[92:95], v[52:55]
	s_waitcnt lgkmcnt(1)
	v_mfma_f32_16x16x32_bf16 v[8:11], a[16:19], v[88:91], v[8:11]
	v_mfma_f32_16x16x32_bf16 v[24:27], a[20:23], v[88:91], v[24:27]
	v_mfma_f32_16x16x32_bf16 v[40:43], a[24:27], v[88:91], v[40:43]
	v_mfma_f32_16x16x32_bf16 v[56:59], a[28:31], v[88:91], v[56:59]
	s_waitcnt lgkmcnt(0)
	v_mfma_f32_16x16x32_bf16 v[12:15], a[16:19], v[84:87], v[12:15]
	v_mfma_f32_16x16x32_bf16 v[28:31], a[20:23], v[84:87], v[28:31]
	v_mfma_f32_16x16x32_bf16 v[44:47], a[24:27], v[84:87], v[44:47]
	v_mfma_f32_16x16x32_bf16 v[60:63], a[28:31], v[84:87], v[60:63]
	s_setprio 0
	s_waitcnt vmcnt(0) lgkmcnt(0)
	s_barrier
	ds_read_b128 a[0:3], v115 offset:32768
	ds_read_b128 v[80:83], v116 offset:32768
	ds_read_b128 a[4:7], v115 offset:34816
	ds_read_b128 a[8:11], v115 offset:36864
	ds_read_b128 a[12:15], v115 offset:38912
	ds_read_b128 v[92:95], v116 offset:34816
	ds_read_b128 v[88:91], v116 offset:36864
	ds_read_b128 v[84:87], v116 offset:38912
	ds_read_b128 a[16:19], v117 offset:32768
	ds_read_b128 a[20:23], v117 offset:34816
	ds_read_b128 a[24:27], v117 offset:36864
	ds_read_b128 a[28:31], v117 offset:38912
	s_setprio 1
	s_waitcnt lgkmcnt(10)
	v_mfma_f32_16x16x32_bf16 v[0:3], a[0:3], v[80:83], v[0:3]
	s_waitcnt lgkmcnt(9)
	v_mfma_f32_16x16x32_bf16 v[16:19], a[4:7], v[80:83], v[16:19]
	s_waitcnt lgkmcnt(8)
	v_mfma_f32_16x16x32_bf16 v[32:35], a[8:11], v[80:83], v[32:35]
	s_waitcnt lgkmcnt(7)
	v_mfma_f32_16x16x32_bf16 v[48:51], a[12:15], v[80:83], v[48:51]
	ds_read_b128 v[80:83], v118 offset:32768
	s_waitcnt lgkmcnt(7)
	v_mfma_f32_16x16x32_bf16 v[4:7], a[0:3], v[92:95], v[4:7]
	v_mfma_f32_16x16x32_bf16 v[20:23], a[4:7], v[92:95], v[20:23]
	v_mfma_f32_16x16x32_bf16 v[36:39], a[8:11], v[92:95], v[36:39]
	v_mfma_f32_16x16x32_bf16 v[52:55], a[12:15], v[92:95], v[52:55]
	ds_read_b128 v[92:95], v118 offset:34816
	s_waitcnt lgkmcnt(7)
	v_mfma_f32_16x16x32_bf16 v[8:11], a[0:3], v[88:91], v[8:11]
	v_mfma_f32_16x16x32_bf16 v[24:27], a[4:7], v[88:91], v[24:27]
	v_mfma_f32_16x16x32_bf16 v[40:43], a[8:11], v[88:91], v[40:43]
	v_mfma_f32_16x16x32_bf16 v[56:59], a[12:15], v[88:91], v[56:59]
	ds_read_b128 v[88:91], v118 offset:36864
	s_waitcnt lgkmcnt(7)
	v_mfma_f32_16x16x32_bf16 v[12:15], a[0:3], v[84:87], v[12:15]
	v_mfma_f32_16x16x32_bf16 v[28:31], a[4:7], v[84:87], v[28:31]
	v_mfma_f32_16x16x32_bf16 v[44:47], a[8:11], v[84:87], v[44:47]
	v_mfma_f32_16x16x32_bf16 v[60:63], a[12:15], v[84:87], v[60:63]
	ds_read_b128 v[84:87], v118 offset:38912
	s_waitcnt lgkmcnt(3)
	v_mfma_f32_16x16x32_bf16 v[0:3], a[16:19], v[80:83], v[0:3]
	v_mfma_f32_16x16x32_bf16 v[16:19], a[20:23], v[80:83], v[16:19]
	v_mfma_f32_16x16x32_bf16 v[32:35], a[24:27], v[80:83], v[32:35]
	v_mfma_f32_16x16x32_bf16 v[48:51], a[28:31], v[80:83], v[48:51]
	s_waitcnt lgkmcnt(2)
	v_mfma_f32_16x16x32_bf16 v[4:7], a[16:19], v[92:95], v[4:7]
	v_mfma_f32_16x16x32_bf16 v[20:23], a[20:23], v[92:95], v[20:23]
	v_mfma_f32_16x16x32_bf16 v[36:39], a[24:27], v[92:95], v[36:39]
	v_mfma_f32_16x16x32_bf16 v[52:55], a[28:31], v[92:95], v[52:55]
	s_waitcnt lgkmcnt(1)
	v_mfma_f32_16x16x32_bf16 v[8:11], a[16:19], v[88:91], v[8:11]
	v_mfma_f32_16x16x32_bf16 v[24:27], a[20:23], v[88:91], v[24:27]
	v_mfma_f32_16x16x32_bf16 v[40:43], a[24:27], v[88:91], v[40:43]
	v_mfma_f32_16x16x32_bf16 v[56:59], a[28:31], v[88:91], v[56:59]
	s_waitcnt lgkmcnt(0)
	v_mfma_f32_16x16x32_bf16 v[12:15], a[16:19], v[84:87], v[12:15]
	v_mfma_f32_16x16x32_bf16 v[28:31], a[20:23], v[84:87], v[28:31]
	v_mfma_f32_16x16x32_bf16 v[44:47], a[24:27], v[84:87], v[44:47]
	v_mfma_f32_16x16x32_bf16 v[60:63], a[28:31], v[84:87], v[60:63]
	s_setprio 0
	v_readfirstlane_b32 s1, v107
	v_readfirstlane_b32 s0, v106
	s_lshl_b32 s1, s1, 6
	s_waitcnt lgkmcnt(0)
	s_barrier
	s_add_i32 s1, s1, s15
	s_lshl_b32 s0, s0, 14
	s_lshl_b32 s4, s9, 15
	s_add_i32 s9, s0, s4
	v_or_b32_e32 v64, s1, v108
	s_movk_i32 s0, 0x100
	v_cmp_gt_i32_e64 s[38:39], s0, v64
	s_barrier
	v_and_b32_e32 v124, 15, v143
	v_bfe_u32 v125, v143, 4, 2
	v_xor_b32_e32 v125, v125, v124
	v_lshlrev_b32_e32 v125, 4, v125
	v_lshl_add_u32 v125, v124, 8, v125
	v_lshrrev_b32_e32 v124, 6, v143
	v_lshl_add_u32 v125, v124, 14, v125
	ds_write_b128 v125, v[0:3]
	ds_write_b128 v125, v[4:7] offset:4096
	ds_write_b128 v125, v[8:11] offset:8192
	ds_write_b128 v125, v[12:15] offset:12288
	v_xor_b32_e32 v118, 64, v125
	ds_write_b128 v118, v[16:19]
	ds_write_b128 v118, v[20:23] offset:4096
	ds_write_b128 v118, v[24:27] offset:8192
	ds_write_b128 v118, v[28:31] offset:12288
	v_xor_b32_e32 v118, 128, v125
	ds_write_b128 v118, v[32:35]
	ds_write_b128 v118, v[36:39] offset:4096
	ds_write_b128 v118, v[40:43] offset:8192
	ds_write_b128 v118, v[44:47] offset:12288
	v_xor_b32_e32 v118, 192, v125
	ds_write_b128 v118, v[48:51]
	ds_write_b128 v118, v[52:55] offset:4096
	ds_write_b128 v118, v[56:59] offset:8192
	ds_write_b128 v118, v[60:63] offset:12288
	v_and_b32_e32 v115, 31, v143
	v_bfe_u32 v117, v143, 5, 1
	v_and_b32_e32 v125, 15, v115
	v_xor_b32_e32 v117, v117, v125
	v_lshlrev_b32_e32 v117, 4, v117
	v_lshl_add_u32 v117, v115, 8, v117
	v_lshl_add_u32 v117, v124, 14, v117
	ds_read_b128 v[48:51], v117
	ds_read_b128 v[32:35], v117 offset:8192
	v_xor_b32_e32 v116, 32, v117
	ds_read_b128 v[52:55], v116
	ds_read_b128 v[36:39], v116 offset:8192
	v_xor_b32_e32 v116, 64, v117
	ds_read_b128 v[56:59], v116
	ds_read_b128 v[40:43], v116 offset:8192
	v_xor_b32_e32 v116, 96, v117
	ds_read_b128 v[60:63], v116
	ds_read_b128 v[44:47], v116 offset:8192
	v_xor_b32_e32 v116, 128, v117
	ds_read_b128 v[16:19], v116
	ds_read_b128 v[0:3], v116 offset:8192
	v_xor_b32_e32 v116, 160, v117
	ds_read_b128 v[20:23], v116
	ds_read_b128 v[4:7], v116 offset:8192
	v_xor_b32_e32 v116, 192, v117
	ds_read_b128 v[24:27], v116
	ds_read_b128 v[8:11], v116 offset:8192
	v_xor_b32_e32 v116, 224, v117
	ds_read_b128 v[28:31], v116
	ds_read_b128 v[12:15], v116 offset:8192
	s_waitcnt lgkmcnt(0)
	s_barrier
	s_and_saveexec_b64 s[0:1], s[38:39]
	s_cbranch_execz .LBB0_907
	v_mul_f32_e32 v48, 0xbfb8aa3b, v48
	v_exp_f32_e32 v48, v48
	v_add_u32_e32 v65, s9, v64
	v_add_f32_e32 v48, 1.0, v48
	v_div_scale_f32 v66, s[22:23], v48, v48, 1.0
	v_rcp_f32_e32 v67, v66
	s_nop 0
	v_fma_f32 v68, -v66, v67, 1.0
	v_fmac_f32_e32 v67, v68, v67
	v_div_scale_f32 v68, vcc, 1.0, v48, 1.0
	v_mul_f32_e32 v69, v68, v67
	v_fma_f32 v70, -v66, v69, v68
	v_fmac_f32_e32 v69, v70, v67
	v_fma_f32 v66, -v66, v69, v68
	v_div_fmas_f32 v66, v66, v67, v69
	v_div_fixup_f32 v48, v66, v48, 1.0
	v_add_u32_e32 v66, v65, v111
	v_mov_b32_e32 v67, v140
	v_cvt_pk_bf16_f32 v48, v48, s0
	v_lshl_add_u64 v[68:69], v[66:67], 1, s[26:27]
	global_store_short v[68:69], v48, off
	v_mul_f32_e32 v48, 0xbfb8aa3b, v49
	v_exp_f32_e32 v48, v48
	s_nop 0
	v_add_f32_e32 v48, 1.0, v48
	v_div_scale_f32 v49, s[22:23], v48, v48, 1.0
	v_rcp_f32_e32 v67, v49
	s_nop 0
	v_fma_f32 v68, -v49, v67, 1.0
	v_fmac_f32_e32 v67, v68, v67
	v_div_scale_f32 v68, vcc, 1.0, v48, 1.0
	v_mul_f32_e32 v69, v68, v67
	v_fma_f32 v70, -v49, v69, v68
	v_fmac_f32_e32 v69, v70, v67
	v_fma_f32 v49, -v49, v69, v68
	v_div_fmas_f32 v49, v49, v67, v69
	v_div_fixup_f32 v48, v49, v48, 1.0
	v_cvt_pk_bf16_f32 v67, v48, s0
	v_add_u32_e32 v48, 0x100, v66
	v_mov_b32_e32 v49, v140
	v_lshl_add_u64 v[48:49], v[48:49], 1, s[26:27]
	global_store_short v[48:49], v67, off
	v_mul_f32_e32 v48, 0xbfb8aa3b, v50
	v_exp_f32_e32 v48, v48
	s_nop 0
	v_add_f32_e32 v48, 1.0, v48
	v_div_scale_f32 v49, s[22:23], v48, v48, 1.0
	v_rcp_f32_e32 v50, v49
	s_nop 0
	v_fma_f32 v67, -v49, v50, 1.0
	v_fmac_f32_e32 v50, v67, v50
	v_div_scale_f32 v67, vcc, 1.0, v48, 1.0
	v_mul_f32_e32 v68, v67, v50
	v_fma_f32 v69, -v49, v68, v67
	v_fmac_f32_e32 v68, v69, v50
	v_fma_f32 v49, -v49, v68, v67
	v_div_fmas_f32 v49, v49, v50, v68
	v_div_fixup_f32 v48, v49, v48, 1.0
	v_cvt_pk_bf16_f32 v50, v48, s0
	v_add_u32_e32 v48, 0x200, v66
	v_mov_b32_e32 v49, v140
	v_lshl_add_u64 v[48:49], v[48:49], 1, s[26:27]
	global_store_short v[48:49], v50, off
	v_mul_f32_e32 v48, 0xbfb8aa3b, v51
	v_exp_f32_e32 v48, v48
	s_nop 0
	v_add_f32_e32 v48, 1.0, v48
	v_div_scale_f32 v49, s[22:23], v48, v48, 1.0
	v_rcp_f32_e32 v50, v49
	s_nop 0
	v_fma_f32 v51, -v49, v50, 1.0
	v_fmac_f32_e32 v50, v51, v50
	v_div_scale_f32 v51, vcc, 1.0, v48, 1.0
	v_mul_f32_e32 v67, v51, v50
	v_fma_f32 v68, -v49, v67, v51
	v_fmac_f32_e32 v67, v68, v50
	v_fma_f32 v49, -v49, v67, v51
	v_div_fmas_f32 v49, v49, v50, v67
	v_div_fixup_f32 v48, v49, v48, 1.0
	v_cvt_pk_bf16_f32 v50, v48, s0
	v_add_u32_e32 v48, 0x300, v66
	v_mov_b32_e32 v49, v140
	v_lshl_add_u64 v[48:49], v[48:49], 1, s[26:27]
	global_store_short v[48:49], v50, off
	v_mul_f32_e32 v48, 0xbfb8aa3b, v52
	v_exp_f32_e32 v48, v48
	s_nop 0
	v_add_f32_e32 v48, 1.0, v48
	v_div_scale_f32 v49, s[22:23], v48, v48, 1.0
	v_rcp_f32_e32 v50, v49
	s_nop 0
	v_fma_f32 v51, -v49, v50, 1.0
	v_fmac_f32_e32 v50, v51, v50
	v_div_scale_f32 v51, vcc, 1.0, v48, 1.0
	v_mul_f32_e32 v52, v51, v50
	v_fma_f32 v66, -v49, v52, v51
	v_fmac_f32_e32 v52, v66, v50
	v_fma_f32 v49, -v49, v52, v51
	v_div_fmas_f32 v49, v49, v50, v52
	v_div_fixup_f32 v48, v49, v48, 1.0
	v_cvt_pk_bf16_f32 v52, v48, s0
	v_add_u32_e32 v48, v65, v112
	v_mov_b32_e32 v49, v140
	v_lshl_add_u64 v[50:51], v[48:49], 1, s[26:27]
	v_mul_f32_e32 v49, 0xbfb8aa3b, v53
	v_exp_f32_e32 v49, v49
	global_store_short v[50:51], v52, off
	v_add_f32_e32 v49, 1.0, v49
	v_div_scale_f32 v50, s[22:23], v49, v49, 1.0
	v_rcp_f32_e32 v51, v50
	s_nop 0
	v_fma_f32 v52, -v50, v51, 1.0
	v_fmac_f32_e32 v51, v52, v51
	v_div_scale_f32 v52, vcc, 1.0, v49, 1.0
	v_mul_f32_e32 v53, v52, v51
	v_fma_f32 v66, -v50, v53, v52
	v_fmac_f32_e32 v53, v66, v51
	v_fma_f32 v50, -v50, v53, v52
	v_div_fmas_f32 v50, v50, v51, v53
	v_div_fixup_f32 v49, v50, v49, 1.0
	v_add_u32_e32 v50, 0x100, v48
	v_mov_b32_e32 v51, v140
	v_cvt_pk_bf16_f32 v49, v49, s0
	v_lshl_add_u64 v[50:51], v[50:51], 1, s[26:27]
	global_store_short v[50:51], v49, off
	v_mul_f32_e32 v49, 0xbfb8aa3b, v54
	v_exp_f32_e32 v49, v49
	s_nop 0
	v_add_f32_e32 v49, 1.0, v49
	v_div_scale_f32 v50, s[22:23], v49, v49, 1.0
	v_rcp_f32_e32 v51, v50
	s_nop 0
	v_fma_f32 v52, -v50, v51, 1.0
	v_fmac_f32_e32 v51, v52, v51
	v_div_scale_f32 v52, vcc, 1.0, v49, 1.0
	v_mul_f32_e32 v53, v52, v51
	v_fma_f32 v54, -v50, v53, v52
	v_fmac_f32_e32 v53, v54, v51
	v_fma_f32 v50, -v50, v53, v52
	v_div_fmas_f32 v50, v50, v51, v53
	v_div_fixup_f32 v49, v50, v49, 1.0
	v_add_u32_e32 v50, 0x200, v48
	v_mov_b32_e32 v51, v140
	v_cvt_pk_bf16_f32 v49, v49, s0
	v_lshl_add_u64 v[50:51], v[50:51], 1, s[26:27]
	global_store_short v[50:51], v49, off
	v_mul_f32_e32 v49, 0xbfb8aa3b, v55
	v_exp_f32_e32 v49, v49
	v_add_u32_e32 v48, 0x300, v48
	v_add_f32_e32 v49, 1.0, v49
	v_div_scale_f32 v50, s[22:23], v49, v49, 1.0
	v_rcp_f32_e32 v51, v50
	s_nop 0
	v_fma_f32 v52, -v50, v51, 1.0
	v_fmac_f32_e32 v51, v52, v51
	v_div_scale_f32 v52, vcc, 1.0, v49, 1.0
	v_mul_f32_e32 v53, v52, v51
	v_fma_f32 v54, -v50, v53, v52
	v_fmac_f32_e32 v53, v54, v51
	v_fma_f32 v50, -v50, v53, v52
	v_div_fmas_f32 v50, v50, v51, v53
	v_div_fixup_f32 v49, v50, v49, 1.0
	v_cvt_pk_bf16_f32 v50, v49, s0
	v_mov_b32_e32 v49, v140
	v_lshl_add_u64 v[48:49], v[48:49], 1, s[26:27]
	global_store_short v[48:49], v50, off
	v_mul_f32_e32 v48, 0xbfb8aa3b, v56
	v_exp_f32_e32 v48, v48
	s_nop 0
	v_add_f32_e32 v48, 1.0, v48
	v_div_scale_f32 v49, s[22:23], v48, v48, 1.0
	v_rcp_f32_e32 v50, v49
	s_nop 0
	v_fma_f32 v51, -v49, v50, 1.0
	v_fmac_f32_e32 v50, v51, v50
	v_div_scale_f32 v51, vcc, 1.0, v48, 1.0
	v_mul_f32_e32 v52, v51, v50
	v_fma_f32 v53, -v49, v52, v51
	v_fmac_f32_e32 v52, v53, v50
	v_fma_f32 v49, -v49, v52, v51
	v_div_fmas_f32 v49, v49, v50, v52
	v_div_fixup_f32 v48, v49, v48, 1.0
	v_cvt_pk_bf16_f32 v52, v48, s0
	v_add_u32_e32 v48, v65, v113
	v_mov_b32_e32 v49, v140
	v_lshl_add_u64 v[50:51], v[48:49], 1, s[26:27]
	v_mul_f32_e32 v49, 0xbfb8aa3b, v57
	v_exp_f32_e32 v49, v49
	global_store_short v[50:51], v52, off
	v_add_f32_e32 v49, 1.0, v49
	v_div_scale_f32 v50, s[22:23], v49, v49, 1.0
	v_rcp_f32_e32 v51, v50
	s_nop 0
	v_fma_f32 v52, -v50, v51, 1.0
	v_fmac_f32_e32 v51, v52, v51
	v_div_scale_f32 v52, vcc, 1.0, v49, 1.0
	v_mul_f32_e32 v53, v52, v51
	v_fma_f32 v54, -v50, v53, v52
	v_fmac_f32_e32 v53, v54, v51
	v_fma_f32 v50, -v50, v53, v52
	v_div_fmas_f32 v50, v50, v51, v53
	v_div_fixup_f32 v49, v50, v49, 1.0
	v_add_u32_e32 v50, 0x100, v48
	v_mov_b32_e32 v51, v140
	v_cvt_pk_bf16_f32 v49, v49, s0
	v_lshl_add_u64 v[50:51], v[50:51], 1, s[26:27]
	global_store_short v[50:51], v49, off
	v_mul_f32_e32 v49, 0xbfb8aa3b, v58
	v_exp_f32_e32 v49, v49
	s_nop 0
	v_add_f32_e32 v49, 1.0, v49
	v_div_scale_f32 v50, s[22:23], v49, v49, 1.0
	v_rcp_f32_e32 v51, v50
	s_nop 0
	v_fma_f32 v52, -v50, v51, 1.0
	v_fmac_f32_e32 v51, v52, v51
	v_div_scale_f32 v52, vcc, 1.0, v49, 1.0
	v_mul_f32_e32 v53, v52, v51
	v_fma_f32 v54, -v50, v53, v52
	v_fmac_f32_e32 v53, v54, v51
	v_fma_f32 v50, -v50, v53, v52
	v_div_fmas_f32 v50, v50, v51, v53
	v_div_fixup_f32 v49, v50, v49, 1.0
	v_add_u32_e32 v50, 0x200, v48
	v_mov_b32_e32 v51, v140
	v_cvt_pk_bf16_f32 v49, v49, s0
	v_lshl_add_u64 v[50:51], v[50:51], 1, s[26:27]
	global_store_short v[50:51], v49, off
	v_mul_f32_e32 v49, 0xbfb8aa3b, v59
	v_exp_f32_e32 v49, v49
	v_add_u32_e32 v48, 0x300, v48
	v_add_f32_e32 v49, 1.0, v49
	v_div_scale_f32 v50, s[22:23], v49, v49, 1.0
	v_rcp_f32_e32 v51, v50
	s_nop 0
	v_fma_f32 v52, -v50, v51, 1.0
	v_fmac_f32_e32 v51, v52, v51
	v_div_scale_f32 v52, vcc, 1.0, v49, 1.0
	v_mul_f32_e32 v53, v52, v51
	v_fma_f32 v54, -v50, v53, v52
	v_fmac_f32_e32 v53, v54, v51
	v_fma_f32 v50, -v50, v53, v52
	v_div_fmas_f32 v50, v50, v51, v53
	v_div_fixup_f32 v49, v50, v49, 1.0
	v_cvt_pk_bf16_f32 v50, v49, s0
	v_mov_b32_e32 v49, v140
	v_lshl_add_u64 v[48:49], v[48:49], 1, s[26:27]
	global_store_short v[48:49], v50, off
	v_mul_f32_e32 v48, 0xbfb8aa3b, v60
	v_exp_f32_e32 v48, v48
	v_mul_f32_e32 v49, 0xbfb8aa3b, v61
	v_exp_f32_e32 v49, v49
	v_add_f32_e32 v48, 1.0, v48
	v_div_scale_f32 v50, s[22:23], v48, v48, 1.0
	v_rcp_f32_e32 v51, v50
	v_div_scale_f32 v52, vcc, 1.0, v48, 1.0
	v_fma_f32 v53, -v50, v51, 1.0
	v_fmac_f32_e32 v51, v53, v51
	v_mul_f32_e32 v53, v52, v51
	v_fma_f32 v54, -v50, v53, v52
	v_fmac_f32_e32 v53, v54, v51
	v_fma_f32 v50, -v50, v53, v52
	v_div_fmas_f32 v50, v50, v51, v53
	v_add_f32_e32 v53, 1.0, v49
	v_div_scale_f32 v54, s[22:23], v53, v53, 1.0
	v_rcp_f32_e32 v55, v54
	v_div_fixup_f32 v48, v50, v48, 1.0
	v_cvt_pk_bf16_f32 v52, v48, s0
	v_add_u32_e32 v48, v65, v114
	v_mov_b32_e32 v49, v140
	v_lshl_add_u64 v[50:51], v[48:49], 1, s[26:27]
	v_fma_f32 v49, -v54, v55, 1.0
	v_fmac_f32_e32 v55, v49, v55
	v_div_scale_f32 v49, vcc, 1.0, v53, 1.0
	global_store_short v[50:51], v52, off
	v_mul_f32_e32 v50, v49, v55
	v_fma_f32 v51, -v54, v50, v49
	v_fmac_f32_e32 v50, v51, v55
	v_fma_f32 v49, -v54, v50, v49
	v_div_fmas_f32 v49, v49, v55, v50
	v_mul_f32_e32 v50, 0xbfb8aa3b, v62
	v_exp_f32_e32 v51, v50
	v_div_fixup_f32 v49, v49, v53, 1.0
	v_add_u32_e32 v50, 0x100, v48
	v_cvt_pk_bf16_f32 v49, v49, s0
	v_add_f32_e32 v52, 1.0, v51
	v_div_scale_f32 v53, s[22:23], v52, v52, 1.0
	v_rcp_f32_e32 v54, v53
	v_mov_b32_e32 v51, v140
	v_lshl_add_u64 v[50:51], v[50:51], 1, s[26:27]
	global_store_short v[50:51], v49, off
	v_fma_f32 v49, -v53, v54, 1.0
	v_fmac_f32_e32 v54, v49, v54
	v_div_scale_f32 v49, vcc, 1.0, v52, 1.0
	v_mul_f32_e32 v50, v49, v54
	v_fma_f32 v51, -v53, v50, v49
	v_fmac_f32_e32 v50, v51, v54
	v_fma_f32 v49, -v53, v50, v49
	v_div_fmas_f32 v49, v49, v54, v50
	v_mul_f32_e32 v50, 0xbfb8aa3b, v63
	v_exp_f32_e32 v51, v50
	v_div_fixup_f32 v49, v49, v52, 1.0
	v_add_u32_e32 v50, 0x200, v48
	v_cvt_pk_bf16_f32 v49, v49, s0
	v_add_f32_e32 v52, 1.0, v51
	v_div_scale_f32 v53, s[22:23], v52, v52, 1.0
	v_rcp_f32_e32 v54, v53
	v_mov_b32_e32 v51, v140
	v_lshl_add_u64 v[50:51], v[50:51], 1, s[26:27]
	global_store_short v[50:51], v49, off
	v_fma_f32 v49, -v53, v54, 1.0
	v_fmac_f32_e32 v54, v49, v54
	v_div_scale_f32 v49, vcc, 1.0, v52, 1.0
	v_mul_f32_e32 v50, v49, v54
	v_fma_f32 v51, -v53, v50, v49
	v_fmac_f32_e32 v50, v51, v54
	v_fma_f32 v49, -v53, v50, v49
	v_div_fmas_f32 v49, v49, v54, v50
	v_div_fixup_f32 v49, v49, v52, 1.0
	v_cvt_pk_bf16_f32 v50, v49, s0
	v_add_u32_e32 v48, 0x300, v48
	v_mov_b32_e32 v49, v140
	v_lshl_add_u64 v[48:49], v[48:49], 1, s[26:27]
	global_store_short v[48:49], v50, off

.LBB0_969:
	s_mul_hi_i32 s4, s40, 0x38e38e39
	s_lshr_b32 s8, s4, 31
	s_ashr_i32 s4, s4, 4
	s_add_i32 s4, s4, s8
	s_mul_i32 s8, s4, 0x48
	s_sub_i32 s8, s40, s8
	s_lshl_b32 s8, s8, 7
	v_add_u32_e32 v0, s8, v123
	v_ashrrev_i32_e32 v1, 31, v0
	v_lshlrev_b64 v[32:33], 14, v[0:1]
	v_lshl_add_u64 v[34:35], v[98:99], 0, v[32:33]
	v_add_co_u32_e32 v40, vcc, s41, v34
	s_lshl_b32 s9, s4, 7
	s_nop 0
	v_addc_co_u32_e32 v41, vcc, 0, v35, vcc
	v_add_co_u32_e32 v42, vcc, s42, v34
	v_add_u32_e32 v0, s9, v123
	s_nop 0
	v_addc_co_u32_e32 v43, vcc, 0, v35, vcc
	v_ashrrev_i32_e32 v1, 31, v0
	v_add_co_u32_e32 v44, vcc, s19, v34
	v_lshlrev_b64 v[36:37], 14, v[0:1]
	s_nop 0
	v_addc_co_u32_e32 v45, vcc, 0, v35, vcc
	v_lshl_add_u64 v[38:39], v[100:101], 0, v[36:37]
	v_readfirstlane_b32 s100, v114
	s_nop 3
	s_add_u32 m0, s100, 0x0
	s_nop 0
	global_load_lds_dwordx4 v[34:35], off
	s_add_u32 m0, s100, 0x1000
	s_nop 0
	global_load_lds_dwordx4 v[40:41], off
	s_add_u32 m0, s100, 0x2000
	s_nop 0
	global_load_lds_dwordx4 v[42:43], off
	s_add_u32 m0, s100, 0x3000
	s_nop 0
	global_load_lds_dwordx4 v[44:45], off
	s_add_u32 m0, s100, 0x4000
	s_nop 0
	global_load_lds_dwordx4 v[38:39], off
	v_add_co_u32_e32 v46, vcc, s41, v38
	v_lshl_add_u64 v[106:107], v[102:103], 0, v[36:37]
	s_nop 0
	v_addc_co_u32_e32 v47, vcc, 0, v39, vcc
	s_waitcnt vmcnt(16)
	v_add_co_u32_e32 v48, vcc, s42, v38
	s_add_u32 m0, s100, 0x5000
	s_nop 0
	global_load_lds_dwordx4 v[46:47], off
	s_nop 0
	v_addc_co_u32_e32 v49, vcc, 0, v39, vcc
	v_add_co_u32_e32 v50, vcc, s19, v38
	s_add_u32 m0, s100, 0x6000
	s_nop 0
	global_load_lds_dwordx4 v[48:49], off
	s_nop 0
	v_addc_co_u32_e32 v51, vcc, 0, v39, vcc
	s_add_u32 m0, s100, 0x7000
	s_nop 0
	global_load_lds_dwordx4 v[50:51], off
	v_lshl_add_u64 v[108:109], v[104:105], 0, v[32:33]
	s_mov_b64 s[36:37], 0
	v_mov_b32_e32 v0, 0
	v_mov_b32_e32 v1, v0
	v_mov_b32_e32 v2, v0
	v_mov_b32_e32 v3, v0
	v_mov_b32_e32 v4, v0
	v_mov_b32_e32 v5, v0
	v_mov_b32_e32 v6, v0
	v_mov_b32_e32 v7, v0
	v_mov_b32_e32 v8, v0
	v_mov_b32_e32 v9, v0
	v_mov_b32_e32 v10, v0
	v_mov_b32_e32 v11, v0
	v_mov_b32_e32 v12, v0
	v_mov_b32_e32 v13, v0
	v_mov_b32_e32 v14, v0
	v_mov_b32_e32 v15, v0
	v_mov_b32_e32 v16, v0
	v_mov_b32_e32 v17, v0
	v_mov_b32_e32 v18, v0
	v_mov_b32_e32 v19, v0
	v_mov_b32_e32 v20, v0
	v_mov_b32_e32 v21, v0
	v_mov_b32_e32 v22, v0
	v_mov_b32_e32 v23, v0
	v_mov_b32_e32 v24, v0
	v_mov_b32_e32 v25, v0
	v_mov_b32_e32 v26, v0
	v_mov_b32_e32 v27, v0
	v_mov_b32_e32 v28, v0
	v_mov_b32_e32 v29, v0
	v_mov_b32_e32 v30, v0
	v_mov_b32_e32 v31, v0
	v_mov_b32_e32 v32, v0
	v_mov_b32_e32 v33, v0
	v_mov_b32_e32 v34, v0
	v_mov_b32_e32 v35, v0
	v_mov_b32_e32 v36, v0
	v_mov_b32_e32 v37, v0
	v_mov_b32_e32 v38, v0
	v_mov_b32_e32 v39, v0
	v_mov_b32_e32 v40, v0
	v_mov_b32_e32 v41, v0
	v_mov_b32_e32 v42, v0
	v_mov_b32_e32 v43, v0
	v_mov_b32_e32 v44, v0
	v_mov_b32_e32 v45, v0
	v_mov_b32_e32 v46, v0
	v_mov_b32_e32 v47, v0
	v_mov_b32_e32 v48, v0
	v_mov_b32_e32 v49, v0
	v_mov_b32_e32 v50, v0
	v_mov_b32_e32 v51, v0
	v_mov_b32_e32 v52, v0
	v_mov_b32_e32 v53, v0
	v_mov_b32_e32 v54, v0
	v_mov_b32_e32 v55, v0
	v_mov_b32_e32 v56, v0
	v_mov_b32_e32 v57, v0
	v_mov_b32_e32 v58, v0
	v_mov_b32_e32 v59, v0
	v_mov_b32_e32 v60, v0
	v_mov_b32_e32 v61, v0
	v_mov_b32_e32 v62, v0
	v_mov_b32_e32 v63, v0
	v_lshl_add_u64 v[144:145], v[108:109], 0, s[36:37]
	v_add_co_u32_e32 v152, vcc, s6, v144
	v_lshl_add_u64 v[146:147], v[106:107], 0, s[36:37]
	s_nop 0
	v_addc_co_u32_e32 v153, vcc, 0, v145, vcc
	v_add_co_u32_e32 v154, vcc, s78, v144
	s_nop 1
	v_addc_co_u32_e32 v155, vcc, 0, v145, vcc
	v_add_co_u32_e32 v156, vcc, s63, v144
	v_addc_co_u32_e32 v157, vcc, 0, v145, vcc
	v_add_co_u32_e32 v178, vcc, s7, v144
	s_nop 1
	v_addc_co_u32_e32 v179, vcc, 0, v145, vcc
	v_add_co_u32_e32 v180, vcc, s79, v146
	v_addc_co_u32_e32 v181, vcc, 0, v147, vcc
	v_add_co_u32_e32 v182, vcc, s82, v146
	s_nop 1
	v_addc_co_u32_e32 v183, vcc, 0, v147, vcc
	v_add_co_u32_e32 v184, vcc, s2, v146
	v_addc_co_u32_e32 v185, vcc, 0, v147, vcc
	v_add_co_u32_e32 v186, vcc, s17, v146
	s_nop 1
	v_addc_co_u32_e32 v187, vcc, 0, v147, vcc
	v_lshl_add_u64 v[152:153], 8, 4, v[152:153]
	v_lshl_add_u64 v[154:155], 8, 4, v[154:155]
	v_lshl_add_u64 v[156:157], 8, 4, v[156:157]
	v_lshl_add_u64 v[178:179], 8, 4, v[178:179]
	v_lshl_add_u64 v[180:181], 8, 4, v[180:181]
	v_lshl_add_u64 v[182:183], 8, 4, v[182:183]
	v_lshl_add_u64 v[184:185], 8, 4, v[184:185]
	v_lshl_add_u64 v[186:187], 8, 4, v[186:187]
	v_and_b32_e32 v132, 15, v143
	v_lshrrev_b32_e32 v133, 1, v132
	v_bfe_u32 v126, v143, 4, 2
	v_xor_b32_e32 v133, v133, v126
	v_lshlrev_b32_e32 v133, 4, v133
	v_lshl_add_u32 v133, v132, 7, v133
	v_lshrrev_b32_e32 v132, 6, v143
	v_lshrrev_b32_e32 v124, 1, v132
	v_and_b32_e32 v132, 1, v132
	v_lshl_add_u32 v124, v124, 13, v133
	v_lshl_add_u32 v125, v132, 13, v133
	v_add_u32_e32 v125, 0x4000, v125
	v_xor_b32_e32 v126, 64, v124
	v_xor_b32_e32 v127, 64, v125
	s_waitcnt vmcnt(0) lgkmcnt(0)
	s_barrier
.LBB0_970:
	s_add_u32 m0, s100, 0x8000
	s_nop 0
	global_load_lds_dwordx4 v[152:153], off
	s_add_u32 m0, s100, 0x9000
	s_nop 0
	global_load_lds_dwordx4 v[154:155], off
	s_add_u32 m0, s100, 0xa000
	s_nop 0
	global_load_lds_dwordx4 v[156:157], off
	s_add_u32 m0, s100, 0xb000
	s_nop 0
	global_load_lds_dwordx4 v[178:179], off
	s_add_u32 m0, s100, 0xc000
	s_nop 0
	global_load_lds_dwordx4 v[180:181], off
	s_add_u32 m0, s100, 0xd000
	s_nop 0
	global_load_lds_dwordx4 v[182:183], off
	s_add_u32 m0, s100, 0xe000
	s_nop 0
	global_load_lds_dwordx4 v[184:185], off
	s_add_u32 m0, s100, 0xf000
	s_nop 0
	global_load_lds_dwordx4 v[186:187], off
	ds_read_b128 a[0:3], v124
	ds_read_b128 v[80:83], v125
	ds_read_b128 a[4:7], v124 offset:2048
	ds_read_b128 a[8:11], v124 offset:4096
	ds_read_b128 a[12:15], v124 offset:6144
	ds_read_b128 v[92:95], v125 offset:2048
	ds_read_b128 v[88:91], v125 offset:4096
	ds_read_b128 v[84:87], v125 offset:6144
	ds_read_b128 a[16:19], v126
	ds_read_b128 a[20:23], v126 offset:2048
	ds_read_b128 a[24:27], v126 offset:4096
	ds_read_b128 a[28:31], v126 offset:6144
	s_setprio 1
	s_waitcnt lgkmcnt(10)
	v_mfma_f32_16x16x32_bf16 v[0:3], a[0:3], v[80:83], v[0:3]
	s_waitcnt lgkmcnt(9)
	v_mfma_f32_16x16x32_bf16 v[16:19], a[4:7], v[80:83], v[16:19]
	s_waitcnt lgkmcnt(8)
	v_mfma_f32_16x16x32_bf16 v[32:35], a[8:11], v[80:83], v[32:35]
	s_waitcnt lgkmcnt(7)
	v_mfma_f32_16x16x32_bf16 v[48:51], a[12:15], v[80:83], v[48:51]
	ds_read_b128 v[80:83], v127
	s_waitcnt lgkmcnt(7)
	v_mfma_f32_16x16x32_bf16 v[4:7], a[0:3], v[92:95], v[4:7]
	v_lshl_add_u64 v[64:65], 8, 4, v[152:153]
	v_lshl_add_u64 v[66:67], 8, 4, v[154:155]
	v_lshl_add_u64 v[68:69], 8, 4, v[156:157]
	v_mfma_f32_16x16x32_bf16 v[20:23], a[4:7], v[92:95], v[20:23]
	v_lshl_add_u64 v[70:71], 8, 4, v[178:179]
	v_lshl_add_u64 v[76:77], 8, 4, v[180:181]
	v_lshl_add_u64 v[78:79], 8, 4, v[182:183]
	v_mfma_f32_16x16x32_bf16 v[36:39], a[8:11], v[92:95], v[36:39]
	v_lshl_add_u64 v[72:73], 8, 4, v[184:185]
	v_lshl_add_u64 v[74:75], 8, 4, v[186:187]
	v_mfma_f32_16x16x32_bf16 v[52:55], a[12:15], v[92:95], v[52:55]
	ds_read_b128 v[92:95], v127 offset:2048
	s_waitcnt lgkmcnt(7)
	v_mfma_f32_16x16x32_bf16 v[8:11], a[0:3], v[88:91], v[8:11]
	v_mfma_f32_16x16x32_bf16 v[24:27], a[4:7], v[88:91], v[24:27]
	v_mfma_f32_16x16x32_bf16 v[40:43], a[8:11], v[88:91], v[40:43]
	v_mfma_f32_16x16x32_bf16 v[56:59], a[12:15], v[88:91], v[56:59]
	ds_read_b128 v[88:91], v127 offset:4096
	s_waitcnt lgkmcnt(7)
	v_mfma_f32_16x16x32_bf16 v[12:15], a[0:3], v[84:87], v[12:15]
	v_mfma_f32_16x16x32_bf16 v[28:31], a[4:7], v[84:87], v[28:31]
	v_mfma_f32_16x16x32_bf16 v[44:47], a[8:11], v[84:87], v[44:47]
	v_mfma_f32_16x16x32_bf16 v[60:63], a[12:15], v[84:87], v[60:63]
	ds_read_b128 v[84:87], v127 offset:6144
	s_waitcnt lgkmcnt(3)
	v_mfma_f32_16x16x32_bf16 v[0:3], a[16:19], v[80:83], v[0:3]
	v_mfma_f32_16x16x32_bf16 v[16:19], a[20:23], v[80:83], v[16:19]
	v_mfma_f32_16x16x32_bf16 v[32:35], a[24:27], v[80:83], v[32:35]
	v_mfma_f32_16x16x32_bf16 v[48:51], a[28:31], v[80:83], v[48:51]
	s_waitcnt lgkmcnt(2)
	v_mfma_f32_16x16x32_bf16 v[4:7], a[16:19], v[92:95], v[4:7]
	v_mfma_f32_16x16x32_bf16 v[20:23], a[20:23], v[92:95], v[20:23]
	v_mfma_f32_16x16x32_bf16 v[36:39], a[24:27], v[92:95], v[36:39]
	v_mfma_f32_16x16x32_bf16 v[52:55], a[28:31], v[92:95], v[52:55]
	s_waitcnt lgkmcnt(1)
	v_mfma_f32_16x16x32_bf16 v[8:11], a[16:19], v[88:91], v[8:11]
	v_mfma_f32_16x16x32_bf16 v[24:27], a[20:23], v[88:91], v[24:27]
	v_mfma_f32_16x16x32_bf16 v[40:43], a[24:27], v[88:91], v[40:43]
	v_mfma_f32_16x16x32_bf16 v[56:59], a[28:31], v[88:91], v[56:59]
	s_waitcnt lgkmcnt(0)
	v_mfma_f32_16x16x32_bf16 v[12:15], a[16:19], v[84:87], v[12:15]
	v_mfma_f32_16x16x32_bf16 v[28:31], a[20:23], v[84:87], v[28:31]
	v_mfma_f32_16x16x32_bf16 v[44:47], a[24:27], v[84:87], v[44:47]
	v_mfma_f32_16x16x32_bf16 v[60:63], a[28:31], v[84:87], v[60:63]
	s_setprio 0
	s_waitcnt vmcnt(0) lgkmcnt(0)
	s_barrier
	s_add_u32 s36, s36, 0x100
	s_addc_u32 s37, s37, 0
	s_add_u32 m0, s100, 0x0
	s_nop 0
	global_load_lds_dwordx4 v[64:65], off
	s_add_u32 m0, s100, 0x1000
	s_nop 0
	global_load_lds_dwordx4 v[66:67], off
	s_add_u32 m0, s100, 0x2000
	s_nop 0
	global_load_lds_dwordx4 v[68:69], off
	s_add_u32 m0, s100, 0x3000
	s_nop 0
	global_load_lds_dwordx4 v[70:71], off
	s_add_u32 m0, s100, 0x4000
	s_nop 0
	global_load_lds_dwordx4 v[76:77], off
	s_add_u32 m0, s100, 0x5000
	s_nop 0
	global_load_lds_dwordx4 v[78:79], off
	s_add_u32 m0, s100, 0x6000
	s_nop 0
	global_load_lds_dwordx4 v[72:73], off
	s_add_u32 m0, s100, 0x7000
	s_nop 0
	global_load_lds_dwordx4 v[74:75], off
	ds_read_b128 a[0:3], v124 offset:32768
	ds_read_b128 v[80:83], v125 offset:32768
	ds_read_b128 a[4:7], v124 offset:34816
	ds_read_b128 a[8:11], v124 offset:36864
	ds_read_b128 a[12:15], v124 offset:38912
	ds_read_b128 v[92:95], v125 offset:34816
	ds_read_b128 v[88:91], v125 offset:36864
	ds_read_b128 v[84:87], v125 offset:38912
	ds_read_b128 a[16:19], v126 offset:32768
	ds_read_b128 a[20:23], v126 offset:34816
	ds_read_b128 a[24:27], v126 offset:36864
	ds_read_b128 a[28:31], v126 offset:38912
	s_setprio 1
	s_waitcnt lgkmcnt(10)
	v_mfma_f32_16x16x32_bf16 v[0:3], a[0:3], v[80:83], v[0:3]
	s_waitcnt lgkmcnt(9)
	v_mfma_f32_16x16x32_bf16 v[16:19], a[4:7], v[80:83], v[16:19]
	s_waitcnt lgkmcnt(8)
	v_mfma_f32_16x16x32_bf16 v[32:35], a[8:11], v[80:83], v[32:35]
	s_waitcnt lgkmcnt(7)
	v_mfma_f32_16x16x32_bf16 v[48:51], a[12:15], v[80:83], v[48:51]
	ds_read_b128 v[80:83], v127 offset:32768
	s_waitcnt lgkmcnt(7)
	v_mfma_f32_16x16x32_bf16 v[4:7], a[0:3], v[92:95], v[4:7]
	v_lshl_add_u64 v[144:145], v[108:109], 0, s[36:37]
	v_add_co_u32_e32 v152, vcc, s6, v144
	v_lshl_add_u64 v[146:147], v[106:107], 0, s[36:37]
	v_mfma_f32_16x16x32_bf16 v[20:23], a[4:7], v[92:95], v[20:23]
	s_nop 0
	v_addc_co_u32_e32 v153, vcc, 0, v145, vcc
	v_add_co_u32_e32 v154, vcc, s78, v144
	v_mfma_f32_16x16x32_bf16 v[36:39], a[8:11], v[92:95], v[36:39]
	s_nop 1
	v_addc_co_u32_e32 v155, vcc, 0, v145, vcc
	v_add_co_u32_e32 v156, vcc, s63, v144
	v_mfma_f32_16x16x32_bf16 v[52:55], a[12:15], v[92:95], v[52:55]
	v_addc_co_u32_e32 v157, vcc, 0, v145, vcc
	v_add_co_u32_e32 v178, vcc, s7, v144
	s_nop 1
	ds_read_b128 v[92:95], v127 offset:34816
	s_waitcnt lgkmcnt(7)
	v_mfma_f32_16x16x32_bf16 v[8:11], a[0:3], v[88:91], v[8:11]
	v_addc_co_u32_e32 v179, vcc, 0, v145, vcc
	v_add_co_u32_e32 v180, vcc, s79, v146
	v_addc_co_u32_e32 v181, vcc, 0, v147, vcc
	v_mfma_f32_16x16x32_bf16 v[24:27], a[4:7], v[88:91], v[24:27]
	v_add_co_u32_e32 v182, vcc, s82, v146
	s_nop 1
	v_addc_co_u32_e32 v183, vcc, 0, v147, vcc
	v_mfma_f32_16x16x32_bf16 v[40:43], a[8:11], v[88:91], v[40:43]
	v_add_co_u32_e32 v184, vcc, s2, v146
	v_addc_co_u32_e32 v185, vcc, 0, v147, vcc
	v_add_co_u32_e32 v186, vcc, s17, v146
	v_mfma_f32_16x16x32_bf16 v[56:59], a[12:15], v[88:91], v[56:59]
	s_nop 1
	v_addc_co_u32_e32 v187, vcc, 0, v147, vcc
	v_lshl_add_u64 v[152:153], 8, 4, v[152:153]
	ds_read_b128 v[88:91], v127 offset:36864
	s_waitcnt lgkmcnt(7)
	v_mfma_f32_16x16x32_bf16 v[12:15], a[0:3], v[84:87], v[12:15]
	v_lshl_add_u64 v[154:155], 8, 4, v[154:155]
	v_lshl_add_u64 v[156:157], 8, 4, v[156:157]
	v_lshl_add_u64 v[178:179], 8, 4, v[178:179]
	v_mfma_f32_16x16x32_bf16 v[28:31], a[4:7], v[84:87], v[28:31]
	v_lshl_add_u64 v[180:181], 8, 4, v[180:181]
	v_lshl_add_u64 v[182:183], 8, 4, v[182:183]
	v_lshl_add_u64 v[184:185], 8, 4, v[184:185]
	v_mfma_f32_16x16x32_bf16 v[44:47], a[8:11], v[84:87], v[44:47]
	v_lshl_add_u64 v[186:187], 8, 4, v[186:187]
	v_mfma_f32_16x16x32_bf16 v[60:63], a[12:15], v[84:87], v[60:63]
	ds_read_b128 v[84:87], v127 offset:38912
	s_waitcnt lgkmcnt(3)
	v_mfma_f32_16x16x32_bf16 v[0:3], a[16:19], v[80:83], v[0:3]
	v_mfma_f32_16x16x32_bf16 v[16:19], a[20:23], v[80:83], v[16:19]
	v_mfma_f32_16x16x32_bf16 v[32:35], a[24:27], v[80:83], v[32:35]
	v_mfma_f32_16x16x32_bf16 v[48:51], a[28:31], v[80:83], v[48:51]
	s_waitcnt lgkmcnt(2)
	v_mfma_f32_16x16x32_bf16 v[4:7], a[16:19], v[92:95], v[4:7]
	v_mfma_f32_16x16x32_bf16 v[20:23], a[20:23], v[92:95], v[20:23]
	v_mfma_f32_16x16x32_bf16 v[36:39], a[24:27], v[92:95], v[36:39]
	v_mfma_f32_16x16x32_bf16 v[52:55], a[28:31], v[92:95], v[52:55]
	s_waitcnt lgkmcnt(1)
	v_mfma_f32_16x16x32_bf16 v[8:11], a[16:19], v[88:91], v[8:11]
	v_mfma_f32_16x16x32_bf16 v[24:27], a[20:23], v[88:91], v[24:27]
	v_mfma_f32_16x16x32_bf16 v[40:43], a[24:27], v[88:91], v[40:43]
	v_mfma_f32_16x16x32_bf16 v[56:59], a[28:31], v[88:91], v[56:59]
	s_waitcnt lgkmcnt(0)
	v_mfma_f32_16x16x32_bf16 v[12:15], a[16:19], v[84:87], v[12:15]
	v_mfma_f32_16x16x32_bf16 v[28:31], a[20:23], v[84:87], v[28:31]
	v_mfma_f32_16x16x32_bf16 v[44:47], a[24:27], v[84:87], v[44:47]
	v_mfma_f32_16x16x32_bf16 v[60:63], a[28:31], v[84:87], v[60:63]
	s_setprio 0
	s_waitcnt vmcnt(0) lgkmcnt(0)
	s_barrier
	s_cmpk_eq_i32 s36, 0x3f00
	s_cbranch_scc0 .LBB0_970
	v_lshl_add_u64 v[64:65], 8, 4, v[64:65]
	v_lshl_add_u64 v[66:67], 8, 4, v[66:67]
	v_lshl_add_u64 v[68:69], 8, 4, v[68:69]
	v_lshl_add_u64 v[70:71], 8, 4, v[70:71]
	v_lshl_add_u64 v[76:77], 8, 4, v[76:77]
	v_lshl_add_u64 v[78:79], 8, 4, v[78:79]
	v_lshl_add_u64 v[72:73], 8, 4, v[72:73]
	v_lshl_add_u64 v[74:75], 8, 4, v[74:75]
	s_add_u32 m0, s100, 0x8000
	s_nop 0
	global_load_lds_dwordx4 v[64:65], off
	s_add_u32 m0, s100, 0x9000
	s_nop 0
	global_load_lds_dwordx4 v[66:67], off
	s_add_u32 m0, s100, 0xa000
	s_nop 0
	global_load_lds_dwordx4 v[68:69], off
	s_add_u32 m0, s100, 0xb000
	s_nop 0
	global_load_lds_dwordx4 v[70:71], off
	s_add_u32 m0, s100, 0xc000
	s_nop 0
	global_load_lds_dwordx4 v[76:77], off
	s_add_u32 m0, s100, 0xd000
	s_nop 0
	global_load_lds_dwordx4 v[78:79], off
	s_add_u32 m0, s100, 0xe000
	s_nop 0
	global_load_lds_dwordx4 v[72:73], off
	s_add_u32 m0, s100, 0xf000
	s_nop 0
	global_load_lds_dwordx4 v[74:75], off
	ds_read_b128 a[0:3], v124
	ds_read_b128 v[80:83], v125
	ds_read_b128 a[4:7], v124 offset:2048
	ds_read_b128 a[8:11], v124 offset:4096
	ds_read_b128 a[12:15], v124 offset:6144
	ds_read_b128 v[92:95], v125 offset:2048
	ds_read_b128 v[88:91], v125 offset:4096
	ds_read_b128 v[84:87], v125 offset:6144
	ds_read_b128 a[16:19], v126
	ds_read_b128 a[20:23], v126 offset:2048
	ds_read_b128 a[24:27], v126 offset:4096
	ds_read_b128 a[28:31], v126 offset:6144
	s_setprio 1
	s_waitcnt lgkmcnt(10)
	v_mfma_f32_16x16x32_bf16 v[0:3], a[0:3], v[80:83], v[0:3]
	s_waitcnt lgkmcnt(9)
	v_mfma_f32_16x16x32_bf16 v[16:19], a[4:7], v[80:83], v[16:19]
	s_waitcnt lgkmcnt(8)
	v_mfma_f32_16x16x32_bf16 v[32:35], a[8:11], v[80:83], v[32:35]
	s_waitcnt lgkmcnt(7)
	v_mfma_f32_16x16x32_bf16 v[48:51], a[12:15], v[80:83], v[48:51]
	ds_read_b128 v[80:83], v127
	s_waitcnt lgkmcnt(7)
	v_mfma_f32_16x16x32_bf16 v[4:7], a[0:3], v[92:95], v[4:7]
	v_mfma_f32_16x16x32_bf16 v[20:23], a[4:7], v[92:95], v[20:23]
	v_mfma_f32_16x16x32_bf16 v[36:39], a[8:11], v[92:95], v[36:39]
	v_mfma_f32_16x16x32_bf16 v[52:55], a[12:15], v[92:95], v[52:55]
	ds_read_b128 v[92:95], v127 offset:2048
	s_waitcnt lgkmcnt(7)
	v_mfma_f32_16x16x32_bf16 v[8:11], a[0:3], v[88:91], v[8:11]
	v_mfma_f32_16x16x32_bf16 v[24:27], a[4:7], v[88:91], v[24:27]
	v_mfma_f32_16x16x32_bf16 v[40:43], a[8:11], v[88:91], v[40:43]
	v_mfma_f32_16x16x32_bf16 v[56:59], a[12:15], v[88:91], v[56:59]
	ds_read_b128 v[88:91], v127 offset:4096
	s_waitcnt lgkmcnt(7)
	v_mfma_f32_16x16x32_bf16 v[12:15], a[0:3], v[84:87], v[12:15]
	v_mfma_f32_16x16x32_bf16 v[28:31], a[4:7], v[84:87], v[28:31]
	v_mfma_f32_16x16x32_bf16 v[44:47], a[8:11], v[84:87], v[44:47]
	v_mfma_f32_16x16x32_bf16 v[60:63], a[12:15], v[84:87], v[60:63]
	ds_read_b128 v[84:87], v127 offset:6144
	s_waitcnt lgkmcnt(3)
	v_mfma_f32_16x16x32_bf16 v[0:3], a[16:19], v[80:83], v[0:3]
	v_mfma_f32_16x16x32_bf16 v[16:19], a[20:23], v[80:83], v[16:19]
	v_mfma_f32_16x16x32_bf16 v[32:35], a[24:27], v[80:83], v[32:35]
	v_mfma_f32_16x16x32_bf16 v[48:51], a[28:31], v[80:83], v[48:51]
	s_waitcnt lgkmcnt(2)
	v_mfma_f32_16x16x32_bf16 v[4:7], a[16:19], v[92:95], v[4:7]
	v_mfma_f32_16x16x32_bf16 v[20:23], a[20:23], v[92:95], v[20:23]
	v_mfma_f32_16x16x32_bf16 v[36:39], a[24:27], v[92:95], v[36:39]
	v_mfma_f32_16x16x32_bf16 v[52:55], a[28:31], v[92:95], v[52:55]
	s_waitcnt lgkmcnt(1)
	v_mfma_f32_16x16x32_bf16 v[8:11], a[16:19], v[88:91], v[8:11]
	v_mfma_f32_16x16x32_bf16 v[24:27], a[20:23], v[88:91], v[24:27]
	v_mfma_f32_16x16x32_bf16 v[40:43], a[24:27], v[88:91], v[40:43]
	v_mfma_f32_16x16x32_bf16 v[56:59], a[28:31], v[88:91], v[56:59]
	s_waitcnt lgkmcnt(0)
	v_mfma_f32_16x16x32_bf16 v[12:15], a[16:19], v[84:87], v[12:15]
	v_mfma_f32_16x16x32_bf16 v[28:31], a[20:23], v[84:87], v[28:31]
	v_mfma_f32_16x16x32_bf16 v[44:47], a[24:27], v[84:87], v[44:47]
	v_mfma_f32_16x16x32_bf16 v[60:63], a[28:31], v[84:87], v[60:63]
	s_setprio 0
	s_waitcnt vmcnt(0) lgkmcnt(0)
	s_barrier
	ds_read_b128 a[0:3], v124 offset:32768
	ds_read_b128 v[80:83], v125 offset:32768
	ds_read_b128 a[4:7], v124 offset:34816
	ds_read_b128 a[8:11], v124 offset:36864
	ds_read_b128 a[12:15], v124 offset:38912
	ds_read_b128 v[92:95], v125 offset:34816
	ds_read_b128 v[88:91], v125 offset:36864
	ds_read_b128 v[84:87], v125 offset:38912
	ds_read_b128 a[16:19], v126 offset:32768
	ds_read_b128 a[20:23], v126 offset:34816
	ds_read_b128 a[24:27], v126 offset:36864
	ds_read_b128 a[28:31], v126 offset:38912
	s_setprio 1
	s_waitcnt lgkmcnt(10)
	v_mfma_f32_16x16x32_bf16 v[0:3], a[0:3], v[80:83], v[0:3]
	s_waitcnt lgkmcnt(9)
	v_mfma_f32_16x16x32_bf16 v[16:19], a[4:7], v[80:83], v[16:19]
	s_waitcnt lgkmcnt(8)
	v_mfma_f32_16x16x32_bf16 v[32:35], a[8:11], v[80:83], v[32:35]
	s_waitcnt lgkmcnt(7)
	v_mfma_f32_16x16x32_bf16 v[48:51], a[12:15], v[80:83], v[48:51]
	ds_read_b128 v[80:83], v127 offset:32768
	s_waitcnt lgkmcnt(7)
	v_mfma_f32_16x16x32_bf16 v[4:7], a[0:3], v[92:95], v[4:7]
	v_mfma_f32_16x16x32_bf16 v[20:23], a[4:7], v[92:95], v[20:23]
	v_mfma_f32_16x16x32_bf16 v[36:39], a[8:11], v[92:95], v[36:39]
	v_mfma_f32_16x16x32_bf16 v[52:55], a[12:15], v[92:95], v[52:55]
	ds_read_b128 v[92:95], v127 offset:34816
	s_waitcnt lgkmcnt(7)
	v_mfma_f32_16x16x32_bf16 v[8:11], a[0:3], v[88:91], v[8:11]
	v_mfma_f32_16x16x32_bf16 v[24:27], a[4:7], v[88:91], v[24:27]
	v_mfma_f32_16x16x32_bf16 v[40:43], a[8:11], v[88:91], v[40:43]
	v_mfma_f32_16x16x32_bf16 v[56:59], a[12:15], v[88:91], v[56:59]
	ds_read_b128 v[88:91], v127 offset:36864
	s_waitcnt lgkmcnt(7)
	v_mfma_f32_16x16x32_bf16 v[12:15], a[0:3], v[84:87], v[12:15]
	v_mfma_f32_16x16x32_bf16 v[28:31], a[4:7], v[84:87], v[28:31]
	v_mfma_f32_16x16x32_bf16 v[44:47], a[8:11], v[84:87], v[44:47]
	v_mfma_f32_16x16x32_bf16 v[60:63], a[12:15], v[84:87], v[60:63]
	ds_read_b128 v[84:87], v127 offset:38912
	s_waitcnt lgkmcnt(3)
	v_mfma_f32_16x16x32_bf16 v[0:3], a[16:19], v[80:83], v[0:3]
	v_mfma_f32_16x16x32_bf16 v[16:19], a[20:23], v[80:83], v[16:19]
	v_mfma_f32_16x16x32_bf16 v[32:35], a[24:27], v[80:83], v[32:35]
	v_mfma_f32_16x16x32_bf16 v[48:51], a[28:31], v[80:83], v[48:51]
	s_waitcnt lgkmcnt(2)
	v_mfma_f32_16x16x32_bf16 v[4:7], a[16:19], v[92:95], v[4:7]
	v_mfma_f32_16x16x32_bf16 v[20:23], a[20:23], v[92:95], v[20:23]
	v_mfma_f32_16x16x32_bf16 v[36:39], a[24:27], v[92:95], v[36:39]
	v_mfma_f32_16x16x32_bf16 v[52:55], a[28:31], v[92:95], v[52:55]
	s_waitcnt lgkmcnt(1)
	v_mfma_f32_16x16x32_bf16 v[8:11], a[16:19], v[88:91], v[8:11]
	v_mfma_f32_16x16x32_bf16 v[24:27], a[20:23], v[88:91], v[24:27]
	v_mfma_f32_16x16x32_bf16 v[40:43], a[24:27], v[88:91], v[40:43]
	v_mfma_f32_16x16x32_bf16 v[56:59], a[28:31], v[88:91], v[56:59]
	s_waitcnt lgkmcnt(0)
	v_mfma_f32_16x16x32_bf16 v[12:15], a[16:19], v[84:87], v[12:15]
	v_mfma_f32_16x16x32_bf16 v[28:31], a[20:23], v[84:87], v[28:31]
	v_mfma_f32_16x16x32_bf16 v[44:47], a[24:27], v[84:87], v[44:47]
	v_mfma_f32_16x16x32_bf16 v[60:63], a[28:31], v[84:87], v[60:63]
	s_setprio 0
	v_readfirstlane_b32 s15, v113
	v_readfirstlane_b32 s4, v112
	s_lshl_b32 s15, s15, 6
	s_waitcnt lgkmcnt(0)
	s_barrier
	s_add_i32 s15, s15, s9
	s_lshl_b32 s23, s4, 6
	s_add_i32 s23, s23, s8
	v_or_b32_e32 v67, s15, v111
	s_movk_i32 s4, 0x800
	s_ashr_i32 s22, s23, 11
	v_cmp_gt_i32_e32 vcc, s4, v67
	v_add_u32_e32 v65, 0x2800, v67
	v_add_u32_e32 v64, v67, v97
	v_lshl_or_b32 v66, s23, 11, v97
	s_barrier
	v_and_b32_e32 v132, 15, v143
	v_bfe_u32 v133, v143, 4, 2
	v_xor_b32_e32 v133, v133, v132
	v_lshlrev_b32_e32 v133, 4, v133
	v_lshl_add_u32 v133, v132, 8, v133
	v_lshrrev_b32_e32 v132, 6, v143
	v_lshl_add_u32 v133, v132, 14, v133
	ds_write_b128 v133, v[0:3]
	ds_write_b128 v133, v[4:7] offset:4096
	ds_write_b128 v133, v[8:11] offset:8192
	ds_write_b128 v133, v[12:15] offset:12288
	v_xor_b32_e32 v127, 64, v133
	ds_write_b128 v127, v[16:19]
	ds_write_b128 v127, v[20:23] offset:4096
	ds_write_b128 v127, v[24:27] offset:8192
	ds_write_b128 v127, v[28:31] offset:12288
	v_xor_b32_e32 v127, 128, v133
	ds_write_b128 v127, v[32:35]
	ds_write_b128 v127, v[36:39] offset:4096
	ds_write_b128 v127, v[40:43] offset:8192
	ds_write_b128 v127, v[44:47] offset:12288
	v_xor_b32_e32 v127, 192, v133
	ds_write_b128 v127, v[48:51]
	ds_write_b128 v127, v[52:55] offset:4096
	ds_write_b128 v127, v[56:59] offset:8192
	ds_write_b128 v127, v[60:63] offset:12288
	v_and_b32_e32 v124, 31, v143
	v_bfe_u32 v126, v143, 5, 1
	v_and_b32_e32 v133, 15, v124
	v_xor_b32_e32 v126, v126, v133
	v_lshlrev_b32_e32 v126, 4, v126
	v_lshl_add_u32 v126, v124, 8, v126
	v_lshl_add_u32 v126, v132, 14, v126
	ds_read_b128 v[48:51], v126
	ds_read_b128 v[32:35], v126 offset:8192
	v_xor_b32_e32 v125, 32, v126
	ds_read_b128 v[52:55], v125
	ds_read_b128 v[36:39], v125 offset:8192
	v_xor_b32_e32 v125, 64, v126
	ds_read_b128 v[56:59], v125
	ds_read_b128 v[40:43], v125 offset:8192
	v_xor_b32_e32 v125, 96, v126
	ds_read_b128 v[60:63], v125
	ds_read_b128 v[44:47], v125 offset:8192
	v_xor_b32_e32 v125, 128, v126
	ds_read_b128 v[16:19], v125
	ds_read_b128 v[0:3], v125 offset:8192
	v_xor_b32_e32 v125, 160, v126
	ds_read_b128 v[20:23], v125
	ds_read_b128 v[4:7], v125 offset:8192
	v_xor_b32_e32 v125, 192, v126
	ds_read_b128 v[24:27], v125
	ds_read_b128 v[8:11], v125 offset:8192
	v_xor_b32_e32 v125, 224, v126
	ds_read_b128 v[28:31], v125
	ds_read_b128 v[12:15], v125 offset:8192
	s_waitcnt lgkmcnt(0)
	s_barrier
	s_and_saveexec_b64 s[8:9], vcc
	s_cbranch_execz .LBB0_973
	s_add_i32 s4, s23, 0xffffe000
	s_lshr_b32 s4, s4, 3
	s_or_b32 s4, s4, 4
	s_cmpk_lt_i32 s23, 0x2000
	s_cselect_b32 s4, s22, s4
	s_mulk_i32 s4, 0x3000
	v_add_u32_e32 v68, s4, v65
	v_mov_b32_e32 v69, v140
	v_lshl_add_u64 v[68:69], v[68:69], 2, s[26:27]
	global_load_dword v72, v[68:69], off
	v_add_u32_e32 v68, v66, v67
	v_mov_b32_e32 v69, v140
	v_lshl_add_u64 v[70:71], v[68:69], 2, s[0:1]
	global_load_dword v69, v[70:71], off
	s_waitcnt vmcnt(0)
	v_fmac_f32_e32 v69, v48, v72
	global_store_dword v[70:71], v69, off
	v_add_u32_e32 v70, 0x800, v68
	v_mov_b32_e32 v71, v140
	v_lshl_add_u64 v[70:71], v[70:71], 2, s[0:1]
	global_load_dword v48, v[70:71], off
	s_waitcnt vmcnt(0)
	v_fmac_f32_e32 v48, v49, v72
	global_store_dword v[70:71], v48, off
	v_add_u32_e32 v48, 0x1000, v68
	v_mov_b32_e32 v49, v140
	v_lshl_add_u64 v[48:49], v[48:49], 2, s[0:1]
	global_load_dword v69, v[48:49], off
	s_waitcnt vmcnt(0)
	v_fmac_f32_e32 v69, v50, v72
	global_store_dword v[48:49], v69, off
	v_add_u32_e32 v48, 0x1800, v68
	v_mov_b32_e32 v49, v140
	v_lshl_add_u64 v[48:49], v[48:49], 2, s[0:1]
	global_load_dword v50, v[48:49], off
	s_waitcnt vmcnt(0)
	v_fmac_f32_e32 v50, v51, v72
	global_store_dword v[48:49], v50, off
	s_add_i32 s15, s23, 0xffffe008
	s_lshr_b32 s15, s15, 3
	s_or_b32 s4, s23, 8
	s_or_b32 s15, s15, 4
	s_cmpk_lt_i32 s4, 0x2000
	s_cselect_b32 s15, s22, s15
	s_mulk_i32 s15, 0x3000
	v_add_u32_e32 v48, s15, v65
	v_mov_b32_e32 v49, v140
	v_lshl_add_u64 v[48:49], v[48:49], 2, s[26:27]
	global_load_dword v68, v[48:49], off
	v_lshl_add_u32 v48, s4, 11, v64
	v_mov_b32_e32 v49, v140
	v_lshl_add_u64 v[50:51], v[48:49], 2, s[0:1]
	global_load_dword v49, v[50:51], off
	s_waitcnt vmcnt(0)
	v_fmac_f32_e32 v49, v52, v68
	global_store_dword v[50:51], v49, off
	v_add_u32_e32 v50, 0x800, v48
	v_mov_b32_e32 v51, v140
	v_lshl_add_u64 v[50:51], v[50:51], 2, s[0:1]
	global_load_dword v49, v[50:51], off
	s_waitcnt vmcnt(0)
	v_fmac_f32_e32 v49, v53, v68
	global_store_dword v[50:51], v49, off
	v_add_u32_e32 v50, 0x1000, v48
	v_mov_b32_e32 v51, v140
	v_lshl_add_u64 v[50:51], v[50:51], 2, s[0:1]
	global_load_dword v49, v[50:51], off
	v_add_u32_e32 v48, 0x1800, v48
	s_waitcnt vmcnt(0)
	v_fmac_f32_e32 v49, v54, v68
	global_store_dword v[50:51], v49, off
	v_mov_b32_e32 v49, v140
	v_lshl_add_u64 v[48:49], v[48:49], 2, s[0:1]
	global_load_dword v50, v[48:49], off
	s_waitcnt vmcnt(0)
	v_fmac_f32_e32 v50, v55, v68
	global_store_dword v[48:49], v50, off
	s_add_i32 s15, s23, 0xffffe010
	s_lshr_b32 s15, s15, 3
	s_or_b32 s4, s23, 16
	s_or_b32 s15, s15, 4
	s_cmpk_lt_i32 s4, 0x2000
	s_cselect_b32 s15, s22, s15
	s_mulk_i32 s15, 0x3000
	v_add_u32_e32 v48, s15, v65
	v_mov_b32_e32 v49, v140
	v_lshl_add_u64 v[48:49], v[48:49], 2, s[26:27]
	global_load_dword v52, v[48:49], off
	v_lshl_add_u32 v48, s4, 11, v64
	v_mov_b32_e32 v49, v140
	v_lshl_add_u64 v[50:51], v[48:49], 2, s[0:1]
	global_load_dword v49, v[50:51], off
	s_waitcnt vmcnt(0)
	v_fmac_f32_e32 v49, v56, v52
	global_store_dword v[50:51], v49, off
	v_add_u32_e32 v50, 0x800, v48
	v_mov_b32_e32 v51, v140
	v_lshl_add_u64 v[50:51], v[50:51], 2, s[0:1]
	global_load_dword v49, v[50:51], off
	s_waitcnt vmcnt(0)
	v_fmac_f32_e32 v49, v57, v52
	global_store_dword v[50:51], v49, off
	v_add_u32_e32 v50, 0x1000, v48
	v_mov_b32_e32 v51, v140
	v_lshl_add_u64 v[50:51], v[50:51], 2, s[0:1]
	global_load_dword v49, v[50:51], off
	v_add_u32_e32 v48, 0x1800, v48
	s_waitcnt vmcnt(0)
	v_fmac_f32_e32 v49, v58, v52
	global_store_dword v[50:51], v49, off
	v_mov_b32_e32 v49, v140
	v_lshl_add_u64 v[48:49], v[48:49], 2, s[0:1]
	global_load_dword v50, v[48:49], off
	s_waitcnt vmcnt(0)
	v_fmac_f32_e32 v50, v59, v52
	global_store_dword v[48:49], v50, off
	s_add_i32 s15, s23, 0xffffe018
	s_lshr_b32 s15, s15, 3
	s_or_b32 s4, s23, 24
	s_or_b32 s15, s15, 4
	s_cmpk_lt_i32 s4, 0x2000
	s_cselect_b32 s15, s22, s15
	s_mulk_i32 s15, 0x3000
	v_add_u32_e32 v48, s15, v65
	v_mov_b32_e32 v49, v140
	v_lshl_add_u64 v[48:49], v[48:49], 2, s[26:27]
	global_load_dword v52, v[48:49], off
	v_lshl_add_u32 v48, s4, 11, v64
	v_mov_b32_e32 v49, v140
	v_lshl_add_u64 v[50:51], v[48:49], 2, s[0:1]
	global_load_dword v49, v[50:51], off
	s_waitcnt vmcnt(0)
	v_fmac_f32_e32 v49, v60, v52
	global_store_dword v[50:51], v49, off
	v_add_u32_e32 v50, 0x800, v48
	v_mov_b32_e32 v51, v140
	v_lshl_add_u64 v[50:51], v[50:51], 2, s[0:1]
	global_load_dword v49, v[50:51], off
	s_waitcnt vmcnt(0)
	v_fmac_f32_e32 v49, v61, v52
	global_store_dword v[50:51], v49, off
	v_add_u32_e32 v50, 0x1000, v48
	v_mov_b32_e32 v51, v140
	v_lshl_add_u64 v[50:51], v[50:51], 2, s[0:1]
	global_load_dword v49, v[50:51], off
	v_add_u32_e32 v48, 0x1800, v48
	s_waitcnt vmcnt(0)
	v_fmac_f32_e32 v49, v62, v52
	global_store_dword v[50:51], v49, off
	v_mov_b32_e32 v49, v140
	v_lshl_add_u64 v[48:49], v[48:49], 2, s[0:1]
	global_load_dword v50, v[48:49], off
	s_waitcnt vmcnt(0)
	v_fmac_f32_e32 v50, v63, v52
	global_store_dword v[48:49], v50, off

.LBB0_979:
	v_readlane_b32 s8, v219, 0
	v_readlane_b32 s9, v219, 1
	s_and_b64 vcc, exec, s[8:9]
	s_cbranch_vccz .LBB0_991
	v_readlane_b32 s4, v219, 2
	v_mov_b32_e32 v97, v140
	v_readlane_b32 s8, v219, 26
	v_add_u32_e32 v0, s4, v123
	v_ashrrev_i32_e32 v1, 31, v0
	v_lshlrev_b64 v[34:35], 14, v[0:1]
	v_lshl_add_u64 v[0:1], s[30:31], 0, v[34:35]
	v_lshl_add_u64 v[0:1], v[0:1], 0, v[96:97]
	v_readlane_b32 s9, v219, 27
	v_readlane_b32 s4, v219, 3
	v_lshlrev_b32_e32 v54, 4, v120
	v_lshl_add_u64 v[36:37], v[0:1], 0, s[8:9]
	v_add_u32_e32 v0, s4, v123
	v_add_co_u32_e32 v42, vcc, s41, v36
	v_ashrrev_i32_e32 v1, 31, v0
	s_nop 0
	v_addc_co_u32_e32 v43, vcc, 0, v37, vcc
	v_lshlrev_b64 v[38:39], 14, v[0:1]
	v_add_co_u32_e32 v44, vcc, s42, v36
	v_lshl_add_u64 v[0:1], s[34:35], 0, v[38:39]
	s_nop 0
	v_addc_co_u32_e32 v45, vcc, 0, v37, vcc
	v_lshl_add_u64 v[0:1], v[0:1], 0, v[96:97]
	v_add_co_u32_e32 v46, vcc, s19, v36
	v_lshl_add_u64 v[40:41], v[0:1], 0, s[8:9]
	s_nop 0
	v_addc_co_u32_e32 v47, vcc, 0, v37, vcc
	s_waitcnt vmcnt(11)
	v_add_co_u32_e32 v48, vcc, s41, v40
	v_readfirstlane_b32 s100, v114
	s_nop 3
	s_add_u32 m0, s100, 0x0
	s_nop 0
	global_load_lds_dwordx4 v[36:37], off
	s_add_u32 m0, s100, 0x1000
	s_nop 0
	global_load_lds_dwordx4 v[42:43], off
	v_addc_co_u32_e32 v49, vcc, 0, v41, vcc
	v_add_co_u32_e32 v50, vcc, s42, v40
	s_add_u32 m0, s100, 0x2000
	s_nop 0
	global_load_lds_dwordx4 v[44:45], off
	s_nop 0
	v_addc_co_u32_e32 v51, vcc, 0, v41, vcc
	v_add_co_u32_e32 v52, vcc, s19, v40
	s_add_u32 m0, s100, 0x3000
	s_nop 0
	global_load_lds_dwordx4 v[46:47], off
	s_add_u32 m0, s100, 0x4000
	s_nop 0
	global_load_lds_dwordx4 v[40:41], off
	v_addc_co_u32_e32 v53, vcc, 0, v41, vcc
	s_add_u32 m0, s100, 0x5000
	s_nop 0
	global_load_lds_dwordx4 v[48:49], off
	s_add_u32 m0, s100, 0x6000
	s_nop 0
	global_load_lds_dwordx4 v[50:51], off
	s_add_u32 m0, s100, 0x7000
	s_nop 0
	global_load_lds_dwordx4 v[52:53], off
	v_lshlrev_b32_e32 v58, 4, v118
	v_lshlrev_b32_e32 v1, 4, v119
	v_lshlrev_b32_e32 v56, 4, v121
	v_lshlrev_b32_e32 v57, 4, v122
	s_add_u32 s8, s28, s8
	v_mov_b32_e32 v55, v140
	v_or_b32_e32 v60, v54, v116
	v_or_b32_e32 v61, v54, v117
	v_and_b32_e32 v54, 0x70, v58
	v_lshl_add_u64 v[38:39], s[94:95], 0, v[38:39]
	v_mov_b32_e32 v0, 0
	v_or_b32_e32 v59, v1, v116
	v_or_b32_e32 v1, v1, v117
	v_or_b32_e32 v62, v56, v116
	v_or_b32_e32 v56, v56, v117
	v_or_b32_e32 v63, v57, v116
	v_or_b32_e32 v57, v57, v117
	s_addc_u32 s9, s29, s9
	v_or_b32_e32 v34, v34, v54
	v_lshl_add_u64 v[38:39], v[38:39], 0, v[54:55]
	s_mov_b64 s[30:31], 0
	v_lshl_add_u64 v[96:97], s[8:9], 0, v[34:35]
	v_lshl_add_u64 v[98:99], s[8:9], 0, v[38:39]
	v_add_u32_e32 v104, v59, v115
	v_add_u32_e32 v107, v1, v115
	v_add_u32_e32 v105, v60, v115
	v_add_u32_e32 v106, v61, v115
	v_add_u32_e32 v102, v62, v115
	v_add_u32_e32 v103, v56, v115
	v_add_u32_e32 v100, v63, v115
	v_add_u32_e32 v101, v57, v115
	v_mov_b32_e32 v1, v0
	v_mov_b32_e32 v34, v0
	v_mov_b32_e32 v35, v0
	v_mov_b32_e32 v36, v0
	v_mov_b32_e32 v37, v0
	v_mov_b32_e32 v38, v0
	v_mov_b32_e32 v39, v0
	v_mov_b32_e32 v40, v0
	v_mov_b32_e32 v41, v0
	v_mov_b32_e32 v42, v0
	v_mov_b32_e32 v43, v0
	v_mov_b32_e32 v44, v0
	v_mov_b32_e32 v2, v0
	v_mov_b32_e32 v3, v0
	v_mov_b32_e32 v4, v0
	v_mov_b32_e32 v5, v0
	v_mov_b32_e32 v6, v0
	v_mov_b32_e32 v7, v0
	v_mov_b32_e32 v8, v0
	v_mov_b32_e32 v9, v0
	v_mov_b32_e32 v10, v0
	v_mov_b32_e32 v11, v0
	v_mov_b32_e32 v12, v0
	v_mov_b32_e32 v13, v0
	v_mov_b32_e32 v14, v0
	v_mov_b32_e32 v15, v0
	v_mov_b32_e32 v16, v0
	v_mov_b32_e32 v17, v0
	v_mov_b32_e32 v18, v0
	v_mov_b32_e32 v19, v0
	v_mov_b32_e32 v20, v0
	v_mov_b32_e32 v21, v0
	v_mov_b32_e32 v22, v0
	v_mov_b32_e32 v23, v0
	v_mov_b32_e32 v24, v0
	v_mov_b32_e32 v25, v0
	v_mov_b32_e32 v26, v0
	v_mov_b32_e32 v27, v0
	v_mov_b32_e32 v28, v0
	v_mov_b32_e32 v29, v0
	v_mov_b32_e32 v30, v0
	v_mov_b32_e32 v31, v0
	v_mov_b32_e32 v32, v0
	v_mov_b32_e32 v33, v0
	v_mov_b32_e32 v45, v0
	v_mov_b32_e32 v46, v0
	v_mov_b32_e32 v47, v0
	v_mov_b32_e32 v48, v0
	v_mov_b32_e32 v49, v0
	v_mov_b32_e32 v50, v0
	v_mov_b32_e32 v51, v0
	v_mov_b32_e32 v52, v0
	v_mov_b32_e32 v53, v0
	v_mov_b32_e32 v54, v0
	v_mov_b32_e32 v55, v0
	v_mov_b32_e32 v56, v0
	v_mov_b32_e32 v57, v0
	v_mov_b32_e32 v58, v0
	v_mov_b32_e32 v59, v0
	v_mov_b32_e32 v60, v0
	v_mov_b32_e32 v61, v0
	v_mov_b32_e32 v62, v0
	v_mov_b32_e32 v63, v0
	v_lshl_add_u64 v[120:121], v[96:97], 0, s[30:31]
	v_add_co_u32_e32 v108, vcc, s6, v120
	v_lshl_add_u64 v[122:123], v[98:99], 0, s[30:31]
	s_nop 0
	v_addc_co_u32_e32 v109, vcc, 0, v121, vcc
	v_add_co_u32_e32 v128, vcc, s78, v120
	s_nop 1
	v_addc_co_u32_e32 v129, vcc, 0, v121, vcc
	v_add_co_u32_e32 v130, vcc, s63, v120
	v_addc_co_u32_e32 v131, vcc, 0, v121, vcc
	v_add_co_u32_e32 v132, vcc, s7, v120
	s_nop 1
	v_addc_co_u32_e32 v133, vcc, 0, v121, vcc
	v_add_co_u32_e32 v134, vcc, s79, v122
	v_addc_co_u32_e32 v135, vcc, 0, v123, vcc
	v_add_co_u32_e32 v144, vcc, s82, v122
	s_nop 1
	v_addc_co_u32_e32 v145, vcc, 0, v123, vcc
	v_add_co_u32_e32 v146, vcc, s2, v122
	v_addc_co_u32_e32 v147, vcc, 0, v123, vcc
	v_add_co_u32_e32 v148, vcc, s17, v122
	s_nop 1
	v_addc_co_u32_e32 v149, vcc, 0, v123, vcc
	v_lshl_add_u64 v[108:109], 8, 4, v[108:109]
	v_lshl_add_u64 v[128:129], 8, 4, v[128:129]
	v_lshl_add_u64 v[130:131], 8, 4, v[130:131]
	v_lshl_add_u64 v[132:133], 8, 4, v[132:133]
	v_lshl_add_u64 v[134:135], 8, 4, v[134:135]
	v_lshl_add_u64 v[144:145], 8, 4, v[144:145]
	v_lshl_add_u64 v[146:147], 8, 4, v[146:147]
	v_lshl_add_u64 v[148:149], 8, 4, v[148:149]
	v_and_b32_e32 v116, 15, v143
	v_lshrrev_b32_e32 v117, 1, v116
	v_bfe_u32 v105, v143, 4, 2
	v_xor_b32_e32 v117, v117, v105
	v_lshlrev_b32_e32 v117, 4, v117
	v_lshl_add_u32 v117, v116, 7, v117
	v_lshrrev_b32_e32 v116, 6, v143
	v_lshrrev_b32_e32 v104, 1, v116
	v_and_b32_e32 v116, 1, v116
	v_lshl_add_u32 v104, v104, 13, v117
	v_lshl_add_u32 v107, v116, 13, v117
	v_add_u32_e32 v107, 0x4000, v107
	v_xor_b32_e32 v105, 64, v104
	v_xor_b32_e32 v106, 64, v107
	s_waitcnt vmcnt(0) lgkmcnt(0)
	s_barrier
.LBB0_981:
	s_add_u32 m0, s100, 0x8000
	s_nop 0
	global_load_lds_dwordx4 v[108:109], off
	s_add_u32 m0, s100, 0x9000
	s_nop 0
	global_load_lds_dwordx4 v[128:129], off
	s_add_u32 m0, s100, 0xa000
	s_nop 0
	global_load_lds_dwordx4 v[130:131], off
	s_add_u32 m0, s100, 0xb000
	s_nop 0
	global_load_lds_dwordx4 v[132:133], off
	s_add_u32 m0, s100, 0xc000
	s_nop 0
	global_load_lds_dwordx4 v[134:135], off
	s_add_u32 m0, s100, 0xd000
	s_nop 0
	global_load_lds_dwordx4 v[144:145], off
	s_add_u32 m0, s100, 0xe000
	s_nop 0
	global_load_lds_dwordx4 v[146:147], off
	s_add_u32 m0, s100, 0xf000
	s_nop 0
	global_load_lds_dwordx4 v[148:149], off
	ds_read_b128 a[0:3], v104
	ds_read_b128 v[64:67], v107
	ds_read_b128 a[4:7], v104 offset:2048
	ds_read_b128 a[8:11], v104 offset:4096
	ds_read_b128 a[12:15], v104 offset:6144
	ds_read_b128 v[80:83], v107 offset:2048
	ds_read_b128 v[76:79], v107 offset:4096
	ds_read_b128 v[72:75], v107 offset:6144
	ds_read_b128 a[16:19], v105
	ds_read_b128 a[20:23], v105 offset:2048
	ds_read_b128 a[24:27], v105 offset:4096
	ds_read_b128 a[28:31], v105 offset:6144
	s_setprio 1
	s_waitcnt lgkmcnt(10)
	v_mfma_f32_16x16x32_bf16 v[0:3], a[0:3], v[64:67], v[0:3]
	s_waitcnt lgkmcnt(9)
	v_mfma_f32_16x16x32_bf16 v[16:19], a[4:7], v[64:67], v[16:19]
	s_waitcnt lgkmcnt(8)
	v_mfma_f32_16x16x32_bf16 v[32:35], a[8:11], v[64:67], v[32:35]
	s_waitcnt lgkmcnt(7)
	v_mfma_f32_16x16x32_bf16 v[48:51], a[12:15], v[64:67], v[48:51]
	ds_read_b128 v[64:67], v106
	s_waitcnt lgkmcnt(7)
	v_mfma_f32_16x16x32_bf16 v[4:7], a[0:3], v[80:83], v[4:7]
	v_lshl_add_u64 v[68:69], 8, 4, v[108:109]
	v_lshl_add_u64 v[70:71], 8, 4, v[128:129]
	v_lshl_add_u64 v[84:85], 8, 4, v[130:131]
	v_mfma_f32_16x16x32_bf16 v[20:23], a[4:7], v[80:83], v[20:23]
	v_lshl_add_u64 v[86:87], 8, 4, v[132:133]
	v_lshl_add_u64 v[92:93], 8, 4, v[134:135]
	v_lshl_add_u64 v[94:95], 8, 4, v[144:145]
	v_mfma_f32_16x16x32_bf16 v[36:39], a[8:11], v[80:83], v[36:39]
	v_lshl_add_u64 v[88:89], 8, 4, v[146:147]
	v_lshl_add_u64 v[90:91], 8, 4, v[148:149]
	v_mfma_f32_16x16x32_bf16 v[52:55], a[12:15], v[80:83], v[52:55]
	ds_read_b128 v[80:83], v106 offset:2048
	s_waitcnt lgkmcnt(7)
	v_mfma_f32_16x16x32_bf16 v[8:11], a[0:3], v[76:79], v[8:11]
	v_mfma_f32_16x16x32_bf16 v[24:27], a[4:7], v[76:79], v[24:27]
	v_mfma_f32_16x16x32_bf16 v[40:43], a[8:11], v[76:79], v[40:43]
	v_mfma_f32_16x16x32_bf16 v[56:59], a[12:15], v[76:79], v[56:59]
	ds_read_b128 v[76:79], v106 offset:4096
	s_waitcnt lgkmcnt(7)
	v_mfma_f32_16x16x32_bf16 v[12:15], a[0:3], v[72:75], v[12:15]
	v_mfma_f32_16x16x32_bf16 v[28:31], a[4:7], v[72:75], v[28:31]
	v_mfma_f32_16x16x32_bf16 v[44:47], a[8:11], v[72:75], v[44:47]
	v_mfma_f32_16x16x32_bf16 v[60:63], a[12:15], v[72:75], v[60:63]
	ds_read_b128 v[72:75], v106 offset:6144
	s_waitcnt lgkmcnt(3)
	v_mfma_f32_16x16x32_bf16 v[0:3], a[16:19], v[64:67], v[0:3]
	v_mfma_f32_16x16x32_bf16 v[16:19], a[20:23], v[64:67], v[16:19]
	v_mfma_f32_16x16x32_bf16 v[32:35], a[24:27], v[64:67], v[32:35]
	v_mfma_f32_16x16x32_bf16 v[48:51], a[28:31], v[64:67], v[48:51]
	s_waitcnt lgkmcnt(2)
	v_mfma_f32_16x16x32_bf16 v[4:7], a[16:19], v[80:83], v[4:7]
	v_mfma_f32_16x16x32_bf16 v[20:23], a[20:23], v[80:83], v[20:23]
	v_mfma_f32_16x16x32_bf16 v[36:39], a[24:27], v[80:83], v[36:39]
	v_mfma_f32_16x16x32_bf16 v[52:55], a[28:31], v[80:83], v[52:55]
	s_waitcnt lgkmcnt(1)
	v_mfma_f32_16x16x32_bf16 v[8:11], a[16:19], v[76:79], v[8:11]
	v_mfma_f32_16x16x32_bf16 v[24:27], a[20:23], v[76:79], v[24:27]
	v_mfma_f32_16x16x32_bf16 v[40:43], a[24:27], v[76:79], v[40:43]
	v_mfma_f32_16x16x32_bf16 v[56:59], a[28:31], v[76:79], v[56:59]
	s_waitcnt lgkmcnt(0)
	v_mfma_f32_16x16x32_bf16 v[12:15], a[16:19], v[72:75], v[12:15]
	v_mfma_f32_16x16x32_bf16 v[28:31], a[20:23], v[72:75], v[28:31]
	v_mfma_f32_16x16x32_bf16 v[44:47], a[24:27], v[72:75], v[44:47]
	v_mfma_f32_16x16x32_bf16 v[60:63], a[28:31], v[72:75], v[60:63]
	s_setprio 0
	s_waitcnt vmcnt(0) lgkmcnt(0)
	s_barrier
	s_add_u32 s30, s30, 0x100
	s_addc_u32 s31, s31, 0
	s_add_u32 m0, s100, 0x0
	s_nop 0
	global_load_lds_dwordx4 v[68:69], off
	s_add_u32 m0, s100, 0x1000
	s_nop 0
	global_load_lds_dwordx4 v[70:71], off
	s_add_u32 m0, s100, 0x2000
	s_nop 0
	global_load_lds_dwordx4 v[84:85], off
	s_add_u32 m0, s100, 0x3000
	s_nop 0
	global_load_lds_dwordx4 v[86:87], off
	s_add_u32 m0, s100, 0x4000
	s_nop 0
	global_load_lds_dwordx4 v[92:93], off
	s_add_u32 m0, s100, 0x5000
	s_nop 0
	global_load_lds_dwordx4 v[94:95], off
	s_add_u32 m0, s100, 0x6000
	s_nop 0
	global_load_lds_dwordx4 v[88:89], off
	s_add_u32 m0, s100, 0x7000
	s_nop 0
	global_load_lds_dwordx4 v[90:91], off
	ds_read_b128 a[0:3], v104 offset:32768
	ds_read_b128 v[64:67], v107 offset:32768
	ds_read_b128 a[4:7], v104 offset:34816
	ds_read_b128 a[8:11], v104 offset:36864
	ds_read_b128 a[12:15], v104 offset:38912
	ds_read_b128 v[80:83], v107 offset:34816
	ds_read_b128 v[76:79], v107 offset:36864
	ds_read_b128 v[72:75], v107 offset:38912
	ds_read_b128 a[16:19], v105 offset:32768
	ds_read_b128 a[20:23], v105 offset:34816
	ds_read_b128 a[24:27], v105 offset:36864
	ds_read_b128 a[28:31], v105 offset:38912
	s_setprio 1
	s_waitcnt lgkmcnt(10)
	v_mfma_f32_16x16x32_bf16 v[0:3], a[0:3], v[64:67], v[0:3]
	s_waitcnt lgkmcnt(9)
	v_mfma_f32_16x16x32_bf16 v[16:19], a[4:7], v[64:67], v[16:19]
	s_waitcnt lgkmcnt(8)
	v_mfma_f32_16x16x32_bf16 v[32:35], a[8:11], v[64:67], v[32:35]
	s_waitcnt lgkmcnt(7)
	v_mfma_f32_16x16x32_bf16 v[48:51], a[12:15], v[64:67], v[48:51]
	ds_read_b128 v[64:67], v106 offset:32768
	s_waitcnt lgkmcnt(7)
	v_mfma_f32_16x16x32_bf16 v[4:7], a[0:3], v[80:83], v[4:7]
	v_lshl_add_u64 v[120:121], v[96:97], 0, s[30:31]
	v_add_co_u32_e32 v108, vcc, s6, v120
	v_lshl_add_u64 v[122:123], v[98:99], 0, s[30:31]
	v_mfma_f32_16x16x32_bf16 v[20:23], a[4:7], v[80:83], v[20:23]
	s_nop 0
	v_addc_co_u32_e32 v109, vcc, 0, v121, vcc
	v_add_co_u32_e32 v128, vcc, s78, v120
	v_mfma_f32_16x16x32_bf16 v[36:39], a[8:11], v[80:83], v[36:39]
	s_nop 1
	v_addc_co_u32_e32 v129, vcc, 0, v121, vcc
	v_add_co_u32_e32 v130, vcc, s63, v120
	v_mfma_f32_16x16x32_bf16 v[52:55], a[12:15], v[80:83], v[52:55]
	v_addc_co_u32_e32 v131, vcc, 0, v121, vcc
	v_add_co_u32_e32 v132, vcc, s7, v120
	s_nop 1
	ds_read_b128 v[80:83], v106 offset:34816
	s_waitcnt lgkmcnt(7)
	v_mfma_f32_16x16x32_bf16 v[8:11], a[0:3], v[76:79], v[8:11]
	v_addc_co_u32_e32 v133, vcc, 0, v121, vcc
	v_add_co_u32_e32 v134, vcc, s79, v122
	v_addc_co_u32_e32 v135, vcc, 0, v123, vcc
	v_mfma_f32_16x16x32_bf16 v[24:27], a[4:7], v[76:79], v[24:27]
	v_add_co_u32_e32 v144, vcc, s82, v122
	s_nop 1
	v_addc_co_u32_e32 v145, vcc, 0, v123, vcc
	v_mfma_f32_16x16x32_bf16 v[40:43], a[8:11], v[76:79], v[40:43]
	v_add_co_u32_e32 v146, vcc, s2, v122
	v_addc_co_u32_e32 v147, vcc, 0, v123, vcc
	v_add_co_u32_e32 v148, vcc, s17, v122
	v_mfma_f32_16x16x32_bf16 v[56:59], a[12:15], v[76:79], v[56:59]
	s_nop 1
	v_addc_co_u32_e32 v149, vcc, 0, v123, vcc
	v_lshl_add_u64 v[108:109], 8, 4, v[108:109]
	ds_read_b128 v[76:79], v106 offset:36864
	s_waitcnt lgkmcnt(7)
	v_mfma_f32_16x16x32_bf16 v[12:15], a[0:3], v[72:75], v[12:15]
	v_lshl_add_u64 v[128:129], 8, 4, v[128:129]
	v_lshl_add_u64 v[130:131], 8, 4, v[130:131]
	v_lshl_add_u64 v[132:133], 8, 4, v[132:133]
	v_mfma_f32_16x16x32_bf16 v[28:31], a[4:7], v[72:75], v[28:31]
	v_lshl_add_u64 v[134:135], 8, 4, v[134:135]
	v_lshl_add_u64 v[144:145], 8, 4, v[144:145]
	v_lshl_add_u64 v[146:147], 8, 4, v[146:147]
	v_mfma_f32_16x16x32_bf16 v[44:47], a[8:11], v[72:75], v[44:47]
	v_lshl_add_u64 v[148:149], 8, 4, v[148:149]
	v_mfma_f32_16x16x32_bf16 v[60:63], a[12:15], v[72:75], v[60:63]
	ds_read_b128 v[72:75], v106 offset:38912
	s_waitcnt lgkmcnt(3)
	v_mfma_f32_16x16x32_bf16 v[0:3], a[16:19], v[64:67], v[0:3]
	v_mfma_f32_16x16x32_bf16 v[16:19], a[20:23], v[64:67], v[16:19]
	v_mfma_f32_16x16x32_bf16 v[32:35], a[24:27], v[64:67], v[32:35]
	v_mfma_f32_16x16x32_bf16 v[48:51], a[28:31], v[64:67], v[48:51]
	s_waitcnt lgkmcnt(2)
	v_mfma_f32_16x16x32_bf16 v[4:7], a[16:19], v[80:83], v[4:7]
	v_mfma_f32_16x16x32_bf16 v[20:23], a[20:23], v[80:83], v[20:23]
	v_mfma_f32_16x16x32_bf16 v[36:39], a[24:27], v[80:83], v[36:39]
	v_mfma_f32_16x16x32_bf16 v[52:55], a[28:31], v[80:83], v[52:55]
	s_waitcnt lgkmcnt(1)
	v_mfma_f32_16x16x32_bf16 v[8:11], a[16:19], v[76:79], v[8:11]
	v_mfma_f32_16x16x32_bf16 v[24:27], a[20:23], v[76:79], v[24:27]
	v_mfma_f32_16x16x32_bf16 v[40:43], a[24:27], v[76:79], v[40:43]
	v_mfma_f32_16x16x32_bf16 v[56:59], a[28:31], v[76:79], v[56:59]
	s_waitcnt lgkmcnt(0)
	v_mfma_f32_16x16x32_bf16 v[12:15], a[16:19], v[72:75], v[12:15]
	v_mfma_f32_16x16x32_bf16 v[28:31], a[20:23], v[72:75], v[28:31]
	v_mfma_f32_16x16x32_bf16 v[44:47], a[24:27], v[72:75], v[44:47]
	v_mfma_f32_16x16x32_bf16 v[60:63], a[28:31], v[72:75], v[60:63]
	s_setprio 0
	s_waitcnt vmcnt(0) lgkmcnt(0)
	s_barrier
	s_cmpk_eq_i32 s30, 0xf00
	s_cbranch_scc0 .LBB0_981
	v_lshl_add_u64 v[68:69], 8, 4, v[68:69]
	v_lshl_add_u64 v[70:71], 8, 4, v[70:71]
	v_lshl_add_u64 v[84:85], 8, 4, v[84:85]
	v_lshl_add_u64 v[86:87], 8, 4, v[86:87]
	v_lshl_add_u64 v[92:93], 8, 4, v[92:93]
	v_lshl_add_u64 v[94:95], 8, 4, v[94:95]
	v_lshl_add_u64 v[88:89], 8, 4, v[88:89]
	v_lshl_add_u64 v[90:91], 8, 4, v[90:91]
	s_add_u32 m0, s100, 0x8000
	s_nop 0
	global_load_lds_dwordx4 v[68:69], off
	s_add_u32 m0, s100, 0x9000
	s_nop 0
	global_load_lds_dwordx4 v[70:71], off
	s_add_u32 m0, s100, 0xa000
	s_nop 0
	global_load_lds_dwordx4 v[84:85], off
	s_add_u32 m0, s100, 0xb000
	s_nop 0
	global_load_lds_dwordx4 v[86:87], off
	s_add_u32 m0, s100, 0xc000
	s_nop 0
	global_load_lds_dwordx4 v[92:93], off
	s_add_u32 m0, s100, 0xd000
	s_nop 0
	global_load_lds_dwordx4 v[94:95], off
	s_add_u32 m0, s100, 0xe000
	s_nop 0
	global_load_lds_dwordx4 v[88:89], off
	s_add_u32 m0, s100, 0xf000
	s_nop 0
	global_load_lds_dwordx4 v[90:91], off
	ds_read_b128 a[0:3], v104
	ds_read_b128 v[64:67], v107
	ds_read_b128 a[4:7], v104 offset:2048
	ds_read_b128 a[8:11], v104 offset:4096
	ds_read_b128 a[12:15], v104 offset:6144
	ds_read_b128 v[80:83], v107 offset:2048
	ds_read_b128 v[76:79], v107 offset:4096
	ds_read_b128 v[72:75], v107 offset:6144
	ds_read_b128 a[16:19], v105
	ds_read_b128 a[20:23], v105 offset:2048
	ds_read_b128 a[24:27], v105 offset:4096
	ds_read_b128 a[28:31], v105 offset:6144
	s_setprio 1
	s_waitcnt lgkmcnt(10)
	v_mfma_f32_16x16x32_bf16 v[0:3], a[0:3], v[64:67], v[0:3]
	s_waitcnt lgkmcnt(9)
	v_mfma_f32_16x16x32_bf16 v[16:19], a[4:7], v[64:67], v[16:19]
	s_waitcnt lgkmcnt(8)
	v_mfma_f32_16x16x32_bf16 v[32:35], a[8:11], v[64:67], v[32:35]
	s_waitcnt lgkmcnt(7)
	v_mfma_f32_16x16x32_bf16 v[48:51], a[12:15], v[64:67], v[48:51]
	ds_read_b128 v[64:67], v106
	s_waitcnt lgkmcnt(7)
	v_mfma_f32_16x16x32_bf16 v[4:7], a[0:3], v[80:83], v[4:7]
	v_mfma_f32_16x16x32_bf16 v[20:23], a[4:7], v[80:83], v[20:23]
	v_mfma_f32_16x16x32_bf16 v[36:39], a[8:11], v[80:83], v[36:39]
	v_mfma_f32_16x16x32_bf16 v[52:55], a[12:15], v[80:83], v[52:55]
	ds_read_b128 v[80:83], v106 offset:2048
	s_waitcnt lgkmcnt(7)
	v_mfma_f32_16x16x32_bf16 v[8:11], a[0:3], v[76:79], v[8:11]
	v_mfma_f32_16x16x32_bf16 v[24:27], a[4:7], v[76:79], v[24:27]
	v_mfma_f32_16x16x32_bf16 v[40:43], a[8:11], v[76:79], v[40:43]
	v_mfma_f32_16x16x32_bf16 v[56:59], a[12:15], v[76:79], v[56:59]
	ds_read_b128 v[76:79], v106 offset:4096
	s_waitcnt lgkmcnt(7)
	v_mfma_f32_16x16x32_bf16 v[12:15], a[0:3], v[72:75], v[12:15]
	v_mfma_f32_16x16x32_bf16 v[28:31], a[4:7], v[72:75], v[28:31]
	v_mfma_f32_16x16x32_bf16 v[44:47], a[8:11], v[72:75], v[44:47]
	v_mfma_f32_16x16x32_bf16 v[60:63], a[12:15], v[72:75], v[60:63]
	ds_read_b128 v[72:75], v106 offset:6144
	s_waitcnt lgkmcnt(3)
	v_mfma_f32_16x16x32_bf16 v[0:3], a[16:19], v[64:67], v[0:3]
	v_mfma_f32_16x16x32_bf16 v[16:19], a[20:23], v[64:67], v[16:19]
	v_mfma_f32_16x16x32_bf16 v[32:35], a[24:27], v[64:67], v[32:35]
	v_mfma_f32_16x16x32_bf16 v[48:51], a[28:31], v[64:67], v[48:51]
	s_waitcnt lgkmcnt(2)
	v_mfma_f32_16x16x32_bf16 v[4:7], a[16:19], v[80:83], v[4:7]
	v_mfma_f32_16x16x32_bf16 v[20:23], a[20:23], v[80:83], v[20:23]
	v_mfma_f32_16x16x32_bf16 v[36:39], a[24:27], v[80:83], v[36:39]
	v_mfma_f32_16x16x32_bf16 v[52:55], a[28:31], v[80:83], v[52:55]
	s_waitcnt lgkmcnt(1)
	v_mfma_f32_16x16x32_bf16 v[8:11], a[16:19], v[76:79], v[8:11]
	v_mfma_f32_16x16x32_bf16 v[24:27], a[20:23], v[76:79], v[24:27]
	v_mfma_f32_16x16x32_bf16 v[40:43], a[24:27], v[76:79], v[40:43]
	v_mfma_f32_16x16x32_bf16 v[56:59], a[28:31], v[76:79], v[56:59]
	s_waitcnt lgkmcnt(0)
	v_mfma_f32_16x16x32_bf16 v[12:15], a[16:19], v[72:75], v[12:15]
	v_mfma_f32_16x16x32_bf16 v[28:31], a[20:23], v[72:75], v[28:31]
	v_mfma_f32_16x16x32_bf16 v[44:47], a[24:27], v[72:75], v[44:47]
	v_mfma_f32_16x16x32_bf16 v[60:63], a[28:31], v[72:75], v[60:63]
	s_setprio 0
	s_waitcnt vmcnt(0) lgkmcnt(0)
	s_barrier
	ds_read_b128 a[0:3], v104 offset:32768
	ds_read_b128 v[64:67], v107 offset:32768
	ds_read_b128 a[4:7], v104 offset:34816
	ds_read_b128 a[8:11], v104 offset:36864
	ds_read_b128 a[12:15], v104 offset:38912
	ds_read_b128 v[80:83], v107 offset:34816
	ds_read_b128 v[76:79], v107 offset:36864
	ds_read_b128 v[72:75], v107 offset:38912
	ds_read_b128 a[16:19], v105 offset:32768
	ds_read_b128 a[20:23], v105 offset:34816
	ds_read_b128 a[24:27], v105 offset:36864
	ds_read_b128 a[28:31], v105 offset:38912
	s_setprio 1
	s_waitcnt lgkmcnt(10)
	v_mfma_f32_16x16x32_bf16 v[0:3], a[0:3], v[64:67], v[0:3]
	s_waitcnt lgkmcnt(9)
	v_mfma_f32_16x16x32_bf16 v[16:19], a[4:7], v[64:67], v[16:19]
	s_waitcnt lgkmcnt(8)
	v_mfma_f32_16x16x32_bf16 v[32:35], a[8:11], v[64:67], v[32:35]
	s_waitcnt lgkmcnt(7)
	v_mfma_f32_16x16x32_bf16 v[48:51], a[12:15], v[64:67], v[48:51]
	ds_read_b128 v[64:67], v106 offset:32768
	s_waitcnt lgkmcnt(7)
	v_mfma_f32_16x16x32_bf16 v[4:7], a[0:3], v[80:83], v[4:7]
	v_mfma_f32_16x16x32_bf16 v[20:23], a[4:7], v[80:83], v[20:23]
	v_mfma_f32_16x16x32_bf16 v[36:39], a[8:11], v[80:83], v[36:39]
	v_mfma_f32_16x16x32_bf16 v[52:55], a[12:15], v[80:83], v[52:55]
	ds_read_b128 v[80:83], v106 offset:34816
	s_waitcnt lgkmcnt(7)
	v_mfma_f32_16x16x32_bf16 v[8:11], a[0:3], v[76:79], v[8:11]
	v_mfma_f32_16x16x32_bf16 v[24:27], a[4:7], v[76:79], v[24:27]
	v_mfma_f32_16x16x32_bf16 v[40:43], a[8:11], v[76:79], v[40:43]
	v_mfma_f32_16x16x32_bf16 v[56:59], a[12:15], v[76:79], v[56:59]
	ds_read_b128 v[76:79], v106 offset:36864
	s_waitcnt lgkmcnt(7)
	v_mfma_f32_16x16x32_bf16 v[12:15], a[0:3], v[72:75], v[12:15]
	v_mfma_f32_16x16x32_bf16 v[28:31], a[4:7], v[72:75], v[28:31]
	v_mfma_f32_16x16x32_bf16 v[44:47], a[8:11], v[72:75], v[44:47]
	v_mfma_f32_16x16x32_bf16 v[60:63], a[12:15], v[72:75], v[60:63]
	ds_read_b128 v[72:75], v106 offset:38912
	s_waitcnt lgkmcnt(3)
	v_mfma_f32_16x16x32_bf16 v[0:3], a[16:19], v[64:67], v[0:3]
	v_mfma_f32_16x16x32_bf16 v[16:19], a[20:23], v[64:67], v[16:19]
	v_mfma_f32_16x16x32_bf16 v[32:35], a[24:27], v[64:67], v[32:35]
	v_mfma_f32_16x16x32_bf16 v[48:51], a[28:31], v[64:67], v[48:51]
	s_waitcnt lgkmcnt(2)
	v_mfma_f32_16x16x32_bf16 v[4:7], a[16:19], v[80:83], v[4:7]
	v_mfma_f32_16x16x32_bf16 v[20:23], a[20:23], v[80:83], v[20:23]
	v_mfma_f32_16x16x32_bf16 v[36:39], a[24:27], v[80:83], v[36:39]
	v_mfma_f32_16x16x32_bf16 v[52:55], a[28:31], v[80:83], v[52:55]
	s_waitcnt lgkmcnt(1)
	v_mfma_f32_16x16x32_bf16 v[8:11], a[16:19], v[76:79], v[8:11]
	v_mfma_f32_16x16x32_bf16 v[24:27], a[20:23], v[76:79], v[24:27]
	v_mfma_f32_16x16x32_bf16 v[40:43], a[24:27], v[76:79], v[40:43]
	v_mfma_f32_16x16x32_bf16 v[56:59], a[28:31], v[76:79], v[56:59]
	s_waitcnt lgkmcnt(0)
	v_mfma_f32_16x16x32_bf16 v[12:15], a[16:19], v[72:75], v[12:15]
	v_mfma_f32_16x16x32_bf16 v[28:31], a[20:23], v[72:75], v[28:31]
	v_mfma_f32_16x16x32_bf16 v[44:47], a[24:27], v[72:75], v[44:47]
	v_mfma_f32_16x16x32_bf16 v[60:63], a[28:31], v[72:75], v[60:63]
	s_setprio 0
	v_readfirstlane_b32 s8, v113
	v_readfirstlane_b32 s4, v112
	s_lshl_b32 s8, s8, 6
	v_readlane_b32 s9, v219, 3
	s_waitcnt lgkmcnt(0)
	s_barrier
	s_add_i32 s8, s8, s9
	s_lshl_b32 s15, s4, 6
	v_readlane_b32 s4, v219, 2
	s_add_i32 s15, s15, s4
	v_or_b32_e32 v65, s8, v111
	s_movk_i32 s4, 0x800
	v_cmp_gt_i32_e64 s[38:39], s4, v65
	v_add_u32_e32 v64, 0x2800, v65
	v_lshl_or_b32 v66, v110, 2, s15
	s_barrier
	v_and_b32_e32 v116, 15, v143
	v_bfe_u32 v117, v143, 4, 2
	v_xor_b32_e32 v117, v117, v116
	v_lshlrev_b32_e32 v117, 4, v117
	v_lshl_add_u32 v117, v116, 8, v117
	v_lshrrev_b32_e32 v116, 6, v143
	v_lshl_add_u32 v117, v116, 14, v117
	ds_write_b128 v117, v[0:3]
	ds_write_b128 v117, v[4:7] offset:4096
	ds_write_b128 v117, v[8:11] offset:8192
	ds_write_b128 v117, v[12:15] offset:12288
	v_xor_b32_e32 v106, 64, v117
	ds_write_b128 v106, v[16:19]
	ds_write_b128 v106, v[20:23] offset:4096
	ds_write_b128 v106, v[24:27] offset:8192
	ds_write_b128 v106, v[28:31] offset:12288
	v_xor_b32_e32 v106, 128, v117
	ds_write_b128 v106, v[32:35]
	ds_write_b128 v106, v[36:39] offset:4096
	ds_write_b128 v106, v[40:43] offset:8192
	ds_write_b128 v106, v[44:47] offset:12288
	v_xor_b32_e32 v106, 192, v117
	ds_write_b128 v106, v[48:51]
	ds_write_b128 v106, v[52:55] offset:4096
	ds_write_b128 v106, v[56:59] offset:8192
	ds_write_b128 v106, v[60:63] offset:12288
	v_and_b32_e32 v104, 31, v143
	v_bfe_u32 v105, v143, 5, 1
	v_and_b32_e32 v117, 15, v104
	v_xor_b32_e32 v105, v105, v117
	v_lshlrev_b32_e32 v105, 4, v105
	v_lshl_add_u32 v105, v104, 8, v105
	v_lshl_add_u32 v105, v116, 14, v105
	ds_read_b128 v[48:51], v105
	ds_read_b128 v[32:35], v105 offset:8192
	v_xor_b32_e32 v107, 32, v105
	ds_read_b128 v[52:55], v107
	ds_read_b128 v[36:39], v107 offset:8192
	v_xor_b32_e32 v107, 64, v105
	ds_read_b128 v[56:59], v107
	ds_read_b128 v[40:43], v107 offset:8192
	v_xor_b32_e32 v107, 96, v105
	ds_read_b128 v[60:63], v107
	ds_read_b128 v[44:47], v107 offset:8192
	v_xor_b32_e32 v107, 128, v105
	ds_read_b128 v[16:19], v107
	ds_read_b128 v[0:3], v107 offset:8192
	v_xor_b32_e32 v107, 160, v105
	ds_read_b128 v[20:23], v107
	ds_read_b128 v[4:7], v107 offset:8192
	v_xor_b32_e32 v107, 192, v105
	ds_read_b128 v[24:27], v107
	ds_read_b128 v[8:11], v107 offset:8192
	v_xor_b32_e32 v107, 224, v105
	ds_read_b128 v[28:31], v107
	ds_read_b128 v[12:15], v107 offset:8192
	s_waitcnt lgkmcnt(0)
	s_barrier
	s_and_saveexec_b64 s[8:9], s[38:39]
	s_cbranch_execz .LBB0_984
	s_add_i32 s22, s15, 0xffffe000
	s_lshr_b32 s22, s22, 3
	s_ashr_i32 s4, s15, 11
	s_or_b32 s22, s22, 4
	v_mov_b32_e32 v67, s22
	v_mov_b32_e32 v78, s4
	v_cmp_gt_i32_e32 vcc, s51, v66
	v_mov_b32_e32 v71, v140
	v_mov_b32_e32 v73, v140
	v_cndmask_b32_e32 v67, v67, v78, vcc
	v_mad_u64_u32 v[68:69], s[22:23], v67, s69, v[64:65]
	v_mov_b32_e32 v69, v140
	v_lshl_add_u64 v[68:69], v[68:69], 2, s[26:27]
	global_load_dword v67, v[68:69], off
	v_lshl_add_u32 v68, v66, 11, v65
	v_mov_b32_e32 v69, v140
	v_lshl_add_u64 v[76:77], v[68:69], 2, s[0:1]
	v_add_u32_e32 v70, 0x800, v68
	v_add_u32_e32 v72, 0x1000, v68
	v_mov_b32_e32 v75, v140
	v_add_u32_e32 v74, 0x1800, v68
	v_lshl_add_u64 v[68:69], v[70:71], 2, s[0:1]
	v_lshl_add_u64 v[70:71], v[72:73], 2, s[0:1]
	v_lshl_add_u64 v[72:73], v[74:75], 2, s[0:1]
	s_waitcnt vmcnt(0)
	v_mul_f32_e32 v48, v48, v67
	v_mul_f32_e32 v49, v49, v67
	v_mul_f32_e32 v50, v50, v67
	global_atomic_add_f32 v[76:77], v48, off
	global_atomic_add_f32 v[68:69], v49, off
	global_atomic_add_f32 v[70:71], v50, off
	v_mul_f32_e32 v48, v51, v67
	global_atomic_add_f32 v[72:73], v48, off
	s_add_i32 s4, s15, 0xffffe008
	s_lshr_b32 s4, s4, 3
	v_or_b32_e32 v50, 8, v66
	s_or_b32 s4, s4, 4
	v_mov_b32_e32 v48, s4
	v_cmp_gt_i32_e32 vcc, s51, v50
	v_mov_b32_e32 v51, v140
	v_mov_b32_e32 v69, v140
	v_cndmask_b32_e32 v48, v48, v78, vcc
	v_mad_u64_u32 v[48:49], s[22:23], v48, s69, v[64:65]
	v_mov_b32_e32 v49, v140
	v_lshl_add_u64 v[48:49], v[48:49], 2, s[26:27]
	global_load_dword v67, v[48:49], off
	v_mov_b32_e32 v49, v140
	v_lshl_add_u32 v48, v50, 11, v65
	v_lshl_add_u64 v[72:73], v[48:49], 2, s[0:1]
	v_add_u32_e32 v50, 0x800, v48
	v_add_u32_e32 v68, 0x1000, v48
	v_mov_b32_e32 v71, v140
	v_add_u32_e32 v70, 0x1800, v48
	v_lshl_add_u64 v[48:49], v[50:51], 2, s[0:1]
	v_lshl_add_u64 v[50:51], v[68:69], 2, s[0:1]
	v_lshl_add_u64 v[68:69], v[70:71], 2, s[0:1]
	s_waitcnt vmcnt(0)
	v_mul_f32_e32 v52, v52, v67
	v_mul_f32_e32 v53, v53, v67
	v_mul_f32_e32 v54, v54, v67
	global_atomic_add_f32 v[72:73], v52, off
	global_atomic_add_f32 v[48:49], v53, off
	global_atomic_add_f32 v[50:51], v54, off
	v_mul_f32_e32 v48, v55, v67
	global_atomic_add_f32 v[68:69], v48, off
	s_add_i32 s4, s15, 0xffffe010
	s_lshr_b32 s4, s4, 3
	v_or_b32_e32 v50, 16, v66
	s_or_b32 s4, s4, 4
	v_cmp_gt_i32_e32 vcc, s51, v50
	v_mov_b32_e32 v48, s4
	s_nop 0
	v_cndmask_b32_e32 v48, v48, v78, vcc
	v_mad_u64_u32 v[48:49], s[22:23], v48, s69, v[64:65]
	v_mov_b32_e32 v49, v140
	v_lshl_add_u64 v[48:49], v[48:49], 2, s[26:27]
	global_load_dword v52, v[48:49], off
	v_lshl_add_u32 v48, v50, 11, v65
	v_mov_b32_e32 v49, v140
	v_lshl_add_u64 v[50:51], v[48:49], 2, s[0:1]
	s_waitcnt vmcnt(0)
	v_mul_f32_e32 v49, v56, v52
	global_atomic_add_f32 v[50:51], v49, off
	v_add_u32_e32 v50, 0x800, v48
	v_mov_b32_e32 v51, v140
	v_lshl_add_u64 v[50:51], v[50:51], 2, s[0:1]
	v_mul_f32_e32 v49, v57, v52
	global_atomic_add_f32 v[50:51], v49, off
	v_add_u32_e32 v50, 0x1000, v48
	v_mov_b32_e32 v51, v140
	v_lshl_add_u64 v[50:51], v[50:51], 2, s[0:1]
	v_mul_f32_e32 v49, v58, v52
	global_atomic_add_f32 v[50:51], v49, off
	v_add_u32_e32 v48, 0x1800, v48
	v_mov_b32_e32 v49, v140
	v_lshl_add_u64 v[48:49], v[48:49], 2, s[0:1]
	v_mul_f32_e32 v50, v59, v52
	global_atomic_add_f32 v[48:49], v50, off
	s_add_i32 s4, s15, 0xffffe018
	s_lshr_b32 s4, s4, 3
	v_or_b32_e32 v50, 24, v66
	s_or_b32 s4, s4, 4
	v_mov_b32_e32 v48, s4
	v_cmp_gt_i32_e32 vcc, s51, v50
	v_mov_b32_e32 v51, v140
	v_mov_b32_e32 v53, v140
	v_cndmask_b32_e32 v48, v48, v78, vcc
	v_mad_u64_u32 v[48:49], s[22:23], v48, s69, v[64:65]
	v_mov_b32_e32 v49, v140
	v_lshl_add_u64 v[48:49], v[48:49], 2, s[26:27]
	global_load_dword v58, v[48:49], off
	v_lshl_add_u32 v48, v50, 11, v65
	v_mov_b32_e32 v49, v140
	v_mov_b32_e32 v55, v140
	v_add_u32_e32 v50, 0x800, v48
	v_add_u32_e32 v52, 0x1000, v48
	v_add_u32_e32 v54, 0x1800, v48
	v_lshl_add_u64 v[56:57], v[48:49], 2, s[0:1]
	v_lshl_add_u64 v[48:49], v[50:51], 2, s[0:1]
	v_lshl_add_u64 v[50:51], v[52:53], 2, s[0:1]
	v_lshl_add_u64 v[52:53], v[54:55], 2, s[0:1]
	s_waitcnt vmcnt(0)
	v_mul_f32_e32 v54, v60, v58
	v_mul_f32_e32 v55, v61, v58
	v_mul_f32_e32 v59, v62, v58
	global_atomic_add_f32 v[56:57], v54, off
	global_atomic_add_f32 v[48:49], v55, off
	global_atomic_add_f32 v[50:51], v59, off
	v_mul_f32_e32 v48, v63, v58
	global_atomic_add_f32 v[52:53], v48, off

.LBB0_1005:
	s_mul_hi_i32 s4, s22, 0x38e38e39
	s_lshr_b32 s8, s4, 31
	s_ashr_i32 s4, s4, 4
	s_add_i32 s4, s4, s8
	s_mul_i32 s8, s4, 0x48
	s_sub_i32 s8, s22, s8
	v_lshl_add_u32 v0, s8, 7, v111
	v_ashrrev_i32_e32 v1, 31, v0
	v_lshlrev_b64 v[32:33], 12, v[0:1]
	v_lshl_add_u64 v[34:35], v[96:97], 0, v[32:33]
	v_add_co_u32_e32 v40, vcc, s87, v34
	s_lshl_b32 s9, s4, 7
	s_nop 0
	v_addc_co_u32_e32 v41, vcc, 0, v35, vcc
	v_add_co_u32_e32 v42, vcc, s66, v34
	v_add_u32_e32 v0, s9, v111
	s_nop 0
	v_addc_co_u32_e32 v43, vcc, 0, v35, vcc
	v_ashrrev_i32_e32 v1, 31, v0
	v_add_co_u32_e32 v44, vcc, s20, v34
	v_lshlrev_b64 v[36:37], 12, v[0:1]
	s_nop 0
	v_addc_co_u32_e32 v45, vcc, 0, v35, vcc
	v_lshl_add_u64 v[38:39], v[98:99], 0, v[36:37]
	v_readfirstlane_b32 s100, v112
	s_nop 3
	s_add_u32 m0, s100, 0x0
	s_nop 0
	global_load_lds_dwordx4 v[34:35], off
	s_add_u32 m0, s100, 0x1000
	s_nop 0
	global_load_lds_dwordx4 v[40:41], off
	s_add_u32 m0, s100, 0x2000
	s_nop 0
	global_load_lds_dwordx4 v[42:43], off
	s_add_u32 m0, s100, 0x3000
	s_nop 0
	global_load_lds_dwordx4 v[44:45], off
	s_add_u32 m0, s100, 0x4000
	s_nop 0
	global_load_lds_dwordx4 v[38:39], off
	v_add_co_u32_e32 v46, vcc, s87, v38
	v_lshl_add_u64 v[104:105], v[100:101], 0, v[36:37]
	s_nop 0
	v_addc_co_u32_e32 v47, vcc, 0, v39, vcc
	s_waitcnt vmcnt(16)
	v_add_co_u32_e32 v48, vcc, s66, v38
	s_add_u32 m0, s100, 0x5000
	s_nop 0
	global_load_lds_dwordx4 v[46:47], off
	s_nop 0
	v_addc_co_u32_e32 v49, vcc, 0, v39, vcc
	v_add_co_u32_e32 v50, vcc, s20, v38
	s_add_u32 m0, s100, 0x6000
	s_nop 0
	global_load_lds_dwordx4 v[48:49], off
	s_nop 0
	v_addc_co_u32_e32 v51, vcc, 0, v39, vcc
	s_add_u32 m0, s100, 0x7000
	s_nop 0
	global_load_lds_dwordx4 v[50:51], off
	v_lshl_add_u64 v[106:107], v[102:103], 0, v[32:33]
	s_mov_b64 s[30:31], 0
	v_mov_b32_e32 v0, 0
	v_mov_b32_e32 v1, v0
	v_mov_b32_e32 v2, v0
	v_mov_b32_e32 v3, v0
	v_mov_b32_e32 v4, v0
	v_mov_b32_e32 v5, v0
	v_mov_b32_e32 v6, v0
	v_mov_b32_e32 v7, v0
	v_mov_b32_e32 v8, v0
	v_mov_b32_e32 v9, v0
	v_mov_b32_e32 v10, v0
	v_mov_b32_e32 v11, v0
	v_mov_b32_e32 v12, v0
	v_mov_b32_e32 v13, v0
	v_mov_b32_e32 v14, v0
	v_mov_b32_e32 v15, v0
	v_mov_b32_e32 v16, v0
	v_mov_b32_e32 v17, v0
	v_mov_b32_e32 v18, v0
	v_mov_b32_e32 v19, v0
	v_mov_b32_e32 v20, v0
	v_mov_b32_e32 v21, v0
	v_mov_b32_e32 v22, v0
	v_mov_b32_e32 v23, v0
	v_mov_b32_e32 v24, v0
	v_mov_b32_e32 v25, v0
	v_mov_b32_e32 v26, v0
	v_mov_b32_e32 v27, v0
	v_mov_b32_e32 v28, v0
	v_mov_b32_e32 v29, v0
	v_mov_b32_e32 v30, v0
	v_mov_b32_e32 v31, v0
	v_mov_b32_e32 v32, v0
	v_mov_b32_e32 v33, v0
	v_mov_b32_e32 v34, v0
	v_mov_b32_e32 v35, v0
	v_mov_b32_e32 v36, v0
	v_mov_b32_e32 v37, v0
	v_mov_b32_e32 v38, v0
	v_mov_b32_e32 v39, v0
	v_mov_b32_e32 v40, v0
	v_mov_b32_e32 v41, v0
	v_mov_b32_e32 v42, v0
	v_mov_b32_e32 v43, v0
	v_mov_b32_e32 v44, v0
	v_mov_b32_e32 v45, v0
	v_mov_b32_e32 v46, v0
	v_mov_b32_e32 v47, v0
	v_mov_b32_e32 v48, v0
	v_mov_b32_e32 v49, v0
	v_mov_b32_e32 v50, v0
	v_mov_b32_e32 v51, v0
	v_mov_b32_e32 v52, v0
	v_mov_b32_e32 v53, v0
	v_mov_b32_e32 v54, v0
	v_mov_b32_e32 v55, v0
	v_mov_b32_e32 v56, v0
	v_mov_b32_e32 v57, v0
	v_mov_b32_e32 v58, v0
	v_mov_b32_e32 v59, v0
	v_mov_b32_e32 v60, v0
	v_mov_b32_e32 v61, v0
	v_mov_b32_e32 v62, v0
	v_mov_b32_e32 v63, v0
	v_lshl_add_u64 v[130:131], v[106:107], 0, s[30:31]
	v_add_co_u32_e32 v134, vcc, s21, v130
	v_lshl_add_u64 v[132:133], v[104:105], 0, s[30:31]
	s_nop 0
	v_addc_co_u32_e32 v135, vcc, 0, v131, vcc
	v_add_co_u32_e32 v148, vcc, s74, v130
	s_mov_b32 s4, 0x2eb80000
	s_nop 0
	v_addc_co_u32_e32 v149, vcc, 0, v131, vcc
	v_add_co_u32_e32 v150, vcc, s75, v130
	v_addc_co_u32_e32 v151, vcc, 0, v131, vcc
	v_add_co_u32_e32 v152, vcc, s14, v130
	s_nop 1
	v_addc_co_u32_e32 v153, vcc, 0, v131, vcc
	v_add_co_u32_e32 v154, vcc, s4, v132
	s_mov_b32 s4, 0x2eba0000
	s_nop 0
	v_addc_co_u32_e32 v155, vcc, 0, v133, vcc
	v_add_co_u32_e32 v156, vcc, s4, v132
	s_mov_b32 s4, 0x2ebc0000
	s_nop 0
	v_addc_co_u32_e32 v157, vcc, 0, v133, vcc
	v_add_co_u32_e32 v178, vcc, s4, v132
	s_mov_b32 s4, 0x2ebe0000
	s_nop 0
	v_addc_co_u32_e32 v179, vcc, 0, v133, vcc
	v_add_co_u32_e32 v180, vcc, s4, v132
	v_addc_co_u32_e32 v181, vcc, 0, v133, vcc
	v_lshl_add_u64 v[134:135], 8, 4, v[134:135]
	v_lshl_add_u64 v[148:149], 8, 4, v[148:149]
	v_lshl_add_u64 v[150:151], 8, 4, v[150:151]
	v_lshl_add_u64 v[152:153], 8, 4, v[152:153]
	v_lshl_add_u64 v[154:155], 8, 4, v[154:155]
	v_lshl_add_u64 v[156:157], 8, 4, v[156:157]
	v_lshl_add_u64 v[178:179], 8, 4, v[178:179]
	v_lshl_add_u64 v[180:181], 8, 4, v[180:181]
	v_and_b32_e32 v126, 15, v143
	v_lshrrev_b32_e32 v127, 1, v126
	v_bfe_u32 v120, v143, 4, 2
	v_xor_b32_e32 v127, v127, v120
	v_lshlrev_b32_e32 v127, 4, v127
	v_lshl_add_u32 v127, v126, 7, v127
	v_lshrrev_b32_e32 v126, 6, v143
	v_lshrrev_b32_e32 v118, 1, v126
	v_and_b32_e32 v126, 1, v126
	v_lshl_add_u32 v118, v118, 13, v127
	v_lshl_add_u32 v119, v126, 13, v127
	v_add_u32_e32 v119, 0x4000, v119
	v_xor_b32_e32 v120, 64, v118
	v_xor_b32_e32 v121, 64, v119
	s_waitcnt vmcnt(0) lgkmcnt(0)
	s_barrier
.LBB0_1006:
	s_add_u32 m0, s100, 0x8000
	s_nop 0
	global_load_lds_dwordx4 v[134:135], off
	s_add_u32 m0, s100, 0x9000
	s_nop 0
	global_load_lds_dwordx4 v[148:149], off
	s_add_u32 m0, s100, 0xa000
	s_nop 0
	global_load_lds_dwordx4 v[150:151], off
	s_add_u32 m0, s100, 0xb000
	s_nop 0
	global_load_lds_dwordx4 v[152:153], off
	s_add_u32 m0, s100, 0xc000
	s_nop 0
	global_load_lds_dwordx4 v[154:155], off
	s_add_u32 m0, s100, 0xd000
	s_nop 0
	global_load_lds_dwordx4 v[156:157], off
	s_add_u32 m0, s100, 0xe000
	s_nop 0
	global_load_lds_dwordx4 v[178:179], off
	s_add_u32 m0, s100, 0xf000
	s_nop 0
	global_load_lds_dwordx4 v[180:181], off
	ds_read_b128 a[0:3], v118
	ds_read_b128 v[80:83], v119
	ds_read_b128 a[4:7], v118 offset:2048
	ds_read_b128 a[8:11], v118 offset:4096
	ds_read_b128 a[12:15], v118 offset:6144
	ds_read_b128 v[92:95], v119 offset:2048
	ds_read_b128 v[88:91], v119 offset:4096
	ds_read_b128 v[84:87], v119 offset:6144
	ds_read_b128 a[16:19], v120
	ds_read_b128 a[20:23], v120 offset:2048
	ds_read_b128 a[24:27], v120 offset:4096
	ds_read_b128 a[28:31], v120 offset:6144
	s_setprio 1
	s_waitcnt lgkmcnt(10)
	v_mfma_f32_16x16x32_bf16 v[0:3], a[0:3], v[80:83], v[0:3]
	s_waitcnt lgkmcnt(9)
	v_mfma_f32_16x16x32_bf16 v[16:19], a[4:7], v[80:83], v[16:19]
	s_waitcnt lgkmcnt(8)
	v_mfma_f32_16x16x32_bf16 v[32:35], a[8:11], v[80:83], v[32:35]
	s_waitcnt lgkmcnt(7)
	v_mfma_f32_16x16x32_bf16 v[48:51], a[12:15], v[80:83], v[48:51]
	ds_read_b128 v[80:83], v121
	s_waitcnt lgkmcnt(7)
	v_mfma_f32_16x16x32_bf16 v[4:7], a[0:3], v[92:95], v[4:7]
	v_lshl_add_u64 v[64:65], 8, 4, v[134:135]
	v_lshl_add_u64 v[66:67], 8, 4, v[148:149]
	v_lshl_add_u64 v[68:69], 8, 4, v[150:151]
	v_mfma_f32_16x16x32_bf16 v[20:23], a[4:7], v[92:95], v[20:23]
	v_lshl_add_u64 v[70:71], 8, 4, v[152:153]
	v_lshl_add_u64 v[76:77], 8, 4, v[154:155]
	v_lshl_add_u64 v[78:79], 8, 4, v[156:157]
	v_mfma_f32_16x16x32_bf16 v[36:39], a[8:11], v[92:95], v[36:39]
	v_lshl_add_u64 v[72:73], 8, 4, v[178:179]
	v_lshl_add_u64 v[74:75], 8, 4, v[180:181]
	v_mfma_f32_16x16x32_bf16 v[52:55], a[12:15], v[92:95], v[52:55]
	ds_read_b128 v[92:95], v121 offset:2048
	s_waitcnt lgkmcnt(7)
	v_mfma_f32_16x16x32_bf16 v[8:11], a[0:3], v[88:91], v[8:11]
	v_mfma_f32_16x16x32_bf16 v[24:27], a[4:7], v[88:91], v[24:27]
	v_mfma_f32_16x16x32_bf16 v[40:43], a[8:11], v[88:91], v[40:43]
	v_mfma_f32_16x16x32_bf16 v[56:59], a[12:15], v[88:91], v[56:59]
	ds_read_b128 v[88:91], v121 offset:4096
	s_waitcnt lgkmcnt(7)
	v_mfma_f32_16x16x32_bf16 v[12:15], a[0:3], v[84:87], v[12:15]
	v_mfma_f32_16x16x32_bf16 v[28:31], a[4:7], v[84:87], v[28:31]
	v_mfma_f32_16x16x32_bf16 v[44:47], a[8:11], v[84:87], v[44:47]
	v_mfma_f32_16x16x32_bf16 v[60:63], a[12:15], v[84:87], v[60:63]
	ds_read_b128 v[84:87], v121 offset:6144
	s_waitcnt lgkmcnt(3)
	v_mfma_f32_16x16x32_bf16 v[0:3], a[16:19], v[80:83], v[0:3]
	v_mfma_f32_16x16x32_bf16 v[16:19], a[20:23], v[80:83], v[16:19]
	v_mfma_f32_16x16x32_bf16 v[32:35], a[24:27], v[80:83], v[32:35]
	v_mfma_f32_16x16x32_bf16 v[48:51], a[28:31], v[80:83], v[48:51]
	s_waitcnt lgkmcnt(2)
	v_mfma_f32_16x16x32_bf16 v[4:7], a[16:19], v[92:95], v[4:7]
	v_mfma_f32_16x16x32_bf16 v[20:23], a[20:23], v[92:95], v[20:23]
	v_mfma_f32_16x16x32_bf16 v[36:39], a[24:27], v[92:95], v[36:39]
	v_mfma_f32_16x16x32_bf16 v[52:55], a[28:31], v[92:95], v[52:55]
	s_waitcnt lgkmcnt(1)
	v_mfma_f32_16x16x32_bf16 v[8:11], a[16:19], v[88:91], v[8:11]
	v_mfma_f32_16x16x32_bf16 v[24:27], a[20:23], v[88:91], v[24:27]
	v_mfma_f32_16x16x32_bf16 v[40:43], a[24:27], v[88:91], v[40:43]
	v_mfma_f32_16x16x32_bf16 v[56:59], a[28:31], v[88:91], v[56:59]
	s_waitcnt lgkmcnt(0)
	v_mfma_f32_16x16x32_bf16 v[12:15], a[16:19], v[84:87], v[12:15]
	v_mfma_f32_16x16x32_bf16 v[28:31], a[20:23], v[84:87], v[28:31]
	v_mfma_f32_16x16x32_bf16 v[44:47], a[24:27], v[84:87], v[44:47]
	v_mfma_f32_16x16x32_bf16 v[60:63], a[28:31], v[84:87], v[60:63]
	s_setprio 0
	s_waitcnt vmcnt(0) lgkmcnt(0)
	s_barrier
	s_add_u32 s30, s30, 0x100
	s_addc_u32 s31, s31, 0
	s_add_u32 m0, s100, 0x0
	s_nop 0
	global_load_lds_dwordx4 v[64:65], off
	s_add_u32 m0, s100, 0x1000
	s_nop 0
	global_load_lds_dwordx4 v[66:67], off
	s_add_u32 m0, s100, 0x2000
	s_nop 0
	global_load_lds_dwordx4 v[68:69], off
	s_add_u32 m0, s100, 0x3000
	s_nop 0
	global_load_lds_dwordx4 v[70:71], off
	s_add_u32 m0, s100, 0x4000
	s_nop 0
	global_load_lds_dwordx4 v[76:77], off
	s_add_u32 m0, s100, 0x5000
	s_nop 0
	global_load_lds_dwordx4 v[78:79], off
	s_add_u32 m0, s100, 0x6000
	s_nop 0
	global_load_lds_dwordx4 v[72:73], off
	s_add_u32 m0, s100, 0x7000
	s_nop 0
	global_load_lds_dwordx4 v[74:75], off
	ds_read_b128 a[0:3], v118 offset:32768
	ds_read_b128 v[80:83], v119 offset:32768
	ds_read_b128 a[4:7], v118 offset:34816
	ds_read_b128 a[8:11], v118 offset:36864
	ds_read_b128 a[12:15], v118 offset:38912
	ds_read_b128 v[92:95], v119 offset:34816
	ds_read_b128 v[88:91], v119 offset:36864
	ds_read_b128 v[84:87], v119 offset:38912
	ds_read_b128 a[16:19], v120 offset:32768
	ds_read_b128 a[20:23], v120 offset:34816
	ds_read_b128 a[24:27], v120 offset:36864
	ds_read_b128 a[28:31], v120 offset:38912
	s_setprio 1
	s_waitcnt lgkmcnt(10)
	v_mfma_f32_16x16x32_bf16 v[0:3], a[0:3], v[80:83], v[0:3]
	s_waitcnt lgkmcnt(9)
	v_mfma_f32_16x16x32_bf16 v[16:19], a[4:7], v[80:83], v[16:19]
	s_waitcnt lgkmcnt(8)
	v_mfma_f32_16x16x32_bf16 v[32:35], a[8:11], v[80:83], v[32:35]
	s_waitcnt lgkmcnt(7)
	v_mfma_f32_16x16x32_bf16 v[48:51], a[12:15], v[80:83], v[48:51]
	ds_read_b128 v[80:83], v121 offset:32768
	s_waitcnt lgkmcnt(7)
	v_mfma_f32_16x16x32_bf16 v[4:7], a[0:3], v[92:95], v[4:7]
	v_lshl_add_u64 v[130:131], v[106:107], 0, s[30:31]
	v_add_co_u32_e32 v134, vcc, s21, v130
	v_lshl_add_u64 v[132:133], v[104:105], 0, s[30:31]
	v_mfma_f32_16x16x32_bf16 v[20:23], a[4:7], v[92:95], v[20:23]
	s_nop 0
	v_addc_co_u32_e32 v135, vcc, 0, v131, vcc
	v_add_co_u32_e32 v148, vcc, s74, v130
	v_mfma_f32_16x16x32_bf16 v[36:39], a[8:11], v[92:95], v[36:39]
	s_mov_b32 s4, 0x2eb80000
	s_nop 0
	v_addc_co_u32_e32 v149, vcc, 0, v131, vcc
	v_mfma_f32_16x16x32_bf16 v[52:55], a[12:15], v[92:95], v[52:55]
	v_add_co_u32_e32 v150, vcc, s75, v130
	v_addc_co_u32_e32 v151, vcc, 0, v131, vcc
	v_add_co_u32_e32 v152, vcc, s14, v130
	ds_read_b128 v[92:95], v121 offset:34816
	s_waitcnt lgkmcnt(7)
	v_mfma_f32_16x16x32_bf16 v[8:11], a[0:3], v[88:91], v[8:11]
	s_nop 1
	v_addc_co_u32_e32 v153, vcc, 0, v131, vcc
	v_add_co_u32_e32 v154, vcc, s4, v132
	v_mfma_f32_16x16x32_bf16 v[24:27], a[4:7], v[88:91], v[24:27]
	s_mov_b32 s4, 0x2eba0000
	s_nop 0
	v_addc_co_u32_e32 v155, vcc, 0, v133, vcc
	v_mfma_f32_16x16x32_bf16 v[40:43], a[8:11], v[88:91], v[40:43]
	v_add_co_u32_e32 v156, vcc, s4, v132
	s_mov_b32 s4, 0x2ebc0000
	s_nop 0
	v_mfma_f32_16x16x32_bf16 v[56:59], a[12:15], v[88:91], v[56:59]
	v_addc_co_u32_e32 v157, vcc, 0, v133, vcc
	v_add_co_u32_e32 v178, vcc, s4, v132
	s_mov_b32 s4, 0x2ebe0000
	ds_read_b128 v[88:91], v121 offset:36864
	s_waitcnt lgkmcnt(7)
	v_mfma_f32_16x16x32_bf16 v[12:15], a[0:3], v[84:87], v[12:15]
	s_nop 0
	v_addc_co_u32_e32 v179, vcc, 0, v133, vcc
	v_add_co_u32_e32 v180, vcc, s4, v132
	v_mfma_f32_16x16x32_bf16 v[28:31], a[4:7], v[84:87], v[28:31]
	v_addc_co_u32_e32 v181, vcc, 0, v133, vcc
	v_lshl_add_u64 v[134:135], 8, 4, v[134:135]
	v_lshl_add_u64 v[148:149], 8, 4, v[148:149]
	v_mfma_f32_16x16x32_bf16 v[44:47], a[8:11], v[84:87], v[44:47]
	v_lshl_add_u64 v[150:151], 8, 4, v[150:151]
	v_lshl_add_u64 v[152:153], 8, 4, v[152:153]
	v_lshl_add_u64 v[154:155], 8, 4, v[154:155]
	v_mfma_f32_16x16x32_bf16 v[60:63], a[12:15], v[84:87], v[60:63]
	v_lshl_add_u64 v[156:157], 8, 4, v[156:157]
	v_lshl_add_u64 v[178:179], 8, 4, v[178:179]
	v_lshl_add_u64 v[180:181], 8, 4, v[180:181]
	ds_read_b128 v[84:87], v121 offset:38912
	s_waitcnt lgkmcnt(3)
	v_mfma_f32_16x16x32_bf16 v[0:3], a[16:19], v[80:83], v[0:3]
	v_mfma_f32_16x16x32_bf16 v[16:19], a[20:23], v[80:83], v[16:19]
	v_mfma_f32_16x16x32_bf16 v[32:35], a[24:27], v[80:83], v[32:35]
	v_mfma_f32_16x16x32_bf16 v[48:51], a[28:31], v[80:83], v[48:51]
	s_waitcnt lgkmcnt(2)
	v_mfma_f32_16x16x32_bf16 v[4:7], a[16:19], v[92:95], v[4:7]
	v_mfma_f32_16x16x32_bf16 v[20:23], a[20:23], v[92:95], v[20:23]
	v_mfma_f32_16x16x32_bf16 v[36:39], a[24:27], v[92:95], v[36:39]
	v_mfma_f32_16x16x32_bf16 v[52:55], a[28:31], v[92:95], v[52:55]
	s_waitcnt lgkmcnt(1)
	v_mfma_f32_16x16x32_bf16 v[8:11], a[16:19], v[88:91], v[8:11]
	v_mfma_f32_16x16x32_bf16 v[24:27], a[20:23], v[88:91], v[24:27]
	v_mfma_f32_16x16x32_bf16 v[40:43], a[24:27], v[88:91], v[40:43]
	v_mfma_f32_16x16x32_bf16 v[56:59], a[28:31], v[88:91], v[56:59]
	s_waitcnt lgkmcnt(0)
	v_mfma_f32_16x16x32_bf16 v[12:15], a[16:19], v[84:87], v[12:15]
	v_mfma_f32_16x16x32_bf16 v[28:31], a[20:23], v[84:87], v[28:31]
	v_mfma_f32_16x16x32_bf16 v[44:47], a[24:27], v[84:87], v[44:47]
	v_mfma_f32_16x16x32_bf16 v[60:63], a[28:31], v[84:87], v[60:63]
	s_setprio 0
	s_waitcnt vmcnt(0) lgkmcnt(0)
	s_barrier
	s_cmpk_eq_i32 s30, 0xf00
	s_cbranch_scc0 .LBB0_1006
	v_lshl_add_u64 v[64:65], 8, 4, v[64:65]
	v_lshl_add_u64 v[66:67], 8, 4, v[66:67]
	v_lshl_add_u64 v[68:69], 8, 4, v[68:69]
	v_lshl_add_u64 v[70:71], 8, 4, v[70:71]
	v_lshl_add_u64 v[76:77], 8, 4, v[76:77]
	v_lshl_add_u64 v[78:79], 8, 4, v[78:79]
	v_lshl_add_u64 v[72:73], 8, 4, v[72:73]
	v_lshl_add_u64 v[74:75], 8, 4, v[74:75]
	s_add_u32 m0, s100, 0x8000
	s_nop 0
	global_load_lds_dwordx4 v[64:65], off
	s_add_u32 m0, s100, 0x9000
	s_nop 0
	global_load_lds_dwordx4 v[66:67], off
	s_add_u32 m0, s100, 0xa000
	s_nop 0
	global_load_lds_dwordx4 v[68:69], off
	s_add_u32 m0, s100, 0xb000
	s_nop 0
	global_load_lds_dwordx4 v[70:71], off
	s_add_u32 m0, s100, 0xc000
	s_nop 0
	global_load_lds_dwordx4 v[76:77], off
	s_add_u32 m0, s100, 0xd000
	s_nop 0
	global_load_lds_dwordx4 v[78:79], off
	s_add_u32 m0, s100, 0xe000
	s_nop 0
	global_load_lds_dwordx4 v[72:73], off
	s_add_u32 m0, s100, 0xf000
	s_nop 0
	global_load_lds_dwordx4 v[74:75], off
	ds_read_b128 a[0:3], v118
	ds_read_b128 v[80:83], v119
	ds_read_b128 a[4:7], v118 offset:2048
	ds_read_b128 a[8:11], v118 offset:4096
	ds_read_b128 a[12:15], v118 offset:6144
	ds_read_b128 v[92:95], v119 offset:2048
	ds_read_b128 v[88:91], v119 offset:4096
	ds_read_b128 v[84:87], v119 offset:6144
	ds_read_b128 a[16:19], v120
	ds_read_b128 a[20:23], v120 offset:2048
	ds_read_b128 a[24:27], v120 offset:4096
	ds_read_b128 a[28:31], v120 offset:6144
	s_setprio 1
	s_waitcnt lgkmcnt(10)
	v_mfma_f32_16x16x32_bf16 v[0:3], a[0:3], v[80:83], v[0:3]
	s_waitcnt lgkmcnt(9)
	v_mfma_f32_16x16x32_bf16 v[16:19], a[4:7], v[80:83], v[16:19]
	s_waitcnt lgkmcnt(8)
	v_mfma_f32_16x16x32_bf16 v[32:35], a[8:11], v[80:83], v[32:35]
	s_waitcnt lgkmcnt(7)
	v_mfma_f32_16x16x32_bf16 v[48:51], a[12:15], v[80:83], v[48:51]
	ds_read_b128 v[80:83], v121
	s_waitcnt lgkmcnt(7)
	v_mfma_f32_16x16x32_bf16 v[4:7], a[0:3], v[92:95], v[4:7]
	v_mfma_f32_16x16x32_bf16 v[20:23], a[4:7], v[92:95], v[20:23]
	v_mfma_f32_16x16x32_bf16 v[36:39], a[8:11], v[92:95], v[36:39]
	v_mfma_f32_16x16x32_bf16 v[52:55], a[12:15], v[92:95], v[52:55]
	ds_read_b128 v[92:95], v121 offset:2048
	s_waitcnt lgkmcnt(7)
	v_mfma_f32_16x16x32_bf16 v[8:11], a[0:3], v[88:91], v[8:11]
	v_mfma_f32_16x16x32_bf16 v[24:27], a[4:7], v[88:91], v[24:27]
	v_mfma_f32_16x16x32_bf16 v[40:43], a[8:11], v[88:91], v[40:43]
	v_mfma_f32_16x16x32_bf16 v[56:59], a[12:15], v[88:91], v[56:59]
	ds_read_b128 v[88:91], v121 offset:4096
	s_waitcnt lgkmcnt(7)
	v_mfma_f32_16x16x32_bf16 v[12:15], a[0:3], v[84:87], v[12:15]
	v_mfma_f32_16x16x32_bf16 v[28:31], a[4:7], v[84:87], v[28:31]
	v_mfma_f32_16x16x32_bf16 v[44:47], a[8:11], v[84:87], v[44:47]
	v_mfma_f32_16x16x32_bf16 v[60:63], a[12:15], v[84:87], v[60:63]
	ds_read_b128 v[84:87], v121 offset:6144
	s_waitcnt lgkmcnt(3)
	v_mfma_f32_16x16x32_bf16 v[0:3], a[16:19], v[80:83], v[0:3]
	v_mfma_f32_16x16x32_bf16 v[16:19], a[20:23], v[80:83], v[16:19]
	v_mfma_f32_16x16x32_bf16 v[32:35], a[24:27], v[80:83], v[32:35]
	v_mfma_f32_16x16x32_bf16 v[48:51], a[28:31], v[80:83], v[48:51]
	s_waitcnt lgkmcnt(2)
	v_mfma_f32_16x16x32_bf16 v[4:7], a[16:19], v[92:95], v[4:7]
	v_mfma_f32_16x16x32_bf16 v[20:23], a[20:23], v[92:95], v[20:23]
	v_mfma_f32_16x16x32_bf16 v[36:39], a[24:27], v[92:95], v[36:39]
	v_mfma_f32_16x16x32_bf16 v[52:55], a[28:31], v[92:95], v[52:55]
	s_waitcnt lgkmcnt(1)
	v_mfma_f32_16x16x32_bf16 v[8:11], a[16:19], v[88:91], v[8:11]
	v_mfma_f32_16x16x32_bf16 v[24:27], a[20:23], v[88:91], v[24:27]
	v_mfma_f32_16x16x32_bf16 v[40:43], a[24:27], v[88:91], v[40:43]
	v_mfma_f32_16x16x32_bf16 v[56:59], a[28:31], v[88:91], v[56:59]
	s_waitcnt lgkmcnt(0)
	v_mfma_f32_16x16x32_bf16 v[12:15], a[16:19], v[84:87], v[12:15]
	v_mfma_f32_16x16x32_bf16 v[28:31], a[20:23], v[84:87], v[28:31]
	v_mfma_f32_16x16x32_bf16 v[44:47], a[24:27], v[84:87], v[44:47]
	v_mfma_f32_16x16x32_bf16 v[60:63], a[28:31], v[84:87], v[60:63]
	s_setprio 0
	s_waitcnt vmcnt(0) lgkmcnt(0)
	s_barrier
	ds_read_b128 a[0:3], v118 offset:32768
	ds_read_b128 v[80:83], v119 offset:32768
	ds_read_b128 a[4:7], v118 offset:34816
	ds_read_b128 a[8:11], v118 offset:36864
	ds_read_b128 a[12:15], v118 offset:38912
	ds_read_b128 v[92:95], v119 offset:34816
	ds_read_b128 v[88:91], v119 offset:36864
	ds_read_b128 v[84:87], v119 offset:38912
	ds_read_b128 a[16:19], v120 offset:32768
	ds_read_b128 a[20:23], v120 offset:34816
	ds_read_b128 a[24:27], v120 offset:36864
	ds_read_b128 a[28:31], v120 offset:38912
	s_setprio 1
	s_waitcnt lgkmcnt(10)
	v_mfma_f32_16x16x32_bf16 v[0:3], a[0:3], v[80:83], v[0:3]
	s_waitcnt lgkmcnt(9)
	v_mfma_f32_16x16x32_bf16 v[16:19], a[4:7], v[80:83], v[16:19]
	s_waitcnt lgkmcnt(8)
	v_mfma_f32_16x16x32_bf16 v[32:35], a[8:11], v[80:83], v[32:35]
	s_waitcnt lgkmcnt(7)
	v_mfma_f32_16x16x32_bf16 v[48:51], a[12:15], v[80:83], v[48:51]
	ds_read_b128 v[80:83], v121 offset:32768
	s_waitcnt lgkmcnt(7)
	v_mfma_f32_16x16x32_bf16 v[4:7], a[0:3], v[92:95], v[4:7]
	v_mfma_f32_16x16x32_bf16 v[20:23], a[4:7], v[92:95], v[20:23]
	v_mfma_f32_16x16x32_bf16 v[36:39], a[8:11], v[92:95], v[36:39]
	v_mfma_f32_16x16x32_bf16 v[52:55], a[12:15], v[92:95], v[52:55]
	ds_read_b128 v[92:95], v121 offset:34816
	s_waitcnt lgkmcnt(7)
	v_mfma_f32_16x16x32_bf16 v[8:11], a[0:3], v[88:91], v[8:11]
	v_mfma_f32_16x16x32_bf16 v[24:27], a[4:7], v[88:91], v[24:27]
	v_mfma_f32_16x16x32_bf16 v[40:43], a[8:11], v[88:91], v[40:43]
	v_mfma_f32_16x16x32_bf16 v[56:59], a[12:15], v[88:91], v[56:59]
	ds_read_b128 v[88:91], v121 offset:36864
	s_waitcnt lgkmcnt(7)
	v_mfma_f32_16x16x32_bf16 v[12:15], a[0:3], v[84:87], v[12:15]
	v_mfma_f32_16x16x32_bf16 v[28:31], a[4:7], v[84:87], v[28:31]
	v_mfma_f32_16x16x32_bf16 v[44:47], a[8:11], v[84:87], v[44:47]
	v_mfma_f32_16x16x32_bf16 v[60:63], a[12:15], v[84:87], v[60:63]
	ds_read_b128 v[84:87], v121 offset:38912
	s_waitcnt lgkmcnt(3)
	v_mfma_f32_16x16x32_bf16 v[0:3], a[16:19], v[80:83], v[0:3]
	v_mfma_f32_16x16x32_bf16 v[16:19], a[20:23], v[80:83], v[16:19]
	v_mfma_f32_16x16x32_bf16 v[32:35], a[24:27], v[80:83], v[32:35]
	v_mfma_f32_16x16x32_bf16 v[48:51], a[28:31], v[80:83], v[48:51]
	s_waitcnt lgkmcnt(2)
	v_mfma_f32_16x16x32_bf16 v[4:7], a[16:19], v[92:95], v[4:7]
	v_mfma_f32_16x16x32_bf16 v[20:23], a[20:23], v[92:95], v[20:23]
	v_mfma_f32_16x16x32_bf16 v[36:39], a[24:27], v[92:95], v[36:39]
	v_mfma_f32_16x16x32_bf16 v[52:55], a[28:31], v[92:95], v[52:55]
	s_waitcnt lgkmcnt(1)
	v_mfma_f32_16x16x32_bf16 v[8:11], a[16:19], v[88:91], v[8:11]
	v_mfma_f32_16x16x32_bf16 v[24:27], a[20:23], v[88:91], v[24:27]
	v_mfma_f32_16x16x32_bf16 v[40:43], a[24:27], v[88:91], v[40:43]
	v_mfma_f32_16x16x32_bf16 v[56:59], a[28:31], v[88:91], v[56:59]
	s_waitcnt lgkmcnt(0)
	v_mfma_f32_16x16x32_bf16 v[12:15], a[16:19], v[84:87], v[12:15]
	v_mfma_f32_16x16x32_bf16 v[28:31], a[20:23], v[84:87], v[28:31]
	v_mfma_f32_16x16x32_bf16 v[44:47], a[24:27], v[84:87], v[44:47]
	v_mfma_f32_16x16x32_bf16 v[60:63], a[28:31], v[84:87], v[60:63]
	s_setprio 0
	v_readfirstlane_b32 s15, v109
	v_readfirstlane_b32 s4, v108
	s_lshl_b32 s15, s15, 6
	s_waitcnt lgkmcnt(0)
	s_barrier
	s_add_i32 s9, s15, s9
	s_lshl_b32 s15, s4, 19
	s_lshl_b32 s4, s8, 20
	s_add_i32 s15, s15, s4
	v_or_b32_e32 v66, s9, v110
	v_cmp_gt_i32_e64 s[40:41], s51, v66
	v_and_b32_e32 v64, 0xffffffde, v66
	v_or_b32_e32 v65, s15, v113
	s_barrier
	v_and_b32_e32 v126, 15, v143
	v_bfe_u32 v127, v143, 4, 2
	v_xor_b32_e32 v127, v127, v126
	v_lshlrev_b32_e32 v127, 4, v127
	v_lshl_add_u32 v127, v126, 8, v127
	v_lshrrev_b32_e32 v126, 6, v143
	v_lshl_add_u32 v127, v126, 14, v127
	ds_write_b128 v127, v[0:3]
	ds_write_b128 v127, v[4:7] offset:4096
	ds_write_b128 v127, v[8:11] offset:8192
	ds_write_b128 v127, v[12:15] offset:12288
	v_xor_b32_e32 v121, 64, v127
	ds_write_b128 v121, v[16:19]
	ds_write_b128 v121, v[20:23] offset:4096
	ds_write_b128 v121, v[24:27] offset:8192
	ds_write_b128 v121, v[28:31] offset:12288
	v_xor_b32_e32 v121, 128, v127
	ds_write_b128 v121, v[32:35]
	ds_write_b128 v121, v[36:39] offset:4096
	ds_write_b128 v121, v[40:43] offset:8192
	ds_write_b128 v121, v[44:47] offset:12288
	v_xor_b32_e32 v121, 192, v127
	ds_write_b128 v121, v[48:51]
	ds_write_b128 v121, v[52:55] offset:4096
	ds_write_b128 v121, v[56:59] offset:8192
	ds_write_b128 v121, v[60:63] offset:12288
	v_and_b32_e32 v118, 31, v143
	v_bfe_u32 v120, v143, 5, 1
	v_and_b32_e32 v127, 15, v118
	v_xor_b32_e32 v120, v120, v127
	v_lshlrev_b32_e32 v120, 4, v120
	v_lshl_add_u32 v120, v118, 8, v120
	v_lshl_add_u32 v120, v126, 14, v120
	ds_read_b128 v[48:51], v120
	ds_read_b128 v[32:35], v120 offset:8192
	v_xor_b32_e32 v119, 32, v120
	ds_read_b128 v[52:55], v119
	ds_read_b128 v[36:39], v119 offset:8192
	v_xor_b32_e32 v119, 64, v120
	ds_read_b128 v[56:59], v119
	ds_read_b128 v[40:43], v119 offset:8192
	v_xor_b32_e32 v119, 96, v120
	ds_read_b128 v[60:63], v119
	ds_read_b128 v[44:47], v119 offset:8192
	v_xor_b32_e32 v119, 128, v120
	ds_read_b128 v[16:19], v119
	ds_read_b128 v[0:3], v119 offset:8192
	v_xor_b32_e32 v119, 160, v120
	ds_read_b128 v[20:23], v119
	ds_read_b128 v[4:7], v119 offset:8192
	v_xor_b32_e32 v119, 192, v120
	ds_read_b128 v[24:27], v119
	ds_read_b128 v[8:11], v119 offset:8192
	v_xor_b32_e32 v119, 224, v120
	ds_read_b128 v[28:31], v119
	ds_read_b128 v[12:15], v119 offset:8192
	s_waitcnt lgkmcnt(0)
	s_barrier
	s_and_saveexec_b64 s[8:9], s[40:41]
	s_cbranch_execz .LBB0_1009
	v_max_f32_e32 v48, v48, v48
	v_max_f32_e32 v49, v49, v49
	v_max_f32_e32 v50, v50, v50
	v_max_f32_e32 v51, v51, v51
	v_max_f32_e32 v48, 0, v48
	v_max_f32_e32 v49, 0, v49
	v_max_f32_e32 v50, 0, v50
	v_max_f32_e32 v51, 0, v51
	v_mul_f32_e32 v48, v48, v48
	v_mul_f32_e32 v49, v49, v49
	v_mul_f32_e32 v50, v50, v50
	v_mul_f32_e32 v51, v51, v51
	v_mov_b32_e32 v68, v140
	v_mov_b32_e32 v69, v140
	v_mov_b32_e32 v70, v140
	v_mov_b32_e32 v71, v140
	v_mov_b32_dpp v68, v48 quad_perm:[1,0,3,2] row_mask:0xf bank_mask:0xf
	v_mov_b32_dpp v69, v49 quad_perm:[1,0,3,2] row_mask:0xf bank_mask:0xf
	v_mov_b32_dpp v70, v50 quad_perm:[1,0,3,2] row_mask:0xf bank_mask:0xf
	v_mov_b32_dpp v71, v51 quad_perm:[1,0,3,2] row_mask:0xf bank_mask:0xf
	v_add_u32_e32 v67, v64, v65
	v_cndmask_b32_e64 v50, v50, v68, s[38:39]
	v_cndmask_b32_e64 v48, v70, v48, s[38:39]
	v_cndmask_b32_e64 v51, v51, v69, s[38:39]
	v_cndmask_b32_e64 v49, v71, v49, s[38:39]
	v_cvt_pk_bf16_f32 v51, v49, v51
	v_cvt_pk_bf16_f32 v50, v48, v50
	v_add_u32_e32 v48, v67, v114
	v_mov_b32_e32 v49, v140
	v_lshl_add_u64 v[48:49], v[48:49], 1, s[28:29]
	global_store_dword v[48:49], v50, off
	v_add_co_u32_e32 v48, vcc, s80, v48
	s_nop 1
	v_addc_co_u32_e32 v49, vcc, 0, v49, vcc
	global_store_dword v[48:49], v51, off
	v_max_f32_e32 v48, v52, v52
	v_max_f32_e32 v49, v53, v53
	v_max_f32_e32 v50, v54, v54
	v_max_f32_e32 v51, v55, v55
	v_max_f32_e32 v48, 0, v48
	v_max_f32_e32 v49, 0, v49
	v_max_f32_e32 v50, 0, v50
	v_max_f32_e32 v51, 0, v51
	v_mul_f32_e32 v48, v48, v48
	v_mul_f32_e32 v49, v49, v49
	v_mul_f32_e32 v50, v50, v50
	v_mul_f32_e32 v51, v51, v51
	v_mov_b32_e32 v52, v140
	v_mov_b32_e32 v53, v140
	v_mov_b32_e32 v54, v140
	v_mov_b32_e32 v55, v140
	v_mov_b32_dpp v52, v48 quad_perm:[1,0,3,2] row_mask:0xf bank_mask:0xf
	v_mov_b32_dpp v53, v49 quad_perm:[1,0,3,2] row_mask:0xf bank_mask:0xf
	v_mov_b32_dpp v54, v50 quad_perm:[1,0,3,2] row_mask:0xf bank_mask:0xf
	v_mov_b32_dpp v55, v51 quad_perm:[1,0,3,2] row_mask:0xf bank_mask:0xf
	v_cndmask_b32_e64 v50, v50, v52, s[38:39]
	v_cndmask_b32_e64 v48, v54, v48, s[38:39]
	v_cndmask_b32_e64 v51, v51, v53, s[38:39]
	v_cndmask_b32_e64 v49, v55, v49, s[38:39]
	v_cvt_pk_bf16_f32 v51, v49, v51
	v_cvt_pk_bf16_f32 v50, v48, v50
	v_add_u32_e32 v48, v67, v115
	v_mov_b32_e32 v49, v140
	v_lshl_add_u64 v[48:49], v[48:49], 1, s[28:29]
	global_store_dword v[48:49], v50, off
	v_add_co_u32_e32 v48, vcc, s80, v48
	s_nop 1
	v_addc_co_u32_e32 v49, vcc, 0, v49, vcc
	global_store_dword v[48:49], v51, off
	v_max_f32_e32 v48, v56, v56
	v_max_f32_e32 v49, v57, v57
	v_max_f32_e32 v50, v58, v58
	v_max_f32_e32 v51, v59, v59
	v_max_f32_e32 v48, 0, v48
	v_max_f32_e32 v49, 0, v49
	v_max_f32_e32 v50, 0, v50
	v_max_f32_e32 v51, 0, v51
	v_mul_f32_e32 v48, v48, v48
	v_mul_f32_e32 v49, v49, v49
	v_mul_f32_e32 v50, v50, v50
	v_mul_f32_e32 v51, v51, v51
	v_mov_b32_e32 v52, v140
	v_mov_b32_e32 v53, v140
	v_mov_b32_e32 v54, v140
	v_mov_b32_e32 v55, v140
	v_mov_b32_dpp v52, v48 quad_perm:[1,0,3,2] row_mask:0xf bank_mask:0xf
	v_mov_b32_dpp v53, v49 quad_perm:[1,0,3,2] row_mask:0xf bank_mask:0xf
	v_mov_b32_dpp v54, v50 quad_perm:[1,0,3,2] row_mask:0xf bank_mask:0xf
	v_mov_b32_dpp v55, v51 quad_perm:[1,0,3,2] row_mask:0xf bank_mask:0xf
	v_cndmask_b32_e64 v50, v50, v52, s[38:39]
	v_cndmask_b32_e64 v48, v54, v48, s[38:39]
	v_cndmask_b32_e64 v51, v51, v53, s[38:39]
	v_cndmask_b32_e64 v49, v55, v49, s[38:39]
	v_cvt_pk_bf16_f32 v51, v49, v51
	v_cvt_pk_bf16_f32 v50, v48, v50
	v_add_u32_e32 v48, v67, v116
	v_mov_b32_e32 v49, v140
	v_lshl_add_u64 v[48:49], v[48:49], 1, s[28:29]
	global_store_dword v[48:49], v50, off
	v_add_co_u32_e32 v48, vcc, s80, v48
	s_nop 1
	v_addc_co_u32_e32 v49, vcc, 0, v49, vcc
	global_store_dword v[48:49], v51, off
	v_max_f32_e32 v48, v60, v60
	v_max_f32_e32 v49, v61, v61
	v_max_f32_e32 v50, v62, v62
	v_max_f32_e32 v51, v63, v63
	v_max_f32_e32 v48, 0, v48
	v_max_f32_e32 v49, 0, v49
	v_max_f32_e32 v50, 0, v50
	v_max_f32_e32 v51, 0, v51
	v_mul_f32_e32 v48, v48, v48
	v_mul_f32_e32 v49, v49, v49
	v_mul_f32_e32 v50, v50, v50
	v_mul_f32_e32 v51, v51, v51
	v_mov_b32_e32 v52, v140
	v_mov_b32_e32 v53, v140
	v_mov_b32_e32 v54, v140
	v_mov_b32_e32 v55, v140
	v_mov_b32_dpp v52, v48 quad_perm:[1,0,3,2] row_mask:0xf bank_mask:0xf
	v_mov_b32_dpp v53, v49 quad_perm:[1,0,3,2] row_mask:0xf bank_mask:0xf
	v_mov_b32_dpp v54, v50 quad_perm:[1,0,3,2] row_mask:0xf bank_mask:0xf
	v_mov_b32_dpp v55, v51 quad_perm:[1,0,3,2] row_mask:0xf bank_mask:0xf
	v_cndmask_b32_e64 v50, v50, v52, s[38:39]
	v_cndmask_b32_e64 v48, v54, v48, s[38:39]
	v_cndmask_b32_e64 v51, v51, v53, s[38:39]
	v_cndmask_b32_e64 v49, v55, v49, s[38:39]
	v_cvt_pk_bf16_f32 v51, v49, v51
	v_cvt_pk_bf16_f32 v50, v48, v50
	v_add_u32_e32 v48, v67, v117
	v_mov_b32_e32 v49, v140
	v_lshl_add_u64 v[48:49], v[48:49], 1, s[28:29]
	global_store_dword v[48:49], v50, off
	v_add_co_u32_e32 v48, vcc, 0x4000, v48
	s_nop 1
	v_addc_co_u32_e32 v49, vcc, 0, v49, vcc
	global_store_dword v[48:49], v51, off

.LBB0_1026:
	s_mul_hi_i32 s4, s42, 0x38e38e39
	s_lshr_b32 s8, s4, 31
	s_ashr_i32 s4, s4, 4
	s_add_i32 s4, s4, s8
	s_mul_i32 s8, s4, 0x48
	s_sub_i32 s8, s42, s8
	s_lshl_b32 s8, s8, 7
	v_add_u32_e32 v0, s8, v109
	v_ashrrev_i32_e32 v1, 31, v0
	v_lshlrev_b64 v[32:33], 12, v[0:1]
	v_lshl_add_u64 v[34:35], v[96:97], 0, v[32:33]
	v_add_co_u32_e32 v40, vcc, s87, v34
	s_lshl_b32 s9, s4, 7
	s_nop 0
	v_addc_co_u32_e32 v41, vcc, 0, v35, vcc
	v_add_co_u32_e32 v42, vcc, s66, v34
	v_add_u32_e32 v0, s9, v109
	s_nop 0
	v_addc_co_u32_e32 v43, vcc, 0, v35, vcc
	v_ashrrev_i32_e32 v1, 31, v0
	v_add_co_u32_e32 v44, vcc, s20, v34
	v_lshlrev_b64 v[36:37], 12, v[0:1]
	s_nop 0
	v_addc_co_u32_e32 v45, vcc, 0, v35, vcc
	v_lshl_add_u64 v[38:39], v[98:99], 0, v[36:37]
	v_readfirstlane_b32 s100, v110
	s_nop 3
	s_add_u32 m0, s100, 0x0
	s_nop 0
	global_load_lds_dwordx4 v[34:35], off
	s_add_u32 m0, s100, 0x1000
	s_nop 0
	global_load_lds_dwordx4 v[40:41], off
	s_add_u32 m0, s100, 0x2000
	s_nop 0
	global_load_lds_dwordx4 v[42:43], off
	s_add_u32 m0, s100, 0x3000
	s_nop 0
	global_load_lds_dwordx4 v[44:45], off
	s_add_u32 m0, s100, 0x4000
	s_nop 0
	global_load_lds_dwordx4 v[38:39], off
	v_add_co_u32_e32 v46, vcc, s87, v38
	v_lshl_add_u64 v[102:103], v[100:101], 0, v[36:37]
	s_nop 0
	v_addc_co_u32_e32 v47, vcc, 0, v39, vcc
	s_waitcnt vmcnt(16)
	v_add_co_u32_e32 v48, vcc, s66, v38
	s_add_u32 m0, s100, 0x5000
	s_nop 0
	global_load_lds_dwordx4 v[46:47], off
	s_nop 0
	v_addc_co_u32_e32 v49, vcc, 0, v39, vcc
	v_add_co_u32_e32 v50, vcc, s20, v38
	s_add_u32 m0, s100, 0x6000
	s_nop 0
	global_load_lds_dwordx4 v[48:49], off
	s_nop 0
	v_addc_co_u32_e32 v51, vcc, 0, v39, vcc
	s_add_u32 m0, s100, 0x7000
	s_nop 0
	global_load_lds_dwordx4 v[50:51], off
	v_lshl_add_u64 v[104:105], v[100:101], 0, v[32:33]
	s_mov_b64 s[34:35], 0
	v_mov_b32_e32 v0, 0
	v_mov_b32_e32 v1, v0
	v_mov_b32_e32 v2, v0
	v_mov_b32_e32 v3, v0
	v_mov_b32_e32 v4, v0
	v_mov_b32_e32 v5, v0
	v_mov_b32_e32 v6, v0
	v_mov_b32_e32 v7, v0
	v_mov_b32_e32 v8, v0
	v_mov_b32_e32 v9, v0
	v_mov_b32_e32 v10, v0
	v_mov_b32_e32 v11, v0
	v_mov_b32_e32 v12, v0
	v_mov_b32_e32 v13, v0
	v_mov_b32_e32 v14, v0
	v_mov_b32_e32 v15, v0
	v_mov_b32_e32 v16, v0
	v_mov_b32_e32 v17, v0
	v_mov_b32_e32 v18, v0
	v_mov_b32_e32 v19, v0
	v_mov_b32_e32 v20, v0
	v_mov_b32_e32 v21, v0
	v_mov_b32_e32 v22, v0
	v_mov_b32_e32 v23, v0
	v_mov_b32_e32 v24, v0
	v_mov_b32_e32 v25, v0
	v_mov_b32_e32 v26, v0
	v_mov_b32_e32 v27, v0
	v_mov_b32_e32 v28, v0
	v_mov_b32_e32 v29, v0
	v_mov_b32_e32 v30, v0
	v_mov_b32_e32 v31, v0
	v_mov_b32_e32 v32, v0
	v_mov_b32_e32 v33, v0
	v_mov_b32_e32 v34, v0
	v_mov_b32_e32 v35, v0
	v_mov_b32_e32 v36, v0
	v_mov_b32_e32 v37, v0
	v_mov_b32_e32 v38, v0
	v_mov_b32_e32 v39, v0
	v_mov_b32_e32 v40, v0
	v_mov_b32_e32 v41, v0
	v_mov_b32_e32 v42, v0
	v_mov_b32_e32 v43, v0
	v_mov_b32_e32 v44, v0
	v_mov_b32_e32 v45, v0
	v_mov_b32_e32 v46, v0
	v_mov_b32_e32 v47, v0
	v_mov_b32_e32 v48, v0
	v_mov_b32_e32 v49, v0
	v_mov_b32_e32 v50, v0
	v_mov_b32_e32 v51, v0
	v_mov_b32_e32 v52, v0
	v_mov_b32_e32 v53, v0
	v_mov_b32_e32 v54, v0
	v_mov_b32_e32 v55, v0
	v_mov_b32_e32 v56, v0
	v_mov_b32_e32 v57, v0
	v_mov_b32_e32 v58, v0
	v_mov_b32_e32 v59, v0
	v_mov_b32_e32 v60, v0
	v_mov_b32_e32 v61, v0
	v_mov_b32_e32 v62, v0
	v_mov_b32_e32 v63, v0
	v_lshl_add_u64 v[124:125], v[104:105], 0, s[34:35]
	v_add_co_u32_e32 v132, vcc, s21, v124
	v_lshl_add_u64 v[126:127], v[102:103], 0, s[34:35]
	s_nop 0
	v_addc_co_u32_e32 v133, vcc, 0, v125, vcc
	v_add_co_u32_e32 v134, vcc, s74, v124
	s_mov_b32 s4, 0x2e380000
	s_nop 0
	v_addc_co_u32_e32 v135, vcc, 0, v125, vcc
	v_add_co_u32_e32 v144, vcc, s75, v124
	v_addc_co_u32_e32 v145, vcc, 0, v125, vcc
	v_add_co_u32_e32 v146, vcc, s14, v124
	s_nop 1
	v_addc_co_u32_e32 v147, vcc, 0, v125, vcc
	v_add_co_u32_e32 v148, vcc, s4, v126
	s_mov_b32 s4, 0x2e3a0000
	s_nop 0
	v_addc_co_u32_e32 v149, vcc, 0, v127, vcc
	v_add_co_u32_e32 v150, vcc, s4, v126
	s_mov_b32 s4, 0x2e3c0000
	s_nop 0
	v_addc_co_u32_e32 v151, vcc, 0, v127, vcc
	v_add_co_u32_e32 v152, vcc, s4, v126
	s_mov_b32 s4, 0x2e3e0000
	s_nop 0
	v_addc_co_u32_e32 v153, vcc, 0, v127, vcc
	v_add_co_u32_e32 v154, vcc, s4, v126
	v_addc_co_u32_e32 v155, vcc, 0, v127, vcc
	v_lshl_add_u64 v[132:133], 8, 4, v[132:133]
	v_lshl_add_u64 v[134:135], 8, 4, v[134:135]
	v_lshl_add_u64 v[144:145], 8, 4, v[144:145]
	v_lshl_add_u64 v[146:147], 8, 4, v[146:147]
	v_lshl_add_u64 v[148:149], 8, 4, v[148:149]
	v_lshl_add_u64 v[150:151], 8, 4, v[150:151]
	v_lshl_add_u64 v[152:153], 8, 4, v[152:153]
	v_lshl_add_u64 v[154:155], 8, 4, v[154:155]
	v_and_b32_e32 v120, 15, v143
	v_lshrrev_b32_e32 v121, 1, v120
	v_bfe_u32 v114, v143, 4, 2
	v_xor_b32_e32 v121, v121, v114
	v_lshlrev_b32_e32 v121, 4, v121
	v_lshl_add_u32 v121, v120, 7, v121
	v_lshrrev_b32_e32 v120, 6, v143
	v_lshrrev_b32_e32 v112, 1, v120
	v_and_b32_e32 v120, 1, v120
	v_lshl_add_u32 v112, v112, 13, v121
	v_lshl_add_u32 v113, v120, 13, v121
	v_add_u32_e32 v113, 0x4000, v113
	v_xor_b32_e32 v114, 64, v112
	v_xor_b32_e32 v115, 64, v113
	s_waitcnt vmcnt(0) lgkmcnt(0)
	s_barrier
.LBB0_1027:
	s_add_u32 m0, s100, 0x8000
	s_nop 0
	global_load_lds_dwordx4 v[132:133], off
	s_add_u32 m0, s100, 0x9000
	s_nop 0
	global_load_lds_dwordx4 v[134:135], off
	s_add_u32 m0, s100, 0xa000
	s_nop 0
	global_load_lds_dwordx4 v[144:145], off
	s_add_u32 m0, s100, 0xb000
	s_nop 0
	global_load_lds_dwordx4 v[146:147], off
	s_add_u32 m0, s100, 0xc000
	s_nop 0
	global_load_lds_dwordx4 v[148:149], off
	s_add_u32 m0, s100, 0xd000
	s_nop 0
	global_load_lds_dwordx4 v[150:151], off
	s_add_u32 m0, s100, 0xe000
	s_nop 0
	global_load_lds_dwordx4 v[152:153], off
	s_add_u32 m0, s100, 0xf000
	s_nop 0
	global_load_lds_dwordx4 v[154:155], off
	ds_read_b128 a[0:3], v112
	ds_read_b128 v[80:83], v113
	ds_read_b128 a[4:7], v112 offset:2048
	ds_read_b128 a[8:11], v112 offset:4096
	ds_read_b128 a[12:15], v112 offset:6144
	ds_read_b128 v[92:95], v113 offset:2048
	ds_read_b128 v[88:91], v113 offset:4096
	ds_read_b128 v[84:87], v113 offset:6144
	ds_read_b128 a[16:19], v114
	ds_read_b128 a[20:23], v114 offset:2048
	ds_read_b128 a[24:27], v114 offset:4096
	ds_read_b128 a[28:31], v114 offset:6144
	s_setprio 1
	s_waitcnt lgkmcnt(10)
	v_mfma_f32_16x16x32_bf16 v[0:3], a[0:3], v[80:83], v[0:3]
	s_waitcnt lgkmcnt(9)
	v_mfma_f32_16x16x32_bf16 v[16:19], a[4:7], v[80:83], v[16:19]
	s_waitcnt lgkmcnt(8)
	v_mfma_f32_16x16x32_bf16 v[32:35], a[8:11], v[80:83], v[32:35]
	s_waitcnt lgkmcnt(7)
	v_mfma_f32_16x16x32_bf16 v[48:51], a[12:15], v[80:83], v[48:51]
	ds_read_b128 v[80:83], v115
	s_waitcnt lgkmcnt(7)
	v_mfma_f32_16x16x32_bf16 v[4:7], a[0:3], v[92:95], v[4:7]
	v_lshl_add_u64 v[64:65], 8, 4, v[132:133]
	v_lshl_add_u64 v[66:67], 8, 4, v[134:135]
	v_lshl_add_u64 v[68:69], 8, 4, v[144:145]
	v_mfma_f32_16x16x32_bf16 v[20:23], a[4:7], v[92:95], v[20:23]
	v_lshl_add_u64 v[70:71], 8, 4, v[146:147]
	v_lshl_add_u64 v[76:77], 8, 4, v[148:149]
	v_lshl_add_u64 v[78:79], 8, 4, v[150:151]
	v_mfma_f32_16x16x32_bf16 v[36:39], a[8:11], v[92:95], v[36:39]
	v_lshl_add_u64 v[72:73], 8, 4, v[152:153]
	v_lshl_add_u64 v[74:75], 8, 4, v[154:155]
	v_mfma_f32_16x16x32_bf16 v[52:55], a[12:15], v[92:95], v[52:55]
	ds_read_b128 v[92:95], v115 offset:2048
	s_waitcnt lgkmcnt(7)
	v_mfma_f32_16x16x32_bf16 v[8:11], a[0:3], v[88:91], v[8:11]
	v_mfma_f32_16x16x32_bf16 v[24:27], a[4:7], v[88:91], v[24:27]
	v_mfma_f32_16x16x32_bf16 v[40:43], a[8:11], v[88:91], v[40:43]
	v_mfma_f32_16x16x32_bf16 v[56:59], a[12:15], v[88:91], v[56:59]
	ds_read_b128 v[88:91], v115 offset:4096
	s_waitcnt lgkmcnt(7)
	v_mfma_f32_16x16x32_bf16 v[12:15], a[0:3], v[84:87], v[12:15]
	v_mfma_f32_16x16x32_bf16 v[28:31], a[4:7], v[84:87], v[28:31]
	v_mfma_f32_16x16x32_bf16 v[44:47], a[8:11], v[84:87], v[44:47]
	v_mfma_f32_16x16x32_bf16 v[60:63], a[12:15], v[84:87], v[60:63]
	ds_read_b128 v[84:87], v115 offset:6144
	s_waitcnt lgkmcnt(3)
	v_mfma_f32_16x16x32_bf16 v[0:3], a[16:19], v[80:83], v[0:3]
	v_mfma_f32_16x16x32_bf16 v[16:19], a[20:23], v[80:83], v[16:19]
	v_mfma_f32_16x16x32_bf16 v[32:35], a[24:27], v[80:83], v[32:35]
	v_mfma_f32_16x16x32_bf16 v[48:51], a[28:31], v[80:83], v[48:51]
	s_waitcnt lgkmcnt(2)
	v_mfma_f32_16x16x32_bf16 v[4:7], a[16:19], v[92:95], v[4:7]
	v_mfma_f32_16x16x32_bf16 v[20:23], a[20:23], v[92:95], v[20:23]
	v_mfma_f32_16x16x32_bf16 v[36:39], a[24:27], v[92:95], v[36:39]
	v_mfma_f32_16x16x32_bf16 v[52:55], a[28:31], v[92:95], v[52:55]
	s_waitcnt lgkmcnt(1)
	v_mfma_f32_16x16x32_bf16 v[8:11], a[16:19], v[88:91], v[8:11]
	v_mfma_f32_16x16x32_bf16 v[24:27], a[20:23], v[88:91], v[24:27]
	v_mfma_f32_16x16x32_bf16 v[40:43], a[24:27], v[88:91], v[40:43]
	v_mfma_f32_16x16x32_bf16 v[56:59], a[28:31], v[88:91], v[56:59]
	s_waitcnt lgkmcnt(0)
	v_mfma_f32_16x16x32_bf16 v[12:15], a[16:19], v[84:87], v[12:15]
	v_mfma_f32_16x16x32_bf16 v[28:31], a[20:23], v[84:87], v[28:31]
	v_mfma_f32_16x16x32_bf16 v[44:47], a[24:27], v[84:87], v[44:47]
	v_mfma_f32_16x16x32_bf16 v[60:63], a[28:31], v[84:87], v[60:63]
	s_setprio 0
	s_waitcnt vmcnt(0) lgkmcnt(0)
	s_barrier
	s_add_u32 s34, s34, 0x100
	s_addc_u32 s35, s35, 0
	s_add_u32 m0, s100, 0x0
	s_nop 0
	global_load_lds_dwordx4 v[64:65], off
	s_add_u32 m0, s100, 0x1000
	s_nop 0
	global_load_lds_dwordx4 v[66:67], off
	s_add_u32 m0, s100, 0x2000
	s_nop 0
	global_load_lds_dwordx4 v[68:69], off
	s_add_u32 m0, s100, 0x3000
	s_nop 0
	global_load_lds_dwordx4 v[70:71], off
	s_add_u32 m0, s100, 0x4000
	s_nop 0
	global_load_lds_dwordx4 v[76:77], off
	s_add_u32 m0, s100, 0x5000
	s_nop 0
	global_load_lds_dwordx4 v[78:79], off
	s_add_u32 m0, s100, 0x6000
	s_nop 0
	global_load_lds_dwordx4 v[72:73], off
	s_add_u32 m0, s100, 0x7000
	s_nop 0
	global_load_lds_dwordx4 v[74:75], off
	ds_read_b128 a[0:3], v112 offset:32768
	ds_read_b128 v[80:83], v113 offset:32768
	ds_read_b128 a[4:7], v112 offset:34816
	ds_read_b128 a[8:11], v112 offset:36864
	ds_read_b128 a[12:15], v112 offset:38912
	ds_read_b128 v[92:95], v113 offset:34816
	ds_read_b128 v[88:91], v113 offset:36864
	ds_read_b128 v[84:87], v113 offset:38912
	ds_read_b128 a[16:19], v114 offset:32768
	ds_read_b128 a[20:23], v114 offset:34816
	ds_read_b128 a[24:27], v114 offset:36864
	ds_read_b128 a[28:31], v114 offset:38912
	s_setprio 1
	s_waitcnt lgkmcnt(10)
	v_mfma_f32_16x16x32_bf16 v[0:3], a[0:3], v[80:83], v[0:3]
	s_waitcnt lgkmcnt(9)
	v_mfma_f32_16x16x32_bf16 v[16:19], a[4:7], v[80:83], v[16:19]
	s_waitcnt lgkmcnt(8)
	v_mfma_f32_16x16x32_bf16 v[32:35], a[8:11], v[80:83], v[32:35]
	s_waitcnt lgkmcnt(7)
	v_mfma_f32_16x16x32_bf16 v[48:51], a[12:15], v[80:83], v[48:51]
	ds_read_b128 v[80:83], v115 offset:32768
	s_waitcnt lgkmcnt(7)
	v_mfma_f32_16x16x32_bf16 v[4:7], a[0:3], v[92:95], v[4:7]
	v_lshl_add_u64 v[124:125], v[104:105], 0, s[34:35]
	v_add_co_u32_e32 v132, vcc, s21, v124
	v_lshl_add_u64 v[126:127], v[102:103], 0, s[34:35]
	v_mfma_f32_16x16x32_bf16 v[20:23], a[4:7], v[92:95], v[20:23]
	s_nop 0
	v_addc_co_u32_e32 v133, vcc, 0, v125, vcc
	v_add_co_u32_e32 v134, vcc, s74, v124
	v_mfma_f32_16x16x32_bf16 v[36:39], a[8:11], v[92:95], v[36:39]
	s_mov_b32 s4, 0x2e380000
	s_nop 0
	v_addc_co_u32_e32 v135, vcc, 0, v125, vcc
	v_mfma_f32_16x16x32_bf16 v[52:55], a[12:15], v[92:95], v[52:55]
	v_add_co_u32_e32 v144, vcc, s75, v124
	v_addc_co_u32_e32 v145, vcc, 0, v125, vcc
	v_add_co_u32_e32 v146, vcc, s14, v124
	ds_read_b128 v[92:95], v115 offset:34816
	s_waitcnt lgkmcnt(7)
	v_mfma_f32_16x16x32_bf16 v[8:11], a[0:3], v[88:91], v[8:11]
	s_nop 1
	v_addc_co_u32_e32 v147, vcc, 0, v125, vcc
	v_add_co_u32_e32 v148, vcc, s4, v126
	v_mfma_f32_16x16x32_bf16 v[24:27], a[4:7], v[88:91], v[24:27]
	s_mov_b32 s4, 0x2e3a0000
	s_nop 0
	v_addc_co_u32_e32 v149, vcc, 0, v127, vcc
	v_mfma_f32_16x16x32_bf16 v[40:43], a[8:11], v[88:91], v[40:43]
	v_add_co_u32_e32 v150, vcc, s4, v126
	s_mov_b32 s4, 0x2e3c0000
	s_nop 0
	v_mfma_f32_16x16x32_bf16 v[56:59], a[12:15], v[88:91], v[56:59]
	v_addc_co_u32_e32 v151, vcc, 0, v127, vcc
	v_add_co_u32_e32 v152, vcc, s4, v126
	s_mov_b32 s4, 0x2e3e0000
	ds_read_b128 v[88:91], v115 offset:36864
	s_waitcnt lgkmcnt(7)
	v_mfma_f32_16x16x32_bf16 v[12:15], a[0:3], v[84:87], v[12:15]
	s_nop 0
	v_addc_co_u32_e32 v153, vcc, 0, v127, vcc
	v_add_co_u32_e32 v154, vcc, s4, v126
	v_mfma_f32_16x16x32_bf16 v[28:31], a[4:7], v[84:87], v[28:31]
	v_addc_co_u32_e32 v155, vcc, 0, v127, vcc
	v_lshl_add_u64 v[132:133], 8, 4, v[132:133]
	v_lshl_add_u64 v[134:135], 8, 4, v[134:135]
	v_mfma_f32_16x16x32_bf16 v[44:47], a[8:11], v[84:87], v[44:47]
	v_lshl_add_u64 v[144:145], 8, 4, v[144:145]
	v_lshl_add_u64 v[146:147], 8, 4, v[146:147]
	v_lshl_add_u64 v[148:149], 8, 4, v[148:149]
	v_mfma_f32_16x16x32_bf16 v[60:63], a[12:15], v[84:87], v[60:63]
	v_lshl_add_u64 v[150:151], 8, 4, v[150:151]
	v_lshl_add_u64 v[152:153], 8, 4, v[152:153]
	v_lshl_add_u64 v[154:155], 8, 4, v[154:155]
	ds_read_b128 v[84:87], v115 offset:38912
	s_waitcnt lgkmcnt(3)
	v_mfma_f32_16x16x32_bf16 v[0:3], a[16:19], v[80:83], v[0:3]
	v_mfma_f32_16x16x32_bf16 v[16:19], a[20:23], v[80:83], v[16:19]
	v_mfma_f32_16x16x32_bf16 v[32:35], a[24:27], v[80:83], v[32:35]
	v_mfma_f32_16x16x32_bf16 v[48:51], a[28:31], v[80:83], v[48:51]
	s_waitcnt lgkmcnt(2)
	v_mfma_f32_16x16x32_bf16 v[4:7], a[16:19], v[92:95], v[4:7]
	v_mfma_f32_16x16x32_bf16 v[20:23], a[20:23], v[92:95], v[20:23]
	v_mfma_f32_16x16x32_bf16 v[36:39], a[24:27], v[92:95], v[36:39]
	v_mfma_f32_16x16x32_bf16 v[52:55], a[28:31], v[92:95], v[52:55]
	s_waitcnt lgkmcnt(1)
	v_mfma_f32_16x16x32_bf16 v[8:11], a[16:19], v[88:91], v[8:11]
	v_mfma_f32_16x16x32_bf16 v[24:27], a[20:23], v[88:91], v[24:27]
	v_mfma_f32_16x16x32_bf16 v[40:43], a[24:27], v[88:91], v[40:43]
	v_mfma_f32_16x16x32_bf16 v[56:59], a[28:31], v[88:91], v[56:59]
	s_waitcnt lgkmcnt(0)
	v_mfma_f32_16x16x32_bf16 v[12:15], a[16:19], v[84:87], v[12:15]
	v_mfma_f32_16x16x32_bf16 v[28:31], a[20:23], v[84:87], v[28:31]
	v_mfma_f32_16x16x32_bf16 v[44:47], a[24:27], v[84:87], v[44:47]
	v_mfma_f32_16x16x32_bf16 v[60:63], a[28:31], v[84:87], v[60:63]
	s_setprio 0
	s_waitcnt vmcnt(0) lgkmcnt(0)
	s_barrier
	s_cmpk_eq_i32 s34, 0xf00
	s_cbranch_scc0 .LBB0_1027
	v_lshl_add_u64 v[64:65], 8, 4, v[64:65]
	v_lshl_add_u64 v[66:67], 8, 4, v[66:67]
	v_lshl_add_u64 v[68:69], 8, 4, v[68:69]
	v_lshl_add_u64 v[70:71], 8, 4, v[70:71]
	v_lshl_add_u64 v[76:77], 8, 4, v[76:77]
	v_lshl_add_u64 v[78:79], 8, 4, v[78:79]
	v_lshl_add_u64 v[72:73], 8, 4, v[72:73]
	v_lshl_add_u64 v[74:75], 8, 4, v[74:75]
	s_add_u32 m0, s100, 0x8000
	s_nop 0
	global_load_lds_dwordx4 v[64:65], off
	s_add_u32 m0, s100, 0x9000
	s_nop 0
	global_load_lds_dwordx4 v[66:67], off
	s_add_u32 m0, s100, 0xa000
	s_nop 0
	global_load_lds_dwordx4 v[68:69], off
	s_add_u32 m0, s100, 0xb000
	s_nop 0
	global_load_lds_dwordx4 v[70:71], off
	s_add_u32 m0, s100, 0xc000
	s_nop 0
	global_load_lds_dwordx4 v[76:77], off
	s_add_u32 m0, s100, 0xd000
	s_nop 0
	global_load_lds_dwordx4 v[78:79], off
	s_add_u32 m0, s100, 0xe000
	s_nop 0
	global_load_lds_dwordx4 v[72:73], off
	s_add_u32 m0, s100, 0xf000
	s_nop 0
	global_load_lds_dwordx4 v[74:75], off
	ds_read_b128 a[0:3], v112
	ds_read_b128 v[80:83], v113
	ds_read_b128 a[4:7], v112 offset:2048
	ds_read_b128 a[8:11], v112 offset:4096
	ds_read_b128 a[12:15], v112 offset:6144
	ds_read_b128 v[92:95], v113 offset:2048
	ds_read_b128 v[88:91], v113 offset:4096
	ds_read_b128 v[84:87], v113 offset:6144
	ds_read_b128 a[16:19], v114
	ds_read_b128 a[20:23], v114 offset:2048
	ds_read_b128 a[24:27], v114 offset:4096
	ds_read_b128 a[28:31], v114 offset:6144
	s_setprio 1
	s_waitcnt lgkmcnt(10)
	v_mfma_f32_16x16x32_bf16 v[0:3], a[0:3], v[80:83], v[0:3]
	s_waitcnt lgkmcnt(9)
	v_mfma_f32_16x16x32_bf16 v[16:19], a[4:7], v[80:83], v[16:19]
	s_waitcnt lgkmcnt(8)
	v_mfma_f32_16x16x32_bf16 v[32:35], a[8:11], v[80:83], v[32:35]
	s_waitcnt lgkmcnt(7)
	v_mfma_f32_16x16x32_bf16 v[48:51], a[12:15], v[80:83], v[48:51]
	ds_read_b128 v[80:83], v115
	s_waitcnt lgkmcnt(7)
	v_mfma_f32_16x16x32_bf16 v[4:7], a[0:3], v[92:95], v[4:7]
	v_mfma_f32_16x16x32_bf16 v[20:23], a[4:7], v[92:95], v[20:23]
	v_mfma_f32_16x16x32_bf16 v[36:39], a[8:11], v[92:95], v[36:39]
	v_mfma_f32_16x16x32_bf16 v[52:55], a[12:15], v[92:95], v[52:55]
	ds_read_b128 v[92:95], v115 offset:2048
	s_waitcnt lgkmcnt(7)
	v_mfma_f32_16x16x32_bf16 v[8:11], a[0:3], v[88:91], v[8:11]
	v_mfma_f32_16x16x32_bf16 v[24:27], a[4:7], v[88:91], v[24:27]
	v_mfma_f32_16x16x32_bf16 v[40:43], a[8:11], v[88:91], v[40:43]
	v_mfma_f32_16x16x32_bf16 v[56:59], a[12:15], v[88:91], v[56:59]
	ds_read_b128 v[88:91], v115 offset:4096
	s_waitcnt lgkmcnt(7)
	v_mfma_f32_16x16x32_bf16 v[12:15], a[0:3], v[84:87], v[12:15]
	v_mfma_f32_16x16x32_bf16 v[28:31], a[4:7], v[84:87], v[28:31]
	v_mfma_f32_16x16x32_bf16 v[44:47], a[8:11], v[84:87], v[44:47]
	v_mfma_f32_16x16x32_bf16 v[60:63], a[12:15], v[84:87], v[60:63]
	ds_read_b128 v[84:87], v115 offset:6144
	s_waitcnt lgkmcnt(3)
	v_mfma_f32_16x16x32_bf16 v[0:3], a[16:19], v[80:83], v[0:3]
	v_mfma_f32_16x16x32_bf16 v[16:19], a[20:23], v[80:83], v[16:19]
	v_mfma_f32_16x16x32_bf16 v[32:35], a[24:27], v[80:83], v[32:35]
	v_mfma_f32_16x16x32_bf16 v[48:51], a[28:31], v[80:83], v[48:51]
	s_waitcnt lgkmcnt(2)
	v_mfma_f32_16x16x32_bf16 v[4:7], a[16:19], v[92:95], v[4:7]
	v_mfma_f32_16x16x32_bf16 v[20:23], a[20:23], v[92:95], v[20:23]
	v_mfma_f32_16x16x32_bf16 v[36:39], a[24:27], v[92:95], v[36:39]
	v_mfma_f32_16x16x32_bf16 v[52:55], a[28:31], v[92:95], v[52:55]
	s_waitcnt lgkmcnt(1)
	v_mfma_f32_16x16x32_bf16 v[8:11], a[16:19], v[88:91], v[8:11]
	v_mfma_f32_16x16x32_bf16 v[24:27], a[20:23], v[88:91], v[24:27]
	v_mfma_f32_16x16x32_bf16 v[40:43], a[24:27], v[88:91], v[40:43]
	v_mfma_f32_16x16x32_bf16 v[56:59], a[28:31], v[88:91], v[56:59]
	s_waitcnt lgkmcnt(0)
	v_mfma_f32_16x16x32_bf16 v[12:15], a[16:19], v[84:87], v[12:15]
	v_mfma_f32_16x16x32_bf16 v[28:31], a[20:23], v[84:87], v[28:31]
	v_mfma_f32_16x16x32_bf16 v[44:47], a[24:27], v[84:87], v[44:47]
	v_mfma_f32_16x16x32_bf16 v[60:63], a[28:31], v[84:87], v[60:63]
	s_setprio 0
	s_waitcnt vmcnt(0) lgkmcnt(0)
	s_barrier
	ds_read_b128 a[0:3], v112 offset:32768
	ds_read_b128 v[80:83], v113 offset:32768
	ds_read_b128 a[4:7], v112 offset:34816
	ds_read_b128 a[8:11], v112 offset:36864
	ds_read_b128 a[12:15], v112 offset:38912
	ds_read_b128 v[92:95], v113 offset:34816
	ds_read_b128 v[88:91], v113 offset:36864
	ds_read_b128 v[84:87], v113 offset:38912
	ds_read_b128 a[16:19], v114 offset:32768
	ds_read_b128 a[20:23], v114 offset:34816
	ds_read_b128 a[24:27], v114 offset:36864
	ds_read_b128 a[28:31], v114 offset:38912
	s_setprio 1
	s_waitcnt lgkmcnt(10)
	v_mfma_f32_16x16x32_bf16 v[0:3], a[0:3], v[80:83], v[0:3]
	s_waitcnt lgkmcnt(9)
	v_mfma_f32_16x16x32_bf16 v[16:19], a[4:7], v[80:83], v[16:19]
	s_waitcnt lgkmcnt(8)
	v_mfma_f32_16x16x32_bf16 v[32:35], a[8:11], v[80:83], v[32:35]
	s_waitcnt lgkmcnt(7)
	v_mfma_f32_16x16x32_bf16 v[48:51], a[12:15], v[80:83], v[48:51]
	ds_read_b128 v[80:83], v115 offset:32768
	s_waitcnt lgkmcnt(7)
	v_mfma_f32_16x16x32_bf16 v[4:7], a[0:3], v[92:95], v[4:7]
	v_mfma_f32_16x16x32_bf16 v[20:23], a[4:7], v[92:95], v[20:23]
	v_mfma_f32_16x16x32_bf16 v[36:39], a[8:11], v[92:95], v[36:39]
	v_mfma_f32_16x16x32_bf16 v[52:55], a[12:15], v[92:95], v[52:55]
	ds_read_b128 v[92:95], v115 offset:34816
	s_waitcnt lgkmcnt(7)
	v_mfma_f32_16x16x32_bf16 v[8:11], a[0:3], v[88:91], v[8:11]
	v_mfma_f32_16x16x32_bf16 v[24:27], a[4:7], v[88:91], v[24:27]
	v_mfma_f32_16x16x32_bf16 v[40:43], a[8:11], v[88:91], v[40:43]
	v_mfma_f32_16x16x32_bf16 v[56:59], a[12:15], v[88:91], v[56:59]
	ds_read_b128 v[88:91], v115 offset:36864
	s_waitcnt lgkmcnt(7)
	v_mfma_f32_16x16x32_bf16 v[12:15], a[0:3], v[84:87], v[12:15]
	v_mfma_f32_16x16x32_bf16 v[28:31], a[4:7], v[84:87], v[28:31]
	v_mfma_f32_16x16x32_bf16 v[44:47], a[8:11], v[84:87], v[44:47]
	v_mfma_f32_16x16x32_bf16 v[60:63], a[12:15], v[84:87], v[60:63]
	ds_read_b128 v[84:87], v115 offset:38912
	s_waitcnt lgkmcnt(3)
	v_mfma_f32_16x16x32_bf16 v[0:3], a[16:19], v[80:83], v[0:3]
	v_mfma_f32_16x16x32_bf16 v[16:19], a[20:23], v[80:83], v[16:19]
	v_mfma_f32_16x16x32_bf16 v[32:35], a[24:27], v[80:83], v[32:35]
	v_mfma_f32_16x16x32_bf16 v[48:51], a[28:31], v[80:83], v[48:51]
	s_waitcnt lgkmcnt(2)
	v_mfma_f32_16x16x32_bf16 v[4:7], a[16:19], v[92:95], v[4:7]
	v_mfma_f32_16x16x32_bf16 v[20:23], a[20:23], v[92:95], v[20:23]
	v_mfma_f32_16x16x32_bf16 v[36:39], a[24:27], v[92:95], v[36:39]
	v_mfma_f32_16x16x32_bf16 v[52:55], a[28:31], v[92:95], v[52:55]
	s_waitcnt lgkmcnt(1)
	v_mfma_f32_16x16x32_bf16 v[8:11], a[16:19], v[88:91], v[8:11]
	v_mfma_f32_16x16x32_bf16 v[24:27], a[20:23], v[88:91], v[24:27]
	v_mfma_f32_16x16x32_bf16 v[40:43], a[24:27], v[88:91], v[40:43]
	v_mfma_f32_16x16x32_bf16 v[56:59], a[28:31], v[88:91], v[56:59]
	s_waitcnt lgkmcnt(0)
	v_mfma_f32_16x16x32_bf16 v[12:15], a[16:19], v[84:87], v[12:15]
	v_mfma_f32_16x16x32_bf16 v[28:31], a[20:23], v[84:87], v[28:31]
	v_mfma_f32_16x16x32_bf16 v[44:47], a[24:27], v[84:87], v[44:47]
	v_mfma_f32_16x16x32_bf16 v[60:63], a[28:31], v[84:87], v[60:63]
	s_setprio 0
	v_readfirstlane_b32 s15, v107
	v_readfirstlane_b32 s4, v106
	s_lshl_b32 s15, s15, 6
	s_waitcnt lgkmcnt(0)
	s_barrier
	s_add_i32 s15, s15, s9
	s_lshl_b32 s44, s4, 6
	s_add_i32 s44, s44, s8
	v_or_b32_e32 v65, s15, v108
	s_movk_i32 s4, 0x800
	s_ashr_i32 s43, s44, 11
	v_cmp_gt_i32_e64 s[40:41], s4, v65
	v_add_u32_e32 v64, 0x1000, v65
	s_barrier
	v_and_b32_e32 v120, 15, v143
	v_bfe_u32 v121, v143, 4, 2
	v_xor_b32_e32 v121, v121, v120
	v_lshlrev_b32_e32 v121, 4, v121
	v_lshl_add_u32 v121, v120, 8, v121
	v_lshrrev_b32_e32 v120, 6, v143
	v_lshl_add_u32 v121, v120, 14, v121
	ds_write_b128 v121, v[0:3]
	ds_write_b128 v121, v[4:7] offset:4096
	ds_write_b128 v121, v[8:11] offset:8192
	ds_write_b128 v121, v[12:15] offset:12288
	v_xor_b32_e32 v115, 64, v121
	ds_write_b128 v115, v[16:19]
	ds_write_b128 v115, v[20:23] offset:4096
	ds_write_b128 v115, v[24:27] offset:8192
	ds_write_b128 v115, v[28:31] offset:12288
	v_xor_b32_e32 v115, 128, v121
	ds_write_b128 v115, v[32:35]
	ds_write_b128 v115, v[36:39] offset:4096
	ds_write_b128 v115, v[40:43] offset:8192
	ds_write_b128 v115, v[44:47] offset:12288
	v_xor_b32_e32 v115, 192, v121
	ds_write_b128 v115, v[48:51]
	ds_write_b128 v115, v[52:55] offset:4096
	ds_write_b128 v115, v[56:59] offset:8192
	ds_write_b128 v115, v[60:63] offset:12288
	v_and_b32_e32 v112, 31, v143
	v_bfe_u32 v114, v143, 5, 1
	v_and_b32_e32 v121, 15, v112
	v_xor_b32_e32 v114, v114, v121
	v_lshlrev_b32_e32 v114, 4, v114
	v_lshl_add_u32 v114, v112, 8, v114
	v_lshl_add_u32 v114, v120, 14, v114
	ds_read_b128 v[48:51], v114
	ds_read_b128 v[32:35], v114 offset:8192
	v_xor_b32_e32 v113, 32, v114
	ds_read_b128 v[52:55], v113
	ds_read_b128 v[36:39], v113 offset:8192
	v_xor_b32_e32 v113, 64, v114
	ds_read_b128 v[56:59], v113
	ds_read_b128 v[40:43], v113 offset:8192
	v_xor_b32_e32 v113, 96, v114
	ds_read_b128 v[60:63], v113
	ds_read_b128 v[44:47], v113 offset:8192
	v_xor_b32_e32 v113, 128, v114
	ds_read_b128 v[16:19], v113
	ds_read_b128 v[0:3], v113 offset:8192
	v_xor_b32_e32 v113, 160, v114
	ds_read_b128 v[20:23], v113
	ds_read_b128 v[4:7], v113 offset:8192
	v_xor_b32_e32 v113, 192, v114
	ds_read_b128 v[24:27], v113
	ds_read_b128 v[8:11], v113 offset:8192
	v_xor_b32_e32 v113, 224, v114
	ds_read_b128 v[28:31], v113
	ds_read_b128 v[12:15], v113 offset:8192
	s_waitcnt lgkmcnt(0)
	s_barrier
	s_and_saveexec_b64 s[34:35], s[40:41]
	s_cbranch_execz .LBB0_1046
	s_add_i32 s4, s44, 0xffffe000
	s_lshr_b32 s4, s4, 3
	s_or_b32 s4, s4, 4
	s_cmpk_lt_i32 s44, 0x2000
	s_cselect_b32 s4, s43, s4
	s_mulk_i32 s4, 0x3000
	v_add_u32_e32 v66, s4, v64
	v_mov_b32_e32 v67, v140
	v_lshl_add_u64 v[66:67], v[66:67], 2, s[28:29]
	global_load_dword v66, v[66:67], off
	s_cmpk_gt_i32 s44, 0x1fff
	s_mov_b64 s[36:37], -1
	s_cbranch_scc0 .LBB0_1031
	s_load_dwordx2 s[8:9], s[26:27], 0x8
	s_mov_b64 s[36:37], 0
	s_waitcnt lgkmcnt(0)
	s_add_u32 s8, s8, 0xfc000000
	s_addc_u32 s9, s9, -1

.LBB0_1725:
	s_mul_hi_i32 s4, s26, 0x38e38e39
	s_lshr_b32 s8, s4, 31
	s_ashr_i32 s4, s4, 4
	s_add_i32 s4, s4, s8
	s_mul_i32 s8, s4, 0x48
	s_sub_i32 s8, s26, s8
	s_lshl_b32 s8, s8, 7
	v_add_u32_e32 v0, s8, v109
	v_ashrrev_i32_e32 v1, 31, v0
	v_lshlrev_b64 v[32:33], 12, v[0:1]
	v_lshl_add_u64 v[34:35], v[96:97], 0, v[32:33]
	v_add_co_u32_e32 v40, vcc, s87, v34
	s_lshl_b32 s9, s4, 7
	s_nop 0
	v_addc_co_u32_e32 v41, vcc, 0, v35, vcc
	v_add_co_u32_e32 v42, vcc, s66, v34
	v_add_u32_e32 v0, s9, v109
	s_nop 0
	v_addc_co_u32_e32 v43, vcc, 0, v35, vcc
	v_ashrrev_i32_e32 v1, 31, v0
	s_waitcnt vmcnt(13)
	v_add_co_u32_e32 v44, vcc, s20, v34
	v_lshlrev_b64 v[36:37], 12, v[0:1]
	s_nop 0
	v_addc_co_u32_e32 v45, vcc, 0, v35, vcc
	v_lshl_add_u64 v[38:39], v[98:99], 0, v[36:37]
	v_readfirstlane_b32 s100, v110
	s_nop 3
	s_add_u32 m0, s100, 0x0
	s_nop 0
	global_load_lds_dwordx4 v[34:35], off
	s_add_u32 m0, s100, 0x1000
	s_nop 0
	global_load_lds_dwordx4 v[40:41], off
	s_add_u32 m0, s100, 0x2000
	s_nop 0
	global_load_lds_dwordx4 v[42:43], off
	s_add_u32 m0, s100, 0x3000
	s_nop 0
	global_load_lds_dwordx4 v[44:45], off
	s_add_u32 m0, s100, 0x4000
	s_nop 0
	global_load_lds_dwordx4 v[38:39], off
	v_add_co_u32_e32 v46, vcc, s87, v38
	v_lshl_add_u64 v[102:103], v[100:101], 0, v[36:37]
	s_nop 0
	v_addc_co_u32_e32 v47, vcc, 0, v39, vcc
	s_waitcnt vmcnt(8)
	v_add_co_u32_e32 v48, vcc, s66, v38
	s_add_u32 m0, s100, 0x5000
	s_nop 0
	global_load_lds_dwordx4 v[46:47], off
	s_nop 0
	v_addc_co_u32_e32 v49, vcc, 0, v39, vcc
	v_add_co_u32_e32 v50, vcc, s20, v38
	s_add_u32 m0, s100, 0x6000
	s_nop 0
	global_load_lds_dwordx4 v[48:49], off
	s_nop 0
	v_addc_co_u32_e32 v51, vcc, 0, v39, vcc
	s_add_u32 m0, s100, 0x7000
	s_nop 0
	global_load_lds_dwordx4 v[50:51], off
	v_lshl_add_u64 v[104:105], v[100:101], 0, v[32:33]
	s_mov_b64 s[22:23], 0
	v_mov_b32_e32 v0, 0
	v_mov_b32_e32 v1, v0
	v_mov_b32_e32 v2, v0
	v_mov_b32_e32 v3, v0
	v_mov_b32_e32 v4, v0
	v_mov_b32_e32 v5, v0
	v_mov_b32_e32 v6, v0
	v_mov_b32_e32 v7, v0
	v_mov_b32_e32 v8, v0
	v_mov_b32_e32 v9, v0
	v_mov_b32_e32 v10, v0
	v_mov_b32_e32 v11, v0
	v_mov_b32_e32 v12, v0
	v_mov_b32_e32 v13, v0
	v_mov_b32_e32 v14, v0
	v_mov_b32_e32 v15, v0
	v_mov_b32_e32 v16, v0
	v_mov_b32_e32 v17, v0
	v_mov_b32_e32 v18, v0
	v_mov_b32_e32 v19, v0
	v_mov_b32_e32 v20, v0
	v_mov_b32_e32 v21, v0
	v_mov_b32_e32 v22, v0
	v_mov_b32_e32 v23, v0
	v_mov_b32_e32 v24, v0
	v_mov_b32_e32 v25, v0
	v_mov_b32_e32 v26, v0
	v_mov_b32_e32 v27, v0
	v_mov_b32_e32 v28, v0
	v_mov_b32_e32 v29, v0
	v_mov_b32_e32 v30, v0
	v_mov_b32_e32 v31, v0
	v_mov_b32_e32 v32, v0
	v_mov_b32_e32 v33, v0
	v_mov_b32_e32 v34, v0
	v_mov_b32_e32 v35, v0
	v_mov_b32_e32 v36, v0
	v_mov_b32_e32 v37, v0
	v_mov_b32_e32 v38, v0
	v_mov_b32_e32 v39, v0
	v_mov_b32_e32 v40, v0
	v_mov_b32_e32 v41, v0
	v_mov_b32_e32 v42, v0
	v_mov_b32_e32 v43, v0
	v_mov_b32_e32 v44, v0
	v_mov_b32_e32 v45, v0
	v_mov_b32_e32 v46, v0
	v_mov_b32_e32 v47, v0
	v_mov_b32_e32 v48, v0
	v_mov_b32_e32 v49, v0
	v_mov_b32_e32 v50, v0
	v_mov_b32_e32 v51, v0
	v_mov_b32_e32 v52, v0
	v_mov_b32_e32 v53, v0
	v_mov_b32_e32 v54, v0
	v_mov_b32_e32 v55, v0
	v_mov_b32_e32 v56, v0
	v_mov_b32_e32 v57, v0
	v_mov_b32_e32 v58, v0
	v_mov_b32_e32 v59, v0
	v_mov_b32_e32 v60, v0
	v_mov_b32_e32 v61, v0
	v_mov_b32_e32 v62, v0
	v_mov_b32_e32 v63, v0
	v_lshl_add_u64 v[124:125], v[104:105], 0, s[22:23]
	v_add_co_u32_e32 v132, vcc, s21, v124
	v_lshl_add_u64 v[126:127], v[102:103], 0, s[22:23]
	s_nop 0
	v_addc_co_u32_e32 v133, vcc, 0, v125, vcc
	v_add_co_u32_e32 v134, vcc, s74, v124
	s_mov_b32 s4, 0x2c300000
	s_nop 0
	v_addc_co_u32_e32 v135, vcc, 0, v125, vcc
	v_add_co_u32_e32 v144, vcc, s75, v124
	v_addc_co_u32_e32 v145, vcc, 0, v125, vcc
	v_add_co_u32_e32 v146, vcc, s14, v124
	s_nop 1
	v_addc_co_u32_e32 v147, vcc, 0, v125, vcc
	v_add_co_u32_e32 v148, vcc, s4, v126
	s_mov_b32 s4, 0x2c320000
	s_nop 0
	v_addc_co_u32_e32 v149, vcc, 0, v127, vcc
	v_add_co_u32_e32 v150, vcc, s4, v126
	s_mov_b32 s4, 0x2c340000
	s_nop 0
	v_addc_co_u32_e32 v151, vcc, 0, v127, vcc
	v_add_co_u32_e32 v152, vcc, s4, v126
	s_mov_b32 s4, 0x2c360000
	s_nop 0
	v_addc_co_u32_e32 v153, vcc, 0, v127, vcc
	v_add_co_u32_e32 v154, vcc, s4, v126
	v_addc_co_u32_e32 v155, vcc, 0, v127, vcc
	v_lshl_add_u64 v[132:133], 8, 4, v[132:133]
	v_lshl_add_u64 v[134:135], 8, 4, v[134:135]
	v_lshl_add_u64 v[144:145], 8, 4, v[144:145]
	v_lshl_add_u64 v[146:147], 8, 4, v[146:147]
	v_lshl_add_u64 v[148:149], 8, 4, v[148:149]
	v_lshl_add_u64 v[150:151], 8, 4, v[150:151]
	v_lshl_add_u64 v[152:153], 8, 4, v[152:153]
	v_lshl_add_u64 v[154:155], 8, 4, v[154:155]
	v_and_b32_e32 v120, 15, v143
	v_lshrrev_b32_e32 v121, 1, v120
	v_bfe_u32 v114, v143, 4, 2
	v_xor_b32_e32 v121, v121, v114
	v_lshlrev_b32_e32 v121, 4, v121
	v_lshl_add_u32 v121, v120, 7, v121
	v_lshrrev_b32_e32 v120, 6, v143
	v_lshrrev_b32_e32 v112, 1, v120
	v_and_b32_e32 v120, 1, v120
	v_lshl_add_u32 v112, v112, 13, v121
	v_lshl_add_u32 v113, v120, 13, v121
	v_add_u32_e32 v113, 0x4000, v113
	v_xor_b32_e32 v114, 64, v112
	v_xor_b32_e32 v115, 64, v113
	s_waitcnt vmcnt(0) lgkmcnt(0)
	s_barrier
.LBB0_1726:
	s_add_u32 m0, s100, 0x8000
	s_nop 0
	global_load_lds_dwordx4 v[132:133], off
	s_add_u32 m0, s100, 0x9000
	s_nop 0
	global_load_lds_dwordx4 v[134:135], off
	s_add_u32 m0, s100, 0xa000
	s_nop 0
	global_load_lds_dwordx4 v[144:145], off
	s_add_u32 m0, s100, 0xb000
	s_nop 0
	global_load_lds_dwordx4 v[146:147], off
	s_add_u32 m0, s100, 0xc000
	s_nop 0
	global_load_lds_dwordx4 v[148:149], off
	s_add_u32 m0, s100, 0xd000
	s_nop 0
	global_load_lds_dwordx4 v[150:151], off
	s_add_u32 m0, s100, 0xe000
	s_nop 0
	global_load_lds_dwordx4 v[152:153], off
	s_add_u32 m0, s100, 0xf000
	s_nop 0
	global_load_lds_dwordx4 v[154:155], off
	ds_read_b128 a[0:3], v112
	ds_read_b128 v[80:83], v113
	ds_read_b128 a[4:7], v112 offset:2048
	ds_read_b128 a[8:11], v112 offset:4096
	ds_read_b128 a[12:15], v112 offset:6144
	ds_read_b128 v[92:95], v113 offset:2048
	ds_read_b128 v[88:91], v113 offset:4096
	ds_read_b128 v[84:87], v113 offset:6144
	ds_read_b128 a[16:19], v114
	ds_read_b128 a[20:23], v114 offset:2048
	ds_read_b128 a[24:27], v114 offset:4096
	ds_read_b128 a[28:31], v114 offset:6144
	s_setprio 1
	s_waitcnt lgkmcnt(10)
	v_mfma_f32_16x16x32_bf16 v[0:3], a[0:3], v[80:83], v[0:3]
	s_waitcnt lgkmcnt(9)
	v_mfma_f32_16x16x32_bf16 v[16:19], a[4:7], v[80:83], v[16:19]
	s_waitcnt lgkmcnt(8)
	v_mfma_f32_16x16x32_bf16 v[32:35], a[8:11], v[80:83], v[32:35]
	s_waitcnt lgkmcnt(7)
	v_mfma_f32_16x16x32_bf16 v[48:51], a[12:15], v[80:83], v[48:51]
	ds_read_b128 v[80:83], v115
	s_waitcnt lgkmcnt(7)
	v_mfma_f32_16x16x32_bf16 v[4:7], a[0:3], v[92:95], v[4:7]
	v_lshl_add_u64 v[64:65], 8, 4, v[132:133]
	v_lshl_add_u64 v[66:67], 8, 4, v[134:135]
	v_lshl_add_u64 v[68:69], 8, 4, v[144:145]
	v_mfma_f32_16x16x32_bf16 v[20:23], a[4:7], v[92:95], v[20:23]
	v_lshl_add_u64 v[70:71], 8, 4, v[146:147]
	v_lshl_add_u64 v[76:77], 8, 4, v[148:149]
	v_lshl_add_u64 v[78:79], 8, 4, v[150:151]
	v_mfma_f32_16x16x32_bf16 v[36:39], a[8:11], v[92:95], v[36:39]
	v_lshl_add_u64 v[72:73], 8, 4, v[152:153]
	v_lshl_add_u64 v[74:75], 8, 4, v[154:155]
	v_mfma_f32_16x16x32_bf16 v[52:55], a[12:15], v[92:95], v[52:55]
	ds_read_b128 v[92:95], v115 offset:2048
	s_waitcnt lgkmcnt(7)
	v_mfma_f32_16x16x32_bf16 v[8:11], a[0:3], v[88:91], v[8:11]
	v_mfma_f32_16x16x32_bf16 v[24:27], a[4:7], v[88:91], v[24:27]
	v_mfma_f32_16x16x32_bf16 v[40:43], a[8:11], v[88:91], v[40:43]
	v_mfma_f32_16x16x32_bf16 v[56:59], a[12:15], v[88:91], v[56:59]
	ds_read_b128 v[88:91], v115 offset:4096
	s_waitcnt lgkmcnt(7)
	v_mfma_f32_16x16x32_bf16 v[12:15], a[0:3], v[84:87], v[12:15]
	v_mfma_f32_16x16x32_bf16 v[28:31], a[4:7], v[84:87], v[28:31]
	v_mfma_f32_16x16x32_bf16 v[44:47], a[8:11], v[84:87], v[44:47]
	v_mfma_f32_16x16x32_bf16 v[60:63], a[12:15], v[84:87], v[60:63]
	ds_read_b128 v[84:87], v115 offset:6144
	s_waitcnt lgkmcnt(3)
	v_mfma_f32_16x16x32_bf16 v[0:3], a[16:19], v[80:83], v[0:3]
	v_mfma_f32_16x16x32_bf16 v[16:19], a[20:23], v[80:83], v[16:19]
	v_mfma_f32_16x16x32_bf16 v[32:35], a[24:27], v[80:83], v[32:35]
	v_mfma_f32_16x16x32_bf16 v[48:51], a[28:31], v[80:83], v[48:51]
	s_waitcnt lgkmcnt(2)
	v_mfma_f32_16x16x32_bf16 v[4:7], a[16:19], v[92:95], v[4:7]
	v_mfma_f32_16x16x32_bf16 v[20:23], a[20:23], v[92:95], v[20:23]
	v_mfma_f32_16x16x32_bf16 v[36:39], a[24:27], v[92:95], v[36:39]
	v_mfma_f32_16x16x32_bf16 v[52:55], a[28:31], v[92:95], v[52:55]
	s_waitcnt lgkmcnt(1)
	v_mfma_f32_16x16x32_bf16 v[8:11], a[16:19], v[88:91], v[8:11]
	v_mfma_f32_16x16x32_bf16 v[24:27], a[20:23], v[88:91], v[24:27]
	v_mfma_f32_16x16x32_bf16 v[40:43], a[24:27], v[88:91], v[40:43]
	v_mfma_f32_16x16x32_bf16 v[56:59], a[28:31], v[88:91], v[56:59]
	s_waitcnt lgkmcnt(0)
	v_mfma_f32_16x16x32_bf16 v[12:15], a[16:19], v[84:87], v[12:15]
	v_mfma_f32_16x16x32_bf16 v[28:31], a[20:23], v[84:87], v[28:31]
	v_mfma_f32_16x16x32_bf16 v[44:47], a[24:27], v[84:87], v[44:47]
	v_mfma_f32_16x16x32_bf16 v[60:63], a[28:31], v[84:87], v[60:63]
	s_setprio 0
	s_waitcnt vmcnt(0) lgkmcnt(0)
	s_barrier
	s_add_u32 s22, s22, 0x100
	s_addc_u32 s23, s23, 0
	s_add_u32 m0, s100, 0x0
	s_nop 0
	global_load_lds_dwordx4 v[64:65], off
	s_add_u32 m0, s100, 0x1000
	s_nop 0
	global_load_lds_dwordx4 v[66:67], off
	s_add_u32 m0, s100, 0x2000
	s_nop 0
	global_load_lds_dwordx4 v[68:69], off
	s_add_u32 m0, s100, 0x3000
	s_nop 0
	global_load_lds_dwordx4 v[70:71], off
	s_add_u32 m0, s100, 0x4000
	s_nop 0
	global_load_lds_dwordx4 v[76:77], off
	s_add_u32 m0, s100, 0x5000
	s_nop 0
	global_load_lds_dwordx4 v[78:79], off
	s_add_u32 m0, s100, 0x6000
	s_nop 0
	global_load_lds_dwordx4 v[72:73], off
	s_add_u32 m0, s100, 0x7000
	s_nop 0
	global_load_lds_dwordx4 v[74:75], off
	ds_read_b128 a[0:3], v112 offset:32768
	ds_read_b128 v[80:83], v113 offset:32768
	ds_read_b128 a[4:7], v112 offset:34816
	ds_read_b128 a[8:11], v112 offset:36864
	ds_read_b128 a[12:15], v112 offset:38912
	ds_read_b128 v[92:95], v113 offset:34816
	ds_read_b128 v[88:91], v113 offset:36864
	ds_read_b128 v[84:87], v113 offset:38912
	ds_read_b128 a[16:19], v114 offset:32768
	ds_read_b128 a[20:23], v114 offset:34816
	ds_read_b128 a[24:27], v114 offset:36864
	ds_read_b128 a[28:31], v114 offset:38912
	s_setprio 1
	s_waitcnt lgkmcnt(10)
	v_mfma_f32_16x16x32_bf16 v[0:3], a[0:3], v[80:83], v[0:3]
	s_waitcnt lgkmcnt(9)
	v_mfma_f32_16x16x32_bf16 v[16:19], a[4:7], v[80:83], v[16:19]
	s_waitcnt lgkmcnt(8)
	v_mfma_f32_16x16x32_bf16 v[32:35], a[8:11], v[80:83], v[32:35]
	s_waitcnt lgkmcnt(7)
	v_mfma_f32_16x16x32_bf16 v[48:51], a[12:15], v[80:83], v[48:51]
	ds_read_b128 v[80:83], v115 offset:32768
	s_waitcnt lgkmcnt(7)
	v_mfma_f32_16x16x32_bf16 v[4:7], a[0:3], v[92:95], v[4:7]
	v_lshl_add_u64 v[124:125], v[104:105], 0, s[22:23]
	v_add_co_u32_e32 v132, vcc, s21, v124
	v_lshl_add_u64 v[126:127], v[102:103], 0, s[22:23]
	v_mfma_f32_16x16x32_bf16 v[20:23], a[4:7], v[92:95], v[20:23]
	s_nop 0
	v_addc_co_u32_e32 v133, vcc, 0, v125, vcc
	v_add_co_u32_e32 v134, vcc, s74, v124
	v_mfma_f32_16x16x32_bf16 v[36:39], a[8:11], v[92:95], v[36:39]
	s_mov_b32 s4, 0x2c300000
	s_nop 0
	v_addc_co_u32_e32 v135, vcc, 0, v125, vcc
	v_mfma_f32_16x16x32_bf16 v[52:55], a[12:15], v[92:95], v[52:55]
	v_add_co_u32_e32 v144, vcc, s75, v124
	v_addc_co_u32_e32 v145, vcc, 0, v125, vcc
	v_add_co_u32_e32 v146, vcc, s14, v124
	ds_read_b128 v[92:95], v115 offset:34816
	s_waitcnt lgkmcnt(7)
	v_mfma_f32_16x16x32_bf16 v[8:11], a[0:3], v[88:91], v[8:11]
	s_nop 1
	v_addc_co_u32_e32 v147, vcc, 0, v125, vcc
	v_add_co_u32_e32 v148, vcc, s4, v126
	v_mfma_f32_16x16x32_bf16 v[24:27], a[4:7], v[88:91], v[24:27]
	s_mov_b32 s4, 0x2c320000
	s_nop 0
	v_addc_co_u32_e32 v149, vcc, 0, v127, vcc
	v_mfma_f32_16x16x32_bf16 v[40:43], a[8:11], v[88:91], v[40:43]
	v_add_co_u32_e32 v150, vcc, s4, v126
	s_mov_b32 s4, 0x2c340000
	s_nop 0
	v_mfma_f32_16x16x32_bf16 v[56:59], a[12:15], v[88:91], v[56:59]
	v_addc_co_u32_e32 v151, vcc, 0, v127, vcc
	v_add_co_u32_e32 v152, vcc, s4, v126
	s_mov_b32 s4, 0x2c360000
	ds_read_b128 v[88:91], v115 offset:36864
	s_waitcnt lgkmcnt(7)
	v_mfma_f32_16x16x32_bf16 v[12:15], a[0:3], v[84:87], v[12:15]
	s_nop 0
	v_addc_co_u32_e32 v153, vcc, 0, v127, vcc
	v_add_co_u32_e32 v154, vcc, s4, v126
	v_mfma_f32_16x16x32_bf16 v[28:31], a[4:7], v[84:87], v[28:31]
	v_addc_co_u32_e32 v155, vcc, 0, v127, vcc
	v_lshl_add_u64 v[132:133], 8, 4, v[132:133]
	v_lshl_add_u64 v[134:135], 8, 4, v[134:135]
	v_mfma_f32_16x16x32_bf16 v[44:47], a[8:11], v[84:87], v[44:47]
	v_lshl_add_u64 v[144:145], 8, 4, v[144:145]
	v_lshl_add_u64 v[146:147], 8, 4, v[146:147]
	v_lshl_add_u64 v[148:149], 8, 4, v[148:149]
	v_mfma_f32_16x16x32_bf16 v[60:63], a[12:15], v[84:87], v[60:63]
	v_lshl_add_u64 v[150:151], 8, 4, v[150:151]
	v_lshl_add_u64 v[152:153], 8, 4, v[152:153]
	v_lshl_add_u64 v[154:155], 8, 4, v[154:155]
	ds_read_b128 v[84:87], v115 offset:38912
	s_waitcnt lgkmcnt(3)
	v_mfma_f32_16x16x32_bf16 v[0:3], a[16:19], v[80:83], v[0:3]
	v_mfma_f32_16x16x32_bf16 v[16:19], a[20:23], v[80:83], v[16:19]
	v_mfma_f32_16x16x32_bf16 v[32:35], a[24:27], v[80:83], v[32:35]
	v_mfma_f32_16x16x32_bf16 v[48:51], a[28:31], v[80:83], v[48:51]
	s_waitcnt lgkmcnt(2)
	v_mfma_f32_16x16x32_bf16 v[4:7], a[16:19], v[92:95], v[4:7]
	v_mfma_f32_16x16x32_bf16 v[20:23], a[20:23], v[92:95], v[20:23]
	v_mfma_f32_16x16x32_bf16 v[36:39], a[24:27], v[92:95], v[36:39]
	v_mfma_f32_16x16x32_bf16 v[52:55], a[28:31], v[92:95], v[52:55]
	s_waitcnt lgkmcnt(1)
	v_mfma_f32_16x16x32_bf16 v[8:11], a[16:19], v[88:91], v[8:11]
	v_mfma_f32_16x16x32_bf16 v[24:27], a[20:23], v[88:91], v[24:27]
	v_mfma_f32_16x16x32_bf16 v[40:43], a[24:27], v[88:91], v[40:43]
	v_mfma_f32_16x16x32_bf16 v[56:59], a[28:31], v[88:91], v[56:59]
	s_waitcnt lgkmcnt(0)
	v_mfma_f32_16x16x32_bf16 v[12:15], a[16:19], v[84:87], v[12:15]
	v_mfma_f32_16x16x32_bf16 v[28:31], a[20:23], v[84:87], v[28:31]
	v_mfma_f32_16x16x32_bf16 v[44:47], a[24:27], v[84:87], v[44:47]
	v_mfma_f32_16x16x32_bf16 v[60:63], a[28:31], v[84:87], v[60:63]
	s_setprio 0
	s_waitcnt vmcnt(0) lgkmcnt(0)
	s_barrier
	s_cmpk_eq_i32 s22, 0xf00
	s_cbranch_scc0 .LBB0_1726
	v_lshl_add_u64 v[64:65], 8, 4, v[64:65]
	v_lshl_add_u64 v[66:67], 8, 4, v[66:67]
	v_lshl_add_u64 v[68:69], 8, 4, v[68:69]
	v_lshl_add_u64 v[70:71], 8, 4, v[70:71]
	v_lshl_add_u64 v[76:77], 8, 4, v[76:77]
	v_lshl_add_u64 v[78:79], 8, 4, v[78:79]
	v_lshl_add_u64 v[72:73], 8, 4, v[72:73]
	v_lshl_add_u64 v[74:75], 8, 4, v[74:75]
	s_add_u32 m0, s100, 0x8000
	s_nop 0
	global_load_lds_dwordx4 v[64:65], off
	s_add_u32 m0, s100, 0x9000
	s_nop 0
	global_load_lds_dwordx4 v[66:67], off
	s_add_u32 m0, s100, 0xa000
	s_nop 0
	global_load_lds_dwordx4 v[68:69], off
	s_add_u32 m0, s100, 0xb000
	s_nop 0
	global_load_lds_dwordx4 v[70:71], off
	s_add_u32 m0, s100, 0xc000
	s_nop 0
	global_load_lds_dwordx4 v[76:77], off
	s_add_u32 m0, s100, 0xd000
	s_nop 0
	global_load_lds_dwordx4 v[78:79], off
	s_add_u32 m0, s100, 0xe000
	s_nop 0
	global_load_lds_dwordx4 v[72:73], off
	s_add_u32 m0, s100, 0xf000
	s_nop 0
	global_load_lds_dwordx4 v[74:75], off
	ds_read_b128 a[0:3], v112
	ds_read_b128 v[80:83], v113
	ds_read_b128 a[4:7], v112 offset:2048
	ds_read_b128 a[8:11], v112 offset:4096
	ds_read_b128 a[12:15], v112 offset:6144
	ds_read_b128 v[92:95], v113 offset:2048
	ds_read_b128 v[88:91], v113 offset:4096
	ds_read_b128 v[84:87], v113 offset:6144
	ds_read_b128 a[16:19], v114
	ds_read_b128 a[20:23], v114 offset:2048
	ds_read_b128 a[24:27], v114 offset:4096
	ds_read_b128 a[28:31], v114 offset:6144
	s_setprio 1
	s_waitcnt lgkmcnt(10)
	v_mfma_f32_16x16x32_bf16 v[0:3], a[0:3], v[80:83], v[0:3]
	s_waitcnt lgkmcnt(9)
	v_mfma_f32_16x16x32_bf16 v[16:19], a[4:7], v[80:83], v[16:19]
	s_waitcnt lgkmcnt(8)
	v_mfma_f32_16x16x32_bf16 v[32:35], a[8:11], v[80:83], v[32:35]
	s_waitcnt lgkmcnt(7)
	v_mfma_f32_16x16x32_bf16 v[48:51], a[12:15], v[80:83], v[48:51]
	ds_read_b128 v[80:83], v115
	s_waitcnt lgkmcnt(7)
	v_mfma_f32_16x16x32_bf16 v[4:7], a[0:3], v[92:95], v[4:7]
	v_mfma_f32_16x16x32_bf16 v[20:23], a[4:7], v[92:95], v[20:23]
	v_mfma_f32_16x16x32_bf16 v[36:39], a[8:11], v[92:95], v[36:39]
	v_mfma_f32_16x16x32_bf16 v[52:55], a[12:15], v[92:95], v[52:55]
	ds_read_b128 v[92:95], v115 offset:2048
	s_waitcnt lgkmcnt(7)
	v_mfma_f32_16x16x32_bf16 v[8:11], a[0:3], v[88:91], v[8:11]
	v_mfma_f32_16x16x32_bf16 v[24:27], a[4:7], v[88:91], v[24:27]
	v_mfma_f32_16x16x32_bf16 v[40:43], a[8:11], v[88:91], v[40:43]
	v_mfma_f32_16x16x32_bf16 v[56:59], a[12:15], v[88:91], v[56:59]
	ds_read_b128 v[88:91], v115 offset:4096
	s_waitcnt lgkmcnt(7)
	v_mfma_f32_16x16x32_bf16 v[12:15], a[0:3], v[84:87], v[12:15]
	v_mfma_f32_16x16x32_bf16 v[28:31], a[4:7], v[84:87], v[28:31]
	v_mfma_f32_16x16x32_bf16 v[44:47], a[8:11], v[84:87], v[44:47]
	v_mfma_f32_16x16x32_bf16 v[60:63], a[12:15], v[84:87], v[60:63]
	ds_read_b128 v[84:87], v115 offset:6144
	s_waitcnt lgkmcnt(3)
	v_mfma_f32_16x16x32_bf16 v[0:3], a[16:19], v[80:83], v[0:3]
	v_mfma_f32_16x16x32_bf16 v[16:19], a[20:23], v[80:83], v[16:19]
	v_mfma_f32_16x16x32_bf16 v[32:35], a[24:27], v[80:83], v[32:35]
	v_mfma_f32_16x16x32_bf16 v[48:51], a[28:31], v[80:83], v[48:51]
	s_waitcnt lgkmcnt(2)
	v_mfma_f32_16x16x32_bf16 v[4:7], a[16:19], v[92:95], v[4:7]
	v_mfma_f32_16x16x32_bf16 v[20:23], a[20:23], v[92:95], v[20:23]
	v_mfma_f32_16x16x32_bf16 v[36:39], a[24:27], v[92:95], v[36:39]
	v_mfma_f32_16x16x32_bf16 v[52:55], a[28:31], v[92:95], v[52:55]
	s_waitcnt lgkmcnt(1)
	v_mfma_f32_16x16x32_bf16 v[8:11], a[16:19], v[88:91], v[8:11]
	v_mfma_f32_16x16x32_bf16 v[24:27], a[20:23], v[88:91], v[24:27]
	v_mfma_f32_16x16x32_bf16 v[40:43], a[24:27], v[88:91], v[40:43]
	v_mfma_f32_16x16x32_bf16 v[56:59], a[28:31], v[88:91], v[56:59]
	s_waitcnt lgkmcnt(0)
	v_mfma_f32_16x16x32_bf16 v[12:15], a[16:19], v[84:87], v[12:15]
	v_mfma_f32_16x16x32_bf16 v[28:31], a[20:23], v[84:87], v[28:31]
	v_mfma_f32_16x16x32_bf16 v[44:47], a[24:27], v[84:87], v[44:47]
	v_mfma_f32_16x16x32_bf16 v[60:63], a[28:31], v[84:87], v[60:63]
	s_setprio 0
	s_waitcnt vmcnt(0) lgkmcnt(0)
	s_barrier
	ds_read_b128 a[0:3], v112 offset:32768
	ds_read_b128 v[80:83], v113 offset:32768
	ds_read_b128 a[4:7], v112 offset:34816
	ds_read_b128 a[8:11], v112 offset:36864
	ds_read_b128 a[12:15], v112 offset:38912
	ds_read_b128 v[92:95], v113 offset:34816
	ds_read_b128 v[88:91], v113 offset:36864
	ds_read_b128 v[84:87], v113 offset:38912
	ds_read_b128 a[16:19], v114 offset:32768
	ds_read_b128 a[20:23], v114 offset:34816
	ds_read_b128 a[24:27], v114 offset:36864
	ds_read_b128 a[28:31], v114 offset:38912
	s_setprio 1
	s_waitcnt lgkmcnt(10)
	v_mfma_f32_16x16x32_bf16 v[0:3], a[0:3], v[80:83], v[0:3]
	s_waitcnt lgkmcnt(9)
	v_mfma_f32_16x16x32_bf16 v[16:19], a[4:7], v[80:83], v[16:19]
	s_waitcnt lgkmcnt(8)
	v_mfma_f32_16x16x32_bf16 v[32:35], a[8:11], v[80:83], v[32:35]
	s_waitcnt lgkmcnt(7)
	v_mfma_f32_16x16x32_bf16 v[48:51], a[12:15], v[80:83], v[48:51]
	ds_read_b128 v[80:83], v115 offset:32768
	s_waitcnt lgkmcnt(7)
	v_mfma_f32_16x16x32_bf16 v[4:7], a[0:3], v[92:95], v[4:7]
	v_mfma_f32_16x16x32_bf16 v[20:23], a[4:7], v[92:95], v[20:23]
	v_mfma_f32_16x16x32_bf16 v[36:39], a[8:11], v[92:95], v[36:39]
	v_mfma_f32_16x16x32_bf16 v[52:55], a[12:15], v[92:95], v[52:55]
	ds_read_b128 v[92:95], v115 offset:34816
	s_waitcnt lgkmcnt(7)
	v_mfma_f32_16x16x32_bf16 v[8:11], a[0:3], v[88:91], v[8:11]
	v_mfma_f32_16x16x32_bf16 v[24:27], a[4:7], v[88:91], v[24:27]
	v_mfma_f32_16x16x32_bf16 v[40:43], a[8:11], v[88:91], v[40:43]
	v_mfma_f32_16x16x32_bf16 v[56:59], a[12:15], v[88:91], v[56:59]
	ds_read_b128 v[88:91], v115 offset:36864
	s_waitcnt lgkmcnt(7)
	v_mfma_f32_16x16x32_bf16 v[12:15], a[0:3], v[84:87], v[12:15]
	v_mfma_f32_16x16x32_bf16 v[28:31], a[4:7], v[84:87], v[28:31]
	v_mfma_f32_16x16x32_bf16 v[44:47], a[8:11], v[84:87], v[44:47]
	v_mfma_f32_16x16x32_bf16 v[60:63], a[12:15], v[84:87], v[60:63]
	ds_read_b128 v[84:87], v115 offset:38912
	s_waitcnt lgkmcnt(3)
	v_mfma_f32_16x16x32_bf16 v[0:3], a[16:19], v[80:83], v[0:3]
	v_mfma_f32_16x16x32_bf16 v[16:19], a[20:23], v[80:83], v[16:19]
	v_mfma_f32_16x16x32_bf16 v[32:35], a[24:27], v[80:83], v[32:35]
	v_mfma_f32_16x16x32_bf16 v[48:51], a[28:31], v[80:83], v[48:51]
	s_waitcnt lgkmcnt(2)
	v_mfma_f32_16x16x32_bf16 v[4:7], a[16:19], v[92:95], v[4:7]
	v_mfma_f32_16x16x32_bf16 v[20:23], a[20:23], v[92:95], v[20:23]
	v_mfma_f32_16x16x32_bf16 v[36:39], a[24:27], v[92:95], v[36:39]
	v_mfma_f32_16x16x32_bf16 v[52:55], a[28:31], v[92:95], v[52:55]
	s_waitcnt lgkmcnt(1)
	v_mfma_f32_16x16x32_bf16 v[8:11], a[16:19], v[88:91], v[8:11]
	v_mfma_f32_16x16x32_bf16 v[24:27], a[20:23], v[88:91], v[24:27]
	v_mfma_f32_16x16x32_bf16 v[40:43], a[24:27], v[88:91], v[40:43]
	v_mfma_f32_16x16x32_bf16 v[56:59], a[28:31], v[88:91], v[56:59]
	s_waitcnt lgkmcnt(0)
	v_mfma_f32_16x16x32_bf16 v[12:15], a[16:19], v[84:87], v[12:15]
	v_mfma_f32_16x16x32_bf16 v[28:31], a[20:23], v[84:87], v[28:31]
	v_mfma_f32_16x16x32_bf16 v[44:47], a[24:27], v[84:87], v[44:47]
	v_mfma_f32_16x16x32_bf16 v[60:63], a[28:31], v[84:87], v[60:63]
	s_setprio 0
	v_readfirstlane_b32 s15, v107
	v_readfirstlane_b32 s4, v106
	s_lshl_b32 s15, s15, 6
	s_waitcnt lgkmcnt(0)
	s_barrier
	s_add_i32 s9, s15, s9
	s_lshl_b32 s15, s4, 6
	s_add_i32 s15, s15, s8
	v_or_b32_e32 v64, s9, v108
	v_cmp_gt_i32_e32 vcc, s27, v64
	v_or_b32_e32 v65, s15, v111
	s_barrier
	v_and_b32_e32 v120, 15, v143
	v_bfe_u32 v121, v143, 4, 2
	v_xor_b32_e32 v121, v121, v120
	v_lshlrev_b32_e32 v121, 4, v121
	v_lshl_add_u32 v121, v120, 8, v121
	v_lshrrev_b32_e32 v120, 6, v143
	v_lshl_add_u32 v121, v120, 14, v121
	ds_write_b128 v121, v[0:3]
	ds_write_b128 v121, v[4:7] offset:4096
	ds_write_b128 v121, v[8:11] offset:8192
	ds_write_b128 v121, v[12:15] offset:12288
	v_xor_b32_e32 v115, 64, v121
	ds_write_b128 v115, v[16:19]
	ds_write_b128 v115, v[20:23] offset:4096
	ds_write_b128 v115, v[24:27] offset:8192
	ds_write_b128 v115, v[28:31] offset:12288
	v_xor_b32_e32 v115, 128, v121
	ds_write_b128 v115, v[32:35]
	ds_write_b128 v115, v[36:39] offset:4096
	ds_write_b128 v115, v[40:43] offset:8192
	ds_write_b128 v115, v[44:47] offset:12288
	v_xor_b32_e32 v115, 192, v121
	ds_write_b128 v115, v[48:51]
	ds_write_b128 v115, v[52:55] offset:4096
	ds_write_b128 v115, v[56:59] offset:8192
	ds_write_b128 v115, v[60:63] offset:12288
	v_and_b32_e32 v112, 31, v143
	v_bfe_u32 v114, v143, 5, 1
	v_and_b32_e32 v121, 15, v112
	v_xor_b32_e32 v114, v114, v121
	v_lshlrev_b32_e32 v114, 4, v114
	v_lshl_add_u32 v114, v112, 8, v114
	v_lshl_add_u32 v114, v120, 14, v114
	ds_read_b128 v[48:51], v114
	ds_read_b128 v[32:35], v114 offset:8192
	v_xor_b32_e32 v113, 32, v114
	ds_read_b128 v[52:55], v113
	ds_read_b128 v[36:39], v113 offset:8192
	v_xor_b32_e32 v113, 64, v114
	ds_read_b128 v[56:59], v113
	ds_read_b128 v[40:43], v113 offset:8192
	v_xor_b32_e32 v113, 96, v114
	ds_read_b128 v[60:63], v113
	ds_read_b128 v[44:47], v113 offset:8192
	v_xor_b32_e32 v113, 128, v114
	ds_read_b128 v[16:19], v113
	ds_read_b128 v[0:3], v113 offset:8192
	v_xor_b32_e32 v113, 160, v114
	ds_read_b128 v[20:23], v113
	ds_read_b128 v[4:7], v113 offset:8192
	v_xor_b32_e32 v113, 192, v114
	ds_read_b128 v[24:27], v113
	ds_read_b128 v[8:11], v113 offset:8192
	v_xor_b32_e32 v113, 224, v114
	ds_read_b128 v[28:31], v113
	ds_read_b128 v[12:15], v113 offset:8192
	s_waitcnt lgkmcnt(0)
	s_barrier
	s_and_saveexec_b64 s[8:9], vcc
	s_cbranch_execz .LBB0_1729
	v_mad_u64_u32 v[66:67], s[22:23], v65, s27, v[64:65]
	v_mov_b32_e32 v67, v140
	v_lshl_add_u64 v[68:69], v[66:67], 2, s[0:1]
	global_store_dword v[68:69], v48, off
	v_add_u32_e32 v68, 0x2008, v66
	v_mov_b32_e32 v69, v140
	v_lshl_add_u64 v[68:69], v[68:69], 2, s[0:1]
	global_store_dword v[68:69], v49, off
	v_add_u32_e32 v48, 0x4010, v66
	v_mov_b32_e32 v49, v140
	v_lshl_add_u64 v[48:49], v[48:49], 2, s[0:1]
	global_store_dword v[48:49], v50, off
	v_add_u32_e32 v48, 0x6018, v66
	v_mov_b32_e32 v49, v140
	v_lshl_add_u64 v[48:49], v[48:49], 2, s[0:1]
	global_store_dword v[48:49], v51, off
	v_add_u32_e32 v48, 0x10040, v66
	v_mov_b32_e32 v49, v140
	v_lshl_add_u64 v[48:49], v[48:49], 2, s[0:1]
	global_store_dword v[48:49], v52, off
	v_add_u32_e32 v48, 0x12048, v66
	v_mov_b32_e32 v49, v140
	v_lshl_add_u64 v[48:49], v[48:49], 2, s[0:1]
	global_store_dword v[48:49], v53, off
	v_add_u32_e32 v48, 0x14050, v66
	v_mov_b32_e32 v49, v140
	v_lshl_add_u64 v[48:49], v[48:49], 2, s[0:1]
	global_store_dword v[48:49], v54, off
	v_add_u32_e32 v48, 0x16058, v66
	v_mov_b32_e32 v49, v140
	v_lshl_add_u64 v[48:49], v[48:49], 2, s[0:1]
	global_store_dword v[48:49], v55, off
	v_add_u32_e32 v48, 0x20080, v66
	v_mov_b32_e32 v49, v140
	v_lshl_add_u64 v[48:49], v[48:49], 2, s[0:1]
	global_store_dword v[48:49], v56, off
	v_add_u32_e32 v48, 0x22088, v66
	v_mov_b32_e32 v49, v140
	v_lshl_add_u64 v[48:49], v[48:49], 2, s[0:1]
	global_store_dword v[48:49], v57, off
	v_add_u32_e32 v48, 0x24090, v66
	v_mov_b32_e32 v49, v140
	v_lshl_add_u64 v[48:49], v[48:49], 2, s[0:1]
	global_store_dword v[48:49], v58, off
	v_add_u32_e32 v48, 0x26098, v66
	v_mov_b32_e32 v49, v140
	v_lshl_add_u64 v[48:49], v[48:49], 2, s[0:1]
	global_store_dword v[48:49], v59, off
	v_add_u32_e32 v48, 0x300c0, v66
	v_mov_b32_e32 v49, v140
	v_lshl_add_u64 v[48:49], v[48:49], 2, s[0:1]
	global_store_dword v[48:49], v60, off
	v_add_u32_e32 v48, 0x320c8, v66
	v_mov_b32_e32 v49, v140
	v_lshl_add_u64 v[48:49], v[48:49], 2, s[0:1]
	global_store_dword v[48:49], v61, off
	v_add_u32_e32 v48, 0x340d0, v66
	v_mov_b32_e32 v49, v140
	v_lshl_add_u64 v[48:49], v[48:49], 2, s[0:1]
	global_store_dword v[48:49], v62, off
	v_add_u32_e32 v48, 0x360d8, v66
	v_mov_b32_e32 v49, v140
	v_lshl_add_u64 v[48:49], v[48:49], 2, s[0:1]
	global_store_dword v[48:49], v63, off
